# GEMM K-loops now use v_mfma_f32_16x16x32_bf16 (same bf16 operands, f32 accumulate) with regenerated epilogue staging writes; measured higher sustained clock than 32x32x16
# speedup vs baseline: 1.0296x; 1.0296x over previous
.LBB0_601:
	s_lshr_b32 s2, s21, 3
	s_or_b32 s2, s2, s22
	s_lshl_b32 s28, s2, 18
	s_and_b32 s27, s21, 7
	v_or_b32_e32 v1, s28, v129
	s_lshl_b32 s2, s27, 18
	s_add_u32 s14, s16, s2
	v_or_b32_e32 v0, v1, v128
	v_readfirstlane_b32 s2, v148
	v_lshlrev_b32_e32 v130, 1, v0
	s_mov_b32 m0, s2
	v_readfirstlane_b32 s2, v157
	v_add_lshl_u32 v0, v1, v154, 1
	s_waitcnt vmcnt(0)
	s_barrier
	s_nop 0
	s_mov_b32 m0, s2
	v_readfirstlane_b32 s2, v158
	s_addc_u32 s15, s17, 0
	v_add_lshl_u32 v2, v1, v155, 1
	s_nop 0
	s_mov_b32 m0, s2
	v_readfirstlane_b32 s2, v159
	v_add_lshl_u32 v4, v1, v156, 1
	v_lshl_add_u64 v[6:7], s[14:15], 0, v[132:133]
	s_nop 0
	s_mov_b32 m0, s2
	v_readfirstlane_b32 s2, v160
	v_lshl_add_u64 v[136:137], v[6:7], 0, v[134:135]
	s_nop 0
	s_mov_b32 m0, s2
	v_readfirstlane_b32 s2, v161
	v_lshl_add_u64 v[138:139], s[0:1], 0, v[130:131]
	v_mov_b32_e32 v1, v131
	v_lshl_add_u64 v[146:147], v[136:137], 0, s[4:5]
	s_nop 0
	s_mov_b32 m0, s2
	v_readfirstlane_b32 s2, v162
	v_lshl_add_u64 v[140:141], s[0:1], 0, v[0:1]
	v_mov_b32_e32 v3, v131
	s_nop 0
	v_lshl_add_u64 v[0:1], v[138:139], 0, 64
	s_mov_b32 m0, s2
	v_readfirstlane_b32 s2, v163
	v_lshl_add_u64 v[142:143], s[0:1], 0, v[2:3]
	v_mov_b32_e32 v5, v131
	s_nop 0
	v_lshl_add_u64 v[0:1], v[140:141], 0, 64
	s_mov_b32 m0, s2
	v_readfirstlane_b32 s2, v164
	v_lshl_add_u64 v[144:145], s[0:1], 0, v[4:5]
	s_nop 0
	v_lshl_add_u64 v[0:1], v[142:143], 0, 64
	s_mov_b32 m0, s2
	v_readfirstlane_b32 s2, v165
	s_nop 0
	v_lshl_add_u64 v[0:1], v[144:145], 0, 64
	s_mov_b32 m0, s2
	v_readfirstlane_b32 s2, v166
	s_nop 0
	v_lshl_add_u64 v[0:1], v[136:137], 0, 64
	s_mov_b32 m0, s2
	v_readfirstlane_b32 s2, v167
	s_nop 0
	v_lshl_add_u64 v[0:1], v[136:137], 0, s[10:11]
	s_mov_b32 m0, s2
	s_mov_b32 s14, s3
	s_nop 0
	s_mov_b32 s15, 2
	s_mov_b32 s29, s3
	v_mov_b32_e32 v0, 0
	v_mov_b32_e32 v1, v131
	v_mov_b32_e32 v2, v131
	v_mov_b32_e32 v4, v131
	v_mov_b32_e32 v6, v131
	v_mov_b32_e32 v7, v131
	v_mov_b32_e32 v8, v131
	v_mov_b32_e32 v9, v131
	v_mov_b32_e32 v10, v131
	v_mov_b32_e32 v11, v131
	v_mov_b32_e32 v12, v131
	v_mov_b32_e32 v13, v131
	v_mov_b32_e32 v14, v131
	v_mov_b32_e32 v15, v131
	v_mov_b32_e32 v16, 0
	v_mov_b32_e32 v17, v131
	v_mov_b32_e32 v18, v131
	v_mov_b32_e32 v19, v131
	v_mov_b32_e32 v20, v131
	v_mov_b32_e32 v21, v131
	v_mov_b32_e32 v22, v131
	v_mov_b32_e32 v23, v131
	v_mov_b32_e32 v24, v131
	v_mov_b32_e32 v25, v131
	v_mov_b32_e32 v26, v131
	v_mov_b32_e32 v27, v131
	v_mov_b32_e32 v28, v131
	v_mov_b32_e32 v29, v131
	v_mov_b32_e32 v30, v131
	v_mov_b32_e32 v31, v131
	v_mov_b32_e32 v32, 0
	v_mov_b32_e32 v33, v131
	v_mov_b32_e32 v34, v131
	v_mov_b32_e32 v35, v131
	v_mov_b32_e32 v36, v131
	v_mov_b32_e32 v37, v131
	v_mov_b32_e32 v38, v131
	v_mov_b32_e32 v39, v131
	v_mov_b32_e32 v40, v131
	v_mov_b32_e32 v41, v131
	v_mov_b32_e32 v42, v131
	v_mov_b32_e32 v43, v131
	v_mov_b32_e32 v44, v131
	v_mov_b32_e32 v45, v131
	v_mov_b32_e32 v46, v131
	v_mov_b32_e32 v47, v131
	v_mov_b32_e32 v48, 0
	v_mov_b32_e32 v49, v131
	v_mov_b32_e32 v50, v131
	v_mov_b32_e32 v51, v131
	v_mov_b32_e32 v52, v131
	v_mov_b32_e32 v53, v131
	v_mov_b32_e32 v54, v131
	v_mov_b32_e32 v55, v131
	v_mov_b32_e32 v56, v131
	v_mov_b32_e32 v57, v131
	v_mov_b32_e32 v58, v131
	v_mov_b32_e32 v59, v131
	v_mov_b32_e32 v60, v131
	v_mov_b32_e32 v61, v131
	v_mov_b32_e32 v62, v131
	v_mov_b32_e32 v63, v131
	v_mov_b32_e32 v64, 0
	v_mov_b32_e32 v65, v131
	v_mov_b32_e32 v66, v131
	v_mov_b32_e32 v67, v131
	v_mov_b32_e32 v68, v131
	v_mov_b32_e32 v69, v131
	v_mov_b32_e32 v70, v131
	v_mov_b32_e32 v71, v131
	v_mov_b32_e32 v72, v131
	v_mov_b32_e32 v73, v131
	v_mov_b32_e32 v74, v131
	v_mov_b32_e32 v75, v131
	v_mov_b32_e32 v76, v131
	v_mov_b32_e32 v77, v131
	v_mov_b32_e32 v78, v131
	v_mov_b32_e32 v79, v131
	v_mov_b32_e32 v80, 0
	v_mov_b32_e32 v81, v131
	v_mov_b32_e32 v82, v131
	v_mov_b32_e32 v83, v131
	v_mov_b32_e32 v84, v131
	v_mov_b32_e32 v85, v131
	v_mov_b32_e32 v86, v131
	v_mov_b32_e32 v87, v131
	v_mov_b32_e32 v88, v131
	v_mov_b32_e32 v89, v131
	v_mov_b32_e32 v90, v131
	v_mov_b32_e32 v91, v131
	v_mov_b32_e32 v92, v131
	v_mov_b32_e32 v93, v131
	v_mov_b32_e32 v94, v131
	v_mov_b32_e32 v95, v131
	v_mov_b32_e32 v96, 0
	v_mov_b32_e32 v97, v131
	v_mov_b32_e32 v98, v131
	v_mov_b32_e32 v99, v131
	v_mov_b32_e32 v100, v131
	v_mov_b32_e32 v101, v131
	v_mov_b32_e32 v102, v131
	v_mov_b32_e32 v103, v131
	v_mov_b32_e32 v104, v131
	v_mov_b32_e32 v105, v131
	v_mov_b32_e32 v106, v131
	v_mov_b32_e32 v107, v131
	v_mov_b32_e32 v108, v131
	v_mov_b32_e32 v109, v131
	v_mov_b32_e32 v110, v131
	v_mov_b32_e32 v111, v131
	v_mov_b32_e32 v112, 0
	v_mov_b32_e32 v113, v131
	v_mov_b32_e32 v114, v131
	v_mov_b32_e32 v115, v131
	v_mov_b32_e32 v116, v131
	v_mov_b32_e32 v117, v131
	v_mov_b32_e32 v118, v131
	v_mov_b32_e32 v119, v131
	v_mov_b32_e32 v120, v131
	v_mov_b32_e32 v121, v131
	v_mov_b32_e32 v122, v131
	v_mov_b32_e32 v123, v131
	v_mov_b32_e32 v124, v131
	v_mov_b32_e32 v125, v131
	v_mov_b32_e32 v126, v131
	v_mov_b32_e32 v127, v131
	s_mov_b64 s[50:51], 0x80
	v_lshrrev_b32_e32 v174, 6, v180
	v_lshlrev_b32_e32 v184, 11, v174
	v_and_b32_e32 v170, 63, v180
	v_readfirstlane_b32 s49, v184
	v_lshrrev_b32_e32 v171, 4, v170
	v_bfe_u32 v172, v170, 1, 3
	v_xor_b32_e32 v172, v171, v172
	v_and_b32_e32 v173, 31, v170
	v_lshlrev_b32_e32 v173, 7, v173
	v_lshrrev_b32_e32 v173, 3, v170
	v_lshlrev_b32_e32 v184, 4, v173
	v_add_u32_e32 v185, 0x80, v184
	v_and_b32_e32 v173, 7, v170
	v_lshrrev_b32_e32 v171, 4, v170
	v_xor_b32_e32 v171, v173, v171
	v_lshrrev_b32_e32 v173, 5, v170
	v_sub_u32_e32 v186, v171, v173
	v_xor_b32_e32 v171, 4, v171
	v_add_u32_e32 v173, 2, v173
	v_sub_u32_e32 v188, v171, v173
	v_lshlrev_b32_e32 v186, 4, v186
	v_ashrrev_i32_e32 v187, 31, v186
	v_lshlrev_b32_e32 v188, 4, v188
	v_ashrrev_i32_e32 v189, 31, v188
	ds_bpermute_b32 v244, v184, v136
	ds_bpermute_b32 v245, v184, v137
	ds_bpermute_b32 v246, v185, v136
	ds_bpermute_b32 v247, v185, v137
	ds_bpermute_b32 v248, v184, v146
	ds_bpermute_b32 v249, v184, v147
	ds_bpermute_b32 v250, v185, v146
	ds_bpermute_b32 v251, v185, v147
	s_waitcnt lgkmcnt(0)
	ds_bpermute_b32 v178, v184, v138
	ds_bpermute_b32 v179, v184, v139
	ds_bpermute_b32 v234, v185, v138
	ds_bpermute_b32 v235, v185, v139
	ds_bpermute_b32 v236, v184, v140
	ds_bpermute_b32 v237, v184, v141
	ds_bpermute_b32 v238, v185, v140
	ds_bpermute_b32 v239, v185, v141
	ds_bpermute_b32 v240, v184, v142
	ds_bpermute_b32 v241, v184, v143
	ds_bpermute_b32 v242, v185, v142
	ds_bpermute_b32 v243, v185, v143
	ds_bpermute_b32 v136, v184, v144
	ds_bpermute_b32 v137, v184, v145
	ds_bpermute_b32 v146, v185, v144
	ds_bpermute_b32 v147, v185, v145
	s_waitcnt lgkmcnt(0)
	v_and_b32_e32 v173, 15, v170
	v_lshlrev_b32_e32 v173, 7, v173
	v_lshrrev_b32_e32 v171, 1, v174
	v_lshl_add_u32 v138, v171, 14, v173
	v_and_b32_e32 v171, 1, v174
	v_lshl_add_u32 v142, v171, 13, v173
	v_add_u32_e32 v142, 0x10000, v142
	v_xor_b32_e32 v173, 4, v172
	v_lshl_add_u32 v139, v173, 4, v138
	v_lshl_add_u32 v143, v173, 4, v142
	v_xor_b32_e32 v173, 0, v172
	v_lshl_add_u32 v138, v173, 4, v138
	v_lshl_add_u32 v142, v173, 4, v142
	v_lshl_add_u64 v[178:179], v[178:179], 0, v[186:187]
	v_lshl_add_u64 v[234:235], v[234:235], 0, v[188:189]
	v_lshl_add_u64 v[236:237], v[236:237], 0, v[186:187]
	v_lshl_add_u64 v[238:239], v[238:239], 0, v[188:189]
	v_lshl_add_u64 v[240:241], v[240:241], 0, v[186:187]
	v_lshl_add_u64 v[242:243], v[242:243], 0, v[188:189]
	v_lshl_add_u64 v[136:137], v[136:137], 0, v[186:187]
	v_lshl_add_u64 v[146:147], v[146:147], 0, v[188:189]
	v_lshl_add_u64 v[244:245], v[244:245], 0, v[186:187]
	v_lshl_add_u64 v[246:247], v[246:247], 0, v[188:189]
	v_lshl_add_u64 v[248:249], v[248:249], 0, v[186:187]
	v_lshl_add_u64 v[250:251], v[250:251], 0, v[188:189]
	s_mov_b32 s54, s49
	s_add_i32 m0, s54, 0x0
	s_nop 0
	global_load_lds_dwordx4 v[178:179], off
	s_add_i32 m0, s54, 0x400
	v_lshl_add_u64 v[178:179], v[178:179], 0, s[50:51]
	global_load_lds_dwordx4 v[234:235], off
	s_add_i32 m0, s54, 0x2000
	v_lshl_add_u64 v[234:235], v[234:235], 0, s[50:51]
	global_load_lds_dwordx4 v[236:237], off
	s_add_i32 m0, s54, 0x2400
	v_lshl_add_u64 v[236:237], v[236:237], 0, s[50:51]
	global_load_lds_dwordx4 v[238:239], off
	s_add_i32 m0, s54, 0x4000
	v_lshl_add_u64 v[238:239], v[238:239], 0, s[50:51]
	global_load_lds_dwordx4 v[240:241], off
	s_add_i32 m0, s54, 0x4400
	v_lshl_add_u64 v[240:241], v[240:241], 0, s[50:51]
	global_load_lds_dwordx4 v[242:243], off
	s_add_i32 m0, s54, 0x6000
	v_lshl_add_u64 v[242:243], v[242:243], 0, s[50:51]
	global_load_lds_dwordx4 v[136:137], off
	s_add_i32 m0, s54, 0x6400
	v_lshl_add_u64 v[136:137], v[136:137], 0, s[50:51]
	global_load_lds_dwordx4 v[146:147], off
	v_lshl_add_u64 v[146:147], v[146:147], 0, s[50:51]
	s_add_i32 s54, s49, 0x10000
	s_add_i32 m0, s54, 0x0
	s_nop 0
	global_load_lds_dwordx4 v[244:245], off
	s_add_i32 m0, s54, 0x400
	v_lshl_add_u64 v[244:245], v[244:245], 0, s[50:51]
	global_load_lds_dwordx4 v[246:247], off
	s_add_i32 m0, s54, 0x2000
	v_lshl_add_u64 v[246:247], v[246:247], 0, s[50:51]
	global_load_lds_dwordx4 v[248:249], off
	s_add_i32 m0, s54, 0x2400
	v_lshl_add_u64 v[248:249], v[248:249], 0, s[50:51]
	global_load_lds_dwordx4 v[250:251], off
	v_lshl_add_u64 v[250:251], v[250:251], 0, s[50:51]
	s_mov_b32 s14, 0
	s_mov_b32 s15, 0

.Lg_ph5_noA:
	ds_read_b128 v[190:193], v142
	ds_read_b128 v[194:197], v142 offset:2048
	ds_read_b128 v[198:201], v142 offset:4096
	ds_read_b128 v[202:205], v142 offset:6144
	ds_read_b128 v[206:209], v143
	ds_read_b128 v[222:225], v143 offset:2048
	ds_read_b128 v[226:229], v143 offset:4096
	ds_read_b128 v[230:233], v143 offset:6144
	ds_read_b128 v[170:173], v138
	ds_read_b128 v[174:177], v138 offset:2048
	ds_read_b128 v[182:185], v138 offset:4096
	ds_read_b128 v[186:189], v138 offset:6144
	s_waitcnt lgkmcnt(4)
	s_barrier
	s_cmp_eq_u32 s14, 15
	s_cbranch_scc1 .Lg_ph5_noB
	s_add_i32 s54, s49, 0x10000
	s_add_i32 m0, s54, 0x0
	s_nop 0
	global_load_lds_dwordx4 v[244:245], off
	s_add_i32 m0, s54, 0x400
	v_lshl_add_u64 v[244:245], v[244:245], 0, s[50:51]
	global_load_lds_dwordx4 v[246:247], off
	s_add_i32 m0, s54, 0x2000
	v_lshl_add_u64 v[246:247], v[246:247], 0, s[50:51]
	global_load_lds_dwordx4 v[248:249], off
	s_add_i32 m0, s54, 0x2400
	v_lshl_add_u64 v[248:249], v[248:249], 0, s[50:51]
	global_load_lds_dwordx4 v[250:251], off
	v_lshl_add_u64 v[250:251], v[250:251], 0, s[50:51]
.Lg_ph5_noB:
	s_waitcnt lgkmcnt(3)
	v_mfma_f32_16x16x32_bf16 v[0:3], v[170:173], v[190:193], v[0:3]
	v_mfma_f32_16x16x32_bf16 v[4:7], v[170:173], v[194:197], v[4:7]
	v_mfma_f32_16x16x32_bf16 v[8:11], v[170:173], v[198:201], v[8:11]
	v_mfma_f32_16x16x32_bf16 v[12:15], v[170:173], v[202:205], v[12:15]
	ds_read_b128 v[170:173], v138 offset:8192
	s_waitcnt lgkmcnt(3)
	v_mfma_f32_16x16x32_bf16 v[16:19], v[174:177], v[190:193], v[16:19]
	v_mfma_f32_16x16x32_bf16 v[20:23], v[174:177], v[194:197], v[20:23]
	v_mfma_f32_16x16x32_bf16 v[24:27], v[174:177], v[198:201], v[24:27]
	v_mfma_f32_16x16x32_bf16 v[28:31], v[174:177], v[202:205], v[28:31]
	ds_read_b128 v[174:177], v138 offset:10240
	s_waitcnt lgkmcnt(3)
	v_mfma_f32_16x16x32_bf16 v[32:35], v[182:185], v[190:193], v[32:35]
	v_mfma_f32_16x16x32_bf16 v[36:39], v[182:185], v[194:197], v[36:39]
	v_mfma_f32_16x16x32_bf16 v[40:43], v[182:185], v[198:201], v[40:43]
	v_mfma_f32_16x16x32_bf16 v[44:47], v[182:185], v[202:205], v[44:47]
	ds_read_b128 v[182:185], v138 offset:12288
	s_waitcnt lgkmcnt(3)
	v_mfma_f32_16x16x32_bf16 v[48:51], v[186:189], v[190:193], v[48:51]
	v_mfma_f32_16x16x32_bf16 v[52:55], v[186:189], v[194:197], v[52:55]
	v_mfma_f32_16x16x32_bf16 v[56:59], v[186:189], v[198:201], v[56:59]
	v_mfma_f32_16x16x32_bf16 v[60:63], v[186:189], v[202:205], v[60:63]
	ds_read_b128 v[186:189], v138 offset:14336
	s_waitcnt lgkmcnt(3)
	v_mfma_f32_16x16x32_bf16 v[64:67], v[170:173], v[190:193], v[64:67]
	v_mfma_f32_16x16x32_bf16 v[68:71], v[170:173], v[194:197], v[68:71]
	v_mfma_f32_16x16x32_bf16 v[72:75], v[170:173], v[198:201], v[72:75]
	v_mfma_f32_16x16x32_bf16 v[76:79], v[170:173], v[202:205], v[76:79]
	ds_read_b128 v[170:173], v139
	s_waitcnt lgkmcnt(3)
	v_mfma_f32_16x16x32_bf16 v[80:83], v[174:177], v[190:193], v[80:83]
	v_mfma_f32_16x16x32_bf16 v[84:87], v[174:177], v[194:197], v[84:87]
	v_mfma_f32_16x16x32_bf16 v[88:91], v[174:177], v[198:201], v[88:91]
	v_mfma_f32_16x16x32_bf16 v[92:95], v[174:177], v[202:205], v[92:95]
	ds_read_b128 v[174:177], v139 offset:2048
	s_waitcnt lgkmcnt(3)
	v_mfma_f32_16x16x32_bf16 v[96:99], v[182:185], v[190:193], v[96:99]
	v_mfma_f32_16x16x32_bf16 v[100:103], v[182:185], v[194:197], v[100:103]
	v_mfma_f32_16x16x32_bf16 v[104:107], v[182:185], v[198:201], v[104:107]
	v_mfma_f32_16x16x32_bf16 v[108:111], v[182:185], v[202:205], v[108:111]
	ds_read_b128 v[182:185], v139 offset:4096
	s_waitcnt lgkmcnt(3)
	v_mfma_f32_16x16x32_bf16 v[112:115], v[186:189], v[190:193], v[112:115]
	v_mfma_f32_16x16x32_bf16 v[116:119], v[186:189], v[194:197], v[116:119]
	v_mfma_f32_16x16x32_bf16 v[120:123], v[186:189], v[198:201], v[120:123]
	v_mfma_f32_16x16x32_bf16 v[124:127], v[186:189], v[202:205], v[124:127]
	ds_read_b128 v[186:189], v139 offset:6144
	s_waitcnt lgkmcnt(3)
	v_mfma_f32_16x16x32_bf16 v[0:3], v[170:173], v[206:209], v[0:3]
	v_mfma_f32_16x16x32_bf16 v[4:7], v[170:173], v[222:225], v[4:7]
	v_mfma_f32_16x16x32_bf16 v[8:11], v[170:173], v[226:229], v[8:11]
	v_mfma_f32_16x16x32_bf16 v[12:15], v[170:173], v[230:233], v[12:15]
	ds_read_b128 v[170:173], v139 offset:8192
	s_waitcnt lgkmcnt(3)
	v_mfma_f32_16x16x32_bf16 v[16:19], v[174:177], v[206:209], v[16:19]
	v_mfma_f32_16x16x32_bf16 v[20:23], v[174:177], v[222:225], v[20:23]
	v_mfma_f32_16x16x32_bf16 v[24:27], v[174:177], v[226:229], v[24:27]
	v_mfma_f32_16x16x32_bf16 v[28:31], v[174:177], v[230:233], v[28:31]
	ds_read_b128 v[174:177], v139 offset:10240
	s_waitcnt lgkmcnt(3)
	v_mfma_f32_16x16x32_bf16 v[32:35], v[182:185], v[206:209], v[32:35]
	v_mfma_f32_16x16x32_bf16 v[36:39], v[182:185], v[222:225], v[36:39]
	v_mfma_f32_16x16x32_bf16 v[40:43], v[182:185], v[226:229], v[40:43]
	v_mfma_f32_16x16x32_bf16 v[44:47], v[182:185], v[230:233], v[44:47]
	ds_read_b128 v[182:185], v139 offset:12288
	s_waitcnt lgkmcnt(3)
	v_mfma_f32_16x16x32_bf16 v[48:51], v[186:189], v[206:209], v[48:51]
	v_mfma_f32_16x16x32_bf16 v[52:55], v[186:189], v[222:225], v[52:55]
	v_mfma_f32_16x16x32_bf16 v[56:59], v[186:189], v[226:229], v[56:59]
	v_mfma_f32_16x16x32_bf16 v[60:63], v[186:189], v[230:233], v[60:63]
	ds_read_b128 v[186:189], v139 offset:14336
	s_waitcnt lgkmcnt(3)
	v_mfma_f32_16x16x32_bf16 v[64:67], v[170:173], v[206:209], v[64:67]
	v_mfma_f32_16x16x32_bf16 v[68:71], v[170:173], v[222:225], v[68:71]
	v_mfma_f32_16x16x32_bf16 v[72:75], v[170:173], v[226:229], v[72:75]
	v_mfma_f32_16x16x32_bf16 v[76:79], v[170:173], v[230:233], v[76:79]
	s_waitcnt lgkmcnt(2)
	v_mfma_f32_16x16x32_bf16 v[80:83], v[174:177], v[206:209], v[80:83]
	v_mfma_f32_16x16x32_bf16 v[84:87], v[174:177], v[222:225], v[84:87]
	v_mfma_f32_16x16x32_bf16 v[88:91], v[174:177], v[226:229], v[88:91]
	v_mfma_f32_16x16x32_bf16 v[92:95], v[174:177], v[230:233], v[92:95]
	s_waitcnt lgkmcnt(1)
	v_mfma_f32_16x16x32_bf16 v[96:99], v[182:185], v[206:209], v[96:99]
	v_mfma_f32_16x16x32_bf16 v[100:103], v[182:185], v[222:225], v[100:103]
	v_mfma_f32_16x16x32_bf16 v[104:107], v[182:185], v[226:229], v[104:107]
	v_mfma_f32_16x16x32_bf16 v[108:111], v[182:185], v[230:233], v[108:111]
	s_waitcnt lgkmcnt(0)
	v_mfma_f32_16x16x32_bf16 v[112:115], v[186:189], v[206:209], v[112:115]
	v_mfma_f32_16x16x32_bf16 v[116:119], v[186:189], v[222:225], v[116:119]
	v_mfma_f32_16x16x32_bf16 v[120:123], v[186:189], v[226:229], v[120:123]
	v_mfma_f32_16x16x32_bf16 v[124:127], v[186:189], v[230:233], v[124:127]
	v_xor_b32_e32 v138, 0x8000, v138
	v_xor_b32_e32 v139, 0x8000, v139
	s_xor_b32 s15, s15, 0x8000
	s_add_i32 s14, s14, 1
	s_cmp_eq_u32 s14, 16
	s_cbranch_scc0 .Lg_ph5_top
	s_waitcnt vmcnt(0)
	v_mov_b32_e32 v130, v180
	v_add_u32_e32 v201, 0x400, v153
	v_add_u32_e32 v200, 0x1000, v153
	v_add_u32_e32 v199, 0x1400, v153
	v_add_u32_e32 v198, 0x2000, v153
	v_add_u32_e32 v192, 0x2400, v153
	v_add_u32_e32 v193, 0x3000, v153
	v_add_u32_e32 v194, 0x3200, v153
	v_add_u32_e32 v195, 0x3400, v153
	v_add_u32_e32 v196, 0x3600, v153
	v_add_u32_e32 v197, 0x4000, v153
	v_add_u32_e32 v189, 0x4400, v153
	v_add_u32_e32 v190, 0x4800, v153
	v_add_u32_e32 v191, 0x5000, v153
	v_add_u32_e32 v186, 0x5400, v153
	v_add_u32_e32 v187, 0x5800, v153
	v_add_u32_e32 v188, 0x6000, v153
	v_add_u32_e32 v179, 0x6400, v153
	v_add_u32_e32 v181, 0x6800, v153
	v_add_u32_e32 v182, 0x7200, v153
	v_add_u32_e32 v183, 0x7400, v153
	v_add_u32_e32 v184, 0x7600, v153
	v_add_u32_e32 v185, 0x7800, v153
	v_add_u32_e32 v178, 0x8400, v153
	v_add_u32_e32 v177, 0x8800, v153
	v_add_u32_e32 v176, 0x9400, v153
	v_add_u32_e32 v175, 0x9800, v153
	v_add_u32_e32 v174, 0xa400, v153
	v_add_u32_e32 v147, 0xa800, v153
	v_add_u32_e32 v169, 0xb400, v153
	v_add_u32_e32 v170, 0xb600, v153
	v_add_u32_e32 v171, 0xb800, v153
	v_add_u32_e32 v172, 0xba00, v153
	s_waitcnt vmcnt(0)
	s_barrier
	s_and_saveexec_b64 s[14:15], s[6:7]
	s_cbranch_execz .LBB0_605
	v_and_b32_e32 v254, 63, v180
	v_lshrrev_b32_e32 v253, 4, v254
	v_mul_u32_u24_e32 v253, 0x840, v253
	v_and_b32_e32 v254, 15, v254
	v_lshl_add_u32 v253, v254, 2, v253
	v_and_b32_e32 v254, 64, v180
	v_lshl_add_u32 v253, v254, 2, v253
	ds_write_b32 v253, v0 offset:0
	ds_write_b32 v253, v1 offset:528
	ds_write_b32 v253, v2 offset:1056
	ds_write_b32 v253, v3 offset:1584
	ds_write_b32 v253, v4 offset:64
	ds_write_b32 v253, v5 offset:592
	ds_write_b32 v253, v6 offset:1120
	ds_write_b32 v253, v7 offset:1648
	ds_write_b32 v253, v8 offset:128
	ds_write_b32 v253, v9 offset:656
	ds_write_b32 v253, v10 offset:1184
	ds_write_b32 v253, v11 offset:1712
	ds_write_b32 v253, v12 offset:192
	ds_write_b32 v253, v13 offset:720
	ds_write_b32 v253, v14 offset:1248
	ds_write_b32 v253, v15 offset:1776
	ds_write_b32 v253, v16 offset:8448
	ds_write_b32 v253, v17 offset:8976
	ds_write_b32 v253, v18 offset:9504
	ds_write_b32 v253, v19 offset:10032
	ds_write_b32 v253, v20 offset:8512
	ds_write_b32 v253, v21 offset:9040
	ds_write_b32 v253, v22 offset:9568
	ds_write_b32 v253, v23 offset:10096
	ds_write_b32 v253, v24 offset:8576
	ds_write_b32 v253, v25 offset:9104
	ds_write_b32 v253, v26 offset:9632
	ds_write_b32 v253, v27 offset:10160
	ds_write_b32 v253, v28 offset:8640
	ds_write_b32 v253, v29 offset:9168
	ds_write_b32 v253, v30 offset:9696
	ds_write_b32 v253, v31 offset:10224
	ds_write_b32 v253, v32 offset:16896
	ds_write_b32 v253, v33 offset:17424
	ds_write_b32 v253, v34 offset:17952
	ds_write_b32 v253, v35 offset:18480
	ds_write_b32 v253, v36 offset:16960
	ds_write_b32 v253, v37 offset:17488
	ds_write_b32 v253, v38 offset:18016
	ds_write_b32 v253, v39 offset:18544
	ds_write_b32 v253, v40 offset:17024
	ds_write_b32 v253, v41 offset:17552
	ds_write_b32 v253, v42 offset:18080
	ds_write_b32 v253, v43 offset:18608
	ds_write_b32 v253, v44 offset:17088
	ds_write_b32 v253, v45 offset:17616
	ds_write_b32 v253, v46 offset:18144
	ds_write_b32 v253, v47 offset:18672
	ds_write_b32 v253, v48 offset:25344
	ds_write_b32 v253, v49 offset:25872
	ds_write_b32 v253, v50 offset:26400
	ds_write_b32 v253, v51 offset:26928
	ds_write_b32 v253, v52 offset:25408
	ds_write_b32 v253, v53 offset:25936
	ds_write_b32 v253, v54 offset:26464
	ds_write_b32 v253, v55 offset:26992
	ds_write_b32 v253, v56 offset:25472
	ds_write_b32 v253, v57 offset:26000
	ds_write_b32 v253, v58 offset:26528
	ds_write_b32 v253, v59 offset:27056
	ds_write_b32 v253, v60 offset:25536
	ds_write_b32 v253, v61 offset:26064
	ds_write_b32 v253, v62 offset:26592
	ds_write_b32 v253, v63 offset:27120
	ds_write_b32 v253, v64 offset:33792
	ds_write_b32 v253, v65 offset:34320
	ds_write_b32 v253, v66 offset:34848
	ds_write_b32 v253, v67 offset:35376
	ds_write_b32 v253, v68 offset:33856
	ds_write_b32 v253, v69 offset:34384
	ds_write_b32 v253, v70 offset:34912
	ds_write_b32 v253, v71 offset:35440
	ds_write_b32 v253, v72 offset:33920
	ds_write_b32 v253, v73 offset:34448
	ds_write_b32 v253, v74 offset:34976
	ds_write_b32 v253, v75 offset:35504
	ds_write_b32 v253, v76 offset:33984
	ds_write_b32 v253, v77 offset:34512
	ds_write_b32 v253, v78 offset:35040
	ds_write_b32 v253, v79 offset:35568
	ds_write_b32 v253, v80 offset:42240
	ds_write_b32 v253, v81 offset:42768
	ds_write_b32 v253, v82 offset:43296
	ds_write_b32 v253, v83 offset:43824
	ds_write_b32 v253, v84 offset:42304
	ds_write_b32 v253, v85 offset:42832
	ds_write_b32 v253, v86 offset:43360
	ds_write_b32 v253, v87 offset:43888
	ds_write_b32 v253, v88 offset:42368
	ds_write_b32 v253, v89 offset:42896
	ds_write_b32 v253, v90 offset:43424
	ds_write_b32 v253, v91 offset:43952
	ds_write_b32 v253, v92 offset:42432
	ds_write_b32 v253, v93 offset:42960
	ds_write_b32 v253, v94 offset:43488
	ds_write_b32 v253, v95 offset:44016
	ds_write_b32 v253, v96 offset:50688
	ds_write_b32 v253, v97 offset:51216
	ds_write_b32 v253, v98 offset:51744
	ds_write_b32 v253, v99 offset:52272
	ds_write_b32 v253, v100 offset:50752
	ds_write_b32 v253, v101 offset:51280
	ds_write_b32 v253, v102 offset:51808
	ds_write_b32 v253, v103 offset:52336
	ds_write_b32 v253, v104 offset:50816
	ds_write_b32 v253, v105 offset:51344
	ds_write_b32 v253, v106 offset:51872
	ds_write_b32 v253, v107 offset:52400
	ds_write_b32 v253, v108 offset:50880
	ds_write_b32 v253, v109 offset:51408
	ds_write_b32 v253, v110 offset:51936
	ds_write_b32 v253, v111 offset:52464
	ds_write_b32 v253, v112 offset:59136
	ds_write_b32 v253, v113 offset:59664
	ds_write_b32 v253, v114 offset:60192
	ds_write_b32 v253, v115 offset:60720
	ds_write_b32 v253, v116 offset:59200
	ds_write_b32 v253, v117 offset:59728
	ds_write_b32 v253, v118 offset:60256
	ds_write_b32 v253, v119 offset:60784
	ds_write_b32 v253, v120 offset:59264
	ds_write_b32 v253, v121 offset:59792
	ds_write_b32 v253, v122 offset:60320
	ds_write_b32 v253, v123 offset:60848
	ds_write_b32 v253, v124 offset:59328
	ds_write_b32 v253, v125 offset:59856
	ds_write_b32 v253, v126 offset:60384
	ds_write_b32 v253, v127 offset:60912
.LBB0_605:
	s_or_b64 exec, exec, s[14:15]
	v_lshlrev_b32_e32 v136, 3, v130
	v_and_b32_e32 v146, 0x78, v136
	v_ashrrev_i32_e32 v206, 4, v130
	v_add_u32_e32 v137, 0x100, v130
	v_lshl_add_u32 v173, v146, 2, 0
	v_mul_lo_u32 v136, v206, s23
	v_ashrrev_i32_e32 v210, 4, v137
	v_add_u32_e32 v137, 0x200, v130
	v_add_u32_e32 v144, v173, v136
	v_ashrrev_i32_e32 v218, 4, v137
	s_waitcnt lgkmcnt(0)
	s_barrier
	ds_read_b128 v[136:139], v144
	ds_read_b128 v[140:143], v144 offset:16
	s_lshl_b32 s2, s28, 1
	v_mul_lo_u32 v145, v210, s23
	s_add_u32 s2, s18, s2
	v_ashrrev_i32_e32 v207, 31, v206
	v_add_u32_e32 v145, v173, v145
	s_addc_u32 s15, s19, 0
	s_lshl_b32 s14, s27, 8
	s_waitcnt lgkmcnt(1)
	v_cvt_pk_bf16_f32 v202, v136, v137
	v_lshlrev_b64 v[136:137], 11, v[206:207]
	ds_read_b128 v[206:209], v145 offset:16
	s_add_u32 s14, s2, s14
	v_cvt_pk_bf16_f32 v203, v138, v139
	s_waitcnt lgkmcnt(1)
	v_cvt_pk_bf16_f32 v204, v140, v141
	ds_read_b128 v[138:141], v145
	s_addc_u32 s15, s15, 0
	v_add_u32_e32 v130, 0x300, v130
	v_mul_lo_u32 v214, v218, s23
	v_ashrrev_i32_e32 v220, 4, v130
	v_lshl_add_u64 v[136:137], s[14:15], 0, v[136:137]
	v_lshlrev_b32_e32 v130, 1, v146
	v_cvt_pk_bf16_f32 v205, v142, v143
	v_lshl_add_u64 v[136:137], v[136:137], 0, v[130:131]
	v_add_u32_e32 v146, v173, v214
	global_store_dwordx4 v[136:137], v[202:205], off
	v_ashrrev_i32_e32 v211, 31, v210
	v_mul_lo_u32 v215, v220, s23
	s_waitcnt lgkmcnt(1)
	v_cvt_pk_bf16_f32 v204, v206, v207
	v_cvt_pk_bf16_f32 v205, v208, v209
	ds_read_b128 v[206:209], v146 offset:16
	s_waitcnt lgkmcnt(1)
	v_cvt_pk_bf16_f32 v202, v138, v139
	v_lshlrev_b64 v[138:139], 11, v[210:211]
	v_cvt_pk_bf16_f32 v203, v140, v141
	ds_read_b128 v[140:143], v146
	v_lshl_add_u64 v[138:139], s[14:15], 0, v[138:139]
	v_lshl_add_u64 v[138:139], v[138:139], 0, v[130:131]
	global_store_dwordx4 v[138:139], v[202:205], off
	v_add_u32_e32 v173, v173, v215
	v_ashrrev_i32_e32 v219, 31, v218
	s_waitcnt lgkmcnt(1)
	v_cvt_pk_bf16_f32 v204, v206, v207
	v_cvt_pk_bf16_f32 v205, v208, v209
	ds_read_b128 v[206:209], v173
	ds_read_b128 v[214:217], v173 offset:16
	s_waitcnt lgkmcnt(2)
	v_cvt_pk_bf16_f32 v202, v140, v141
	v_lshlrev_b64 v[140:141], 11, v[218:219]
	v_lshl_add_u64 v[140:141], s[14:15], 0, v[140:141]
	v_cvt_pk_bf16_f32 v203, v142, v143
	v_lshl_add_u64 v[140:141], v[140:141], 0, v[130:131]
	global_store_dwordx4 v[140:141], v[202:205], off
	v_ashrrev_i32_e32 v221, 31, v220
	v_lshlrev_b64 v[142:143], 11, v[220:221]
	s_waitcnt lgkmcnt(0)
	v_cvt_pk_bf16_f32 v205, v216, v217
	v_cvt_pk_bf16_f32 v204, v214, v215
	v_cvt_pk_bf16_f32 v203, v208, v209
	v_cvt_pk_bf16_f32 v202, v206, v207
	ds_read_b128 v[206:209], v144 offset:33792
	ds_read_b128 v[214:217], v144 offset:33808
	v_lshl_add_u64 v[142:143], s[14:15], 0, v[142:143]
	v_lshl_add_u64 v[142:143], v[142:143], 0, v[130:131]
	global_store_dwordx4 v[142:143], v[202:205], off
	v_add_co_u32_e32 v210, vcc, s24, v136
	s_waitcnt lgkmcnt(1)
	v_cvt_pk_bf16_f32 v202, v206, v207
	v_cvt_pk_bf16_f32 v203, v208, v209
	s_waitcnt lgkmcnt(0)
	v_cvt_pk_bf16_f32 v204, v214, v215
	v_cvt_pk_bf16_f32 v205, v216, v217
	ds_read_b128 v[206:209], v145 offset:33792
	ds_read_b128 v[214:217], v145 offset:33808
	v_addc_co_u32_e32 v211, vcc, 0, v137, vcc
	global_store_dwordx4 v[210:211], v[202:205], off
	v_add_co_u32_e32 v210, vcc, s24, v138
	s_waitcnt lgkmcnt(1)
	v_cvt_pk_bf16_f32 v202, v206, v207
	v_cvt_pk_bf16_f32 v203, v208, v209
	s_waitcnt lgkmcnt(0)
	v_cvt_pk_bf16_f32 v204, v214, v215
	v_cvt_pk_bf16_f32 v205, v216, v217
	ds_read_b128 v[206:209], v146 offset:33792
	ds_read_b128 v[214:217], v146 offset:33808
	v_addc_co_u32_e32 v211, vcc, 0, v139, vcc
	global_store_dwordx4 v[210:211], v[202:205], off
	v_add_co_u32_e32 v210, vcc, s24, v140
	s_waitcnt lgkmcnt(1)
	v_cvt_pk_bf16_f32 v202, v206, v207
	v_cvt_pk_bf16_f32 v203, v208, v209
	s_waitcnt lgkmcnt(0)
	v_cvt_pk_bf16_f32 v204, v214, v215
	v_cvt_pk_bf16_f32 v205, v216, v217
	ds_read_b128 v[206:209], v173 offset:33792
	ds_read_b128 v[214:217], v173 offset:33808
	v_addc_co_u32_e32 v211, vcc, 0, v141, vcc
	global_store_dwordx4 v[210:211], v[202:205], off
	s_waitcnt lgkmcnt(1)
	s_nop 0
	v_cvt_pk_bf16_f32 v202, v206, v207
	v_add_co_u32_e32 v206, vcc, 0x20000, v142
	s_waitcnt lgkmcnt(0)
	v_cvt_pk_bf16_f32 v205, v216, v217
	v_cvt_pk_bf16_f32 v204, v214, v215
	v_cvt_pk_bf16_f32 v203, v208, v209
	v_addc_co_u32_e32 v207, vcc, 0, v143, vcc
	global_store_dwordx4 v[206:207], v[202:205], off
	s_barrier
	s_and_saveexec_b64 s[14:15], s[8:9]
	s_cbranch_execz .LBB0_600
	v_and_b32_e32 v254, 63, v180
	v_lshrrev_b32_e32 v253, 4, v254
	v_mul_u32_u24_e32 v253, 0x840, v253
	v_and_b32_e32 v254, 15, v254
	v_lshl_add_u32 v253, v254, 2, v253
	v_and_b32_e32 v254, 64, v180
	v_lshl_add_u32 v253, v254, 2, v253
	ds_write_b32 v253, v0 offset:0
	ds_write_b32 v253, v1 offset:528
	ds_write_b32 v253, v2 offset:1056
	ds_write_b32 v253, v3 offset:1584
	ds_write_b32 v253, v4 offset:64
	ds_write_b32 v253, v5 offset:592
	ds_write_b32 v253, v6 offset:1120
	ds_write_b32 v253, v7 offset:1648
	ds_write_b32 v253, v8 offset:128
	ds_write_b32 v253, v9 offset:656
	ds_write_b32 v253, v10 offset:1184
	ds_write_b32 v253, v11 offset:1712
	ds_write_b32 v253, v12 offset:192
	ds_write_b32 v253, v13 offset:720
	ds_write_b32 v253, v14 offset:1248
	ds_write_b32 v253, v15 offset:1776
	ds_write_b32 v253, v16 offset:8448
	ds_write_b32 v253, v17 offset:8976
	ds_write_b32 v253, v18 offset:9504
	ds_write_b32 v253, v19 offset:10032
	ds_write_b32 v253, v20 offset:8512
	ds_write_b32 v253, v21 offset:9040
	ds_write_b32 v253, v22 offset:9568
	ds_write_b32 v253, v23 offset:10096
	ds_write_b32 v253, v24 offset:8576
	ds_write_b32 v253, v25 offset:9104
	ds_write_b32 v253, v26 offset:9632
	ds_write_b32 v253, v27 offset:10160
	ds_write_b32 v253, v28 offset:8640
	ds_write_b32 v253, v29 offset:9168
	ds_write_b32 v253, v30 offset:9696
	ds_write_b32 v253, v31 offset:10224
	ds_write_b32 v253, v32 offset:16896
	ds_write_b32 v253, v33 offset:17424
	ds_write_b32 v253, v34 offset:17952
	ds_write_b32 v253, v35 offset:18480
	ds_write_b32 v253, v36 offset:16960
	ds_write_b32 v253, v37 offset:17488
	ds_write_b32 v253, v38 offset:18016
	ds_write_b32 v253, v39 offset:18544
	ds_write_b32 v253, v40 offset:17024
	ds_write_b32 v253, v41 offset:17552
	ds_write_b32 v253, v42 offset:18080
	ds_write_b32 v253, v43 offset:18608
	ds_write_b32 v253, v44 offset:17088
	ds_write_b32 v253, v45 offset:17616
	ds_write_b32 v253, v46 offset:18144
	ds_write_b32 v253, v47 offset:18672
	ds_write_b32 v253, v48 offset:25344
	ds_write_b32 v253, v49 offset:25872
	ds_write_b32 v253, v50 offset:26400
	ds_write_b32 v253, v51 offset:26928
	ds_write_b32 v253, v52 offset:25408
	ds_write_b32 v253, v53 offset:25936
	ds_write_b32 v253, v54 offset:26464
	ds_write_b32 v253, v55 offset:26992
	ds_write_b32 v253, v56 offset:25472
	ds_write_b32 v253, v57 offset:26000
	ds_write_b32 v253, v58 offset:26528
	ds_write_b32 v253, v59 offset:27056
	ds_write_b32 v253, v60 offset:25536
	ds_write_b32 v253, v61 offset:26064
	ds_write_b32 v253, v62 offset:26592
	ds_write_b32 v253, v63 offset:27120
	ds_write_b32 v253, v64 offset:33792
	ds_write_b32 v253, v65 offset:34320
	ds_write_b32 v253, v66 offset:34848
	ds_write_b32 v253, v67 offset:35376
	ds_write_b32 v253, v68 offset:33856
	ds_write_b32 v253, v69 offset:34384
	ds_write_b32 v253, v70 offset:34912
	ds_write_b32 v253, v71 offset:35440
	ds_write_b32 v253, v72 offset:33920
	ds_write_b32 v253, v73 offset:34448
	ds_write_b32 v253, v74 offset:34976
	ds_write_b32 v253, v75 offset:35504
	ds_write_b32 v253, v76 offset:33984
	ds_write_b32 v253, v77 offset:34512
	ds_write_b32 v253, v78 offset:35040
	ds_write_b32 v253, v79 offset:35568
	ds_write_b32 v253, v80 offset:42240
	ds_write_b32 v253, v81 offset:42768
	ds_write_b32 v253, v82 offset:43296
	ds_write_b32 v253, v83 offset:43824
	ds_write_b32 v253, v84 offset:42304
	ds_write_b32 v253, v85 offset:42832
	ds_write_b32 v253, v86 offset:43360
	ds_write_b32 v253, v87 offset:43888
	ds_write_b32 v253, v88 offset:42368
	ds_write_b32 v253, v89 offset:42896
	ds_write_b32 v253, v90 offset:43424
	ds_write_b32 v253, v91 offset:43952
	ds_write_b32 v253, v92 offset:42432
	ds_write_b32 v253, v93 offset:42960
	ds_write_b32 v253, v94 offset:43488
	ds_write_b32 v253, v95 offset:44016
	ds_write_b32 v253, v96 offset:50688
	ds_write_b32 v253, v97 offset:51216
	ds_write_b32 v253, v98 offset:51744
	ds_write_b32 v253, v99 offset:52272
	ds_write_b32 v253, v100 offset:50752
	ds_write_b32 v253, v101 offset:51280
	ds_write_b32 v253, v102 offset:51808
	ds_write_b32 v253, v103 offset:52336
	ds_write_b32 v253, v104 offset:50816
	ds_write_b32 v253, v105 offset:51344
	ds_write_b32 v253, v106 offset:51872
	ds_write_b32 v253, v107 offset:52400
	ds_write_b32 v253, v108 offset:50880
	ds_write_b32 v253, v109 offset:51408
	ds_write_b32 v253, v110 offset:51936
	ds_write_b32 v253, v111 offset:52464
	ds_write_b32 v253, v112 offset:59136
	ds_write_b32 v253, v113 offset:59664
	ds_write_b32 v253, v114 offset:60192
	ds_write_b32 v253, v115 offset:60720
	ds_write_b32 v253, v116 offset:59200
	ds_write_b32 v253, v117 offset:59728
	ds_write_b32 v253, v118 offset:60256
	ds_write_b32 v253, v119 offset:60784
	ds_write_b32 v253, v120 offset:59264
	ds_write_b32 v253, v121 offset:59792
	ds_write_b32 v253, v122 offset:60320
	ds_write_b32 v253, v123 offset:60848
	ds_write_b32 v253, v124 offset:59328
	ds_write_b32 v253, v125 offset:59856
	ds_write_b32 v253, v126 offset:60384
	ds_write_b32 v253, v127 offset:60912
	s_branch .LBB0_600

.LBB0_955:
	s_lshr_b32 s10, s19, 4
	s_and_b32 s10, s10, 12
	s_bfe_u32 s28, s19, 0x20001
	s_or_b32 s10, s10, s20
	s_lshl_b32 s14, s28, 4
	s_and_b32 s26, s19, 1
	s_or_b32 s27, s14, s10
	s_lshl_b32 s14, s27, 9
	s_lshl_b32 s15, s26, 8
	s_or_b32 s14, s14, s15
	v_or_b32_e32 v0, s14, v146
	v_lshlrev_b32_e32 v0, 2, v0
	global_load_dword v2, v0, s[2:3]
	global_load_dword v4, v0, s[2:3] offset:256
	global_load_dword v10, v0, s[2:3] offset:512
	global_load_dword v11, v0, s[2:3] offset:768
	s_lshl_b32 s44, s28, 22
	v_readfirstlane_b32 s30, v148
	s_bfe_u32 s29, s19, 0x30003
	v_readfirstlane_b32 s31, v154
	s_mov_b32 m0, s30
	v_readfirstlane_b32 s34, v155
	s_or_b32 s28, s29, s21
	s_waitcnt vmcnt(0)
	s_barrier
	v_readfirstlane_b32 s35, v156
	s_lshl_b32 s29, s28, 17
	s_lshl_b32 s10, s10, 21
	v_readfirstlane_b32 s36, v157
	s_or_b32 s10, s10, s29
	v_readfirstlane_b32 s37, v158
	v_lshl_add_u64 v[134:135], v[130:131], 0, s[10:11]
	v_mov_b32_e32 v1, v129
	v_readfirstlane_b32 s38, v159
	v_lshl_add_u64 v[136:137], v[132:133], 0, s[10:11]
	v_mov_b32_e32 v3, v129
	v_readfirstlane_b32 s39, v160
	v_mov_b32_e32 v5, v129
	v_readfirstlane_b32 s40, v161
	v_readfirstlane_b32 s41, v162
	v_readfirstlane_b32 s42, v163
	v_readfirstlane_b32 s43, v164
	v_lshl_add_u64 v[6:7], v[134:135], 0, 64
	v_lshl_add_u64 v[8:9], v[136:137], 0, 64
	s_mov_b32 s14, s11
	s_mov_b32 s15, 2
	s_mov_b32 s29, s11
	v_mov_b32_e32 v16, 0
	v_mov_b32_e32 v17, v129
	v_mov_b32_e32 v18, v129
	v_mov_b32_e32 v19, v129
	v_mov_b32_e32 v20, v129
	v_mov_b32_e32 v21, v129
	v_mov_b32_e32 v22, v129
	v_mov_b32_e32 v23, v129
	v_mov_b32_e32 v24, v129
	v_mov_b32_e32 v25, v129
	v_mov_b32_e32 v26, v129
	v_mov_b32_e32 v27, v129
	v_mov_b32_e32 v28, v129
	v_mov_b32_e32 v29, v129
	v_mov_b32_e32 v30, v129
	v_mov_b32_e32 v31, v129
	v_mov_b32_e32 v32, 0
	v_mov_b32_e32 v33, v129
	v_mov_b32_e32 v34, v129
	v_mov_b32_e32 v35, v129
	v_mov_b32_e32 v36, v129
	v_mov_b32_e32 v37, v129
	v_mov_b32_e32 v38, v129
	v_mov_b32_e32 v39, v129
	v_mov_b32_e32 v40, v129
	v_mov_b32_e32 v41, v129
	v_mov_b32_e32 v42, v129
	v_mov_b32_e32 v43, v129
	v_mov_b32_e32 v44, v129
	v_mov_b32_e32 v45, v129
	v_mov_b32_e32 v46, v129
	v_mov_b32_e32 v47, v129
	v_mov_b32_e32 v48, 0
	v_mov_b32_e32 v49, v129
	v_mov_b32_e32 v50, v129
	v_mov_b32_e32 v51, v129
	v_mov_b32_e32 v52, v129
	v_mov_b32_e32 v53, v129
	v_mov_b32_e32 v54, v129
	v_mov_b32_e32 v55, v129
	v_mov_b32_e32 v56, v129
	v_mov_b32_e32 v57, v129
	v_mov_b32_e32 v58, v129
	s_waitcnt vmcnt(3)
	v_lshl_add_u32 v0, v2, 10, s44
	s_waitcnt vmcnt(2)
	v_lshl_add_u32 v2, v4, 10, s44
	v_or_b32_e32 v0, v0, v147
	s_waitcnt vmcnt(1)
	v_lshl_add_u32 v4, v10, 10, s44
	v_or_b32_e32 v2, v2, v147
	v_lshlrev_b32_e32 v128, 1, v0
	s_waitcnt vmcnt(0)
	v_lshl_add_u32 v10, v11, 10, s44
	v_or_b32_e32 v4, v4, v147
	v_lshlrev_b32_e32 v0, 1, v2
	s_nop 0
	s_mov_b32 m0, s31
	v_or_b32_e32 v10, v10, v147
	v_lshlrev_b32_e32 v2, 1, v4
	s_nop 0
	s_mov_b32 m0, s34
	v_lshlrev_b32_e32 v4, 1, v10
	s_nop 0
	s_mov_b32 m0, s35
	v_lshl_add_u64 v[138:139], s[4:5], 0, v[128:129]
	s_nop 0
	s_mov_b32 m0, s36
	v_lshl_add_u64 v[140:141], s[4:5], 0, v[0:1]
	s_nop 0
	s_mov_b32 m0, s37
	v_lshl_add_u64 v[0:1], v[138:139], 0, 64
	s_nop 0
	s_mov_b32 m0, s38
	v_lshl_add_u64 v[142:143], s[4:5], 0, v[2:3]
	v_lshl_add_u64 v[10:11], v[140:141], 0, 64
	s_nop 0
	s_mov_b32 m0, s39
	v_lshl_add_u64 v[144:145], s[4:5], 0, v[4:5]
	v_lshl_add_u64 v[12:13], v[142:143], 0, 64
	s_nop 0
	s_mov_b32 m0, s40
	v_lshl_add_u64 v[14:15], v[144:145], 0, 64
	s_nop 0
	s_mov_b32 m0, s41
	v_mov_b32_e32 v0, 0
	s_nop 0
	s_mov_b32 m0, s42
	v_mov_b32_e32 v1, v129
	s_nop 0
	s_mov_b32 m0, s43
	v_mov_b32_e32 v2, v129
	s_nop 0
	v_mov_b32_e32 v4, v129
	v_mov_b32_e32 v6, v129
	v_mov_b32_e32 v7, v129
	v_mov_b32_e32 v8, v129
	v_mov_b32_e32 v9, v129
	v_mov_b32_e32 v10, v129
	v_mov_b32_e32 v11, v129
	v_mov_b32_e32 v12, v129
	v_mov_b32_e32 v13, v129
	v_mov_b32_e32 v14, v129
	v_mov_b32_e32 v15, v129
	v_mov_b32_e32 v59, v129
	v_mov_b32_e32 v60, v129
	v_mov_b32_e32 v61, v129
	v_mov_b32_e32 v62, v129
	v_mov_b32_e32 v63, v129
	v_mov_b32_e32 v64, 0
	v_mov_b32_e32 v65, v129
	v_mov_b32_e32 v66, v129
	v_mov_b32_e32 v67, v129
	v_mov_b32_e32 v68, v129
	v_mov_b32_e32 v69, v129
	v_mov_b32_e32 v70, v129
	v_mov_b32_e32 v71, v129
	v_mov_b32_e32 v72, v129
	v_mov_b32_e32 v73, v129
	v_mov_b32_e32 v74, v129
	v_mov_b32_e32 v75, v129
	v_mov_b32_e32 v76, v129
	v_mov_b32_e32 v77, v129
	v_mov_b32_e32 v78, v129
	v_mov_b32_e32 v79, v129
	v_mov_b32_e32 v80, 0
	v_mov_b32_e32 v81, v129
	v_mov_b32_e32 v82, v129
	v_mov_b32_e32 v83, v129
	v_mov_b32_e32 v84, v129
	v_mov_b32_e32 v85, v129
	v_mov_b32_e32 v86, v129
	v_mov_b32_e32 v87, v129
	v_mov_b32_e32 v88, v129
	v_mov_b32_e32 v89, v129
	v_mov_b32_e32 v90, v129
	v_mov_b32_e32 v91, v129
	v_mov_b32_e32 v92, v129
	v_mov_b32_e32 v93, v129
	v_mov_b32_e32 v94, v129
	v_mov_b32_e32 v95, v129
	v_mov_b32_e32 v96, 0
	v_mov_b32_e32 v97, v129
	v_mov_b32_e32 v98, v129
	v_mov_b32_e32 v99, v129
	v_mov_b32_e32 v100, v129
	v_mov_b32_e32 v101, v129
	v_mov_b32_e32 v102, v129
	v_mov_b32_e32 v103, v129
	v_mov_b32_e32 v104, v129
	v_mov_b32_e32 v105, v129
	v_mov_b32_e32 v106, v129
	v_mov_b32_e32 v107, v129
	v_mov_b32_e32 v108, v129
	v_mov_b32_e32 v109, v129
	v_mov_b32_e32 v110, v129
	v_mov_b32_e32 v111, v129
	v_mov_b32_e32 v112, 0
	v_mov_b32_e32 v113, v129
	v_mov_b32_e32 v114, v129
	v_mov_b32_e32 v115, v129
	v_mov_b32_e32 v116, v129
	v_mov_b32_e32 v117, v129
	v_mov_b32_e32 v118, v129
	v_mov_b32_e32 v119, v129
	v_mov_b32_e32 v120, v129
	v_mov_b32_e32 v121, v129
	v_mov_b32_e32 v122, v129
	v_mov_b32_e32 v123, v129
	v_mov_b32_e32 v124, v129
	v_mov_b32_e32 v125, v129
	v_mov_b32_e32 v126, v129
	v_mov_b32_e32 v127, v129
	s_mov_b64 s[54:55], 0x80
	v_lshrrev_b32_e32 v170, 6, v180
	v_lshlrev_b32_e32 v176, 11, v170
	v_and_b32_e32 v166, 63, v180
	v_readfirstlane_b32 s53, v176
	v_lshrrev_b32_e32 v167, 4, v166
	v_bfe_u32 v168, v166, 1, 3
	v_xor_b32_e32 v168, v167, v168
	v_and_b32_e32 v169, 31, v166
	v_lshlrev_b32_e32 v169, 7, v169
	v_lshrrev_b32_e32 v169, 3, v166
	v_lshlrev_b32_e32 v176, 4, v169
	v_add_u32_e32 v177, 0x80, v176
	v_and_b32_e32 v169, 7, v166
	v_lshrrev_b32_e32 v167, 4, v166
	v_xor_b32_e32 v167, v169, v167
	v_lshrrev_b32_e32 v169, 5, v166
	v_sub_u32_e32 v182, v167, v169
	v_xor_b32_e32 v167, 4, v167
	v_add_u32_e32 v169, 2, v169
	v_sub_u32_e32 v184, v167, v169
	v_lshlrev_b32_e32 v182, 4, v182
	v_ashrrev_i32_e32 v183, 31, v182
	v_lshlrev_b32_e32 v184, 4, v184
	v_ashrrev_i32_e32 v185, 31, v184
	ds_bpermute_b32 v242, v176, v134
	ds_bpermute_b32 v243, v176, v135
	ds_bpermute_b32 v244, v177, v134
	ds_bpermute_b32 v245, v177, v135
	ds_bpermute_b32 v246, v176, v136
	ds_bpermute_b32 v247, v176, v137
	ds_bpermute_b32 v248, v177, v136
	ds_bpermute_b32 v249, v177, v137
	s_waitcnt lgkmcnt(0)
	ds_bpermute_b32 v178, v176, v138
	ds_bpermute_b32 v179, v176, v139
	ds_bpermute_b32 v232, v177, v138
	ds_bpermute_b32 v233, v177, v139
	ds_bpermute_b32 v234, v176, v140
	ds_bpermute_b32 v235, v176, v141
	ds_bpermute_b32 v236, v177, v140
	ds_bpermute_b32 v237, v177, v141
	ds_bpermute_b32 v238, v176, v142
	ds_bpermute_b32 v239, v176, v143
	ds_bpermute_b32 v240, v177, v142
	ds_bpermute_b32 v241, v177, v143
	ds_bpermute_b32 v134, v176, v144
	ds_bpermute_b32 v135, v176, v145
	ds_bpermute_b32 v136, v177, v144
	ds_bpermute_b32 v137, v177, v145
	s_waitcnt lgkmcnt(0)
	v_and_b32_e32 v169, 15, v166
	v_lshlrev_b32_e32 v169, 7, v169
	v_lshrrev_b32_e32 v167, 1, v170
	v_lshl_add_u32 v138, v167, 14, v169
	v_and_b32_e32 v167, 1, v170
	v_lshl_add_u32 v142, v167, 13, v169
	v_add_u32_e32 v142, 0x10000, v142
	v_xor_b32_e32 v169, 4, v168
	v_lshl_add_u32 v139, v169, 4, v138
	v_lshl_add_u32 v143, v169, 4, v142
	v_xor_b32_e32 v169, 0, v168
	v_lshl_add_u32 v138, v169, 4, v138
	v_lshl_add_u32 v142, v169, 4, v142
	v_lshl_add_u64 v[178:179], v[178:179], 0, v[182:183]
	v_lshl_add_u64 v[232:233], v[232:233], 0, v[184:185]
	v_lshl_add_u64 v[234:235], v[234:235], 0, v[182:183]
	v_lshl_add_u64 v[236:237], v[236:237], 0, v[184:185]
	v_lshl_add_u64 v[238:239], v[238:239], 0, v[182:183]
	v_lshl_add_u64 v[240:241], v[240:241], 0, v[184:185]
	v_lshl_add_u64 v[134:135], v[134:135], 0, v[182:183]
	v_lshl_add_u64 v[136:137], v[136:137], 0, v[184:185]
	v_lshl_add_u64 v[242:243], v[242:243], 0, v[182:183]
	v_lshl_add_u64 v[244:245], v[244:245], 0, v[184:185]
	v_lshl_add_u64 v[246:247], v[246:247], 0, v[182:183]
	v_lshl_add_u64 v[248:249], v[248:249], 0, v[184:185]
	s_mov_b32 s58, s53
	s_add_i32 m0, s58, 0x0
	s_nop 0
	global_load_lds_dwordx4 v[178:179], off
	s_add_i32 m0, s58, 0x400
	v_lshl_add_u64 v[178:179], v[178:179], 0, s[54:55]
	global_load_lds_dwordx4 v[232:233], off
	s_add_i32 m0, s58, 0x2000
	v_lshl_add_u64 v[232:233], v[232:233], 0, s[54:55]
	global_load_lds_dwordx4 v[234:235], off
	s_add_i32 m0, s58, 0x2400
	v_lshl_add_u64 v[234:235], v[234:235], 0, s[54:55]
	global_load_lds_dwordx4 v[236:237], off
	s_add_i32 m0, s58, 0x4000
	v_lshl_add_u64 v[236:237], v[236:237], 0, s[54:55]
	global_load_lds_dwordx4 v[238:239], off
	s_add_i32 m0, s58, 0x4400
	v_lshl_add_u64 v[238:239], v[238:239], 0, s[54:55]
	global_load_lds_dwordx4 v[240:241], off
	s_add_i32 m0, s58, 0x6000
	v_lshl_add_u64 v[240:241], v[240:241], 0, s[54:55]
	global_load_lds_dwordx4 v[134:135], off
	s_add_i32 m0, s58, 0x6400
	v_lshl_add_u64 v[134:135], v[134:135], 0, s[54:55]
	global_load_lds_dwordx4 v[136:137], off
	v_lshl_add_u64 v[136:137], v[136:137], 0, s[54:55]
	s_add_i32 s58, s53, 0x10000
	s_add_i32 m0, s58, 0x0
	s_nop 0
	global_load_lds_dwordx4 v[242:243], off
	s_add_i32 m0, s58, 0x400
	v_lshl_add_u64 v[242:243], v[242:243], 0, s[54:55]
	global_load_lds_dwordx4 v[244:245], off
	s_add_i32 m0, s58, 0x2000
	v_lshl_add_u64 v[244:245], v[244:245], 0, s[54:55]
	global_load_lds_dwordx4 v[246:247], off
	s_add_i32 m0, s58, 0x2400
	v_lshl_add_u64 v[246:247], v[246:247], 0, s[54:55]
	global_load_lds_dwordx4 v[248:249], off
	v_lshl_add_u64 v[248:249], v[248:249], 0, s[54:55]
	s_mov_b32 s14, 0
	s_mov_b32 s15, 0

.Lg_ph8_noA:
	ds_read_b128 v[190:193], v142
	ds_read_b128 v[194:197], v142 offset:2048
	ds_read_b128 v[198:201], v142 offset:4096
	ds_read_b128 v[202:205], v142 offset:6144
	ds_read_b128 v[206:209], v143
	ds_read_b128 v[220:223], v143 offset:2048
	ds_read_b128 v[224:227], v143 offset:4096
	ds_read_b128 v[228:231], v143 offset:6144
	ds_read_b128 v[166:169], v138
	ds_read_b128 v[170:173], v138 offset:2048
	ds_read_b128 v[174:177], v138 offset:4096
	ds_read_b128 v[182:185], v138 offset:6144
	s_waitcnt lgkmcnt(4)
	s_barrier
	s_cmp_eq_u32 s14, 15
	s_cbranch_scc1 .Lg_ph8_noB
	s_add_i32 s58, s53, 0x10000
	s_add_i32 m0, s58, 0x0
	s_nop 0
	global_load_lds_dwordx4 v[242:243], off
	s_add_i32 m0, s58, 0x400
	v_lshl_add_u64 v[242:243], v[242:243], 0, s[54:55]
	global_load_lds_dwordx4 v[244:245], off
	s_add_i32 m0, s58, 0x2000
	v_lshl_add_u64 v[244:245], v[244:245], 0, s[54:55]
	global_load_lds_dwordx4 v[246:247], off
	s_add_i32 m0, s58, 0x2400
	v_lshl_add_u64 v[246:247], v[246:247], 0, s[54:55]
	global_load_lds_dwordx4 v[248:249], off
	v_lshl_add_u64 v[248:249], v[248:249], 0, s[54:55]
.Lg_ph8_noB:
	s_waitcnt lgkmcnt(3)
	v_mfma_f32_16x16x32_bf16 v[0:3], v[166:169], v[190:193], v[0:3]
	v_mfma_f32_16x16x32_bf16 v[4:7], v[166:169], v[194:197], v[4:7]
	v_mfma_f32_16x16x32_bf16 v[8:11], v[166:169], v[198:201], v[8:11]
	v_mfma_f32_16x16x32_bf16 v[12:15], v[166:169], v[202:205], v[12:15]
	ds_read_b128 v[166:169], v138 offset:8192
	s_waitcnt lgkmcnt(3)
	v_mfma_f32_16x16x32_bf16 v[16:19], v[170:173], v[190:193], v[16:19]
	v_mfma_f32_16x16x32_bf16 v[20:23], v[170:173], v[194:197], v[20:23]
	v_mfma_f32_16x16x32_bf16 v[24:27], v[170:173], v[198:201], v[24:27]
	v_mfma_f32_16x16x32_bf16 v[28:31], v[170:173], v[202:205], v[28:31]
	ds_read_b128 v[170:173], v138 offset:10240
	s_waitcnt lgkmcnt(3)
	v_mfma_f32_16x16x32_bf16 v[32:35], v[174:177], v[190:193], v[32:35]
	v_mfma_f32_16x16x32_bf16 v[36:39], v[174:177], v[194:197], v[36:39]
	v_mfma_f32_16x16x32_bf16 v[40:43], v[174:177], v[198:201], v[40:43]
	v_mfma_f32_16x16x32_bf16 v[44:47], v[174:177], v[202:205], v[44:47]
	ds_read_b128 v[174:177], v138 offset:12288
	s_waitcnt lgkmcnt(3)
	v_mfma_f32_16x16x32_bf16 v[48:51], v[182:185], v[190:193], v[48:51]
	v_mfma_f32_16x16x32_bf16 v[52:55], v[182:185], v[194:197], v[52:55]
	v_mfma_f32_16x16x32_bf16 v[56:59], v[182:185], v[198:201], v[56:59]
	v_mfma_f32_16x16x32_bf16 v[60:63], v[182:185], v[202:205], v[60:63]
	ds_read_b128 v[182:185], v138 offset:14336
	s_waitcnt lgkmcnt(3)
	v_mfma_f32_16x16x32_bf16 v[64:67], v[166:169], v[190:193], v[64:67]
	v_mfma_f32_16x16x32_bf16 v[68:71], v[166:169], v[194:197], v[68:71]
	v_mfma_f32_16x16x32_bf16 v[72:75], v[166:169], v[198:201], v[72:75]
	v_mfma_f32_16x16x32_bf16 v[76:79], v[166:169], v[202:205], v[76:79]
	ds_read_b128 v[166:169], v139
	s_waitcnt lgkmcnt(3)
	v_mfma_f32_16x16x32_bf16 v[80:83], v[170:173], v[190:193], v[80:83]
	v_mfma_f32_16x16x32_bf16 v[84:87], v[170:173], v[194:197], v[84:87]
	v_mfma_f32_16x16x32_bf16 v[88:91], v[170:173], v[198:201], v[88:91]
	v_mfma_f32_16x16x32_bf16 v[92:95], v[170:173], v[202:205], v[92:95]
	ds_read_b128 v[170:173], v139 offset:2048
	s_waitcnt lgkmcnt(3)
	v_mfma_f32_16x16x32_bf16 v[96:99], v[174:177], v[190:193], v[96:99]
	v_mfma_f32_16x16x32_bf16 v[100:103], v[174:177], v[194:197], v[100:103]
	v_mfma_f32_16x16x32_bf16 v[104:107], v[174:177], v[198:201], v[104:107]
	v_mfma_f32_16x16x32_bf16 v[108:111], v[174:177], v[202:205], v[108:111]
	ds_read_b128 v[174:177], v139 offset:4096
	s_waitcnt lgkmcnt(3)
	v_mfma_f32_16x16x32_bf16 v[112:115], v[182:185], v[190:193], v[112:115]
	v_mfma_f32_16x16x32_bf16 v[116:119], v[182:185], v[194:197], v[116:119]
	v_mfma_f32_16x16x32_bf16 v[120:123], v[182:185], v[198:201], v[120:123]
	v_mfma_f32_16x16x32_bf16 v[124:127], v[182:185], v[202:205], v[124:127]
	ds_read_b128 v[182:185], v139 offset:6144
	s_waitcnt lgkmcnt(3)
	v_mfma_f32_16x16x32_bf16 v[0:3], v[166:169], v[206:209], v[0:3]
	v_mfma_f32_16x16x32_bf16 v[4:7], v[166:169], v[220:223], v[4:7]
	v_mfma_f32_16x16x32_bf16 v[8:11], v[166:169], v[224:227], v[8:11]
	v_mfma_f32_16x16x32_bf16 v[12:15], v[166:169], v[228:231], v[12:15]
	ds_read_b128 v[166:169], v139 offset:8192
	s_waitcnt lgkmcnt(3)
	v_mfma_f32_16x16x32_bf16 v[16:19], v[170:173], v[206:209], v[16:19]
	v_mfma_f32_16x16x32_bf16 v[20:23], v[170:173], v[220:223], v[20:23]
	v_mfma_f32_16x16x32_bf16 v[24:27], v[170:173], v[224:227], v[24:27]
	v_mfma_f32_16x16x32_bf16 v[28:31], v[170:173], v[228:231], v[28:31]
	ds_read_b128 v[170:173], v139 offset:10240
	s_waitcnt lgkmcnt(3)
	v_mfma_f32_16x16x32_bf16 v[32:35], v[174:177], v[206:209], v[32:35]
	v_mfma_f32_16x16x32_bf16 v[36:39], v[174:177], v[220:223], v[36:39]
	v_mfma_f32_16x16x32_bf16 v[40:43], v[174:177], v[224:227], v[40:43]
	v_mfma_f32_16x16x32_bf16 v[44:47], v[174:177], v[228:231], v[44:47]
	ds_read_b128 v[174:177], v139 offset:12288
	s_waitcnt lgkmcnt(3)
	v_mfma_f32_16x16x32_bf16 v[48:51], v[182:185], v[206:209], v[48:51]
	v_mfma_f32_16x16x32_bf16 v[52:55], v[182:185], v[220:223], v[52:55]
	v_mfma_f32_16x16x32_bf16 v[56:59], v[182:185], v[224:227], v[56:59]
	v_mfma_f32_16x16x32_bf16 v[60:63], v[182:185], v[228:231], v[60:63]
	ds_read_b128 v[182:185], v139 offset:14336
	s_waitcnt lgkmcnt(3)
	v_mfma_f32_16x16x32_bf16 v[64:67], v[166:169], v[206:209], v[64:67]
	v_mfma_f32_16x16x32_bf16 v[68:71], v[166:169], v[220:223], v[68:71]
	v_mfma_f32_16x16x32_bf16 v[72:75], v[166:169], v[224:227], v[72:75]
	v_mfma_f32_16x16x32_bf16 v[76:79], v[166:169], v[228:231], v[76:79]
	s_waitcnt lgkmcnt(2)
	v_mfma_f32_16x16x32_bf16 v[80:83], v[170:173], v[206:209], v[80:83]
	v_mfma_f32_16x16x32_bf16 v[84:87], v[170:173], v[220:223], v[84:87]
	v_mfma_f32_16x16x32_bf16 v[88:91], v[170:173], v[224:227], v[88:91]
	v_mfma_f32_16x16x32_bf16 v[92:95], v[170:173], v[228:231], v[92:95]
	s_waitcnt lgkmcnt(1)
	v_mfma_f32_16x16x32_bf16 v[96:99], v[174:177], v[206:209], v[96:99]
	v_mfma_f32_16x16x32_bf16 v[100:103], v[174:177], v[220:223], v[100:103]
	v_mfma_f32_16x16x32_bf16 v[104:107], v[174:177], v[224:227], v[104:107]
	v_mfma_f32_16x16x32_bf16 v[108:111], v[174:177], v[228:231], v[108:111]
	s_waitcnt lgkmcnt(0)
	v_mfma_f32_16x16x32_bf16 v[112:115], v[182:185], v[206:209], v[112:115]
	v_mfma_f32_16x16x32_bf16 v[116:119], v[182:185], v[220:223], v[116:119]
	v_mfma_f32_16x16x32_bf16 v[120:123], v[182:185], v[224:227], v[120:123]
	v_mfma_f32_16x16x32_bf16 v[124:127], v[182:185], v[228:231], v[124:127]
	v_xor_b32_e32 v138, 0x8000, v138
	v_xor_b32_e32 v139, 0x8000, v139
	s_xor_b32 s15, s15, 0x8000
	s_add_i32 s14, s14, 1
	s_cmp_eq_u32 s14, 16
	s_cbranch_scc0 .Lg_ph8_top
	s_waitcnt vmcnt(0)
	v_mov_b32_e32 v128, v180
	v_add_u32_e32 v193, 0x400, v153
	v_add_u32_e32 v192, 0x1000, v153
	v_add_u32_e32 v191, 0x1400, v153
	v_add_u32_e32 v190, 0x2000, v153
	v_add_u32_e32 v183, 0x2400, v153
	v_add_u32_e32 v184, 0x3000, v153
	v_add_u32_e32 v185, 0x3200, v153
	v_add_u32_e32 v186, 0x3400, v153
	v_add_u32_e32 v187, 0x3600, v153
	v_add_u32_e32 v189, 0x4000, v153
	v_add_u32_e32 v179, 0x4400, v153
	v_add_u32_e32 v181, 0x4800, v153
	v_add_u32_e32 v182, 0x5000, v153
	v_add_u32_e32 v176, 0x5400, v153
	v_add_u32_e32 v177, 0x5800, v153
	v_add_u32_e32 v178, 0x6000, v153
	v_add_u32_e32 v170, 0x6400, v153
	v_add_u32_e32 v171, 0x6800, v153
	v_add_u32_e32 v172, 0x7200, v153
	v_add_u32_e32 v173, 0x7400, v153
	v_add_u32_e32 v174, 0x7600, v153
	v_add_u32_e32 v175, 0x7800, v153
	v_add_u32_e32 v169, 0x8400, v153
	v_add_u32_e32 v168, 0x8800, v153
	v_add_u32_e32 v167, 0x9400, v153
	v_add_u32_e32 v166, 0x9800, v153
	v_add_u32_e32 v145, 0xa400, v153
	v_add_u32_e32 v140, 0xa800, v153
	v_add_u32_e32 v141, 0xb400, v153
	v_add_u32_e32 v142, 0xb600, v153
	v_add_u32_e32 v143, 0xb800, v153
	v_add_u32_e32 v144, 0xba00, v153
	s_waitcnt vmcnt(0)
	s_barrier
	s_and_saveexec_b64 s[14:15], s[6:7]
	s_cbranch_execz .LBB0_959
	v_and_b32_e32 v254, 63, v180
	v_lshrrev_b32_e32 v253, 4, v254
	v_mul_u32_u24_e32 v253, 0x840, v253
	v_and_b32_e32 v254, 15, v254
	v_lshl_add_u32 v253, v254, 2, v253
	v_and_b32_e32 v254, 64, v180
	v_lshl_add_u32 v253, v254, 2, v253
	ds_write_b32 v253, v0 offset:0
	ds_write_b32 v253, v1 offset:528
	ds_write_b32 v253, v2 offset:1056
	ds_write_b32 v253, v3 offset:1584
	ds_write_b32 v253, v4 offset:64
	ds_write_b32 v253, v5 offset:592
	ds_write_b32 v253, v6 offset:1120
	ds_write_b32 v253, v7 offset:1648
	ds_write_b32 v253, v8 offset:128
	ds_write_b32 v253, v9 offset:656
	ds_write_b32 v253, v10 offset:1184
	ds_write_b32 v253, v11 offset:1712
	ds_write_b32 v253, v12 offset:192
	ds_write_b32 v253, v13 offset:720
	ds_write_b32 v253, v14 offset:1248
	ds_write_b32 v253, v15 offset:1776
	ds_write_b32 v253, v16 offset:8448
	ds_write_b32 v253, v17 offset:8976
	ds_write_b32 v253, v18 offset:9504
	ds_write_b32 v253, v19 offset:10032
	ds_write_b32 v253, v20 offset:8512
	ds_write_b32 v253, v21 offset:9040
	ds_write_b32 v253, v22 offset:9568
	ds_write_b32 v253, v23 offset:10096
	ds_write_b32 v253, v24 offset:8576
	ds_write_b32 v253, v25 offset:9104
	ds_write_b32 v253, v26 offset:9632
	ds_write_b32 v253, v27 offset:10160
	ds_write_b32 v253, v28 offset:8640
	ds_write_b32 v253, v29 offset:9168
	ds_write_b32 v253, v30 offset:9696
	ds_write_b32 v253, v31 offset:10224
	ds_write_b32 v253, v32 offset:16896
	ds_write_b32 v253, v33 offset:17424
	ds_write_b32 v253, v34 offset:17952
	ds_write_b32 v253, v35 offset:18480
	ds_write_b32 v253, v36 offset:16960
	ds_write_b32 v253, v37 offset:17488
	ds_write_b32 v253, v38 offset:18016
	ds_write_b32 v253, v39 offset:18544
	ds_write_b32 v253, v40 offset:17024
	ds_write_b32 v253, v41 offset:17552
	ds_write_b32 v253, v42 offset:18080
	ds_write_b32 v253, v43 offset:18608
	ds_write_b32 v253, v44 offset:17088
	ds_write_b32 v253, v45 offset:17616
	ds_write_b32 v253, v46 offset:18144
	ds_write_b32 v253, v47 offset:18672
	ds_write_b32 v253, v48 offset:25344
	ds_write_b32 v253, v49 offset:25872
	ds_write_b32 v253, v50 offset:26400
	ds_write_b32 v253, v51 offset:26928
	ds_write_b32 v253, v52 offset:25408
	ds_write_b32 v253, v53 offset:25936
	ds_write_b32 v253, v54 offset:26464
	ds_write_b32 v253, v55 offset:26992
	ds_write_b32 v253, v56 offset:25472
	ds_write_b32 v253, v57 offset:26000
	ds_write_b32 v253, v58 offset:26528
	ds_write_b32 v253, v59 offset:27056
	ds_write_b32 v253, v60 offset:25536
	ds_write_b32 v253, v61 offset:26064
	ds_write_b32 v253, v62 offset:26592
	ds_write_b32 v253, v63 offset:27120
	ds_write_b32 v253, v64 offset:33792
	ds_write_b32 v253, v65 offset:34320
	ds_write_b32 v253, v66 offset:34848
	ds_write_b32 v253, v67 offset:35376
	ds_write_b32 v253, v68 offset:33856
	ds_write_b32 v253, v69 offset:34384
	ds_write_b32 v253, v70 offset:34912
	ds_write_b32 v253, v71 offset:35440
	ds_write_b32 v253, v72 offset:33920
	ds_write_b32 v253, v73 offset:34448
	ds_write_b32 v253, v74 offset:34976
	ds_write_b32 v253, v75 offset:35504
	ds_write_b32 v253, v76 offset:33984
	ds_write_b32 v253, v77 offset:34512
	ds_write_b32 v253, v78 offset:35040
	ds_write_b32 v253, v79 offset:35568
	ds_write_b32 v253, v80 offset:42240
	ds_write_b32 v253, v81 offset:42768
	ds_write_b32 v253, v82 offset:43296
	ds_write_b32 v253, v83 offset:43824
	ds_write_b32 v253, v84 offset:42304
	ds_write_b32 v253, v85 offset:42832
	ds_write_b32 v253, v86 offset:43360
	ds_write_b32 v253, v87 offset:43888
	ds_write_b32 v253, v88 offset:42368
	ds_write_b32 v253, v89 offset:42896
	ds_write_b32 v253, v90 offset:43424
	ds_write_b32 v253, v91 offset:43952
	ds_write_b32 v253, v92 offset:42432
	ds_write_b32 v253, v93 offset:42960
	ds_write_b32 v253, v94 offset:43488
	ds_write_b32 v253, v95 offset:44016
	ds_write_b32 v253, v96 offset:50688
	ds_write_b32 v253, v97 offset:51216
	ds_write_b32 v253, v98 offset:51744
	ds_write_b32 v253, v99 offset:52272
	ds_write_b32 v253, v100 offset:50752
	ds_write_b32 v253, v101 offset:51280
	ds_write_b32 v253, v102 offset:51808
	ds_write_b32 v253, v103 offset:52336
	ds_write_b32 v253, v104 offset:50816
	ds_write_b32 v253, v105 offset:51344
	ds_write_b32 v253, v106 offset:51872
	ds_write_b32 v253, v107 offset:52400
	ds_write_b32 v253, v108 offset:50880
	ds_write_b32 v253, v109 offset:51408
	ds_write_b32 v253, v110 offset:51936
	ds_write_b32 v253, v111 offset:52464
	ds_write_b32 v253, v112 offset:59136
	ds_write_b32 v253, v113 offset:59664
	ds_write_b32 v253, v114 offset:60192
	ds_write_b32 v253, v115 offset:60720
	ds_write_b32 v253, v116 offset:59200
	ds_write_b32 v253, v117 offset:59728
	ds_write_b32 v253, v118 offset:60256
	ds_write_b32 v253, v119 offset:60784
	ds_write_b32 v253, v120 offset:59264
	ds_write_b32 v253, v121 offset:59792
	ds_write_b32 v253, v122 offset:60320
	ds_write_b32 v253, v123 offset:60848
	ds_write_b32 v253, v124 offset:59328
	ds_write_b32 v253, v125 offset:59856
	ds_write_b32 v253, v126 offset:60384
	ds_write_b32 v253, v127 offset:60912
.LBB0_959:
	s_or_b64 exec, exec, s[14:15]
	v_lshlrev_b32_e32 v134, 3, v128
	v_and_b32_e32 v137, 56, v134
	v_ashrrev_i32_e32 v134, 3, v128
	v_mul_lo_u32 v135, v134, s22
	v_lshlrev_b32_e32 v138, 2, v137
	v_add3_u32 v139, 0, v135, v138
	s_waitcnt lgkmcnt(0)
	s_barrier
	ds_read_b128 v[194:197], v139
	v_add_u32_e32 v128, 0x100, v128
	s_lshl_b32 s10, s26, 19
	s_lshl_b32 s14, s27, 20
	v_ashrrev_i32_e32 v136, 3, v128
	s_waitcnt lgkmcnt(0)
	v_mul_f32_e32 v135, 0xbfb8aa3b, v194
	v_exp_f32_e32 v202, v135
	v_mul_f32_e32 v135, 0xbfb8aa3b, v195
	v_exp_f32_e32 v203, v135
	ds_read_b128 v[198:201], v139 offset:16
	s_or_b32 s10, s14, s10
	s_add_u32 s10, s16, s10
	v_pk_add_f32 v[206:207], v[202:203], 1.0 op_sel_hi:[1,0]
	v_mul_lo_u32 v202, v136, s22
	v_div_scale_f32 v128, s[26:27], v207, v207, v195
	v_rcp_f32_e32 v135, v128
	v_add3_u32 v138, 0, v202, v138
	ds_read_b128 v[202:205], v139 offset:256
	s_addc_u32 s15, s17, 0
	v_fma_f32 v208, -v128, v135, 1.0
	v_fmac_f32_e32 v135, v208, v135
	v_div_scale_f32 v208, vcc, v195, v207, v195
	v_mul_f32_e32 v209, v208, v135
	v_fma_f32 v210, -v128, v209, v208
	v_fmac_f32_e32 v209, v210, v135
	v_div_scale_f32 v210, s[26:27], v206, v206, v194
	v_rcp_f32_e32 v211, v210
	v_fma_f32 v128, -v128, v209, v208
	v_div_fmas_f32 v128, v128, v135, v209
	v_div_fixup_f32 v195, v128, v207, v195
	v_fma_f32 v128, -v210, v211, 1.0
	v_fmac_f32_e32 v211, v128, v211
	v_div_scale_f32 v128, vcc, v194, v206, v194
	v_mul_f32_e32 v135, v128, v211
	v_fma_f32 v207, -v210, v135, v128
	v_fmac_f32_e32 v135, v207, v211
	v_mul_f32_e32 v207, 0xbfb8aa3b, v196
	v_exp_f32_e32 v208, v207
	v_mul_f32_e32 v207, 0xbfb8aa3b, v197
	v_exp_f32_e32 v209, v207
	v_fma_f32 v128, -v210, v135, v128
	v_div_fmas_f32 v128, v128, v211, v135
	v_div_fixup_f32 v194, v128, v206, v194
	v_pk_add_f32 v[210:211], v[208:209], 1.0 op_sel_hi:[1,0]
	s_waitcnt lgkmcnt(0)
	v_pk_mul_f32 v[194:195], v[194:195], v[202:203]
	v_div_scale_f32 v135, s[26:27], v211, v211, v197
	v_rcp_f32_e32 v214, v135
	ds_read_b128 v[206:209], v139 offset:272
	s_lshl_b32 s14, s28, 7
	s_add_u32 s14, s10, s14
	v_fma_f32 v128, -v135, v214, 1.0
	v_fmac_f32_e32 v214, v128, v214
	v_div_scale_f32 v128, vcc, v197, v211, v197
	v_mul_f32_e32 v202, v128, v214
	v_fma_f32 v203, -v135, v202, v128
	v_fmac_f32_e32 v202, v203, v214
	v_fma_f32 v128, -v135, v202, v128
	v_div_scale_f32 v135, s[26:27], v210, v210, v196
	v_rcp_f32_e32 v215, v135
	v_div_fmas_f32 v128, v128, v214, v202
	v_mul_f32_e32 v202, 0xbfb8aa3b, v198
	v_mul_f32_e32 v203, 0xbfb8aa3b, v199
	v_div_fixup_f32 v197, v128, v211, v197
	v_fma_f32 v128, -v135, v215, 1.0
	v_exp_f32_e32 v202, v202
	v_exp_f32_e32 v203, v203
	v_fmac_f32_e32 v215, v128, v215
	v_div_scale_f32 v128, vcc, v196, v210, v196
	v_mul_f32_e32 v211, v128, v215
	v_fma_f32 v214, -v135, v211, v128
	v_fmac_f32_e32 v211, v214, v215
	v_pk_add_f32 v[202:203], v[202:203], 1.0 op_sel_hi:[1,0]
	v_fma_f32 v128, -v135, v211, v128
	v_div_scale_f32 v135, s[26:27], v203, v203, v199
	v_rcp_f32_e32 v214, v135
	v_div_fmas_f32 v128, v128, v215, v211
	v_div_fixup_f32 v196, v128, v210, v196
	v_pk_mul_f32 v[196:197], v[196:197], v[204:205]
	v_fma_f32 v128, -v135, v214, 1.0
	v_fmac_f32_e32 v214, v128, v214
	v_div_scale_f32 v128, vcc, v199, v203, v199
	v_mul_f32_e32 v204, v128, v214
	v_fma_f32 v205, -v135, v204, v128
	v_fmac_f32_e32 v204, v205, v214
	v_fma_f32 v128, -v135, v204, v128
	v_div_scale_f32 v135, s[26:27], v202, v202, v198
	v_rcp_f32_e32 v210, v135
	v_div_fmas_f32 v128, v128, v214, v204
	v_mul_f32_e32 v204, 0xbfb8aa3b, v200
	v_mul_f32_e32 v205, 0xbfb8aa3b, v201
	v_div_fixup_f32 v199, v128, v203, v199
	v_fma_f32 v128, -v135, v210, 1.0
	v_exp_f32_e32 v204, v204
	v_exp_f32_e32 v205, v205
	v_fmac_f32_e32 v210, v128, v210
	v_div_scale_f32 v128, vcc, v198, v202, v198
	v_mul_f32_e32 v203, v128, v210
	v_fma_f32 v211, -v135, v203, v128
	v_fmac_f32_e32 v203, v211, v210
	v_pk_add_f32 v[204:205], v[204:205], 1.0 op_sel_hi:[1,0]
	v_fma_f32 v128, -v135, v203, v128
	v_div_scale_f32 v135, s[26:27], v205, v205, v201
	v_rcp_f32_e32 v211, v135
	v_div_fmas_f32 v128, v128, v210, v203
	v_div_fixup_f32 v198, v128, v202, v198
	s_waitcnt lgkmcnt(0)
	v_pk_mul_f32 v[202:203], v[198:199], v[206:207]
	v_fma_f32 v128, -v135, v211, 1.0
	v_fmac_f32_e32 v211, v128, v211
	v_div_scale_f32 v128, vcc, v201, v205, v201
	v_mul_f32_e32 v198, v128, v211
	v_fma_f32 v199, -v135, v198, v128
	v_fmac_f32_e32 v198, v199, v211
	v_fma_f32 v128, -v135, v198, v128
	v_div_scale_f32 v135, s[26:27], v204, v204, v200
	v_rcp_f32_e32 v206, v135
	v_div_fmas_f32 v128, v128, v211, v198
	v_div_fixup_f32 v199, v128, v205, v201
	s_addc_u32 s15, s15, 0
	v_fma_f32 v128, -v135, v206, 1.0
	v_fmac_f32_e32 v206, v128, v206
	v_div_scale_f32 v128, vcc, v200, v204, v200
	v_mul_f32_e32 v198, v128, v206
	v_fma_f32 v201, -v135, v198, v128
	v_fmac_f32_e32 v198, v201, v206
	v_fma_f32 v128, -v135, v198, v128
	v_div_fmas_f32 v128, v128, v206, v198
	v_div_fixup_f32 v198, v128, v204, v200
	v_pk_mul_f32 v[204:205], v[198:199], v[208:209]
	ds_read_b128 v[198:201], v138
	v_ashrrev_i32_e32 v135, 31, v134
	v_lshlrev_b64 v[134:135], 11, v[134:135]
	v_lshl_add_u64 v[134:135], s[14:15], 0, v[134:135]
	v_cvt_pk_bf16_f32 v194, v194, v195
	s_waitcnt lgkmcnt(0)
	v_mul_f32_e32 v128, 0xbfb8aa3b, v198
	v_exp_f32_e32 v206, v128
	v_mul_f32_e32 v128, 0xbfb8aa3b, v199
	v_exp_f32_e32 v207, v128
	v_lshlrev_b32_e32 v128, 1, v137
	v_cvt_pk_bf16_f32 v195, v196, v197
	v_cvt_pk_bf16_f32 v196, v202, v203
	v_pk_add_f32 v[206:207], v[206:207], 1.0 op_sel_hi:[1,0]
	v_cvt_pk_bf16_f32 v197, v204, v205
	v_div_scale_f32 v137, s[26:27], v207, v207, v199
	v_rcp_f32_e32 v208, v137
	v_lshl_add_u64 v[134:135], v[134:135], 0, v[128:129]
	global_store_dwordx4 v[134:135], v[194:197], off
	ds_read_b128 v[194:197], v138 offset:256
	v_fma_f32 v209, -v137, v208, 1.0
	v_fmac_f32_e32 v208, v209, v208
	v_div_scale_f32 v209, vcc, v199, v207, v199
	v_mul_f32_e32 v210, v209, v208
	v_fma_f32 v211, -v137, v210, v209
	v_fmac_f32_e32 v210, v211, v208
	v_div_scale_f32 v211, s[26:27], v206, v206, v198
	v_rcp_f32_e32 v214, v211
	v_fma_f32 v137, -v137, v210, v209
	v_div_fmas_f32 v137, v137, v208, v210
	v_div_fixup_f32 v199, v137, v207, v199
	v_fma_f32 v137, -v211, v214, 1.0
	v_fmac_f32_e32 v214, v137, v214
	v_div_scale_f32 v137, vcc, v198, v206, v198
	v_mul_f32_e32 v207, v137, v214
	v_fma_f32 v208, -v211, v207, v137
	v_fmac_f32_e32 v207, v208, v214
	v_mul_f32_e32 v208, 0xbfb8aa3b, v200
	v_mul_f32_e32 v209, 0xbfb8aa3b, v201
	v_exp_f32_e32 v208, v208
	v_exp_f32_e32 v209, v209
	v_fma_f32 v137, -v211, v207, v137
	v_div_fmas_f32 v137, v137, v214, v207
	v_div_fixup_f32 v198, v137, v206, v198
	v_pk_add_f32 v[210:211], v[208:209], 1.0 op_sel_hi:[1,0]
	s_waitcnt lgkmcnt(0)
	v_pk_mul_f32 v[214:215], v[198:199], v[194:195]
	v_div_scale_f32 v216, s[26:27], v211, v211, v201
	v_rcp_f32_e32 v217, v216
	ds_read_b128 v[202:205], v138 offset:16
	ds_read_b128 v[206:209], v138 offset:272
	v_fma_f32 v137, -v216, v217, 1.0
	v_fmac_f32_e32 v217, v137, v217
	v_div_scale_f32 v137, vcc, v201, v211, v201
	v_mul_f32_e32 v194, v137, v217
	v_fma_f32 v195, -v216, v194, v137
	v_fmac_f32_e32 v194, v195, v217
	v_fma_f32 v137, -v216, v194, v137
	v_div_scale_f32 v216, s[26:27], v210, v210, v200
	v_rcp_f32_e32 v218, v216
	s_waitcnt lgkmcnt(1)
	v_mul_f32_e32 v198, 0xbfb8aa3b, v202
	v_mul_f32_e32 v199, 0xbfb8aa3b, v203
	v_div_fmas_f32 v137, v137, v217, v194
	v_exp_f32_e32 v198, v198
	v_exp_f32_e32 v199, v199
	v_div_fixup_f32 v195, v137, v211, v201
	v_fma_f32 v137, -v216, v218, 1.0
	v_fmac_f32_e32 v218, v137, v218
	v_div_scale_f32 v137, vcc, v200, v210, v200
	v_mul_f32_e32 v194, v137, v218
	v_fma_f32 v201, -v216, v194, v137
	v_pk_add_f32 v[198:199], v[198:199], 1.0 op_sel_hi:[1,0]
	v_fmac_f32_e32 v194, v201, v218
	v_div_scale_f32 v201, s[26:27], v199, v199, v203
	v_rcp_f32_e32 v211, v201
	v_fma_f32 v137, -v216, v194, v137
	v_div_fmas_f32 v137, v137, v218, v194
	v_div_fixup_f32 v194, v137, v210, v200
	v_fma_f32 v137, -v201, v211, 1.0
	v_fmac_f32_e32 v211, v137, v211
	v_div_scale_f32 v137, vcc, v203, v199, v203
	v_pk_mul_f32 v[194:195], v[194:195], v[196:197]
	v_mul_f32_e32 v196, v137, v211
	v_fma_f32 v197, -v201, v196, v137
	v_fmac_f32_e32 v196, v197, v211
	v_fma_f32 v137, -v201, v196, v137
	v_div_scale_f32 v210, s[26:27], v198, v198, v202
	v_rcp_f32_e32 v216, v210
	v_div_fmas_f32 v137, v137, v211, v196
	v_div_fixup_f32 v197, v137, v199, v203
	v_mul_f32_e32 v199, 0xbfb8aa3b, v204
	v_exp_f32_e32 v200, v199
	v_mul_f32_e32 v199, 0xbfb8aa3b, v205
	v_exp_f32_e32 v201, v199
	v_fma_f32 v137, -v210, v216, 1.0
	v_fmac_f32_e32 v216, v137, v216
	v_div_scale_f32 v137, vcc, v202, v198, v202
	v_mul_f32_e32 v196, v137, v216
	v_fma_f32 v199, -v210, v196, v137
	v_pk_add_f32 v[200:201], v[200:201], 1.0 op_sel_hi:[1,0]
	v_fmac_f32_e32 v196, v199, v216
	v_div_scale_f32 v199, s[26:27], v201, v201, v205
	v_fma_f32 v137, -v210, v196, v137
	v_rcp_f32_e32 v210, v199
	v_div_fmas_f32 v137, v137, v216, v196
	v_div_fixup_f32 v196, v137, v198, v202
	s_waitcnt lgkmcnt(0)
	v_pk_mul_f32 v[202:203], v[196:197], v[206:207]
	v_fma_f32 v137, -v199, v210, 1.0
	v_fmac_f32_e32 v210, v137, v210
	v_div_scale_f32 v137, vcc, v205, v201, v205
	v_mul_f32_e32 v196, v137, v210
	v_fma_f32 v197, -v199, v196, v137
	v_fmac_f32_e32 v196, v197, v210
	v_div_scale_f32 v198, s[26:27], v200, v200, v204
	v_fma_f32 v137, -v199, v196, v137
	v_rcp_f32_e32 v199, v198
	v_div_fmas_f32 v137, v137, v210, v196
	v_div_fixup_f32 v197, v137, v201, v205
	v_cvt_pk_bf16_f32 v195, v194, v195
	v_fma_f32 v137, -v198, v199, 1.0
	v_fmac_f32_e32 v199, v137, v199
	v_div_scale_f32 v137, vcc, v204, v200, v204
	v_mul_f32_e32 v196, v137, v199
	v_fma_f32 v201, -v198, v196, v137
	v_fmac_f32_e32 v196, v201, v199
	v_fma_f32 v137, -v198, v196, v137
	v_div_fmas_f32 v137, v137, v199, v196
	v_div_fixup_f32 v196, v137, v200, v204
	ds_read_b128 v[198:201], v139 offset:33792
	v_pk_mul_f32 v[196:197], v[196:197], v[208:209]
	v_cvt_pk_bf16_f32 v194, v214, v215
	v_cvt_pk_bf16_f32 v197, v196, v197
	v_cvt_pk_bf16_f32 v196, v202, v203
	s_waitcnt lgkmcnt(0)
	v_mul_f32_e32 v137, 0xbfb8aa3b, v198
	v_exp_f32_e32 v206, v137
	v_mul_f32_e32 v137, 0xbfb8aa3b, v199
	v_exp_f32_e32 v207, v137
	v_ashrrev_i32_e32 v137, 31, v136
	v_lshlrev_b64 v[136:137], 11, v[136:137]
	v_lshl_add_u64 v[136:137], s[14:15], 0, v[136:137]
	v_pk_add_f32 v[206:207], v[206:207], 1.0 op_sel_hi:[1,0]
	v_lshl_add_u64 v[136:137], v[136:137], 0, v[128:129]
	v_div_scale_f32 v208, s[14:15], v207, v207, v199
	v_rcp_f32_e32 v209, v208
	global_store_dwordx4 v[136:137], v[194:197], off
	ds_read_b128 v[194:197], v139 offset:34048
	ds_read_b128 v[202:205], v139 offset:33808
	v_fma_f32 v128, -v208, v209, 1.0
	v_fmac_f32_e32 v209, v128, v209
	v_div_scale_f32 v128, vcc, v199, v207, v199
	v_mul_f32_e32 v210, v128, v209
	v_fma_f32 v211, -v208, v210, v128
	v_fmac_f32_e32 v210, v211, v209
	v_div_scale_f32 v211, s[14:15], v206, v206, v198
	v_rcp_f32_e32 v214, v211
	v_fma_f32 v128, -v208, v210, v128
	v_div_fmas_f32 v128, v128, v209, v210
	v_div_fixup_f32 v199, v128, v207, v199
	v_fma_f32 v128, -v211, v214, 1.0
	v_fmac_f32_e32 v214, v128, v214
	v_div_scale_f32 v128, vcc, v198, v206, v198
	v_mul_f32_e32 v207, v128, v214
	v_fma_f32 v208, -v211, v207, v128
	v_fmac_f32_e32 v207, v208, v214
	v_mul_f32_e32 v208, 0xbfb8aa3b, v200
	v_mul_f32_e32 v209, 0xbfb8aa3b, v201
	v_exp_f32_e32 v208, v208
	v_exp_f32_e32 v209, v209
	v_fma_f32 v128, -v211, v207, v128
	v_div_fmas_f32 v128, v128, v214, v207
	v_div_fixup_f32 v198, v128, v206, v198
	v_pk_add_f32 v[210:211], v[208:209], 1.0 op_sel_hi:[1,0]
	s_waitcnt lgkmcnt(1)
	v_pk_mul_f32 v[198:199], v[198:199], v[194:195]
	v_div_scale_f32 v214, s[14:15], v211, v211, v201
	v_rcp_f32_e32 v215, v214
	v_div_scale_f32 v216, s[14:15], v210, v210, v200
	v_rcp_f32_e32 v217, v216
	v_fma_f32 v128, -v214, v215, 1.0
	v_fmac_f32_e32 v215, v128, v215
	v_div_scale_f32 v128, vcc, v201, v211, v201
	v_mul_f32_e32 v194, v128, v215
	v_fma_f32 v195, -v214, v194, v128
	v_fmac_f32_e32 v194, v195, v215
	v_fma_f32 v128, -v214, v194, v128
	v_div_fmas_f32 v128, v128, v215, v194
	v_div_fixup_f32 v195, v128, v211, v201
	s_waitcnt lgkmcnt(0)
	v_mul_f32_e32 v201, 0xbfb8aa3b, v202
	v_exp_f32_e32 v214, v201
	v_mul_f32_e32 v201, 0xbfb8aa3b, v203
	v_exp_f32_e32 v215, v201
	v_fma_f32 v128, -v216, v217, 1.0
	v_fmac_f32_e32 v217, v128, v217
	v_div_scale_f32 v128, vcc, v200, v210, v200
	v_mul_f32_e32 v194, v128, v217
	v_fma_f32 v201, -v216, v194, v128
	v_pk_add_f32 v[214:215], v[214:215], 1.0 op_sel_hi:[1,0]
	v_fmac_f32_e32 v194, v201, v217
	v_div_scale_f32 v211, s[14:15], v215, v215, v203
	v_fma_f32 v128, -v216, v194, v128
	v_rcp_f32_e32 v216, v211
	v_div_fmas_f32 v128, v128, v217, v194
	v_div_fixup_f32 v194, v128, v210, v200
	v_pk_mul_f32 v[200:201], v[194:195], v[196:197]
	v_fma_f32 v128, -v211, v216, 1.0
	v_fmac_f32_e32 v216, v128, v216
	v_div_scale_f32 v128, vcc, v203, v215, v203
	v_mul_f32_e32 v194, v128, v216
	v_div_scale_f32 v210, s[14:15], v214, v214, v202
	v_fma_f32 v195, -v211, v194, v128
	v_rcp_f32_e32 v217, v210
	v_fmac_f32_e32 v194, v195, v216
	v_fma_f32 v128, -v211, v194, v128
	v_div_fmas_f32 v128, v128, v216, v194
	v_div_fixup_f32 v195, v128, v215, v203
	v_fma_f32 v128, -v210, v217, 1.0
	v_mul_f32_e32 v196, 0xbfb8aa3b, v204
	v_mul_f32_e32 v197, 0xbfb8aa3b, v205
	v_fmac_f32_e32 v217, v128, v217
	v_div_scale_f32 v128, vcc, v202, v214, v202
	v_exp_f32_e32 v196, v196
	v_exp_f32_e32 v197, v197
	v_mul_f32_e32 v194, v128, v217
	v_fma_f32 v203, -v210, v194, v128
	v_fmac_f32_e32 v194, v203, v217
	v_fma_f32 v128, -v210, v194, v128
	v_pk_add_f32 v[210:211], v[196:197], 1.0 op_sel_hi:[1,0]
	ds_read_b128 v[206:209], v139 offset:34064
	v_div_scale_f32 v196, s[14:15], v211, v211, v205
	v_rcp_f32_e32 v197, v196
	v_div_fmas_f32 v128, v128, v217, v194
	v_div_fixup_f32 v194, v128, v214, v202
	s_waitcnt lgkmcnt(0)
	v_pk_mul_f32 v[206:207], v[194:195], v[206:207]
	v_fma_f32 v128, -v196, v197, 1.0
	v_fmac_f32_e32 v197, v128, v197
	v_div_scale_f32 v128, vcc, v205, v211, v205
	v_mul_f32_e32 v194, v128, v197
	v_fma_f32 v195, -v196, v194, v128
	v_fmac_f32_e32 v194, v195, v197
	v_div_scale_f32 v195, s[14:15], v210, v210, v204
	v_fma_f32 v128, -v196, v194, v128
	v_rcp_f32_e32 v196, v195
	v_div_fmas_f32 v128, v128, v197, v194
	v_div_fixup_f32 v203, v128, v211, v205
	v_cvt_pk_bf16_f32 v198, v198, v199
	v_fma_f32 v128, -v195, v196, 1.0
	v_fmac_f32_e32 v196, v128, v196
	v_div_scale_f32 v128, vcc, v204, v210, v204
	v_mul_f32_e32 v194, v128, v196
	v_fma_f32 v197, -v195, v194, v128
	v_fmac_f32_e32 v194, v197, v196
	v_fma_f32 v128, -v195, v194, v128
	v_div_fmas_f32 v128, v128, v196, v194
	ds_read_b128 v[194:197], v138 offset:33792
	v_div_fixup_f32 v202, v128, v210, v204
	v_cvt_pk_bf16_f32 v199, v200, v201
	v_cvt_pk_bf16_f32 v200, v206, v207
	v_pk_mul_f32 v[208:209], v[202:203], v[208:209]
	s_waitcnt lgkmcnt(0)
	v_mul_f32_e32 v128, 0xbfb8aa3b, v194
	v_exp_f32_e32 v210, v128
	v_mul_f32_e32 v128, 0xbfb8aa3b, v195
	v_exp_f32_e32 v211, v128
	v_cvt_pk_bf16_f32 v201, v208, v209
	v_add_co_u32_e32 v208, vcc, s23, v134
	v_pk_add_f32 v[206:207], v[210:211], 1.0 op_sel_hi:[1,0]
	s_nop 0
	v_addc_co_u32_e32 v209, vcc, 0, v135, vcc
	v_div_scale_f32 v128, s[14:15], v207, v207, v195
	v_rcp_f32_e32 v210, v128
	global_store_dwordx4 v[208:209], v[198:201], off
	ds_read_b128 v[198:201], v138 offset:34048
	ds_read_b128 v[202:205], v138 offset:33808
	v_fma_f32 v208, -v128, v210, 1.0
	v_fmac_f32_e32 v210, v208, v210
	v_div_scale_f32 v208, vcc, v195, v207, v195
	v_mul_f32_e32 v209, v208, v210
	v_fma_f32 v211, -v128, v209, v208
	v_fmac_f32_e32 v209, v211, v210
	v_div_scale_f32 v211, s[14:15], v206, v206, v194
	v_rcp_f32_e32 v214, v211
	v_fma_f32 v128, -v128, v209, v208
	v_div_fmas_f32 v128, v128, v210, v209
	v_div_fixup_f32 v195, v128, v207, v195
	v_fma_f32 v128, -v211, v214, 1.0
	v_fmac_f32_e32 v214, v128, v214
	v_div_scale_f32 v128, vcc, v194, v206, v194
	v_mul_f32_e32 v207, v128, v214
	v_fma_f32 v208, -v211, v207, v128
	v_fmac_f32_e32 v207, v208, v214
	v_mul_f32_e32 v208, 0xbfb8aa3b, v196
	v_mul_f32_e32 v209, 0xbfb8aa3b, v197
	v_exp_f32_e32 v208, v208
	v_exp_f32_e32 v209, v209
	v_fma_f32 v128, -v211, v207, v128
	v_div_fmas_f32 v128, v128, v214, v207
	v_div_fixup_f32 v194, v128, v206, v194
	v_pk_add_f32 v[210:211], v[208:209], 1.0 op_sel_hi:[1,0]
	s_waitcnt lgkmcnt(1)
	v_pk_mul_f32 v[198:199], v[194:195], v[198:199]
	v_div_scale_f32 v214, s[14:15], v211, v211, v197
	v_rcp_f32_e32 v215, v214
	v_div_scale_f32 v216, s[14:15], v210, v210, v196
	v_rcp_f32_e32 v217, v216
	v_fma_f32 v128, -v214, v215, 1.0
	v_fmac_f32_e32 v215, v128, v215
	v_div_scale_f32 v128, vcc, v197, v211, v197
	v_mul_f32_e32 v194, v128, v215
	v_fma_f32 v195, -v214, v194, v128
	v_fmac_f32_e32 v194, v195, v215
	v_fma_f32 v128, -v214, v194, v128
	v_div_fmas_f32 v128, v128, v215, v194
	v_div_fixup_f32 v195, v128, v211, v197
	s_waitcnt lgkmcnt(0)
	v_mul_f32_e32 v197, 0xbfb8aa3b, v202
	v_exp_f32_e32 v214, v197
	v_mul_f32_e32 v197, 0xbfb8aa3b, v203
	v_exp_f32_e32 v215, v197
	v_fma_f32 v128, -v216, v217, 1.0
	v_fmac_f32_e32 v217, v128, v217
	v_div_scale_f32 v128, vcc, v196, v210, v196
	v_mul_f32_e32 v194, v128, v217
	v_fma_f32 v197, -v216, v194, v128
	v_pk_add_f32 v[214:215], v[214:215], 1.0 op_sel_hi:[1,0]
	v_fmac_f32_e32 v194, v197, v217
	v_div_scale_f32 v197, s[14:15], v215, v215, v203
	v_rcp_f32_e32 v211, v197
	v_fma_f32 v128, -v216, v194, v128
	v_div_fmas_f32 v128, v128, v217, v194
	v_div_fixup_f32 v194, v128, v210, v196
	v_fma_f32 v128, -v197, v211, 1.0
	v_fmac_f32_e32 v211, v128, v211
	v_div_scale_f32 v128, vcc, v203, v215, v203
	v_mul_f32_e32 v196, v128, v211
	v_div_scale_f32 v210, s[14:15], v214, v214, v202
	v_pk_mul_f32 v[194:195], v[194:195], v[200:201]
	v_fma_f32 v200, -v197, v196, v128
	v_rcp_f32_e32 v216, v210
	v_fmac_f32_e32 v196, v200, v211
	v_fma_f32 v128, -v197, v196, v128
	v_div_fmas_f32 v128, v128, v211, v196
	v_mul_f32_e32 v200, 0xbfb8aa3b, v204
	v_mul_f32_e32 v201, 0xbfb8aa3b, v205
	v_div_fixup_f32 v197, v128, v215, v203
	v_fma_f32 v128, -v210, v216, 1.0
	v_exp_f32_e32 v200, v200
	v_exp_f32_e32 v201, v201
	v_fmac_f32_e32 v216, v128, v216
	v_div_scale_f32 v128, vcc, v202, v214, v202
	v_mul_f32_e32 v196, v128, v216
	v_fma_f32 v203, -v210, v196, v128
	v_fmac_f32_e32 v196, v203, v216
	v_pk_add_f32 v[200:201], v[200:201], 1.0 op_sel_hi:[1,0]
	v_fma_f32 v128, -v210, v196, v128
	v_div_scale_f32 v210, s[14:15], v201, v201, v205
	v_rcp_f32_e32 v211, v210
	ds_read_b128 v[206:209], v138 offset:34064
	v_div_fmas_f32 v128, v128, v216, v196
	v_div_fixup_f32 v196, v128, v214, v202
	v_fma_f32 v128, -v210, v211, 1.0
	v_fmac_f32_e32 v211, v128, v211
	v_div_scale_f32 v128, vcc, v205, v201, v205
	s_waitcnt lgkmcnt(0)
	v_pk_mul_f32 v[202:203], v[196:197], v[206:207]
	v_mul_f32_e32 v196, v128, v211
	v_div_scale_f32 v206, s[14:15], v200, v200, v204
	v_fma_f32 v197, -v210, v196, v128
	v_rcp_f32_e32 v207, v206
	v_fmac_f32_e32 v196, v197, v211
	v_fma_f32 v128, -v210, v196, v128
	v_div_fmas_f32 v128, v128, v211, v196
	v_div_fixup_f32 v197, v128, v201, v205
	v_fma_f32 v128, -v206, v207, 1.0
	v_fmac_f32_e32 v207, v128, v207
	v_div_scale_f32 v128, vcc, v204, v200, v204
	v_mul_f32_e32 v196, v128, v207
	v_fma_f32 v201, -v206, v196, v128
	v_fmac_f32_e32 v196, v201, v207
	v_fma_f32 v128, -v206, v196, v128
	v_div_fmas_f32 v128, v128, v207, v196
	v_div_fixup_f32 v196, v128, v200, v204
	v_pk_mul_f32 v[196:197], v[196:197], v[208:209]
	v_cvt_pk_bf16_f32 v195, v194, v195
	v_cvt_pk_bf16_f32 v194, v198, v199
	v_add_co_u32_e32 v198, vcc, 0x20000, v136
	v_cvt_pk_bf16_f32 v197, v196, v197
	v_cvt_pk_bf16_f32 v196, v202, v203
	v_addc_co_u32_e32 v199, vcc, 0, v137, vcc
	global_store_dwordx4 v[198:199], v[194:197], off
	s_barrier
	s_and_saveexec_b64 s[14:15], s[8:9]
	s_cbranch_execz .LBB0_954
	v_and_b32_e32 v254, 63, v180
	v_lshrrev_b32_e32 v253, 4, v254
	v_mul_u32_u24_e32 v253, 0x840, v253
	v_and_b32_e32 v254, 15, v254
	v_lshl_add_u32 v253, v254, 2, v253
	v_and_b32_e32 v254, 64, v180
	v_lshl_add_u32 v253, v254, 2, v253
	ds_write_b32 v253, v0 offset:0
	ds_write_b32 v253, v1 offset:528
	ds_write_b32 v253, v2 offset:1056
	ds_write_b32 v253, v3 offset:1584
	ds_write_b32 v253, v4 offset:64
	ds_write_b32 v253, v5 offset:592
	ds_write_b32 v253, v6 offset:1120
	ds_write_b32 v253, v7 offset:1648
	ds_write_b32 v253, v8 offset:128
	ds_write_b32 v253, v9 offset:656
	ds_write_b32 v253, v10 offset:1184
	ds_write_b32 v253, v11 offset:1712
	ds_write_b32 v253, v12 offset:192
	ds_write_b32 v253, v13 offset:720
	ds_write_b32 v253, v14 offset:1248
	ds_write_b32 v253, v15 offset:1776
	ds_write_b32 v253, v16 offset:8448
	ds_write_b32 v253, v17 offset:8976
	ds_write_b32 v253, v18 offset:9504
	ds_write_b32 v253, v19 offset:10032
	ds_write_b32 v253, v20 offset:8512
	ds_write_b32 v253, v21 offset:9040
	ds_write_b32 v253, v22 offset:9568
	ds_write_b32 v253, v23 offset:10096
	ds_write_b32 v253, v24 offset:8576
	ds_write_b32 v253, v25 offset:9104
	ds_write_b32 v253, v26 offset:9632
	ds_write_b32 v253, v27 offset:10160
	ds_write_b32 v253, v28 offset:8640
	ds_write_b32 v253, v29 offset:9168
	ds_write_b32 v253, v30 offset:9696
	ds_write_b32 v253, v31 offset:10224
	ds_write_b32 v253, v32 offset:16896
	ds_write_b32 v253, v33 offset:17424
	ds_write_b32 v253, v34 offset:17952
	ds_write_b32 v253, v35 offset:18480
	ds_write_b32 v253, v36 offset:16960
	ds_write_b32 v253, v37 offset:17488
	ds_write_b32 v253, v38 offset:18016
	ds_write_b32 v253, v39 offset:18544
	ds_write_b32 v253, v40 offset:17024
	ds_write_b32 v253, v41 offset:17552
	ds_write_b32 v253, v42 offset:18080
	ds_write_b32 v253, v43 offset:18608
	ds_write_b32 v253, v44 offset:17088
	ds_write_b32 v253, v45 offset:17616
	ds_write_b32 v253, v46 offset:18144
	ds_write_b32 v253, v47 offset:18672
	ds_write_b32 v253, v48 offset:25344
	ds_write_b32 v253, v49 offset:25872
	ds_write_b32 v253, v50 offset:26400
	ds_write_b32 v253, v51 offset:26928
	ds_write_b32 v253, v52 offset:25408
	ds_write_b32 v253, v53 offset:25936
	ds_write_b32 v253, v54 offset:26464
	ds_write_b32 v253, v55 offset:26992
	ds_write_b32 v253, v56 offset:25472
	ds_write_b32 v253, v57 offset:26000
	ds_write_b32 v253, v58 offset:26528
	ds_write_b32 v253, v59 offset:27056
	ds_write_b32 v253, v60 offset:25536
	ds_write_b32 v253, v61 offset:26064
	ds_write_b32 v253, v62 offset:26592
	ds_write_b32 v253, v63 offset:27120
	ds_write_b32 v253, v64 offset:33792
	ds_write_b32 v253, v65 offset:34320
	ds_write_b32 v253, v66 offset:34848
	ds_write_b32 v253, v67 offset:35376
	ds_write_b32 v253, v68 offset:33856
	ds_write_b32 v253, v69 offset:34384
	ds_write_b32 v253, v70 offset:34912
	ds_write_b32 v253, v71 offset:35440
	ds_write_b32 v253, v72 offset:33920
	ds_write_b32 v253, v73 offset:34448
	ds_write_b32 v253, v74 offset:34976
	ds_write_b32 v253, v75 offset:35504
	ds_write_b32 v253, v76 offset:33984
	ds_write_b32 v253, v77 offset:34512
	ds_write_b32 v253, v78 offset:35040
	ds_write_b32 v253, v79 offset:35568
	ds_write_b32 v253, v80 offset:42240
	ds_write_b32 v253, v81 offset:42768
	ds_write_b32 v253, v82 offset:43296
	ds_write_b32 v253, v83 offset:43824
	ds_write_b32 v253, v84 offset:42304
	ds_write_b32 v253, v85 offset:42832
	ds_write_b32 v253, v86 offset:43360
	ds_write_b32 v253, v87 offset:43888
	ds_write_b32 v253, v88 offset:42368
	ds_write_b32 v253, v89 offset:42896
	ds_write_b32 v253, v90 offset:43424
	ds_write_b32 v253, v91 offset:43952
	ds_write_b32 v253, v92 offset:42432
	ds_write_b32 v253, v93 offset:42960
	ds_write_b32 v253, v94 offset:43488
	ds_write_b32 v253, v95 offset:44016
	ds_write_b32 v253, v96 offset:50688
	ds_write_b32 v253, v97 offset:51216
	ds_write_b32 v253, v98 offset:51744
	ds_write_b32 v253, v99 offset:52272
	ds_write_b32 v253, v100 offset:50752
	ds_write_b32 v253, v101 offset:51280
	ds_write_b32 v253, v102 offset:51808
	ds_write_b32 v253, v103 offset:52336
	ds_write_b32 v253, v104 offset:50816
	ds_write_b32 v253, v105 offset:51344
	ds_write_b32 v253, v106 offset:51872
	ds_write_b32 v253, v107 offset:52400
	ds_write_b32 v253, v108 offset:50880
	ds_write_b32 v253, v109 offset:51408
	ds_write_b32 v253, v110 offset:51936
	ds_write_b32 v253, v111 offset:52464
	ds_write_b32 v253, v112 offset:59136
	ds_write_b32 v253, v113 offset:59664
	ds_write_b32 v253, v114 offset:60192
	ds_write_b32 v253, v115 offset:60720
	ds_write_b32 v253, v116 offset:59200
	ds_write_b32 v253, v117 offset:59728
	ds_write_b32 v253, v118 offset:60256
	ds_write_b32 v253, v119 offset:60784
	ds_write_b32 v253, v120 offset:59264
	ds_write_b32 v253, v121 offset:59792
	ds_write_b32 v253, v122 offset:60320
	ds_write_b32 v253, v123 offset:60848
	ds_write_b32 v253, v124 offset:59328
	ds_write_b32 v253, v125 offset:59856
	ds_write_b32 v253, v126 offset:60384
	ds_write_b32 v253, v127 offset:60912
	s_branch .LBB0_954

.LBB0_1021:
	s_lshr_b32 s4, s26, 3
	s_and_b32 s4, s4, 8
	s_lshl_b32 s16, s26, 3
	s_or_b32 s4, s4, s24
	s_and_b32 s35, s26, 1
	s_and_b32 s16, s16, 48
	s_or_b32 s36, s4, s16
	s_lshl_b32 s18, s35, 8
	s_lshl_b32 s16, s26, 4
	s_lshl_b32 s19, s36, 9
	v_or_b32_e32 v0, s18, v129
	s_and_b32 s37, s16, 0x380
	v_or_b32_e32 v0, s19, v0
	s_lshl_b32 s16, s37, 11
	s_lshl_b32 s4, s4, 21
	v_lshlrev_b32_e32 v1, 10, v0
	s_or_b32 s4, s4, s16
	s_add_u32 s16, s28, s4
	v_or_b32_e32 v0, v1, v128
	v_readfirstlane_b32 s4, v152
	v_lshlrev_b32_e32 v130, 1, v0
	s_mov_b32 m0, s4
	v_readfirstlane_b32 s4, v161
	v_add_lshl_u32 v0, v1, v158, 1
	s_waitcnt vmcnt(0)
	s_barrier
	s_nop 0
	s_mov_b32 m0, s4
	v_readfirstlane_b32 s4, v162
	s_addc_u32 s17, s29, 0
	v_add_lshl_u32 v2, v1, v159, 1
	s_nop 0
	s_mov_b32 m0, s4
	v_readfirstlane_b32 s4, v163
	v_add_lshl_u32 v4, v1, v160, 1
	v_lshl_add_u64 v[6:7], s[16:17], 0, v[132:133]
	s_nop 0
	s_mov_b32 m0, s4
	v_readfirstlane_b32 s4, v164
	v_lshl_add_u64 v[136:137], v[6:7], 0, v[134:135]
	s_nop 0
	s_mov_b32 m0, s4
	v_readfirstlane_b32 s4, v165
	v_lshl_add_u64 v[138:139], s[2:3], 0, v[130:131]
	v_mov_b32_e32 v1, v131
	v_lshl_add_u64 v[146:147], v[136:137], 0, s[10:11]
	s_nop 0
	s_mov_b32 m0, s4
	v_readfirstlane_b32 s4, v166
	v_lshl_add_u64 v[140:141], s[2:3], 0, v[0:1]
	v_mov_b32_e32 v3, v131
	s_nop 0
	v_lshl_add_u64 v[0:1], v[138:139], 0, 64
	s_mov_b32 m0, s4
	v_readfirstlane_b32 s4, v167
	v_lshl_add_u64 v[142:143], s[2:3], 0, v[2:3]
	v_mov_b32_e32 v5, v131
	s_nop 0
	v_lshl_add_u64 v[0:1], v[140:141], 0, 64
	s_mov_b32 m0, s4
	v_readfirstlane_b32 s4, v168
	v_lshl_add_u64 v[144:145], s[2:3], 0, v[4:5]
	s_nop 0
	v_lshl_add_u64 v[0:1], v[142:143], 0, 64
	s_mov_b32 m0, s4
	v_readfirstlane_b32 s4, v169
	s_nop 0
	v_lshl_add_u64 v[0:1], v[144:145], 0, 64
	s_mov_b32 m0, s4
	v_readfirstlane_b32 s4, v170
	s_nop 0
	v_lshl_add_u64 v[0:1], v[136:137], 0, 64
	s_mov_b32 m0, s4
	v_readfirstlane_b32 s4, v171
	s_nop 0
	v_lshl_add_u64 v[0:1], v[136:137], 0, s[12:13]
	s_mov_b32 m0, s4
	s_mov_b32 s16, s5
	s_nop 0
	s_mov_b32 s17, 2
	s_mov_b32 s38, s5
	v_mov_b32_e32 v0, 0
	v_mov_b32_e32 v1, v131
	v_mov_b32_e32 v2, v131
	v_mov_b32_e32 v4, v131
	v_mov_b32_e32 v6, v131
	v_mov_b32_e32 v7, v131
	v_mov_b32_e32 v8, v131
	v_mov_b32_e32 v9, v131
	v_mov_b32_e32 v10, v131
	v_mov_b32_e32 v11, v131
	v_mov_b32_e32 v12, v131
	v_mov_b32_e32 v13, v131
	v_mov_b32_e32 v14, v131
	v_mov_b32_e32 v15, v131
	v_mov_b32_e32 v16, 0
	v_mov_b32_e32 v17, v131
	v_mov_b32_e32 v18, v131
	v_mov_b32_e32 v19, v131
	v_mov_b32_e32 v20, v131
	v_mov_b32_e32 v21, v131
	v_mov_b32_e32 v22, v131
	v_mov_b32_e32 v23, v131
	v_mov_b32_e32 v24, v131
	v_mov_b32_e32 v25, v131
	v_mov_b32_e32 v26, v131
	v_mov_b32_e32 v27, v131
	v_mov_b32_e32 v28, v131
	v_mov_b32_e32 v29, v131
	v_mov_b32_e32 v30, v131
	v_mov_b32_e32 v31, v131
	v_mov_b32_e32 v32, 0
	v_mov_b32_e32 v33, v131
	v_mov_b32_e32 v34, v131
	v_mov_b32_e32 v35, v131
	v_mov_b32_e32 v36, v131
	v_mov_b32_e32 v37, v131
	v_mov_b32_e32 v38, v131
	v_mov_b32_e32 v39, v131
	v_mov_b32_e32 v40, v131
	v_mov_b32_e32 v41, v131
	v_mov_b32_e32 v42, v131
	v_mov_b32_e32 v43, v131
	v_mov_b32_e32 v44, v131
	v_mov_b32_e32 v45, v131
	v_mov_b32_e32 v46, v131
	v_mov_b32_e32 v47, v131
	v_mov_b32_e32 v48, 0
	v_mov_b32_e32 v49, v131
	v_mov_b32_e32 v50, v131
	v_mov_b32_e32 v51, v131
	v_mov_b32_e32 v52, v131
	v_mov_b32_e32 v53, v131
	v_mov_b32_e32 v54, v131
	v_mov_b32_e32 v55, v131
	v_mov_b32_e32 v56, v131
	v_mov_b32_e32 v57, v131
	v_mov_b32_e32 v58, v131
	v_mov_b32_e32 v59, v131
	v_mov_b32_e32 v60, v131
	v_mov_b32_e32 v61, v131
	v_mov_b32_e32 v62, v131
	v_mov_b32_e32 v63, v131
	v_mov_b32_e32 v64, 0
	v_mov_b32_e32 v65, v131
	v_mov_b32_e32 v66, v131
	v_mov_b32_e32 v67, v131
	v_mov_b32_e32 v68, v131
	v_mov_b32_e32 v69, v131
	v_mov_b32_e32 v70, v131
	v_mov_b32_e32 v71, v131
	v_mov_b32_e32 v72, v131
	v_mov_b32_e32 v73, v131
	v_mov_b32_e32 v74, v131
	v_mov_b32_e32 v75, v131
	v_mov_b32_e32 v76, v131
	v_mov_b32_e32 v77, v131
	v_mov_b32_e32 v78, v131
	v_mov_b32_e32 v79, v131
	v_mov_b32_e32 v80, 0
	v_mov_b32_e32 v81, v131
	v_mov_b32_e32 v82, v131
	v_mov_b32_e32 v83, v131
	v_mov_b32_e32 v84, v131
	v_mov_b32_e32 v85, v131
	v_mov_b32_e32 v86, v131
	v_mov_b32_e32 v87, v131
	v_mov_b32_e32 v88, v131
	v_mov_b32_e32 v89, v131
	v_mov_b32_e32 v90, v131
	v_mov_b32_e32 v91, v131
	v_mov_b32_e32 v92, v131
	v_mov_b32_e32 v93, v131
	v_mov_b32_e32 v94, v131
	v_mov_b32_e32 v95, v131
	v_mov_b32_e32 v96, 0
	v_mov_b32_e32 v97, v131
	v_mov_b32_e32 v98, v131
	v_mov_b32_e32 v99, v131
	v_mov_b32_e32 v100, v131
	v_mov_b32_e32 v101, v131
	v_mov_b32_e32 v102, v131
	v_mov_b32_e32 v103, v131
	v_mov_b32_e32 v104, v131
	v_mov_b32_e32 v105, v131
	v_mov_b32_e32 v106, v131
	v_mov_b32_e32 v107, v131
	v_mov_b32_e32 v108, v131
	v_mov_b32_e32 v109, v131
	v_mov_b32_e32 v110, v131
	v_mov_b32_e32 v111, v131
	v_mov_b32_e32 v112, 0
	v_mov_b32_e32 v113, v131
	v_mov_b32_e32 v114, v131
	v_mov_b32_e32 v115, v131
	v_mov_b32_e32 v116, v131
	v_mov_b32_e32 v117, v131
	v_mov_b32_e32 v118, v131
	v_mov_b32_e32 v119, v131
	v_mov_b32_e32 v120, v131
	v_mov_b32_e32 v121, v131
	v_mov_b32_e32 v122, v131
	v_mov_b32_e32 v123, v131
	v_mov_b32_e32 v124, v131
	v_mov_b32_e32 v125, v131
	v_mov_b32_e32 v126, v131
	v_mov_b32_e32 v127, v131
	s_mov_b64 s[54:55], 0x80
	v_lshrrev_b32_e32 v174, 6, v180
	v_lshlrev_b32_e32 v184, 11, v174
	v_and_b32_e32 v148, 63, v180
	v_readfirstlane_b32 s53, v184
	v_lshrrev_b32_e32 v149, 4, v148
	v_bfe_u32 v150, v148, 1, 3
	v_xor_b32_e32 v150, v149, v150
	v_and_b32_e32 v151, 31, v148
	v_lshlrev_b32_e32 v151, 7, v151
	v_lshrrev_b32_e32 v151, 3, v148
	v_lshlrev_b32_e32 v184, 4, v151
	v_add_u32_e32 v185, 0x80, v184
	v_and_b32_e32 v151, 7, v148
	v_lshrrev_b32_e32 v149, 4, v148
	v_xor_b32_e32 v149, v151, v149
	v_lshrrev_b32_e32 v151, 5, v148
	v_sub_u32_e32 v190, v149, v151
	v_xor_b32_e32 v149, 4, v149
	v_add_u32_e32 v151, 2, v151
	v_sub_u32_e32 v192, v149, v151
	v_lshlrev_b32_e32 v190, 4, v190
	v_ashrrev_i32_e32 v191, 31, v190
	v_lshlrev_b32_e32 v192, 4, v192
	v_ashrrev_i32_e32 v193, 31, v192
	ds_bpermute_b32 v246, v184, v136
	ds_bpermute_b32 v247, v184, v137
	ds_bpermute_b32 v248, v185, v136
	ds_bpermute_b32 v249, v185, v137
	ds_bpermute_b32 v250, v184, v146
	ds_bpermute_b32 v251, v184, v147
	ds_bpermute_b32 v252, v185, v146
	ds_bpermute_b32 v253, v185, v147
	s_waitcnt lgkmcnt(0)
	ds_bpermute_b32 v178, v184, v138
	ds_bpermute_b32 v179, v184, v139
	ds_bpermute_b32 v186, v185, v138
	ds_bpermute_b32 v187, v185, v139
	ds_bpermute_b32 v238, v184, v140
	ds_bpermute_b32 v239, v184, v141
	ds_bpermute_b32 v240, v185, v140
	ds_bpermute_b32 v241, v185, v141
	ds_bpermute_b32 v242, v184, v142
	ds_bpermute_b32 v243, v184, v143
	ds_bpermute_b32 v244, v185, v142
	ds_bpermute_b32 v245, v185, v143
	ds_bpermute_b32 v136, v184, v144
	ds_bpermute_b32 v137, v184, v145
	ds_bpermute_b32 v146, v185, v144
	ds_bpermute_b32 v147, v185, v145
	s_waitcnt lgkmcnt(0)
	v_and_b32_e32 v151, 15, v148
	v_lshlrev_b32_e32 v151, 7, v151
	v_lshrrev_b32_e32 v149, 1, v174
	v_lshl_add_u32 v138, v149, 14, v151
	v_and_b32_e32 v149, 1, v174
	v_lshl_add_u32 v142, v149, 13, v151
	v_add_u32_e32 v142, 0x10000, v142
	v_xor_b32_e32 v151, 4, v150
	v_lshl_add_u32 v139, v151, 4, v138
	v_lshl_add_u32 v143, v151, 4, v142
	v_xor_b32_e32 v151, 0, v150
	v_lshl_add_u32 v138, v151, 4, v138
	v_lshl_add_u32 v142, v151, 4, v142
	v_lshl_add_u64 v[178:179], v[178:179], 0, v[190:191]
	v_lshl_add_u64 v[186:187], v[186:187], 0, v[192:193]
	v_lshl_add_u64 v[238:239], v[238:239], 0, v[190:191]
	v_lshl_add_u64 v[240:241], v[240:241], 0, v[192:193]
	v_lshl_add_u64 v[242:243], v[242:243], 0, v[190:191]
	v_lshl_add_u64 v[244:245], v[244:245], 0, v[192:193]
	v_lshl_add_u64 v[136:137], v[136:137], 0, v[190:191]
	v_lshl_add_u64 v[146:147], v[146:147], 0, v[192:193]
	v_lshl_add_u64 v[246:247], v[246:247], 0, v[190:191]
	v_lshl_add_u64 v[248:249], v[248:249], 0, v[192:193]
	v_lshl_add_u64 v[250:251], v[250:251], 0, v[190:191]
	v_lshl_add_u64 v[252:253], v[252:253], 0, v[192:193]
	s_mov_b32 s58, s53
	s_add_i32 m0, s58, 0x0
	s_nop 0
	global_load_lds_dwordx4 v[178:179], off
	s_add_i32 m0, s58, 0x400
	v_lshl_add_u64 v[178:179], v[178:179], 0, s[54:55]
	global_load_lds_dwordx4 v[186:187], off
	s_add_i32 m0, s58, 0x2000
	v_lshl_add_u64 v[186:187], v[186:187], 0, s[54:55]
	global_load_lds_dwordx4 v[238:239], off
	s_add_i32 m0, s58, 0x2400
	v_lshl_add_u64 v[238:239], v[238:239], 0, s[54:55]
	global_load_lds_dwordx4 v[240:241], off
	s_add_i32 m0, s58, 0x4000
	v_lshl_add_u64 v[240:241], v[240:241], 0, s[54:55]
	global_load_lds_dwordx4 v[242:243], off
	s_add_i32 m0, s58, 0x4400
	v_lshl_add_u64 v[242:243], v[242:243], 0, s[54:55]
	global_load_lds_dwordx4 v[244:245], off
	s_add_i32 m0, s58, 0x6000
	v_lshl_add_u64 v[244:245], v[244:245], 0, s[54:55]
	global_load_lds_dwordx4 v[136:137], off
	s_add_i32 m0, s58, 0x6400
	v_lshl_add_u64 v[136:137], v[136:137], 0, s[54:55]
	global_load_lds_dwordx4 v[146:147], off
	v_lshl_add_u64 v[146:147], v[146:147], 0, s[54:55]
	s_add_i32 s58, s53, 0x10000
	s_add_i32 m0, s58, 0x0
	s_nop 0
	global_load_lds_dwordx4 v[246:247], off
	s_add_i32 m0, s58, 0x400
	v_lshl_add_u64 v[246:247], v[246:247], 0, s[54:55]
	global_load_lds_dwordx4 v[248:249], off
	s_add_i32 m0, s58, 0x2000
	v_lshl_add_u64 v[248:249], v[248:249], 0, s[54:55]
	global_load_lds_dwordx4 v[250:251], off
	s_add_i32 m0, s58, 0x2400
	v_lshl_add_u64 v[250:251], v[250:251], 0, s[54:55]
	global_load_lds_dwordx4 v[252:253], off
	v_lshl_add_u64 v[252:253], v[252:253], 0, s[54:55]
	s_mov_b32 s16, 0
	s_mov_b32 s17, 0

.Lg_ph9_noA:
	ds_read_b128 v[194:197], v142
	ds_read_b128 v[198:201], v142 offset:2048
	ds_read_b128 v[202:205], v142 offset:4096
	ds_read_b128 v[206:209], v142 offset:6144
	ds_read_b128 v[214:217], v143
	ds_read_b128 v[226:229], v143 offset:2048
	ds_read_b128 v[230:233], v143 offset:4096
	ds_read_b128 v[234:237], v143 offset:6144
	ds_read_b128 v[148:151], v138
	ds_read_b128 v[174:177], v138 offset:2048
	ds_read_b128 v[182:185], v138 offset:4096
	ds_read_b128 v[190:193], v138 offset:6144
	s_waitcnt lgkmcnt(4)
	s_barrier
	s_cmp_eq_u32 s16, 15
	s_cbranch_scc1 .Lg_ph9_noB
	s_add_i32 s58, s53, 0x10000
	s_add_i32 m0, s58, 0x0
	s_nop 0
	global_load_lds_dwordx4 v[246:247], off
	s_add_i32 m0, s58, 0x400
	v_lshl_add_u64 v[246:247], v[246:247], 0, s[54:55]
	global_load_lds_dwordx4 v[248:249], off
	s_add_i32 m0, s58, 0x2000
	v_lshl_add_u64 v[248:249], v[248:249], 0, s[54:55]
	global_load_lds_dwordx4 v[250:251], off
	s_add_i32 m0, s58, 0x2400
	v_lshl_add_u64 v[250:251], v[250:251], 0, s[54:55]
	global_load_lds_dwordx4 v[252:253], off
	v_lshl_add_u64 v[252:253], v[252:253], 0, s[54:55]
.Lg_ph9_noB:
	s_waitcnt lgkmcnt(3)
	v_mfma_f32_16x16x32_bf16 v[0:3], v[148:151], v[194:197], v[0:3]
	v_mfma_f32_16x16x32_bf16 v[4:7], v[148:151], v[198:201], v[4:7]
	v_mfma_f32_16x16x32_bf16 v[8:11], v[148:151], v[202:205], v[8:11]
	v_mfma_f32_16x16x32_bf16 v[12:15], v[148:151], v[206:209], v[12:15]
	ds_read_b128 v[148:151], v138 offset:8192
	s_waitcnt lgkmcnt(3)
	v_mfma_f32_16x16x32_bf16 v[16:19], v[174:177], v[194:197], v[16:19]
	v_mfma_f32_16x16x32_bf16 v[20:23], v[174:177], v[198:201], v[20:23]
	v_mfma_f32_16x16x32_bf16 v[24:27], v[174:177], v[202:205], v[24:27]
	v_mfma_f32_16x16x32_bf16 v[28:31], v[174:177], v[206:209], v[28:31]
	ds_read_b128 v[174:177], v138 offset:10240
	s_waitcnt lgkmcnt(3)
	v_mfma_f32_16x16x32_bf16 v[32:35], v[182:185], v[194:197], v[32:35]
	v_mfma_f32_16x16x32_bf16 v[36:39], v[182:185], v[198:201], v[36:39]
	v_mfma_f32_16x16x32_bf16 v[40:43], v[182:185], v[202:205], v[40:43]
	v_mfma_f32_16x16x32_bf16 v[44:47], v[182:185], v[206:209], v[44:47]
	ds_read_b128 v[182:185], v138 offset:12288
	s_waitcnt lgkmcnt(3)
	v_mfma_f32_16x16x32_bf16 v[48:51], v[190:193], v[194:197], v[48:51]
	v_mfma_f32_16x16x32_bf16 v[52:55], v[190:193], v[198:201], v[52:55]
	v_mfma_f32_16x16x32_bf16 v[56:59], v[190:193], v[202:205], v[56:59]
	v_mfma_f32_16x16x32_bf16 v[60:63], v[190:193], v[206:209], v[60:63]
	ds_read_b128 v[190:193], v138 offset:14336
	s_waitcnt lgkmcnt(3)
	v_mfma_f32_16x16x32_bf16 v[64:67], v[148:151], v[194:197], v[64:67]
	v_mfma_f32_16x16x32_bf16 v[68:71], v[148:151], v[198:201], v[68:71]
	v_mfma_f32_16x16x32_bf16 v[72:75], v[148:151], v[202:205], v[72:75]
	v_mfma_f32_16x16x32_bf16 v[76:79], v[148:151], v[206:209], v[76:79]
	ds_read_b128 v[148:151], v139
	s_waitcnt lgkmcnt(3)
	v_mfma_f32_16x16x32_bf16 v[80:83], v[174:177], v[194:197], v[80:83]
	v_mfma_f32_16x16x32_bf16 v[84:87], v[174:177], v[198:201], v[84:87]
	v_mfma_f32_16x16x32_bf16 v[88:91], v[174:177], v[202:205], v[88:91]
	v_mfma_f32_16x16x32_bf16 v[92:95], v[174:177], v[206:209], v[92:95]
	ds_read_b128 v[174:177], v139 offset:2048
	s_waitcnt lgkmcnt(3)
	v_mfma_f32_16x16x32_bf16 v[96:99], v[182:185], v[194:197], v[96:99]
	v_mfma_f32_16x16x32_bf16 v[100:103], v[182:185], v[198:201], v[100:103]
	v_mfma_f32_16x16x32_bf16 v[104:107], v[182:185], v[202:205], v[104:107]
	v_mfma_f32_16x16x32_bf16 v[108:111], v[182:185], v[206:209], v[108:111]
	ds_read_b128 v[182:185], v139 offset:4096
	s_waitcnt lgkmcnt(3)
	v_mfma_f32_16x16x32_bf16 v[112:115], v[190:193], v[194:197], v[112:115]
	v_mfma_f32_16x16x32_bf16 v[116:119], v[190:193], v[198:201], v[116:119]
	v_mfma_f32_16x16x32_bf16 v[120:123], v[190:193], v[202:205], v[120:123]
	v_mfma_f32_16x16x32_bf16 v[124:127], v[190:193], v[206:209], v[124:127]
	ds_read_b128 v[190:193], v139 offset:6144
	s_waitcnt lgkmcnt(3)
	v_mfma_f32_16x16x32_bf16 v[0:3], v[148:151], v[214:217], v[0:3]
	v_mfma_f32_16x16x32_bf16 v[4:7], v[148:151], v[226:229], v[4:7]
	v_mfma_f32_16x16x32_bf16 v[8:11], v[148:151], v[230:233], v[8:11]
	v_mfma_f32_16x16x32_bf16 v[12:15], v[148:151], v[234:237], v[12:15]
	ds_read_b128 v[148:151], v139 offset:8192
	s_waitcnt lgkmcnt(3)
	v_mfma_f32_16x16x32_bf16 v[16:19], v[174:177], v[214:217], v[16:19]
	v_mfma_f32_16x16x32_bf16 v[20:23], v[174:177], v[226:229], v[20:23]
	v_mfma_f32_16x16x32_bf16 v[24:27], v[174:177], v[230:233], v[24:27]
	v_mfma_f32_16x16x32_bf16 v[28:31], v[174:177], v[234:237], v[28:31]
	ds_read_b128 v[174:177], v139 offset:10240
	s_waitcnt lgkmcnt(3)
	v_mfma_f32_16x16x32_bf16 v[32:35], v[182:185], v[214:217], v[32:35]
	v_mfma_f32_16x16x32_bf16 v[36:39], v[182:185], v[226:229], v[36:39]
	v_mfma_f32_16x16x32_bf16 v[40:43], v[182:185], v[230:233], v[40:43]
	v_mfma_f32_16x16x32_bf16 v[44:47], v[182:185], v[234:237], v[44:47]
	ds_read_b128 v[182:185], v139 offset:12288
	s_waitcnt lgkmcnt(3)
	v_mfma_f32_16x16x32_bf16 v[48:51], v[190:193], v[214:217], v[48:51]
	v_mfma_f32_16x16x32_bf16 v[52:55], v[190:193], v[226:229], v[52:55]
	v_mfma_f32_16x16x32_bf16 v[56:59], v[190:193], v[230:233], v[56:59]
	v_mfma_f32_16x16x32_bf16 v[60:63], v[190:193], v[234:237], v[60:63]
	ds_read_b128 v[190:193], v139 offset:14336
	s_waitcnt lgkmcnt(3)
	v_mfma_f32_16x16x32_bf16 v[64:67], v[148:151], v[214:217], v[64:67]
	v_mfma_f32_16x16x32_bf16 v[68:71], v[148:151], v[226:229], v[68:71]
	v_mfma_f32_16x16x32_bf16 v[72:75], v[148:151], v[230:233], v[72:75]
	v_mfma_f32_16x16x32_bf16 v[76:79], v[148:151], v[234:237], v[76:79]
	s_waitcnt lgkmcnt(2)
	v_mfma_f32_16x16x32_bf16 v[80:83], v[174:177], v[214:217], v[80:83]
	v_mfma_f32_16x16x32_bf16 v[84:87], v[174:177], v[226:229], v[84:87]
	v_mfma_f32_16x16x32_bf16 v[88:91], v[174:177], v[230:233], v[88:91]
	v_mfma_f32_16x16x32_bf16 v[92:95], v[174:177], v[234:237], v[92:95]
	s_waitcnt lgkmcnt(1)
	v_mfma_f32_16x16x32_bf16 v[96:99], v[182:185], v[214:217], v[96:99]
	v_mfma_f32_16x16x32_bf16 v[100:103], v[182:185], v[226:229], v[100:103]
	v_mfma_f32_16x16x32_bf16 v[104:107], v[182:185], v[230:233], v[104:107]
	v_mfma_f32_16x16x32_bf16 v[108:111], v[182:185], v[234:237], v[108:111]
	s_waitcnt lgkmcnt(0)
	v_mfma_f32_16x16x32_bf16 v[112:115], v[190:193], v[214:217], v[112:115]
	v_mfma_f32_16x16x32_bf16 v[116:119], v[190:193], v[226:229], v[116:119]
	v_mfma_f32_16x16x32_bf16 v[120:123], v[190:193], v[230:233], v[120:123]
	v_mfma_f32_16x16x32_bf16 v[124:127], v[190:193], v[234:237], v[124:127]
	v_xor_b32_e32 v138, 0x8000, v138
	v_xor_b32_e32 v139, 0x8000, v139
	s_xor_b32 s17, s17, 0x8000
	s_add_i32 s16, s16, 1
	s_cmp_eq_u32 s16, 16
	s_cbranch_scc0 .Lg_ph9_top
	s_waitcnt vmcnt(0)
	v_mov_b32_e32 v146, v180
	v_add_u32_e32 v209, 0x400, v157
	v_add_u32_e32 v208, 0x1000, v157
	v_add_u32_e32 v207, 0x1400, v157
	v_add_u32_e32 v206, 0x2000, v157
	v_add_u32_e32 v200, 0x2400, v157
	v_add_u32_e32 v201, 0x3000, v157
	v_add_u32_e32 v202, 0x3200, v157
	v_add_u32_e32 v203, 0x3400, v157
	v_add_u32_e32 v204, 0x3600, v157
	v_add_u32_e32 v205, 0x4000, v157
	v_add_u32_e32 v197, 0x4400, v157
	v_add_u32_e32 v198, 0x4800, v157
	v_add_u32_e32 v199, 0x5000, v157
	v_add_u32_e32 v194, 0x5400, v157
	v_add_u32_e32 v195, 0x5800, v157
	v_add_u32_e32 v196, 0x6000, v157
	v_add_u32_e32 v187, 0x6400, v157
	v_add_u32_e32 v189, 0x6800, v157
	v_add_u32_e32 v190, 0x7200, v157
	v_add_u32_e32 v191, 0x7400, v157
	v_add_u32_e32 v192, 0x7600, v157
	v_add_u32_e32 v193, 0x7800, v157
	v_add_u32_e32 v186, 0x8400, v157
	v_add_u32_e32 v185, 0x8800, v157
	v_add_u32_e32 v184, 0x9400, v157
	v_add_u32_e32 v183, 0x9800, v157
	v_add_u32_e32 v181, 0xa400, v157
	v_add_u32_e32 v174, 0xa800, v157
	v_add_u32_e32 v175, 0xb400, v157
	v_add_u32_e32 v176, 0xb600, v157
	v_add_u32_e32 v177, 0xb800, v157
	v_add_u32_e32 v178, 0xba00, v157
	s_waitcnt vmcnt(0)
	s_barrier
	s_and_saveexec_b64 s[16:17], s[6:7]
	s_cbranch_execz .LBB0_1025
	v_and_b32_e32 v254, 63, v180
	v_lshrrev_b32_e32 v253, 4, v254
	v_mul_u32_u24_e32 v253, 0x840, v253
	v_and_b32_e32 v254, 15, v254
	v_lshl_add_u32 v253, v254, 2, v253
	v_and_b32_e32 v254, 64, v180
	v_lshl_add_u32 v253, v254, 2, v253
	ds_write_b32 v253, v0 offset:0
	ds_write_b32 v253, v1 offset:528
	ds_write_b32 v253, v2 offset:1056
	ds_write_b32 v253, v3 offset:1584
	ds_write_b32 v253, v4 offset:64
	ds_write_b32 v253, v5 offset:592
	ds_write_b32 v253, v6 offset:1120
	ds_write_b32 v253, v7 offset:1648
	ds_write_b32 v253, v8 offset:128
	ds_write_b32 v253, v9 offset:656
	ds_write_b32 v253, v10 offset:1184
	ds_write_b32 v253, v11 offset:1712
	ds_write_b32 v253, v12 offset:192
	ds_write_b32 v253, v13 offset:720
	ds_write_b32 v253, v14 offset:1248
	ds_write_b32 v253, v15 offset:1776
	ds_write_b32 v253, v16 offset:8448
	ds_write_b32 v253, v17 offset:8976
	ds_write_b32 v253, v18 offset:9504
	ds_write_b32 v253, v19 offset:10032
	ds_write_b32 v253, v20 offset:8512
	ds_write_b32 v253, v21 offset:9040
	ds_write_b32 v253, v22 offset:9568
	ds_write_b32 v253, v23 offset:10096
	ds_write_b32 v253, v24 offset:8576
	ds_write_b32 v253, v25 offset:9104
	ds_write_b32 v253, v26 offset:9632
	ds_write_b32 v253, v27 offset:10160
	ds_write_b32 v253, v28 offset:8640
	ds_write_b32 v253, v29 offset:9168
	ds_write_b32 v253, v30 offset:9696
	ds_write_b32 v253, v31 offset:10224
	ds_write_b32 v253, v32 offset:16896
	ds_write_b32 v253, v33 offset:17424
	ds_write_b32 v253, v34 offset:17952
	ds_write_b32 v253, v35 offset:18480
	ds_write_b32 v253, v36 offset:16960
	ds_write_b32 v253, v37 offset:17488
	ds_write_b32 v253, v38 offset:18016
	ds_write_b32 v253, v39 offset:18544
	ds_write_b32 v253, v40 offset:17024
	ds_write_b32 v253, v41 offset:17552
	ds_write_b32 v253, v42 offset:18080
	ds_write_b32 v253, v43 offset:18608
	ds_write_b32 v253, v44 offset:17088
	ds_write_b32 v253, v45 offset:17616
	ds_write_b32 v253, v46 offset:18144
	ds_write_b32 v253, v47 offset:18672
	ds_write_b32 v253, v48 offset:25344
	ds_write_b32 v253, v49 offset:25872
	ds_write_b32 v253, v50 offset:26400
	ds_write_b32 v253, v51 offset:26928
	ds_write_b32 v253, v52 offset:25408
	ds_write_b32 v253, v53 offset:25936
	ds_write_b32 v253, v54 offset:26464
	ds_write_b32 v253, v55 offset:26992
	ds_write_b32 v253, v56 offset:25472
	ds_write_b32 v253, v57 offset:26000
	ds_write_b32 v253, v58 offset:26528
	ds_write_b32 v253, v59 offset:27056
	ds_write_b32 v253, v60 offset:25536
	ds_write_b32 v253, v61 offset:26064
	ds_write_b32 v253, v62 offset:26592
	ds_write_b32 v253, v63 offset:27120
	ds_write_b32 v253, v64 offset:33792
	ds_write_b32 v253, v65 offset:34320
	ds_write_b32 v253, v66 offset:34848
	ds_write_b32 v253, v67 offset:35376
	ds_write_b32 v253, v68 offset:33856
	ds_write_b32 v253, v69 offset:34384
	ds_write_b32 v253, v70 offset:34912
	ds_write_b32 v253, v71 offset:35440
	ds_write_b32 v253, v72 offset:33920
	ds_write_b32 v253, v73 offset:34448
	ds_write_b32 v253, v74 offset:34976
	ds_write_b32 v253, v75 offset:35504
	ds_write_b32 v253, v76 offset:33984
	ds_write_b32 v253, v77 offset:34512
	ds_write_b32 v253, v78 offset:35040
	ds_write_b32 v253, v79 offset:35568
	ds_write_b32 v253, v80 offset:42240
	ds_write_b32 v253, v81 offset:42768
	ds_write_b32 v253, v82 offset:43296
	ds_write_b32 v253, v83 offset:43824
	ds_write_b32 v253, v84 offset:42304
	ds_write_b32 v253, v85 offset:42832
	ds_write_b32 v253, v86 offset:43360
	ds_write_b32 v253, v87 offset:43888
	ds_write_b32 v253, v88 offset:42368
	ds_write_b32 v253, v89 offset:42896
	ds_write_b32 v253, v90 offset:43424
	ds_write_b32 v253, v91 offset:43952
	ds_write_b32 v253, v92 offset:42432
	ds_write_b32 v253, v93 offset:42960
	ds_write_b32 v253, v94 offset:43488
	ds_write_b32 v253, v95 offset:44016
	ds_write_b32 v253, v96 offset:50688
	ds_write_b32 v253, v97 offset:51216
	ds_write_b32 v253, v98 offset:51744
	ds_write_b32 v253, v99 offset:52272
	ds_write_b32 v253, v100 offset:50752
	ds_write_b32 v253, v101 offset:51280
	ds_write_b32 v253, v102 offset:51808
	ds_write_b32 v253, v103 offset:52336
	ds_write_b32 v253, v104 offset:50816
	ds_write_b32 v253, v105 offset:51344
	ds_write_b32 v253, v106 offset:51872
	ds_write_b32 v253, v107 offset:52400
	ds_write_b32 v253, v108 offset:50880
	ds_write_b32 v253, v109 offset:51408
	ds_write_b32 v253, v110 offset:51936
	ds_write_b32 v253, v111 offset:52464
	ds_write_b32 v253, v112 offset:59136
	ds_write_b32 v253, v113 offset:59664
	ds_write_b32 v253, v114 offset:60192
	ds_write_b32 v253, v115 offset:60720
	ds_write_b32 v253, v116 offset:59200
	ds_write_b32 v253, v117 offset:59728
	ds_write_b32 v253, v118 offset:60256
	ds_write_b32 v253, v119 offset:60784
	ds_write_b32 v253, v120 offset:59264
	ds_write_b32 v253, v121 offset:59792
	ds_write_b32 v253, v122 offset:60320
	ds_write_b32 v253, v123 offset:60848
	ds_write_b32 v253, v124 offset:59328
	ds_write_b32 v253, v125 offset:59856
	ds_write_b32 v253, v126 offset:60384
	ds_write_b32 v253, v127 offset:60912
.LBB0_1025:
	s_or_b64 exec, exec, s[16:17]
	s_lshl_b32 s4, s35, 19
	s_lshl_b32 s16, s36, 20
	s_or_b32 s4, s16, s4
	s_add_u32 s4, s20, s4
	s_addc_u32 s17, s21, 0
	s_lshl_b32 s16, s19, 2
	s_add_u32 s19, s22, s16
	s_addc_u32 s35, s23, 0
	s_lshl_b32 s16, s37, 1
	s_add_u32 s16, s4, s16
	s_addc_u32 s17, s17, 0
	s_lshl_b32 s4, s18, 2
	s_add_u32 s18, s19, s4
	v_ashrrev_i32_e32 v138, 4, v146
	s_addc_u32 s19, s35, 0
	v_ashrrev_i32_e32 v139, 31, v138
	v_lshl_add_u64 v[136:137], v[138:139], 2, s[18:19]
	s_waitcnt lgkmcnt(0)
	s_barrier
	global_load_dword v182, v[136:137], off
	v_lshlrev_b32_e32 v130, 3, v146
	v_and_b32_e32 v130, 0x78, v130
	v_mul_lo_u32 v141, v138, s27
	v_lshl_add_u32 v223, v130, 2, 0
	v_add_u32_e32 v173, v223, v141
	ds_read_b128 v[142:145], v173
	ds_read_b128 v[148:151], v173 offset:16
	v_add_u32_e32 v140, 0x100, v146
	v_lshlrev_b64 v[138:139], 11, v[138:139]
	v_ashrrev_i32_e32 v210, 4, v140
	v_lshlrev_b32_e32 v130, 1, v130
	v_lshl_add_u64 v[138:139], s[16:17], 0, v[138:139]
	v_ashrrev_i32_e32 v211, 31, v210
	v_lshl_add_u64 v[140:141], v[138:139], 0, v[130:131]
	v_lshl_add_u64 v[138:139], v[210:211], 2, s[18:19]
	s_waitcnt vmcnt(0) lgkmcnt(1)
	v_pk_mul_f32 v[142:143], v[142:143], v[182:183] op_sel_hi:[1,0]
	v_pk_mul_f32 v[144:145], v[144:145], v[182:183] op_sel_hi:[1,0]
	s_waitcnt lgkmcnt(0)
	v_pk_mul_f32 v[148:149], v[148:149], v[182:183] op_sel_hi:[1,0]
	v_pk_mul_f32 v[150:151], v[150:151], v[182:183] op_sel_hi:[1,0]
	v_cvt_pk_bf16_f32 v142, v142, v143
	v_cvt_pk_bf16_f32 v143, v144, v145
	v_cvt_pk_bf16_f32 v144, v148, v149
	v_cvt_pk_bf16_f32 v145, v150, v151
	global_store_dwordx4 v[140:141], v[142:145], off
	global_load_dword v182, v[138:139], off
	s_nop 0
	v_add_u32_e32 v142, 0x200, v146
	v_ashrrev_i32_e32 v218, 4, v142
	v_mul_lo_u32 v142, v210, s27
	v_add_u32_e32 v179, v223, v142
	ds_read_b128 v[148:151], v179
	ds_read_b128 v[214:217], v179 offset:16
	v_lshlrev_b64 v[142:143], 11, v[210:211]
	v_lshl_add_u64 v[142:143], s[16:17], 0, v[142:143]
	v_ashrrev_i32_e32 v219, 31, v218
	v_lshl_add_u64 v[144:145], v[142:143], 0, v[130:131]
	v_lshl_add_u64 v[142:143], v[218:219], 2, s[18:19]
	v_add_u32_e32 v146, 0x300, v146
	v_ashrrev_i32_e32 v146, 4, v146
	v_ashrrev_i32_e32 v147, 31, v146
	s_waitcnt vmcnt(0) lgkmcnt(1)
	v_pk_mul_f32 v[148:149], v[148:149], v[182:183] op_sel_hi:[1,0]
	v_pk_mul_f32 v[150:151], v[150:151], v[182:183] op_sel_hi:[1,0]
	s_waitcnt lgkmcnt(0)
	v_pk_mul_f32 v[210:211], v[214:215], v[182:183] op_sel_hi:[1,0]
	v_pk_mul_f32 v[214:215], v[216:217], v[182:183] op_sel_hi:[1,0]
	v_cvt_pk_bf16_f32 v148, v148, v149
	v_cvt_pk_bf16_f32 v149, v150, v151
	v_cvt_pk_bf16_f32 v150, v210, v211
	v_cvt_pk_bf16_f32 v151, v214, v215
	global_store_dwordx4 v[144:145], v[148:151], off
	global_load_dword v182, v[142:143], off
	s_nop 0
	v_mul_lo_u32 v148, v218, s27
	v_add_u32_e32 v210, v223, v148
	v_lshlrev_b64 v[148:149], 11, v[218:219]
	ds_read_b128 v[214:217], v210
	ds_read_b128 v[218:221], v210 offset:16
	v_lshl_add_u64 v[148:149], s[16:17], 0, v[148:149]
	v_lshl_add_u64 v[150:151], v[148:149], 0, v[130:131]
	v_lshl_add_u64 v[148:149], v[146:147], 2, s[18:19]
	s_waitcnt vmcnt(0) lgkmcnt(1)
	v_pk_mul_f32 v[214:215], v[214:215], v[182:183] op_sel_hi:[1,0]
	v_pk_mul_f32 v[216:217], v[216:217], v[182:183] op_sel_hi:[1,0]
	s_waitcnt lgkmcnt(0)
	v_pk_mul_f32 v[218:219], v[218:219], v[182:183] op_sel_hi:[1,0]
	v_pk_mul_f32 v[220:221], v[220:221], v[182:183] op_sel_hi:[1,0]
	v_cvt_pk_bf16_f32 v214, v214, v215
	v_cvt_pk_bf16_f32 v215, v216, v217
	v_cvt_pk_bf16_f32 v216, v218, v219
	v_cvt_pk_bf16_f32 v217, v220, v221
	global_store_dwordx4 v[150:151], v[214:217], off
	global_load_dword v222, v[148:149], off
	v_mul_lo_u32 v182, v146, s27
	v_add_u32_e32 v182, v223, v182
	ds_read_b128 v[214:217], v182
	ds_read_b128 v[218:221], v182 offset:16
	v_lshlrev_b64 v[146:147], 11, v[146:147]
	v_lshl_add_u64 v[146:147], s[16:17], 0, v[146:147]
	v_lshl_add_u64 v[146:147], v[146:147], 0, v[130:131]
	s_waitcnt vmcnt(0) lgkmcnt(1)
	v_pk_mul_f32 v[224:225], v[214:215], v[222:223] op_sel_hi:[1,0]
	v_pk_mul_f32 v[214:215], v[216:217], v[222:223] op_sel_hi:[1,0]
	s_waitcnt lgkmcnt(0)
	v_pk_mul_f32 v[218:219], v[218:219], v[222:223] op_sel_hi:[1,0]
	v_pk_mul_f32 v[216:217], v[220:221], v[222:223] op_sel_hi:[1,0]
	v_cvt_pk_bf16_f32 v215, v214, v215
	v_cvt_pk_bf16_f32 v217, v216, v217
	v_cvt_pk_bf16_f32 v216, v218, v219
	v_cvt_pk_bf16_f32 v214, v224, v225
	global_store_dwordx4 v[146:147], v[214:217], off
	global_load_dword v130, v[136:137], off offset:256
	ds_read_b128 v[214:217], v173 offset:33792
	ds_read_b128 v[218:221], v173 offset:33808
	v_add_co_u32_e32 v222, vcc, s30, v140
	s_waitcnt vmcnt(0) lgkmcnt(1)
	v_pk_mul_f32 v[214:215], v[214:215], v[130:131] op_sel_hi:[1,0]
	v_pk_mul_f32 v[216:217], v[216:217], v[130:131] op_sel_hi:[1,0]
	s_waitcnt lgkmcnt(0)
	v_pk_mul_f32 v[218:219], v[218:219], v[130:131] op_sel_hi:[1,0]
	v_pk_mul_f32 v[220:221], v[220:221], v[130:131] op_sel_hi:[1,0]
	v_addc_co_u32_e32 v223, vcc, 0, v141, vcc
	v_cvt_pk_bf16_f32 v214, v214, v215
	v_cvt_pk_bf16_f32 v215, v216, v217
	v_cvt_pk_bf16_f32 v216, v218, v219
	v_cvt_pk_bf16_f32 v217, v220, v221
	global_store_dwordx4 v[222:223], v[214:217], off
	global_load_dword v130, v[138:139], off offset:256
	ds_read_b128 v[214:217], v179 offset:33792
	ds_read_b128 v[218:221], v179 offset:33808
	v_add_co_u32_e32 v222, vcc, s30, v144
	s_waitcnt vmcnt(0) lgkmcnt(1)
	v_pk_mul_f32 v[214:215], v[214:215], v[130:131] op_sel_hi:[1,0]
	v_pk_mul_f32 v[216:217], v[216:217], v[130:131] op_sel_hi:[1,0]
	s_waitcnt lgkmcnt(0)
	v_pk_mul_f32 v[218:219], v[218:219], v[130:131] op_sel_hi:[1,0]
	v_pk_mul_f32 v[220:221], v[220:221], v[130:131] op_sel_hi:[1,0]
	v_addc_co_u32_e32 v223, vcc, 0, v145, vcc
	v_cvt_pk_bf16_f32 v214, v214, v215
	v_cvt_pk_bf16_f32 v215, v216, v217
	v_cvt_pk_bf16_f32 v216, v218, v219
	v_cvt_pk_bf16_f32 v217, v220, v221
	global_store_dwordx4 v[222:223], v[214:217], off
	global_load_dword v130, v[142:143], off offset:256
	ds_read_b128 v[214:217], v210 offset:33792
	ds_read_b128 v[218:221], v210 offset:33808
	v_add_co_u32_e32 v222, vcc, s30, v150
	s_waitcnt vmcnt(0) lgkmcnt(1)
	v_pk_mul_f32 v[214:215], v[214:215], v[130:131] op_sel_hi:[1,0]
	v_pk_mul_f32 v[216:217], v[216:217], v[130:131] op_sel_hi:[1,0]
	s_waitcnt lgkmcnt(0)
	v_pk_mul_f32 v[218:219], v[218:219], v[130:131] op_sel_hi:[1,0]
	v_pk_mul_f32 v[220:221], v[220:221], v[130:131] op_sel_hi:[1,0]
	v_addc_co_u32_e32 v223, vcc, 0, v151, vcc
	v_cvt_pk_bf16_f32 v214, v214, v215
	v_cvt_pk_bf16_f32 v215, v216, v217
	v_cvt_pk_bf16_f32 v216, v218, v219
	v_cvt_pk_bf16_f32 v217, v220, v221
	global_store_dwordx4 v[222:223], v[214:217], off
	global_load_dword v130, v[148:149], off offset:256
	ds_read_b128 v[214:217], v182 offset:33792
	ds_read_b128 v[218:221], v182 offset:33808
	v_add_co_u32_e32 v222, vcc, 0x20000, v146
	s_waitcnt vmcnt(0) lgkmcnt(1)
	v_pk_mul_f32 v[224:225], v[214:215], v[130:131] op_sel_hi:[1,0]
	v_pk_mul_f32 v[214:215], v[216:217], v[130:131] op_sel_hi:[1,0]
	s_waitcnt lgkmcnt(0)
	v_pk_mul_f32 v[218:219], v[218:219], v[130:131] op_sel_hi:[1,0]
	v_pk_mul_f32 v[216:217], v[220:221], v[130:131] op_sel_hi:[1,0]
	v_addc_co_u32_e32 v223, vcc, 0, v147, vcc
	v_cvt_pk_bf16_f32 v217, v216, v217
	v_cvt_pk_bf16_f32 v216, v218, v219
	v_cvt_pk_bf16_f32 v215, v214, v215
	v_cvt_pk_bf16_f32 v214, v224, v225
	global_store_dwordx4 v[222:223], v[214:217], off
	s_barrier
	s_and_saveexec_b64 s[16:17], s[8:9]
	s_cbranch_execz .LBB0_1020
	v_and_b32_e32 v254, 63, v180
	v_lshrrev_b32_e32 v253, 4, v254
	v_mul_u32_u24_e32 v253, 0x840, v253
	v_and_b32_e32 v254, 15, v254
	v_lshl_add_u32 v253, v254, 2, v253
	v_and_b32_e32 v254, 64, v180
	v_lshl_add_u32 v253, v254, 2, v253
	ds_write_b32 v253, v0 offset:0
	ds_write_b32 v253, v1 offset:528
	ds_write_b32 v253, v2 offset:1056
	ds_write_b32 v253, v3 offset:1584
	ds_write_b32 v253, v4 offset:64
	ds_write_b32 v253, v5 offset:592
	ds_write_b32 v253, v6 offset:1120
	ds_write_b32 v253, v7 offset:1648
	ds_write_b32 v253, v8 offset:128
	ds_write_b32 v253, v9 offset:656
	ds_write_b32 v253, v10 offset:1184
	ds_write_b32 v253, v11 offset:1712
	ds_write_b32 v253, v12 offset:192
	ds_write_b32 v253, v13 offset:720
	ds_write_b32 v253, v14 offset:1248
	ds_write_b32 v253, v15 offset:1776
	ds_write_b32 v253, v16 offset:8448
	ds_write_b32 v253, v17 offset:8976
	ds_write_b32 v253, v18 offset:9504
	ds_write_b32 v253, v19 offset:10032
	ds_write_b32 v253, v20 offset:8512
	ds_write_b32 v253, v21 offset:9040
	ds_write_b32 v253, v22 offset:9568
	ds_write_b32 v253, v23 offset:10096
	ds_write_b32 v253, v24 offset:8576
	ds_write_b32 v253, v25 offset:9104
	ds_write_b32 v253, v26 offset:9632
	ds_write_b32 v253, v27 offset:10160
	ds_write_b32 v253, v28 offset:8640
	ds_write_b32 v253, v29 offset:9168
	ds_write_b32 v253, v30 offset:9696
	ds_write_b32 v253, v31 offset:10224
	ds_write_b32 v253, v32 offset:16896
	ds_write_b32 v253, v33 offset:17424
	ds_write_b32 v253, v34 offset:17952
	ds_write_b32 v253, v35 offset:18480
	ds_write_b32 v253, v36 offset:16960
	ds_write_b32 v253, v37 offset:17488
	ds_write_b32 v253, v38 offset:18016
	ds_write_b32 v253, v39 offset:18544
	ds_write_b32 v253, v40 offset:17024
	ds_write_b32 v253, v41 offset:17552
	ds_write_b32 v253, v42 offset:18080
	ds_write_b32 v253, v43 offset:18608
	ds_write_b32 v253, v44 offset:17088
	ds_write_b32 v253, v45 offset:17616
	ds_write_b32 v253, v46 offset:18144
	ds_write_b32 v253, v47 offset:18672
	ds_write_b32 v253, v48 offset:25344
	ds_write_b32 v253, v49 offset:25872
	ds_write_b32 v253, v50 offset:26400
	ds_write_b32 v253, v51 offset:26928
	ds_write_b32 v253, v52 offset:25408
	ds_write_b32 v253, v53 offset:25936
	ds_write_b32 v253, v54 offset:26464
	ds_write_b32 v253, v55 offset:26992
	ds_write_b32 v253, v56 offset:25472
	ds_write_b32 v253, v57 offset:26000
	ds_write_b32 v253, v58 offset:26528
	ds_write_b32 v253, v59 offset:27056
	ds_write_b32 v253, v60 offset:25536
	ds_write_b32 v253, v61 offset:26064
	ds_write_b32 v253, v62 offset:26592
	ds_write_b32 v253, v63 offset:27120
	ds_write_b32 v253, v64 offset:33792
	ds_write_b32 v253, v65 offset:34320
	ds_write_b32 v253, v66 offset:34848
	ds_write_b32 v253, v67 offset:35376
	ds_write_b32 v253, v68 offset:33856
	ds_write_b32 v253, v69 offset:34384
	ds_write_b32 v253, v70 offset:34912
	ds_write_b32 v253, v71 offset:35440
	ds_write_b32 v253, v72 offset:33920
	ds_write_b32 v253, v73 offset:34448
	ds_write_b32 v253, v74 offset:34976
	ds_write_b32 v253, v75 offset:35504
	ds_write_b32 v253, v76 offset:33984
	ds_write_b32 v253, v77 offset:34512
	ds_write_b32 v253, v78 offset:35040
	ds_write_b32 v253, v79 offset:35568
	ds_write_b32 v253, v80 offset:42240
	ds_write_b32 v253, v81 offset:42768
	ds_write_b32 v253, v82 offset:43296
	ds_write_b32 v253, v83 offset:43824
	ds_write_b32 v253, v84 offset:42304
	ds_write_b32 v253, v85 offset:42832
	ds_write_b32 v253, v86 offset:43360
	ds_write_b32 v253, v87 offset:43888
	ds_write_b32 v253, v88 offset:42368
	ds_write_b32 v253, v89 offset:42896
	ds_write_b32 v253, v90 offset:43424
	ds_write_b32 v253, v91 offset:43952
	ds_write_b32 v253, v92 offset:42432
	ds_write_b32 v253, v93 offset:42960
	ds_write_b32 v253, v94 offset:43488
	ds_write_b32 v253, v95 offset:44016
	ds_write_b32 v253, v96 offset:50688
	ds_write_b32 v253, v97 offset:51216
	ds_write_b32 v253, v98 offset:51744
	ds_write_b32 v253, v99 offset:52272
	ds_write_b32 v253, v100 offset:50752
	ds_write_b32 v253, v101 offset:51280
	ds_write_b32 v253, v102 offset:51808
	ds_write_b32 v253, v103 offset:52336
	ds_write_b32 v253, v104 offset:50816
	ds_write_b32 v253, v105 offset:51344
	ds_write_b32 v253, v106 offset:51872
	ds_write_b32 v253, v107 offset:52400
	ds_write_b32 v253, v108 offset:50880
	ds_write_b32 v253, v109 offset:51408
	ds_write_b32 v253, v110 offset:51936
	ds_write_b32 v253, v111 offset:52464
	ds_write_b32 v253, v112 offset:59136
	ds_write_b32 v253, v113 offset:59664
	ds_write_b32 v253, v114 offset:60192
	ds_write_b32 v253, v115 offset:60720
	ds_write_b32 v253, v116 offset:59200
	ds_write_b32 v253, v117 offset:59728
	ds_write_b32 v253, v118 offset:60256
	ds_write_b32 v253, v119 offset:60784
	ds_write_b32 v253, v120 offset:59264
	ds_write_b32 v253, v121 offset:59792
	ds_write_b32 v253, v122 offset:60320
	ds_write_b32 v253, v123 offset:60848
	ds_write_b32 v253, v124 offset:59328
	ds_write_b32 v253, v125 offset:59856
	ds_write_b32 v253, v126 offset:60384
	ds_write_b32 v253, v127 offset:60912
	s_branch .LBB0_1020

.LBB0_1174:
	s_and_b32 s4, s31, 0xff
	s_mulk_i32 s4, 0xab
	s_lshr_b32 s4, s4, 12
	s_add_i32 s24, s34, s4
	s_lshl_b32 s44, s24, 18
	v_or_b32_e32 v0, s44, v129
	v_or_b32_e32 v1, v0, v128
	s_mul_i32 s4, s4, 24
	v_lshlrev_b32_e32 v130, 1, v1
	v_add_lshl_u32 v1, v0, v128, 1
	s_sub_i32 s4, s31, s4
	v_add_u32_e32 v0, 0x20000, v1
	v_add_u32_e32 v2, 0x40000, v1
	v_add_u32_e32 v4, 0x60000, v1
	v_mov_b32_e32 v1, v131
	v_mov_b32_e32 v3, v131
	v_mov_b32_e32 v5, v131
	s_and_b32 s43, s4, 0xff
	v_lshl_add_u64 v[136:137], s[2:3], 0, v[130:131]
	v_lshl_add_u64 v[138:139], s[2:3], 0, v[0:1]
	v_lshl_add_u64 v[140:141], s[2:3], 0, v[2:3]
	v_lshl_add_u64 v[142:143], s[2:3], 0, v[4:5]
	s_cmp_gt_u32 s43, 15
	v_lshl_add_u64 v[150:151], v[136:137], 0, 64
	s_mov_b64 s[24:25], -1
	v_lshl_add_u64 v[148:149], v[138:139], 0, 64
	v_lshl_add_u64 v[146:147], v[140:141], 0, 64
	v_lshl_add_u64 v[144:145], v[142:143], 0, 64
	s_cbranch_scc0 .LBB0_1182
	s_lshl_b32 s4, s43, 7
	s_add_i32 s24, s4, 0xfffff800
	s_mov_b32 s25, s5
	v_readfirstlane_b32 s4, v160
	s_lshl_b64 s[26:27], s[24:25], 11
	s_mov_b32 m0, s4
	v_readfirstlane_b32 s4, v168
	s_add_u32 s26, s28, s26
	s_waitcnt vmcnt(0)
	s_barrier
	s_nop 0
	s_mov_b32 m0, s4
	v_readfirstlane_b32 s4, v169
	s_addc_u32 s27, s29, s27
	v_mov_b32_e32 v135, v131
	s_nop 0
	s_mov_b32 m0, s4
	v_readfirstlane_b32 s4, v170
	v_lshl_add_u64 v[0:1], s[26:27], 0, v[134:135]
	v_mov_b32_e32 v133, v131
	s_nop 0
	s_mov_b32 m0, s4
	v_readfirstlane_b32 s4, v171
	v_lshl_add_u64 v[152:153], v[0:1], 0, v[132:133]
	s_nop 0
	s_mov_b32 m0, s4
	v_readfirstlane_b32 s4, v172
	v_lshl_add_u64 v[154:155], v[152:153], 0, s[10:11]
	s_nop 0
	s_mov_b32 m0, s4
	v_readfirstlane_b32 s4, v173
	s_nop 0
	s_mov_b32 m0, s4
	v_readfirstlane_b32 s4, v174
	s_nop 0
	s_mov_b32 m0, s4
	v_readfirstlane_b32 s4, v175
	s_nop 0
	s_mov_b32 m0, s4
	v_readfirstlane_b32 s4, v176
	s_nop 0
	s_mov_b32 m0, s4
	v_readfirstlane_b32 s4, v177
	s_nop 0
	v_lshl_add_u64 v[0:1], v[152:153], 0, 64
	s_mov_b32 m0, s4
	v_readfirstlane_b32 s4, v178
	s_nop 0
	v_lshl_add_u64 v[0:1], v[152:153], 0, s[12:13]
	s_mov_b32 m0, s4
	s_mov_b32 s27, 2
	s_nop 0
	v_mov_b32_e32 v0, 0
	s_mov_b32 s26, 0
	s_mov_b32 s45, 0
	v_mov_b32_e32 v1, v0
	v_mov_b32_e32 v2, v0
	v_mov_b32_e32 v3, v0
	v_mov_b32_e32 v4, v0
	v_mov_b32_e32 v5, v0
	v_mov_b32_e32 v6, v0
	v_mov_b32_e32 v7, v0
	v_mov_b32_e32 v8, v0
	v_mov_b32_e32 v9, v0
	v_mov_b32_e32 v10, v0
	v_mov_b32_e32 v11, v0
	v_mov_b32_e32 v12, v0
	v_mov_b32_e32 v13, v0
	v_mov_b32_e32 v14, v0
	v_mov_b32_e32 v15, v0
	v_mov_b32_e32 v48, v0
	v_mov_b32_e32 v49, v0
	v_mov_b32_e32 v50, v0
	v_mov_b32_e32 v51, v0
	v_mov_b32_e32 v52, v0
	v_mov_b32_e32 v53, v0
	v_mov_b32_e32 v54, v0
	v_mov_b32_e32 v55, v0
	v_mov_b32_e32 v56, v0
	v_mov_b32_e32 v57, v0
	v_mov_b32_e32 v58, v0
	v_mov_b32_e32 v59, v0
	v_mov_b32_e32 v60, v0
	v_mov_b32_e32 v61, v0
	v_mov_b32_e32 v62, v0
	v_mov_b32_e32 v63, v0
	v_mov_b32_e32 v16, v0
	v_mov_b32_e32 v17, v0
	v_mov_b32_e32 v18, v0
	v_mov_b32_e32 v19, v0
	v_mov_b32_e32 v20, v0
	v_mov_b32_e32 v21, v0
	v_mov_b32_e32 v22, v0
	v_mov_b32_e32 v23, v0
	v_mov_b32_e32 v24, v0
	v_mov_b32_e32 v25, v0
	v_mov_b32_e32 v26, v0
	v_mov_b32_e32 v27, v0
	v_mov_b32_e32 v28, v0
	v_mov_b32_e32 v29, v0
	v_mov_b32_e32 v30, v0
	v_mov_b32_e32 v31, v0
	v_mov_b32_e32 v64, v0
	v_mov_b32_e32 v65, v0
	v_mov_b32_e32 v66, v0
	v_mov_b32_e32 v67, v0
	v_mov_b32_e32 v68, v0
	v_mov_b32_e32 v69, v0
	v_mov_b32_e32 v70, v0
	v_mov_b32_e32 v71, v0
	v_mov_b32_e32 v72, v0
	v_mov_b32_e32 v73, v0
	v_mov_b32_e32 v74, v0
	v_mov_b32_e32 v75, v0
	v_mov_b32_e32 v76, v0
	v_mov_b32_e32 v77, v0
	v_mov_b32_e32 v78, v0
	v_mov_b32_e32 v79, v0
	v_mov_b32_e32 v32, v0
	v_mov_b32_e32 v33, v0
	v_mov_b32_e32 v34, v0
	v_mov_b32_e32 v35, v0
	v_mov_b32_e32 v36, v0
	v_mov_b32_e32 v37, v0
	v_mov_b32_e32 v38, v0
	v_mov_b32_e32 v39, v0
	v_mov_b32_e32 v40, v0
	v_mov_b32_e32 v41, v0
	v_mov_b32_e32 v42, v0
	v_mov_b32_e32 v43, v0
	v_mov_b32_e32 v44, v0
	v_mov_b32_e32 v45, v0
	v_mov_b32_e32 v46, v0
	v_mov_b32_e32 v47, v0
	v_mov_b32_e32 v112, v0
	v_mov_b32_e32 v113, v0
	v_mov_b32_e32 v114, v0
	v_mov_b32_e32 v115, v0
	v_mov_b32_e32 v116, v0
	v_mov_b32_e32 v117, v0
	v_mov_b32_e32 v118, v0
	v_mov_b32_e32 v119, v0
	v_mov_b32_e32 v120, v0
	v_mov_b32_e32 v121, v0
	v_mov_b32_e32 v122, v0
	v_mov_b32_e32 v123, v0
	v_mov_b32_e32 v124, v0
	v_mov_b32_e32 v125, v0
	v_mov_b32_e32 v126, v0
	v_mov_b32_e32 v127, v0
	v_mov_b32_e32 v80, v0
	v_mov_b32_e32 v81, v0
	v_mov_b32_e32 v82, v0
	v_mov_b32_e32 v83, v0
	v_mov_b32_e32 v84, v0
	v_mov_b32_e32 v85, v0
	v_mov_b32_e32 v86, v0
	v_mov_b32_e32 v87, v0
	v_mov_b32_e32 v88, v0
	v_mov_b32_e32 v89, v0
	v_mov_b32_e32 v90, v0
	v_mov_b32_e32 v91, v0
	v_mov_b32_e32 v92, v0
	v_mov_b32_e32 v93, v0
	v_mov_b32_e32 v94, v0
	v_mov_b32_e32 v95, v0
	v_mov_b32_e32 v96, v0
	v_mov_b32_e32 v97, v0
	v_mov_b32_e32 v98, v0
	v_mov_b32_e32 v99, v0
	v_mov_b32_e32 v100, v0
	v_mov_b32_e32 v101, v0
	v_mov_b32_e32 v102, v0
	v_mov_b32_e32 v103, v0
	v_mov_b32_e32 v104, v0
	v_mov_b32_e32 v105, v0
	v_mov_b32_e32 v106, v0
	v_mov_b32_e32 v107, v0
	v_mov_b32_e32 v108, v0
	v_mov_b32_e32 v109, v0
	v_mov_b32_e32 v110, v0
	v_mov_b32_e32 v111, v0
	s_mov_b64 s[54:55], 0x80
	v_lshrrev_b32_e32 v182, 6, v180
	v_lshlrev_b32_e32 v192, 11, v182
	v_and_b32_e32 v156, 63, v180
	v_readfirstlane_b32 s53, v192
	v_lshrrev_b32_e32 v157, 4, v156
	v_bfe_u32 v158, v156, 1, 3
	v_xor_b32_e32 v158, v157, v158
	v_and_b32_e32 v159, 31, v156
	v_lshlrev_b32_e32 v159, 7, v159
	v_lshrrev_b32_e32 v159, 3, v156
	v_lshlrev_b32_e32 v192, 4, v159
	v_add_u32_e32 v193, 0x80, v192
	v_and_b32_e32 v159, 7, v156
	v_lshrrev_b32_e32 v157, 4, v156
	v_xor_b32_e32 v157, v159, v157
	v_lshrrev_b32_e32 v159, 5, v156
	v_sub_u32_e32 v194, v157, v159
	v_xor_b32_e32 v157, 4, v157
	v_add_u32_e32 v159, 2, v159
	v_sub_u32_e32 v196, v157, v159
	v_lshlrev_b32_e32 v194, 4, v194
	v_ashrrev_i32_e32 v195, 31, v194
	v_lshlrev_b32_e32 v196, 4, v196
	v_ashrrev_i32_e32 v197, 31, v196
	ds_bpermute_b32 v244, v192, v152
	ds_bpermute_b32 v245, v192, v153
	ds_bpermute_b32 v246, v193, v152
	ds_bpermute_b32 v247, v193, v153
	ds_bpermute_b32 v248, v192, v154
	ds_bpermute_b32 v249, v192, v155
	ds_bpermute_b32 v250, v193, v154
	ds_bpermute_b32 v251, v193, v155
	s_waitcnt lgkmcnt(0)
	ds_bpermute_b32 v186, v192, v136
	ds_bpermute_b32 v187, v192, v137
	ds_bpermute_b32 v234, v193, v136
	ds_bpermute_b32 v235, v193, v137
	ds_bpermute_b32 v236, v192, v138
	ds_bpermute_b32 v237, v192, v139
	ds_bpermute_b32 v238, v193, v138
	ds_bpermute_b32 v239, v193, v139
	ds_bpermute_b32 v240, v192, v140
	ds_bpermute_b32 v241, v192, v141
	ds_bpermute_b32 v242, v193, v140
	ds_bpermute_b32 v243, v193, v141
	ds_bpermute_b32 v152, v192, v142
	ds_bpermute_b32 v153, v192, v143
	ds_bpermute_b32 v154, v193, v142
	ds_bpermute_b32 v155, v193, v143
	s_waitcnt lgkmcnt(0)
	v_and_b32_e32 v159, 15, v156
	v_lshlrev_b32_e32 v159, 7, v159
	v_lshrrev_b32_e32 v157, 1, v182
	v_lshl_add_u32 v136, v157, 14, v159
	v_and_b32_e32 v157, 1, v182
	v_lshl_add_u32 v140, v157, 13, v159
	v_add_u32_e32 v140, 0x10000, v140
	v_xor_b32_e32 v159, 4, v158
	v_lshl_add_u32 v137, v159, 4, v136
	v_lshl_add_u32 v141, v159, 4, v140
	v_xor_b32_e32 v159, 0, v158
	v_lshl_add_u32 v136, v159, 4, v136
	v_lshl_add_u32 v140, v159, 4, v140
	v_lshl_add_u64 v[186:187], v[186:187], 0, v[194:195]
	v_lshl_add_u64 v[234:235], v[234:235], 0, v[196:197]
	v_lshl_add_u64 v[236:237], v[236:237], 0, v[194:195]
	v_lshl_add_u64 v[238:239], v[238:239], 0, v[196:197]
	v_lshl_add_u64 v[240:241], v[240:241], 0, v[194:195]
	v_lshl_add_u64 v[242:243], v[242:243], 0, v[196:197]
	v_lshl_add_u64 v[152:153], v[152:153], 0, v[194:195]
	v_lshl_add_u64 v[154:155], v[154:155], 0, v[196:197]
	v_lshl_add_u64 v[244:245], v[244:245], 0, v[194:195]
	v_lshl_add_u64 v[246:247], v[246:247], 0, v[196:197]
	v_lshl_add_u64 v[248:249], v[248:249], 0, v[194:195]
	v_lshl_add_u64 v[250:251], v[250:251], 0, v[196:197]
	s_mov_b32 s58, s53
	s_add_i32 m0, s58, 0x0
	s_nop 0
	global_load_lds_dwordx4 v[186:187], off
	s_add_i32 m0, s58, 0x400
	v_lshl_add_u64 v[186:187], v[186:187], 0, s[54:55]
	global_load_lds_dwordx4 v[234:235], off
	s_add_i32 m0, s58, 0x2000
	v_lshl_add_u64 v[234:235], v[234:235], 0, s[54:55]
	global_load_lds_dwordx4 v[236:237], off
	s_add_i32 m0, s58, 0x2400
	v_lshl_add_u64 v[236:237], v[236:237], 0, s[54:55]
	global_load_lds_dwordx4 v[238:239], off
	s_add_i32 m0, s58, 0x4000
	v_lshl_add_u64 v[238:239], v[238:239], 0, s[54:55]
	global_load_lds_dwordx4 v[240:241], off
	s_add_i32 m0, s58, 0x4400
	v_lshl_add_u64 v[240:241], v[240:241], 0, s[54:55]
	global_load_lds_dwordx4 v[242:243], off
	s_add_i32 m0, s58, 0x6000
	v_lshl_add_u64 v[242:243], v[242:243], 0, s[54:55]
	global_load_lds_dwordx4 v[152:153], off
	s_add_i32 m0, s58, 0x6400
	v_lshl_add_u64 v[152:153], v[152:153], 0, s[54:55]
	global_load_lds_dwordx4 v[154:155], off
	v_lshl_add_u64 v[154:155], v[154:155], 0, s[54:55]
	s_add_i32 s58, s53, 0x10000
	s_add_i32 m0, s58, 0x0
	s_nop 0
	global_load_lds_dwordx4 v[244:245], off
	s_add_i32 m0, s58, 0x400
	v_lshl_add_u64 v[244:245], v[244:245], 0, s[54:55]
	global_load_lds_dwordx4 v[246:247], off
	s_add_i32 m0, s58, 0x2000
	v_lshl_add_u64 v[246:247], v[246:247], 0, s[54:55]
	global_load_lds_dwordx4 v[248:249], off
	s_add_i32 m0, s58, 0x2400
	v_lshl_add_u64 v[248:249], v[248:249], 0, s[54:55]
	global_load_lds_dwordx4 v[250:251], off
	v_lshl_add_u64 v[250:251], v[250:251], 0, s[54:55]
	s_mov_b32 s26, 0
	s_mov_b32 s27, 0

.Lg_ph11a_noA:
	ds_read_b128 v[198:201], v140
	ds_read_b128 v[202:205], v140 offset:2048
	ds_read_b128 v[206:209], v140 offset:4096
	ds_read_b128 v[214:217], v140 offset:6144
	ds_read_b128 v[218:221], v141
	ds_read_b128 v[222:225], v141 offset:2048
	ds_read_b128 v[226:229], v141 offset:4096
	ds_read_b128 v[230:233], v141 offset:6144
	ds_read_b128 v[156:159], v136
	ds_read_b128 v[182:185], v136 offset:2048
	ds_read_b128 v[190:193], v136 offset:4096
	ds_read_b128 v[194:197], v136 offset:6144
	s_waitcnt lgkmcnt(4)
	s_barrier
	s_cmp_eq_u32 s26, 15
	s_cbranch_scc1 .Lg_ph11a_noB
	s_add_i32 s58, s53, 0x10000
	s_add_i32 m0, s58, 0x0
	s_nop 0
	global_load_lds_dwordx4 v[244:245], off
	s_add_i32 m0, s58, 0x400
	v_lshl_add_u64 v[244:245], v[244:245], 0, s[54:55]
	global_load_lds_dwordx4 v[246:247], off
	s_add_i32 m0, s58, 0x2000
	v_lshl_add_u64 v[246:247], v[246:247], 0, s[54:55]
	global_load_lds_dwordx4 v[248:249], off
	s_add_i32 m0, s58, 0x2400
	v_lshl_add_u64 v[248:249], v[248:249], 0, s[54:55]
	global_load_lds_dwordx4 v[250:251], off
	v_lshl_add_u64 v[250:251], v[250:251], 0, s[54:55]
.Lg_ph11a_noB:
	s_waitcnt lgkmcnt(3)
	v_mfma_f32_16x16x32_bf16 v[0:3], v[156:159], v[198:201], v[0:3]
	v_mfma_f32_16x16x32_bf16 v[4:7], v[156:159], v[202:205], v[4:7]
	v_mfma_f32_16x16x32_bf16 v[8:11], v[156:159], v[206:209], v[8:11]
	v_mfma_f32_16x16x32_bf16 v[12:15], v[156:159], v[214:217], v[12:15]
	ds_read_b128 v[156:159], v136 offset:8192
	s_waitcnt lgkmcnt(3)
	v_mfma_f32_16x16x32_bf16 v[16:19], v[182:185], v[198:201], v[16:19]
	v_mfma_f32_16x16x32_bf16 v[20:23], v[182:185], v[202:205], v[20:23]
	v_mfma_f32_16x16x32_bf16 v[24:27], v[182:185], v[206:209], v[24:27]
	v_mfma_f32_16x16x32_bf16 v[28:31], v[182:185], v[214:217], v[28:31]
	ds_read_b128 v[182:185], v136 offset:10240
	s_waitcnt lgkmcnt(3)
	v_mfma_f32_16x16x32_bf16 v[32:35], v[190:193], v[198:201], v[32:35]
	v_mfma_f32_16x16x32_bf16 v[36:39], v[190:193], v[202:205], v[36:39]
	v_mfma_f32_16x16x32_bf16 v[40:43], v[190:193], v[206:209], v[40:43]
	v_mfma_f32_16x16x32_bf16 v[44:47], v[190:193], v[214:217], v[44:47]
	ds_read_b128 v[190:193], v136 offset:12288
	s_waitcnt lgkmcnt(3)
	v_mfma_f32_16x16x32_bf16 v[48:51], v[194:197], v[198:201], v[48:51]
	v_mfma_f32_16x16x32_bf16 v[52:55], v[194:197], v[202:205], v[52:55]
	v_mfma_f32_16x16x32_bf16 v[56:59], v[194:197], v[206:209], v[56:59]
	v_mfma_f32_16x16x32_bf16 v[60:63], v[194:197], v[214:217], v[60:63]
	ds_read_b128 v[194:197], v136 offset:14336
	s_waitcnt lgkmcnt(3)
	v_mfma_f32_16x16x32_bf16 v[64:67], v[156:159], v[198:201], v[64:67]
	v_mfma_f32_16x16x32_bf16 v[68:71], v[156:159], v[202:205], v[68:71]
	v_mfma_f32_16x16x32_bf16 v[72:75], v[156:159], v[206:209], v[72:75]
	v_mfma_f32_16x16x32_bf16 v[76:79], v[156:159], v[214:217], v[76:79]
	ds_read_b128 v[156:159], v137
	s_waitcnt lgkmcnt(3)
	v_mfma_f32_16x16x32_bf16 v[80:83], v[182:185], v[198:201], v[80:83]
	v_mfma_f32_16x16x32_bf16 v[84:87], v[182:185], v[202:205], v[84:87]
	v_mfma_f32_16x16x32_bf16 v[88:91], v[182:185], v[206:209], v[88:91]
	v_mfma_f32_16x16x32_bf16 v[92:95], v[182:185], v[214:217], v[92:95]
	ds_read_b128 v[182:185], v137 offset:2048
	s_waitcnt lgkmcnt(3)
	v_mfma_f32_16x16x32_bf16 v[96:99], v[190:193], v[198:201], v[96:99]
	v_mfma_f32_16x16x32_bf16 v[100:103], v[190:193], v[202:205], v[100:103]
	v_mfma_f32_16x16x32_bf16 v[104:107], v[190:193], v[206:209], v[104:107]
	v_mfma_f32_16x16x32_bf16 v[108:111], v[190:193], v[214:217], v[108:111]
	ds_read_b128 v[190:193], v137 offset:4096
	s_waitcnt lgkmcnt(3)
	v_mfma_f32_16x16x32_bf16 v[112:115], v[194:197], v[198:201], v[112:115]
	v_mfma_f32_16x16x32_bf16 v[116:119], v[194:197], v[202:205], v[116:119]
	v_mfma_f32_16x16x32_bf16 v[120:123], v[194:197], v[206:209], v[120:123]
	v_mfma_f32_16x16x32_bf16 v[124:127], v[194:197], v[214:217], v[124:127]
	ds_read_b128 v[194:197], v137 offset:6144
	s_waitcnt lgkmcnt(3)
	v_mfma_f32_16x16x32_bf16 v[0:3], v[156:159], v[218:221], v[0:3]
	v_mfma_f32_16x16x32_bf16 v[4:7], v[156:159], v[222:225], v[4:7]
	v_mfma_f32_16x16x32_bf16 v[8:11], v[156:159], v[226:229], v[8:11]
	v_mfma_f32_16x16x32_bf16 v[12:15], v[156:159], v[230:233], v[12:15]
	ds_read_b128 v[156:159], v137 offset:8192
	s_waitcnt lgkmcnt(3)
	v_mfma_f32_16x16x32_bf16 v[16:19], v[182:185], v[218:221], v[16:19]
	v_mfma_f32_16x16x32_bf16 v[20:23], v[182:185], v[222:225], v[20:23]
	v_mfma_f32_16x16x32_bf16 v[24:27], v[182:185], v[226:229], v[24:27]
	v_mfma_f32_16x16x32_bf16 v[28:31], v[182:185], v[230:233], v[28:31]
	ds_read_b128 v[182:185], v137 offset:10240
	s_waitcnt lgkmcnt(3)
	v_mfma_f32_16x16x32_bf16 v[32:35], v[190:193], v[218:221], v[32:35]
	v_mfma_f32_16x16x32_bf16 v[36:39], v[190:193], v[222:225], v[36:39]
	v_mfma_f32_16x16x32_bf16 v[40:43], v[190:193], v[226:229], v[40:43]
	v_mfma_f32_16x16x32_bf16 v[44:47], v[190:193], v[230:233], v[44:47]
	ds_read_b128 v[190:193], v137 offset:12288
	s_waitcnt lgkmcnt(3)
	v_mfma_f32_16x16x32_bf16 v[48:51], v[194:197], v[218:221], v[48:51]
	v_mfma_f32_16x16x32_bf16 v[52:55], v[194:197], v[222:225], v[52:55]
	v_mfma_f32_16x16x32_bf16 v[56:59], v[194:197], v[226:229], v[56:59]
	v_mfma_f32_16x16x32_bf16 v[60:63], v[194:197], v[230:233], v[60:63]
	ds_read_b128 v[194:197], v137 offset:14336
	s_waitcnt lgkmcnt(3)
	v_mfma_f32_16x16x32_bf16 v[64:67], v[156:159], v[218:221], v[64:67]
	v_mfma_f32_16x16x32_bf16 v[68:71], v[156:159], v[222:225], v[68:71]
	v_mfma_f32_16x16x32_bf16 v[72:75], v[156:159], v[226:229], v[72:75]
	v_mfma_f32_16x16x32_bf16 v[76:79], v[156:159], v[230:233], v[76:79]
	s_waitcnt lgkmcnt(2)
	v_mfma_f32_16x16x32_bf16 v[80:83], v[182:185], v[218:221], v[80:83]
	v_mfma_f32_16x16x32_bf16 v[84:87], v[182:185], v[222:225], v[84:87]
	v_mfma_f32_16x16x32_bf16 v[88:91], v[182:185], v[226:229], v[88:91]
	v_mfma_f32_16x16x32_bf16 v[92:95], v[182:185], v[230:233], v[92:95]
	s_waitcnt lgkmcnt(1)
	v_mfma_f32_16x16x32_bf16 v[96:99], v[190:193], v[218:221], v[96:99]
	v_mfma_f32_16x16x32_bf16 v[100:103], v[190:193], v[222:225], v[100:103]
	v_mfma_f32_16x16x32_bf16 v[104:107], v[190:193], v[226:229], v[104:107]
	v_mfma_f32_16x16x32_bf16 v[108:111], v[190:193], v[230:233], v[108:111]
	s_waitcnt lgkmcnt(0)
	v_mfma_f32_16x16x32_bf16 v[112:115], v[194:197], v[218:221], v[112:115]
	v_mfma_f32_16x16x32_bf16 v[116:119], v[194:197], v[222:225], v[116:119]
	v_mfma_f32_16x16x32_bf16 v[120:123], v[194:197], v[226:229], v[120:123]
	v_mfma_f32_16x16x32_bf16 v[124:127], v[194:197], v[230:233], v[124:127]
	v_xor_b32_e32 v136, 0x8000, v136
	v_xor_b32_e32 v137, 0x8000, v137
	s_xor_b32 s27, s27, 0x8000
	s_add_i32 s26, s26, 1
	s_cmp_eq_u32 s26, 16
	s_cbranch_scc0 .Lg_ph11a_top
	s_waitcnt vmcnt(0)
	v_mov_b32_e32 v130, v180
	s_waitcnt vmcnt(0)
	s_barrier
	s_and_saveexec_b64 s[26:27], s[6:7]
	s_cbranch_execz .LBB0_1179
	v_and_b32_e32 v254, 63, v180
	v_lshrrev_b32_e32 v253, 4, v254
	v_mul_u32_u24_e32 v253, 0x840, v253
	v_and_b32_e32 v254, 15, v254
	v_lshl_add_u32 v253, v254, 2, v253
	v_and_b32_e32 v254, 64, v180
	v_lshl_add_u32 v253, v254, 2, v253
	ds_write_b32 v253, v0 offset:0
	ds_write_b32 v253, v1 offset:528
	ds_write_b32 v253, v2 offset:1056
	ds_write_b32 v253, v3 offset:1584
	ds_write_b32 v253, v4 offset:64
	ds_write_b32 v253, v5 offset:592
	ds_write_b32 v253, v6 offset:1120
	ds_write_b32 v253, v7 offset:1648
	ds_write_b32 v253, v8 offset:128
	ds_write_b32 v253, v9 offset:656
	ds_write_b32 v253, v10 offset:1184
	ds_write_b32 v253, v11 offset:1712
	ds_write_b32 v253, v12 offset:192
	ds_write_b32 v253, v13 offset:720
	ds_write_b32 v253, v14 offset:1248
	ds_write_b32 v253, v15 offset:1776
	ds_write_b32 v253, v16 offset:8448
	ds_write_b32 v253, v17 offset:8976
	ds_write_b32 v253, v18 offset:9504
	ds_write_b32 v253, v19 offset:10032
	ds_write_b32 v253, v20 offset:8512
	ds_write_b32 v253, v21 offset:9040
	ds_write_b32 v253, v22 offset:9568
	ds_write_b32 v253, v23 offset:10096
	ds_write_b32 v253, v24 offset:8576
	ds_write_b32 v253, v25 offset:9104
	ds_write_b32 v253, v26 offset:9632
	ds_write_b32 v253, v27 offset:10160
	ds_write_b32 v253, v28 offset:8640
	ds_write_b32 v253, v29 offset:9168
	ds_write_b32 v253, v30 offset:9696
	ds_write_b32 v253, v31 offset:10224
	ds_write_b32 v253, v32 offset:16896
	ds_write_b32 v253, v33 offset:17424
	ds_write_b32 v253, v34 offset:17952
	ds_write_b32 v253, v35 offset:18480
	ds_write_b32 v253, v36 offset:16960
	ds_write_b32 v253, v37 offset:17488
	ds_write_b32 v253, v38 offset:18016
	ds_write_b32 v253, v39 offset:18544
	ds_write_b32 v253, v40 offset:17024
	ds_write_b32 v253, v41 offset:17552
	ds_write_b32 v253, v42 offset:18080
	ds_write_b32 v253, v43 offset:18608
	ds_write_b32 v253, v44 offset:17088
	ds_write_b32 v253, v45 offset:17616
	ds_write_b32 v253, v46 offset:18144
	ds_write_b32 v253, v47 offset:18672
	ds_write_b32 v253, v48 offset:25344
	ds_write_b32 v253, v49 offset:25872
	ds_write_b32 v253, v50 offset:26400
	ds_write_b32 v253, v51 offset:26928
	ds_write_b32 v253, v52 offset:25408
	ds_write_b32 v253, v53 offset:25936
	ds_write_b32 v253, v54 offset:26464
	ds_write_b32 v253, v55 offset:26992
	ds_write_b32 v253, v56 offset:25472
	ds_write_b32 v253, v57 offset:26000
	ds_write_b32 v253, v58 offset:26528
	ds_write_b32 v253, v59 offset:27056
	ds_write_b32 v253, v60 offset:25536
	ds_write_b32 v253, v61 offset:26064
	ds_write_b32 v253, v62 offset:26592
	ds_write_b32 v253, v63 offset:27120
	ds_write_b32 v253, v64 offset:33792
	ds_write_b32 v253, v65 offset:34320
	ds_write_b32 v253, v66 offset:34848
	ds_write_b32 v253, v67 offset:35376
	ds_write_b32 v253, v68 offset:33856
	ds_write_b32 v253, v69 offset:34384
	ds_write_b32 v253, v70 offset:34912
	ds_write_b32 v253, v71 offset:35440
	ds_write_b32 v253, v72 offset:33920
	ds_write_b32 v253, v73 offset:34448
	ds_write_b32 v253, v74 offset:34976
	ds_write_b32 v253, v75 offset:35504
	ds_write_b32 v253, v76 offset:33984
	ds_write_b32 v253, v77 offset:34512
	ds_write_b32 v253, v78 offset:35040
	ds_write_b32 v253, v79 offset:35568
	ds_write_b32 v253, v80 offset:42240
	ds_write_b32 v253, v81 offset:42768
	ds_write_b32 v253, v82 offset:43296
	ds_write_b32 v253, v83 offset:43824
	ds_write_b32 v253, v84 offset:42304
	ds_write_b32 v253, v85 offset:42832
	ds_write_b32 v253, v86 offset:43360
	ds_write_b32 v253, v87 offset:43888
	ds_write_b32 v253, v88 offset:42368
	ds_write_b32 v253, v89 offset:42896
	ds_write_b32 v253, v90 offset:43424
	ds_write_b32 v253, v91 offset:43952
	ds_write_b32 v253, v92 offset:42432
	ds_write_b32 v253, v93 offset:42960
	ds_write_b32 v253, v94 offset:43488
	ds_write_b32 v253, v95 offset:44016
	ds_write_b32 v253, v96 offset:50688
	ds_write_b32 v253, v97 offset:51216
	ds_write_b32 v253, v98 offset:51744
	ds_write_b32 v253, v99 offset:52272
	ds_write_b32 v253, v100 offset:50752
	ds_write_b32 v253, v101 offset:51280
	ds_write_b32 v253, v102 offset:51808
	ds_write_b32 v253, v103 offset:52336
	ds_write_b32 v253, v104 offset:50816
	ds_write_b32 v253, v105 offset:51344
	ds_write_b32 v253, v106 offset:51872
	ds_write_b32 v253, v107 offset:52400
	ds_write_b32 v253, v108 offset:50880
	ds_write_b32 v253, v109 offset:51408
	ds_write_b32 v253, v110 offset:51936
	ds_write_b32 v253, v111 offset:52464
	ds_write_b32 v253, v112 offset:59136
	ds_write_b32 v253, v113 offset:59664
	ds_write_b32 v253, v114 offset:60192
	ds_write_b32 v253, v115 offset:60720
	ds_write_b32 v253, v116 offset:59200
	ds_write_b32 v253, v117 offset:59728
	ds_write_b32 v253, v118 offset:60256
	ds_write_b32 v253, v119 offset:60784
	ds_write_b32 v253, v120 offset:59264
	ds_write_b32 v253, v121 offset:59792
	ds_write_b32 v253, v122 offset:60320
	ds_write_b32 v253, v123 offset:60848
	ds_write_b32 v253, v124 offset:59328
	ds_write_b32 v253, v125 offset:59856
	ds_write_b32 v253, v126 offset:60384
	ds_write_b32 v253, v127 offset:60912
.LBB0_1179:
	s_or_b64 exec, exec, s[26:27]
	v_lshlrev_b32_e32 v133, 3, v130
	v_and_b32_e32 v179, 0x78, v133
	v_ashrrev_i32_e32 v186, 4, v130
	v_lshl_add_u32 v181, v179, 2, 0
	v_mul_lo_u32 v133, v186, s35
	v_add_u32_e32 v152, 0x200, v130
	v_add_u32_e32 v133, v181, v133
	v_add_u32_e32 v135, 0x100, v130
	v_ashrrev_i32_e32 v198, 4, v152
	s_waitcnt lgkmcnt(0)
	s_barrier
	ds_read_b128 v[152:155], v133
	ds_read_b128 v[156:159], v133 offset:16
	v_ashrrev_i32_e32 v194, 4, v135
	s_lshl_b32 s4, s44, 1
	v_mul_lo_u32 v135, v194, s35
	s_add_u32 s4, s36, s4
	v_add_u32_e32 v135, v181, v135
	s_addc_u32 s26, s37, 0
	s_lshl_b64 s[24:25], s[24:25], 1
	ds_read_b128 v[190:193], v135 offset:16
	s_add_u32 s24, s4, s24
	s_waitcnt lgkmcnt(2)
	v_cvt_pk_bf16_f32 v183, v154, v155
	s_waitcnt lgkmcnt(1)
	v_cvt_pk_bf16_f32 v184, v156, v157
	v_ashrrev_i32_e32 v187, 31, v186
	ds_read_b128 v[154:157], v135
	s_addc_u32 s25, s26, s25
	v_add_u32_e32 v130, 0x300, v130
	v_cvt_pk_bf16_f32 v182, v152, v153
	v_lshlrev_b64 v[152:153], 11, v[186:187]
	v_mul_lo_u32 v189, v198, s35
	v_ashrrev_i32_e32 v200, 4, v130
	v_lshl_add_u64 v[152:153], s[24:25], 0, v[152:153]
	v_lshlrev_b32_e32 v130, 1, v179
	v_cvt_pk_bf16_f32 v185, v158, v159
	v_lshl_add_u64 v[152:153], v[152:153], 0, v[130:131]
	v_add_u32_e32 v179, v181, v189
	global_store_dwordx4 v[152:153], v[182:185], off
	v_ashrrev_i32_e32 v195, 31, v194
	v_mul_lo_u32 v196, v200, s35
	s_waitcnt lgkmcnt(1)
	v_cvt_pk_bf16_f32 v184, v190, v191
	v_cvt_pk_bf16_f32 v185, v192, v193
	ds_read_b128 v[190:193], v179 offset:16
	s_waitcnt lgkmcnt(1)
	v_cvt_pk_bf16_f32 v182, v154, v155
	v_lshlrev_b64 v[154:155], 11, v[194:195]
	v_cvt_pk_bf16_f32 v183, v156, v157
	ds_read_b128 v[156:159], v179
	v_lshl_add_u64 v[154:155], s[24:25], 0, v[154:155]
	v_lshl_add_u64 v[154:155], v[154:155], 0, v[130:131]
	global_store_dwordx4 v[154:155], v[182:185], off
	v_add_u32_e32 v181, v181, v196
	v_ashrrev_i32_e32 v199, 31, v198
	s_waitcnt lgkmcnt(1)
	v_cvt_pk_bf16_f32 v184, v190, v191
	v_cvt_pk_bf16_f32 v185, v192, v193
	ds_read_b128 v[190:193], v181
	ds_read_b128 v[194:197], v181 offset:16
	s_waitcnt lgkmcnt(2)
	v_cvt_pk_bf16_f32 v182, v156, v157
	v_lshlrev_b64 v[156:157], 11, v[198:199]
	v_lshl_add_u64 v[156:157], s[24:25], 0, v[156:157]
	v_cvt_pk_bf16_f32 v183, v158, v159
	v_lshl_add_u64 v[156:157], v[156:157], 0, v[130:131]
	global_store_dwordx4 v[156:157], v[182:185], off
	v_ashrrev_i32_e32 v201, 31, v200
	v_lshlrev_b64 v[158:159], 11, v[200:201]
	s_waitcnt lgkmcnt(0)
	v_cvt_pk_bf16_f32 v185, v196, v197
	v_cvt_pk_bf16_f32 v184, v194, v195
	v_cvt_pk_bf16_f32 v183, v192, v193
	v_cvt_pk_bf16_f32 v182, v190, v191
	ds_read_b128 v[190:193], v133 offset:33792
	ds_read_b128 v[194:197], v133 offset:33808
	v_lshl_add_u64 v[158:159], s[24:25], 0, v[158:159]
	v_lshl_add_u64 v[158:159], v[158:159], 0, v[130:131]
	global_store_dwordx4 v[158:159], v[182:185], off
	v_add_co_u32_e32 v186, vcc, s40, v152
	s_waitcnt lgkmcnt(1)
	v_cvt_pk_bf16_f32 v182, v190, v191
	v_cvt_pk_bf16_f32 v183, v192, v193
	s_waitcnt lgkmcnt(0)
	v_cvt_pk_bf16_f32 v184, v194, v195
	v_cvt_pk_bf16_f32 v185, v196, v197
	ds_read_b128 v[190:193], v135 offset:33792
	ds_read_b128 v[194:197], v135 offset:33808
	v_addc_co_u32_e32 v187, vcc, 0, v153, vcc
	global_store_dwordx4 v[186:187], v[182:185], off
	v_add_co_u32_e32 v186, vcc, s40, v154
	s_waitcnt lgkmcnt(1)
	v_cvt_pk_bf16_f32 v182, v190, v191
	v_cvt_pk_bf16_f32 v183, v192, v193
	s_waitcnt lgkmcnt(0)
	v_cvt_pk_bf16_f32 v184, v194, v195
	v_cvt_pk_bf16_f32 v185, v196, v197
	ds_read_b128 v[190:193], v179 offset:33792
	ds_read_b128 v[194:197], v179 offset:33808
	v_addc_co_u32_e32 v187, vcc, 0, v155, vcc
	global_store_dwordx4 v[186:187], v[182:185], off
	v_add_co_u32_e32 v186, vcc, s40, v156
	s_waitcnt lgkmcnt(1)
	v_cvt_pk_bf16_f32 v182, v190, v191
	v_cvt_pk_bf16_f32 v183, v192, v193
	s_waitcnt lgkmcnt(0)
	v_cvt_pk_bf16_f32 v184, v194, v195
	v_cvt_pk_bf16_f32 v185, v196, v197
	ds_read_b128 v[190:193], v181 offset:33792
	ds_read_b128 v[194:197], v181 offset:33808
	v_addc_co_u32_e32 v187, vcc, 0, v157, vcc
	global_store_dwordx4 v[186:187], v[182:185], off
	v_add_co_u32_e32 v186, vcc, 0x20000, v158
	s_waitcnt lgkmcnt(0)
	v_cvt_pk_bf16_f32 v185, v196, v197
	v_cvt_pk_bf16_f32 v184, v194, v195
	v_cvt_pk_bf16_f32 v183, v192, v193
	v_cvt_pk_bf16_f32 v182, v190, v191
	v_addc_co_u32_e32 v187, vcc, 0, v159, vcc
	global_store_dwordx4 v[186:187], v[182:185], off
	s_barrier
	s_and_saveexec_b64 s[24:25], s[8:9]
	s_cbranch_execz .LBB0_1181
	v_and_b32_e32 v254, 63, v180
	v_lshrrev_b32_e32 v253, 4, v254
	v_mul_u32_u24_e32 v253, 0x840, v253
	v_and_b32_e32 v254, 15, v254
	v_lshl_add_u32 v253, v254, 2, v253
	v_and_b32_e32 v254, 64, v180
	v_lshl_add_u32 v253, v254, 2, v253
	ds_write_b32 v253, v0 offset:0
	ds_write_b32 v253, v1 offset:528
	ds_write_b32 v253, v2 offset:1056
	ds_write_b32 v253, v3 offset:1584
	ds_write_b32 v253, v4 offset:64
	ds_write_b32 v253, v5 offset:592
	ds_write_b32 v253, v6 offset:1120
	ds_write_b32 v253, v7 offset:1648
	ds_write_b32 v253, v8 offset:128
	ds_write_b32 v253, v9 offset:656
	ds_write_b32 v253, v10 offset:1184
	ds_write_b32 v253, v11 offset:1712
	ds_write_b32 v253, v12 offset:192
	ds_write_b32 v253, v13 offset:720
	ds_write_b32 v253, v14 offset:1248
	ds_write_b32 v253, v15 offset:1776
	ds_write_b32 v253, v16 offset:8448
	ds_write_b32 v253, v17 offset:8976
	ds_write_b32 v253, v18 offset:9504
	ds_write_b32 v253, v19 offset:10032
	ds_write_b32 v253, v20 offset:8512
	ds_write_b32 v253, v21 offset:9040
	ds_write_b32 v253, v22 offset:9568
	ds_write_b32 v253, v23 offset:10096
	ds_write_b32 v253, v24 offset:8576
	ds_write_b32 v253, v25 offset:9104
	ds_write_b32 v253, v26 offset:9632
	ds_write_b32 v253, v27 offset:10160
	ds_write_b32 v253, v28 offset:8640
	ds_write_b32 v253, v29 offset:9168
	ds_write_b32 v253, v30 offset:9696
	ds_write_b32 v253, v31 offset:10224
	ds_write_b32 v253, v32 offset:16896
	ds_write_b32 v253, v33 offset:17424
	ds_write_b32 v253, v34 offset:17952
	ds_write_b32 v253, v35 offset:18480
	ds_write_b32 v253, v36 offset:16960
	ds_write_b32 v253, v37 offset:17488
	ds_write_b32 v253, v38 offset:18016
	ds_write_b32 v253, v39 offset:18544
	ds_write_b32 v253, v40 offset:17024
	ds_write_b32 v253, v41 offset:17552
	ds_write_b32 v253, v42 offset:18080
	ds_write_b32 v253, v43 offset:18608
	ds_write_b32 v253, v44 offset:17088
	ds_write_b32 v253, v45 offset:17616
	ds_write_b32 v253, v46 offset:18144
	ds_write_b32 v253, v47 offset:18672
	ds_write_b32 v253, v48 offset:25344
	ds_write_b32 v253, v49 offset:25872
	ds_write_b32 v253, v50 offset:26400
	ds_write_b32 v253, v51 offset:26928
	ds_write_b32 v253, v52 offset:25408
	ds_write_b32 v253, v53 offset:25936
	ds_write_b32 v253, v54 offset:26464
	ds_write_b32 v253, v55 offset:26992
	ds_write_b32 v253, v56 offset:25472
	ds_write_b32 v253, v57 offset:26000
	ds_write_b32 v253, v58 offset:26528
	ds_write_b32 v253, v59 offset:27056
	ds_write_b32 v253, v60 offset:25536
	ds_write_b32 v253, v61 offset:26064
	ds_write_b32 v253, v62 offset:26592
	ds_write_b32 v253, v63 offset:27120
	ds_write_b32 v253, v64 offset:33792
	ds_write_b32 v253, v65 offset:34320
	ds_write_b32 v253, v66 offset:34848
	ds_write_b32 v253, v67 offset:35376
	ds_write_b32 v253, v68 offset:33856
	ds_write_b32 v253, v69 offset:34384
	ds_write_b32 v253, v70 offset:34912
	ds_write_b32 v253, v71 offset:35440
	ds_write_b32 v253, v72 offset:33920
	ds_write_b32 v253, v73 offset:34448
	ds_write_b32 v253, v74 offset:34976
	ds_write_b32 v253, v75 offset:35504
	ds_write_b32 v253, v76 offset:33984
	ds_write_b32 v253, v77 offset:34512
	ds_write_b32 v253, v78 offset:35040
	ds_write_b32 v253, v79 offset:35568
	ds_write_b32 v253, v80 offset:42240
	ds_write_b32 v253, v81 offset:42768
	ds_write_b32 v253, v82 offset:43296
	ds_write_b32 v253, v83 offset:43824
	ds_write_b32 v253, v84 offset:42304
	ds_write_b32 v253, v85 offset:42832
	ds_write_b32 v253, v86 offset:43360
	ds_write_b32 v253, v87 offset:43888
	ds_write_b32 v253, v88 offset:42368
	ds_write_b32 v253, v89 offset:42896
	ds_write_b32 v253, v90 offset:43424
	ds_write_b32 v253, v91 offset:43952
	ds_write_b32 v253, v92 offset:42432
	ds_write_b32 v253, v93 offset:42960
	ds_write_b32 v253, v94 offset:43488
	ds_write_b32 v253, v95 offset:44016
	ds_write_b32 v253, v96 offset:50688
	ds_write_b32 v253, v97 offset:51216
	ds_write_b32 v253, v98 offset:51744
	ds_write_b32 v253, v99 offset:52272
	ds_write_b32 v253, v100 offset:50752
	ds_write_b32 v253, v101 offset:51280
	ds_write_b32 v253, v102 offset:51808
	ds_write_b32 v253, v103 offset:52336
	ds_write_b32 v253, v104 offset:50816
	ds_write_b32 v253, v105 offset:51344
	ds_write_b32 v253, v106 offset:51872
	ds_write_b32 v253, v107 offset:52400
	ds_write_b32 v253, v108 offset:50880
	ds_write_b32 v253, v109 offset:51408
	ds_write_b32 v253, v110 offset:51936
	ds_write_b32 v253, v111 offset:52464
	ds_write_b32 v253, v112 offset:59136
	ds_write_b32 v253, v113 offset:59664
	ds_write_b32 v253, v114 offset:60192
	ds_write_b32 v253, v115 offset:60720
	ds_write_b32 v253, v116 offset:59200
	ds_write_b32 v253, v117 offset:59728
	ds_write_b32 v253, v118 offset:60256
	ds_write_b32 v253, v119 offset:60784
	ds_write_b32 v253, v120 offset:59264
	ds_write_b32 v253, v121 offset:59792
	ds_write_b32 v253, v122 offset:60320
	ds_write_b32 v253, v123 offset:60848
	ds_write_b32 v253, v124 offset:59328
	ds_write_b32 v253, v125 offset:59856
	ds_write_b32 v253, v126 offset:60384
	ds_write_b32 v253, v127 offset:60912

.LBB0_1182:
	s_and_b64 vcc, exec, s[24:25]
	s_cbranch_vccz .LBB0_1173
	s_lshl_b32 s4, s43, 17
	s_add_u32 s24, s28, s4
	v_readfirstlane_b32 s4, v160
	s_mov_b32 m0, s4
	v_readfirstlane_b32 s4, v168
	s_addc_u32 s25, s29, 0
	v_mov_b32_e32 v135, v131
	s_waitcnt vmcnt(0)
	s_barrier
	s_nop 0
	s_mov_b32 m0, s4
	v_readfirstlane_b32 s4, v169
	v_lshl_add_u64 v[0:1], s[24:25], 0, v[134:135]
	v_mov_b32_e32 v133, v131
	s_nop 0
	s_mov_b32 m0, s4
	v_readfirstlane_b32 s4, v170
	v_lshl_add_u64 v[0:1], v[0:1], 0, v[132:133]
	s_nop 0
	s_mov_b32 m0, s4
	v_readfirstlane_b32 s4, v171
	v_lshl_add_u64 v[152:153], v[0:1], 0, s[16:17]
	s_nop 0
	s_mov_b32 m0, s4
	v_readfirstlane_b32 s4, v172
	v_lshl_add_u64 v[154:155], v[0:1], 0, s[18:19]
	s_nop 0
	s_mov_b32 m0, s4
	v_readfirstlane_b32 s4, v173
	s_nop 0
	s_mov_b32 m0, s4
	v_readfirstlane_b32 s4, v174
	s_nop 0
	s_mov_b32 m0, s4
	v_readfirstlane_b32 s4, v175
	s_nop 0
	s_mov_b32 m0, s4
	v_readfirstlane_b32 s4, v176
	s_nop 0
	s_mov_b32 m0, s4
	v_readfirstlane_b32 s4, v177
	s_nop 0
	v_lshl_add_u64 v[2:3], v[0:1], 0, s[20:21]
	s_mov_b32 m0, s4
	v_readfirstlane_b32 s4, v178
	s_nop 0
	v_lshl_add_u64 v[0:1], v[0:1], 0, s[22:23]
	s_mov_b32 m0, s4
	s_mov_b32 s25, 2
	s_nop 0
	v_mov_b32_e32 v0, 0
	s_mov_b32 s24, 0
	s_mov_b32 s26, 0
	v_mov_b32_e32 v1, v0
	v_mov_b32_e32 v2, v0
	v_mov_b32_e32 v3, v0
	v_mov_b32_e32 v4, v0
	v_mov_b32_e32 v5, v0
	v_mov_b32_e32 v6, v0
	v_mov_b32_e32 v7, v0
	v_mov_b32_e32 v8, v0
	v_mov_b32_e32 v9, v0
	v_mov_b32_e32 v10, v0
	v_mov_b32_e32 v11, v0
	v_mov_b32_e32 v12, v0
	v_mov_b32_e32 v13, v0
	v_mov_b32_e32 v14, v0
	v_mov_b32_e32 v15, v0
	v_mov_b32_e32 v16, v0
	v_mov_b32_e32 v17, v0
	v_mov_b32_e32 v18, v0
	v_mov_b32_e32 v19, v0
	v_mov_b32_e32 v20, v0
	v_mov_b32_e32 v21, v0
	v_mov_b32_e32 v22, v0
	v_mov_b32_e32 v23, v0
	v_mov_b32_e32 v24, v0
	v_mov_b32_e32 v25, v0
	v_mov_b32_e32 v26, v0
	v_mov_b32_e32 v27, v0
	v_mov_b32_e32 v28, v0
	v_mov_b32_e32 v29, v0
	v_mov_b32_e32 v30, v0
	v_mov_b32_e32 v31, v0
	v_mov_b32_e32 v32, v0
	v_mov_b32_e32 v33, v0
	v_mov_b32_e32 v34, v0
	v_mov_b32_e32 v35, v0
	v_mov_b32_e32 v36, v0
	v_mov_b32_e32 v37, v0
	v_mov_b32_e32 v38, v0
	v_mov_b32_e32 v39, v0
	v_mov_b32_e32 v40, v0
	v_mov_b32_e32 v41, v0
	v_mov_b32_e32 v42, v0
	v_mov_b32_e32 v43, v0
	v_mov_b32_e32 v44, v0
	v_mov_b32_e32 v45, v0
	v_mov_b32_e32 v46, v0
	v_mov_b32_e32 v47, v0
	v_mov_b32_e32 v48, v0
	v_mov_b32_e32 v49, v0
	v_mov_b32_e32 v50, v0
	v_mov_b32_e32 v51, v0
	v_mov_b32_e32 v52, v0
	v_mov_b32_e32 v53, v0
	v_mov_b32_e32 v54, v0
	v_mov_b32_e32 v55, v0
	v_mov_b32_e32 v56, v0
	v_mov_b32_e32 v57, v0
	v_mov_b32_e32 v58, v0
	v_mov_b32_e32 v59, v0
	v_mov_b32_e32 v60, v0
	v_mov_b32_e32 v61, v0
	v_mov_b32_e32 v62, v0
	v_mov_b32_e32 v63, v0
	v_mov_b32_e32 v64, v0
	v_mov_b32_e32 v65, v0
	v_mov_b32_e32 v66, v0
	v_mov_b32_e32 v67, v0
	v_mov_b32_e32 v68, v0
	v_mov_b32_e32 v69, v0
	v_mov_b32_e32 v70, v0
	v_mov_b32_e32 v71, v0
	v_mov_b32_e32 v72, v0
	v_mov_b32_e32 v73, v0
	v_mov_b32_e32 v74, v0
	v_mov_b32_e32 v75, v0
	v_mov_b32_e32 v76, v0
	v_mov_b32_e32 v77, v0
	v_mov_b32_e32 v78, v0
	v_mov_b32_e32 v79, v0
	v_mov_b32_e32 v112, v0
	v_mov_b32_e32 v113, v0
	v_mov_b32_e32 v114, v0
	v_mov_b32_e32 v115, v0
	v_mov_b32_e32 v116, v0
	v_mov_b32_e32 v117, v0
	v_mov_b32_e32 v118, v0
	v_mov_b32_e32 v119, v0
	v_mov_b32_e32 v120, v0
	v_mov_b32_e32 v121, v0
	v_mov_b32_e32 v122, v0
	v_mov_b32_e32 v123, v0
	v_mov_b32_e32 v124, v0
	v_mov_b32_e32 v125, v0
	v_mov_b32_e32 v126, v0
	v_mov_b32_e32 v127, v0
	v_mov_b32_e32 v80, v0
	v_mov_b32_e32 v81, v0
	v_mov_b32_e32 v82, v0
	v_mov_b32_e32 v83, v0
	v_mov_b32_e32 v84, v0
	v_mov_b32_e32 v85, v0
	v_mov_b32_e32 v86, v0
	v_mov_b32_e32 v87, v0
	v_mov_b32_e32 v88, v0
	v_mov_b32_e32 v89, v0
	v_mov_b32_e32 v90, v0
	v_mov_b32_e32 v91, v0
	v_mov_b32_e32 v92, v0
	v_mov_b32_e32 v93, v0
	v_mov_b32_e32 v94, v0
	v_mov_b32_e32 v95, v0
	v_mov_b32_e32 v96, v0
	v_mov_b32_e32 v97, v0
	v_mov_b32_e32 v98, v0
	v_mov_b32_e32 v99, v0
	v_mov_b32_e32 v100, v0
	v_mov_b32_e32 v101, v0
	v_mov_b32_e32 v102, v0
	v_mov_b32_e32 v103, v0
	v_mov_b32_e32 v104, v0
	v_mov_b32_e32 v105, v0
	v_mov_b32_e32 v106, v0
	v_mov_b32_e32 v107, v0
	v_mov_b32_e32 v108, v0
	v_mov_b32_e32 v109, v0
	v_mov_b32_e32 v110, v0
	v_mov_b32_e32 v111, v0
	s_mov_b64 s[54:55], 0x80
	v_lshrrev_b32_e32 v148, 6, v180
	v_lshlrev_b32_e32 v158, 11, v148
	v_and_b32_e32 v144, 63, v180
	v_readfirstlane_b32 s53, v158
	v_lshrrev_b32_e32 v145, 4, v144
	v_bfe_u32 v146, v144, 1, 3
	v_xor_b32_e32 v146, v145, v146
	v_and_b32_e32 v147, 31, v144
	v_lshlrev_b32_e32 v147, 7, v147
	v_lshrrev_b32_e32 v147, 3, v144
	v_lshlrev_b32_e32 v158, 4, v147
	v_add_u32_e32 v159, 0x80, v158
	v_and_b32_e32 v147, 7, v144
	v_lshrrev_b32_e32 v145, 4, v144
	v_xor_b32_e32 v145, v147, v145
	v_lshrrev_b32_e32 v147, 5, v144
	v_sub_u32_e32 v182, v145, v147
	v_xor_b32_e32 v145, 4, v145
	v_add_u32_e32 v147, 2, v147
	v_sub_u32_e32 v184, v145, v147
	v_lshlrev_b32_e32 v182, 4, v182
	v_ashrrev_i32_e32 v183, 31, v182
	v_lshlrev_b32_e32 v184, 4, v184
	v_ashrrev_i32_e32 v185, 31, v184
	ds_bpermute_b32 v244, v158, v152
	ds_bpermute_b32 v245, v158, v153
	ds_bpermute_b32 v246, v159, v152
	ds_bpermute_b32 v247, v159, v153
	ds_bpermute_b32 v248, v158, v154
	ds_bpermute_b32 v249, v158, v155
	ds_bpermute_b32 v250, v159, v154
	ds_bpermute_b32 v251, v159, v155
	s_waitcnt lgkmcnt(0)
	ds_bpermute_b32 v186, v158, v136
	ds_bpermute_b32 v187, v158, v137
	ds_bpermute_b32 v234, v159, v136
	ds_bpermute_b32 v235, v159, v137
	ds_bpermute_b32 v236, v158, v138
	ds_bpermute_b32 v237, v158, v139
	ds_bpermute_b32 v238, v159, v138
	ds_bpermute_b32 v239, v159, v139
	ds_bpermute_b32 v240, v158, v140
	ds_bpermute_b32 v241, v158, v141
	ds_bpermute_b32 v242, v159, v140
	ds_bpermute_b32 v243, v159, v141
	ds_bpermute_b32 v152, v158, v142
	ds_bpermute_b32 v153, v158, v143
	ds_bpermute_b32 v154, v159, v142
	ds_bpermute_b32 v155, v159, v143
	s_waitcnt lgkmcnt(0)
	v_and_b32_e32 v147, 15, v144
	v_lshlrev_b32_e32 v147, 7, v147
	v_lshrrev_b32_e32 v145, 1, v148
	v_lshl_add_u32 v136, v145, 14, v147
	v_and_b32_e32 v145, 1, v148
	v_lshl_add_u32 v140, v145, 13, v147
	v_add_u32_e32 v140, 0x10000, v140
	v_xor_b32_e32 v147, 4, v146
	v_lshl_add_u32 v137, v147, 4, v136
	v_lshl_add_u32 v141, v147, 4, v140
	v_xor_b32_e32 v147, 0, v146
	v_lshl_add_u32 v136, v147, 4, v136
	v_lshl_add_u32 v140, v147, 4, v140
	v_lshl_add_u64 v[186:187], v[186:187], 0, v[182:183]
	v_lshl_add_u64 v[234:235], v[234:235], 0, v[184:185]
	v_lshl_add_u64 v[236:237], v[236:237], 0, v[182:183]
	v_lshl_add_u64 v[238:239], v[238:239], 0, v[184:185]
	v_lshl_add_u64 v[240:241], v[240:241], 0, v[182:183]
	v_lshl_add_u64 v[242:243], v[242:243], 0, v[184:185]
	v_lshl_add_u64 v[152:153], v[152:153], 0, v[182:183]
	v_lshl_add_u64 v[154:155], v[154:155], 0, v[184:185]
	v_lshl_add_u64 v[244:245], v[244:245], 0, v[182:183]
	v_lshl_add_u64 v[246:247], v[246:247], 0, v[184:185]
	v_lshl_add_u64 v[248:249], v[248:249], 0, v[182:183]
	v_lshl_add_u64 v[250:251], v[250:251], 0, v[184:185]
	s_mov_b32 s58, s53
	s_add_i32 m0, s58, 0x0
	s_nop 0
	global_load_lds_dwordx4 v[186:187], off
	s_add_i32 m0, s58, 0x400
	v_lshl_add_u64 v[186:187], v[186:187], 0, s[54:55]
	global_load_lds_dwordx4 v[234:235], off
	s_add_i32 m0, s58, 0x2000
	v_lshl_add_u64 v[234:235], v[234:235], 0, s[54:55]
	global_load_lds_dwordx4 v[236:237], off
	s_add_i32 m0, s58, 0x2400
	v_lshl_add_u64 v[236:237], v[236:237], 0, s[54:55]
	global_load_lds_dwordx4 v[238:239], off
	s_add_i32 m0, s58, 0x4000
	v_lshl_add_u64 v[238:239], v[238:239], 0, s[54:55]
	global_load_lds_dwordx4 v[240:241], off
	s_add_i32 m0, s58, 0x4400
	v_lshl_add_u64 v[240:241], v[240:241], 0, s[54:55]
	global_load_lds_dwordx4 v[242:243], off
	s_add_i32 m0, s58, 0x6000
	v_lshl_add_u64 v[242:243], v[242:243], 0, s[54:55]
	global_load_lds_dwordx4 v[152:153], off
	s_add_i32 m0, s58, 0x6400
	v_lshl_add_u64 v[152:153], v[152:153], 0, s[54:55]
	global_load_lds_dwordx4 v[154:155], off
	v_lshl_add_u64 v[154:155], v[154:155], 0, s[54:55]
	s_add_i32 s58, s53, 0x10000
	s_add_i32 m0, s58, 0x0
	s_nop 0
	global_load_lds_dwordx4 v[244:245], off
	s_add_i32 m0, s58, 0x400
	v_lshl_add_u64 v[244:245], v[244:245], 0, s[54:55]
	global_load_lds_dwordx4 v[246:247], off
	s_add_i32 m0, s58, 0x2000
	v_lshl_add_u64 v[246:247], v[246:247], 0, s[54:55]
	global_load_lds_dwordx4 v[248:249], off
	s_add_i32 m0, s58, 0x2400
	v_lshl_add_u64 v[248:249], v[248:249], 0, s[54:55]
	global_load_lds_dwordx4 v[250:251], off
	v_lshl_add_u64 v[250:251], v[250:251], 0, s[54:55]
	s_mov_b32 s24, 0
	s_mov_b32 s25, 0

.Lg_ph11b_noA:
	ds_read_b128 v[190:193], v140
	ds_read_b128 v[194:197], v140 offset:2048
	ds_read_b128 v[198:201], v140 offset:4096
	ds_read_b128 v[202:205], v140 offset:6144
	ds_read_b128 v[206:209], v141
	ds_read_b128 v[222:225], v141 offset:2048
	ds_read_b128 v[226:229], v141 offset:4096
	ds_read_b128 v[230:233], v141 offset:6144
	ds_read_b128 v[144:147], v136
	ds_read_b128 v[148:151], v136 offset:2048
	ds_read_b128 v[156:159], v136 offset:4096
	ds_read_b128 v[182:185], v136 offset:6144
	s_waitcnt lgkmcnt(4)
	s_barrier
	s_cmp_eq_u32 s24, 15
	s_cbranch_scc1 .Lg_ph11b_noB
	s_add_i32 s58, s53, 0x10000
	s_add_i32 m0, s58, 0x0
	s_nop 0
	global_load_lds_dwordx4 v[244:245], off
	s_add_i32 m0, s58, 0x400
	v_lshl_add_u64 v[244:245], v[244:245], 0, s[54:55]
	global_load_lds_dwordx4 v[246:247], off
	s_add_i32 m0, s58, 0x2000
	v_lshl_add_u64 v[246:247], v[246:247], 0, s[54:55]
	global_load_lds_dwordx4 v[248:249], off
	s_add_i32 m0, s58, 0x2400
	v_lshl_add_u64 v[248:249], v[248:249], 0, s[54:55]
	global_load_lds_dwordx4 v[250:251], off
	v_lshl_add_u64 v[250:251], v[250:251], 0, s[54:55]
.Lg_ph11b_noB:
	s_waitcnt lgkmcnt(3)
	v_mfma_f32_16x16x32_bf16 v[0:3], v[144:147], v[190:193], v[0:3]
	v_mfma_f32_16x16x32_bf16 v[4:7], v[144:147], v[194:197], v[4:7]
	v_mfma_f32_16x16x32_bf16 v[8:11], v[144:147], v[198:201], v[8:11]
	v_mfma_f32_16x16x32_bf16 v[12:15], v[144:147], v[202:205], v[12:15]
	ds_read_b128 v[144:147], v136 offset:8192
	s_waitcnt lgkmcnt(3)
	v_mfma_f32_16x16x32_bf16 v[16:19], v[148:151], v[190:193], v[16:19]
	v_mfma_f32_16x16x32_bf16 v[20:23], v[148:151], v[194:197], v[20:23]
	v_mfma_f32_16x16x32_bf16 v[24:27], v[148:151], v[198:201], v[24:27]
	v_mfma_f32_16x16x32_bf16 v[28:31], v[148:151], v[202:205], v[28:31]
	ds_read_b128 v[148:151], v136 offset:10240
	s_waitcnt lgkmcnt(3)
	v_mfma_f32_16x16x32_bf16 v[32:35], v[156:159], v[190:193], v[32:35]
	v_mfma_f32_16x16x32_bf16 v[36:39], v[156:159], v[194:197], v[36:39]
	v_mfma_f32_16x16x32_bf16 v[40:43], v[156:159], v[198:201], v[40:43]
	v_mfma_f32_16x16x32_bf16 v[44:47], v[156:159], v[202:205], v[44:47]
	ds_read_b128 v[156:159], v136 offset:12288
	s_waitcnt lgkmcnt(3)
	v_mfma_f32_16x16x32_bf16 v[48:51], v[182:185], v[190:193], v[48:51]
	v_mfma_f32_16x16x32_bf16 v[52:55], v[182:185], v[194:197], v[52:55]
	v_mfma_f32_16x16x32_bf16 v[56:59], v[182:185], v[198:201], v[56:59]
	v_mfma_f32_16x16x32_bf16 v[60:63], v[182:185], v[202:205], v[60:63]
	ds_read_b128 v[182:185], v136 offset:14336
	s_waitcnt lgkmcnt(3)
	v_mfma_f32_16x16x32_bf16 v[64:67], v[144:147], v[190:193], v[64:67]
	v_mfma_f32_16x16x32_bf16 v[68:71], v[144:147], v[194:197], v[68:71]
	v_mfma_f32_16x16x32_bf16 v[72:75], v[144:147], v[198:201], v[72:75]
	v_mfma_f32_16x16x32_bf16 v[76:79], v[144:147], v[202:205], v[76:79]
	ds_read_b128 v[144:147], v137
	s_waitcnt lgkmcnt(3)
	v_mfma_f32_16x16x32_bf16 v[80:83], v[148:151], v[190:193], v[80:83]
	v_mfma_f32_16x16x32_bf16 v[84:87], v[148:151], v[194:197], v[84:87]
	v_mfma_f32_16x16x32_bf16 v[88:91], v[148:151], v[198:201], v[88:91]
	v_mfma_f32_16x16x32_bf16 v[92:95], v[148:151], v[202:205], v[92:95]
	ds_read_b128 v[148:151], v137 offset:2048
	s_waitcnt lgkmcnt(3)
	v_mfma_f32_16x16x32_bf16 v[96:99], v[156:159], v[190:193], v[96:99]
	v_mfma_f32_16x16x32_bf16 v[100:103], v[156:159], v[194:197], v[100:103]
	v_mfma_f32_16x16x32_bf16 v[104:107], v[156:159], v[198:201], v[104:107]
	v_mfma_f32_16x16x32_bf16 v[108:111], v[156:159], v[202:205], v[108:111]
	ds_read_b128 v[156:159], v137 offset:4096
	s_waitcnt lgkmcnt(3)
	v_mfma_f32_16x16x32_bf16 v[112:115], v[182:185], v[190:193], v[112:115]
	v_mfma_f32_16x16x32_bf16 v[116:119], v[182:185], v[194:197], v[116:119]
	v_mfma_f32_16x16x32_bf16 v[120:123], v[182:185], v[198:201], v[120:123]
	v_mfma_f32_16x16x32_bf16 v[124:127], v[182:185], v[202:205], v[124:127]
	ds_read_b128 v[182:185], v137 offset:6144
	s_waitcnt lgkmcnt(3)
	v_mfma_f32_16x16x32_bf16 v[0:3], v[144:147], v[206:209], v[0:3]
	v_mfma_f32_16x16x32_bf16 v[4:7], v[144:147], v[222:225], v[4:7]
	v_mfma_f32_16x16x32_bf16 v[8:11], v[144:147], v[226:229], v[8:11]
	v_mfma_f32_16x16x32_bf16 v[12:15], v[144:147], v[230:233], v[12:15]
	ds_read_b128 v[144:147], v137 offset:8192
	s_waitcnt lgkmcnt(3)
	v_mfma_f32_16x16x32_bf16 v[16:19], v[148:151], v[206:209], v[16:19]
	v_mfma_f32_16x16x32_bf16 v[20:23], v[148:151], v[222:225], v[20:23]
	v_mfma_f32_16x16x32_bf16 v[24:27], v[148:151], v[226:229], v[24:27]
	v_mfma_f32_16x16x32_bf16 v[28:31], v[148:151], v[230:233], v[28:31]
	ds_read_b128 v[148:151], v137 offset:10240
	s_waitcnt lgkmcnt(3)
	v_mfma_f32_16x16x32_bf16 v[32:35], v[156:159], v[206:209], v[32:35]
	v_mfma_f32_16x16x32_bf16 v[36:39], v[156:159], v[222:225], v[36:39]
	v_mfma_f32_16x16x32_bf16 v[40:43], v[156:159], v[226:229], v[40:43]
	v_mfma_f32_16x16x32_bf16 v[44:47], v[156:159], v[230:233], v[44:47]
	ds_read_b128 v[156:159], v137 offset:12288
	s_waitcnt lgkmcnt(3)
	v_mfma_f32_16x16x32_bf16 v[48:51], v[182:185], v[206:209], v[48:51]
	v_mfma_f32_16x16x32_bf16 v[52:55], v[182:185], v[222:225], v[52:55]
	v_mfma_f32_16x16x32_bf16 v[56:59], v[182:185], v[226:229], v[56:59]
	v_mfma_f32_16x16x32_bf16 v[60:63], v[182:185], v[230:233], v[60:63]
	ds_read_b128 v[182:185], v137 offset:14336
	s_waitcnt lgkmcnt(3)
	v_mfma_f32_16x16x32_bf16 v[64:67], v[144:147], v[206:209], v[64:67]
	v_mfma_f32_16x16x32_bf16 v[68:71], v[144:147], v[222:225], v[68:71]
	v_mfma_f32_16x16x32_bf16 v[72:75], v[144:147], v[226:229], v[72:75]
	v_mfma_f32_16x16x32_bf16 v[76:79], v[144:147], v[230:233], v[76:79]
	s_waitcnt lgkmcnt(2)
	v_mfma_f32_16x16x32_bf16 v[80:83], v[148:151], v[206:209], v[80:83]
	v_mfma_f32_16x16x32_bf16 v[84:87], v[148:151], v[222:225], v[84:87]
	v_mfma_f32_16x16x32_bf16 v[88:91], v[148:151], v[226:229], v[88:91]
	v_mfma_f32_16x16x32_bf16 v[92:95], v[148:151], v[230:233], v[92:95]
	s_waitcnt lgkmcnt(1)
	v_mfma_f32_16x16x32_bf16 v[96:99], v[156:159], v[206:209], v[96:99]
	v_mfma_f32_16x16x32_bf16 v[100:103], v[156:159], v[222:225], v[100:103]
	v_mfma_f32_16x16x32_bf16 v[104:107], v[156:159], v[226:229], v[104:107]
	v_mfma_f32_16x16x32_bf16 v[108:111], v[156:159], v[230:233], v[108:111]
	s_waitcnt lgkmcnt(0)
	v_mfma_f32_16x16x32_bf16 v[112:115], v[182:185], v[206:209], v[112:115]
	v_mfma_f32_16x16x32_bf16 v[116:119], v[182:185], v[222:225], v[116:119]
	v_mfma_f32_16x16x32_bf16 v[120:123], v[182:185], v[226:229], v[120:123]
	v_mfma_f32_16x16x32_bf16 v[124:127], v[182:185], v[230:233], v[124:127]
	v_xor_b32_e32 v136, 0x8000, v136
	v_xor_b32_e32 v137, 0x8000, v137
	s_xor_b32 s25, s25, 0x8000
	s_add_i32 s24, s24, 1
	s_cmp_eq_u32 s24, 16
	s_cbranch_scc0 .Lg_ph11b_top
	s_waitcnt vmcnt(0)
	v_mov_b32_e32 v130, v180
	v_add_u32_e32 v192, 0x400, v166
	v_add_u32_e32 v191, 0x1000, v166
	v_add_u32_e32 v190, 0x1400, v166
	v_add_u32_e32 v189, 0x2000, v166
	v_add_u32_e32 v182, 0x2400, v166
	v_add_u32_e32 v183, 0x3000, v166
	v_add_u32_e32 v184, 0x3200, v166
	v_add_u32_e32 v185, 0x3400, v166
	v_add_u32_e32 v186, 0x3600, v166
	v_add_u32_e32 v187, 0x4000, v166
	v_add_u32_e32 v159, 0x4400, v166
	v_add_u32_e32 v179, 0x4800, v166
	v_add_u32_e32 v181, 0x5000, v166
	v_add_u32_e32 v156, 0x5400, v166
	v_add_u32_e32 v157, 0x5800, v166
	v_add_u32_e32 v158, 0x6000, v166
	v_add_u32_e32 v150, 0x6400, v166
	v_add_u32_e32 v151, 0x6800, v166
	v_add_u32_e32 v152, 0x7200, v166
	v_add_u32_e32 v153, 0x7400, v166
	v_add_u32_e32 v154, 0x7600, v166
	v_add_u32_e32 v155, 0x7800, v166
	v_add_u32_e32 v149, 0x8400, v166
	v_add_u32_e32 v148, 0x8800, v166
	v_add_u32_e32 v147, 0x9400, v166
	v_add_u32_e32 v146, 0x9800, v166
	v_add_u32_e32 v145, 0xa400, v166
	v_add_u32_e32 v140, 0xa800, v166
	v_add_u32_e32 v141, 0xb400, v166
	v_add_u32_e32 v142, 0xb600, v166
	v_add_u32_e32 v143, 0xb800, v166
	v_add_u32_e32 v144, 0xba00, v166
	s_waitcnt vmcnt(0)
	s_barrier
	s_and_saveexec_b64 s[24:25], s[6:7]
	s_cbranch_execz .LBB0_1187
	v_and_b32_e32 v254, 63, v180
	v_lshrrev_b32_e32 v253, 4, v254
	v_mul_u32_u24_e32 v253, 0x840, v253
	v_and_b32_e32 v254, 15, v254
	v_lshl_add_u32 v253, v254, 2, v253
	v_and_b32_e32 v254, 64, v180
	v_lshl_add_u32 v253, v254, 2, v253
	ds_write_b32 v253, v0 offset:0
	ds_write_b32 v253, v1 offset:528
	ds_write_b32 v253, v2 offset:1056
	ds_write_b32 v253, v3 offset:1584
	ds_write_b32 v253, v4 offset:64
	ds_write_b32 v253, v5 offset:592
	ds_write_b32 v253, v6 offset:1120
	ds_write_b32 v253, v7 offset:1648
	ds_write_b32 v253, v8 offset:128
	ds_write_b32 v253, v9 offset:656
	ds_write_b32 v253, v10 offset:1184
	ds_write_b32 v253, v11 offset:1712
	ds_write_b32 v253, v12 offset:192
	ds_write_b32 v253, v13 offset:720
	ds_write_b32 v253, v14 offset:1248
	ds_write_b32 v253, v15 offset:1776
	ds_write_b32 v253, v16 offset:8448
	ds_write_b32 v253, v17 offset:8976
	ds_write_b32 v253, v18 offset:9504
	ds_write_b32 v253, v19 offset:10032
	ds_write_b32 v253, v20 offset:8512
	ds_write_b32 v253, v21 offset:9040
	ds_write_b32 v253, v22 offset:9568
	ds_write_b32 v253, v23 offset:10096
	ds_write_b32 v253, v24 offset:8576
	ds_write_b32 v253, v25 offset:9104
	ds_write_b32 v253, v26 offset:9632
	ds_write_b32 v253, v27 offset:10160
	ds_write_b32 v253, v28 offset:8640
	ds_write_b32 v253, v29 offset:9168
	ds_write_b32 v253, v30 offset:9696
	ds_write_b32 v253, v31 offset:10224
	ds_write_b32 v253, v32 offset:16896
	ds_write_b32 v253, v33 offset:17424
	ds_write_b32 v253, v34 offset:17952
	ds_write_b32 v253, v35 offset:18480
	ds_write_b32 v253, v36 offset:16960
	ds_write_b32 v253, v37 offset:17488
	ds_write_b32 v253, v38 offset:18016
	ds_write_b32 v253, v39 offset:18544
	ds_write_b32 v253, v40 offset:17024
	ds_write_b32 v253, v41 offset:17552
	ds_write_b32 v253, v42 offset:18080
	ds_write_b32 v253, v43 offset:18608
	ds_write_b32 v253, v44 offset:17088
	ds_write_b32 v253, v45 offset:17616
	ds_write_b32 v253, v46 offset:18144
	ds_write_b32 v253, v47 offset:18672
	ds_write_b32 v253, v48 offset:25344
	ds_write_b32 v253, v49 offset:25872
	ds_write_b32 v253, v50 offset:26400
	ds_write_b32 v253, v51 offset:26928
	ds_write_b32 v253, v52 offset:25408
	ds_write_b32 v253, v53 offset:25936
	ds_write_b32 v253, v54 offset:26464
	ds_write_b32 v253, v55 offset:26992
	ds_write_b32 v253, v56 offset:25472
	ds_write_b32 v253, v57 offset:26000
	ds_write_b32 v253, v58 offset:26528
	ds_write_b32 v253, v59 offset:27056
	ds_write_b32 v253, v60 offset:25536
	ds_write_b32 v253, v61 offset:26064
	ds_write_b32 v253, v62 offset:26592
	ds_write_b32 v253, v63 offset:27120
	ds_write_b32 v253, v64 offset:33792
	ds_write_b32 v253, v65 offset:34320
	ds_write_b32 v253, v66 offset:34848
	ds_write_b32 v253, v67 offset:35376
	ds_write_b32 v253, v68 offset:33856
	ds_write_b32 v253, v69 offset:34384
	ds_write_b32 v253, v70 offset:34912
	ds_write_b32 v253, v71 offset:35440
	ds_write_b32 v253, v72 offset:33920
	ds_write_b32 v253, v73 offset:34448
	ds_write_b32 v253, v74 offset:34976
	ds_write_b32 v253, v75 offset:35504
	ds_write_b32 v253, v76 offset:33984
	ds_write_b32 v253, v77 offset:34512
	ds_write_b32 v253, v78 offset:35040
	ds_write_b32 v253, v79 offset:35568
	ds_write_b32 v253, v80 offset:42240
	ds_write_b32 v253, v81 offset:42768
	ds_write_b32 v253, v82 offset:43296
	ds_write_b32 v253, v83 offset:43824
	ds_write_b32 v253, v84 offset:42304
	ds_write_b32 v253, v85 offset:42832
	ds_write_b32 v253, v86 offset:43360
	ds_write_b32 v253, v87 offset:43888
	ds_write_b32 v253, v88 offset:42368
	ds_write_b32 v253, v89 offset:42896
	ds_write_b32 v253, v90 offset:43424
	ds_write_b32 v253, v91 offset:43952
	ds_write_b32 v253, v92 offset:42432
	ds_write_b32 v253, v93 offset:42960
	ds_write_b32 v253, v94 offset:43488
	ds_write_b32 v253, v95 offset:44016
	ds_write_b32 v253, v96 offset:50688
	ds_write_b32 v253, v97 offset:51216
	ds_write_b32 v253, v98 offset:51744
	ds_write_b32 v253, v99 offset:52272
	ds_write_b32 v253, v100 offset:50752
	ds_write_b32 v253, v101 offset:51280
	ds_write_b32 v253, v102 offset:51808
	ds_write_b32 v253, v103 offset:52336
	ds_write_b32 v253, v104 offset:50816
	ds_write_b32 v253, v105 offset:51344
	ds_write_b32 v253, v106 offset:51872
	ds_write_b32 v253, v107 offset:52400
	ds_write_b32 v253, v108 offset:50880
	ds_write_b32 v253, v109 offset:51408
	ds_write_b32 v253, v110 offset:51936
	ds_write_b32 v253, v111 offset:52464
	ds_write_b32 v253, v112 offset:59136
	ds_write_b32 v253, v113 offset:59664
	ds_write_b32 v253, v114 offset:60192
	ds_write_b32 v253, v115 offset:60720
	ds_write_b32 v253, v116 offset:59200
	ds_write_b32 v253, v117 offset:59728
	ds_write_b32 v253, v118 offset:60256
	ds_write_b32 v253, v119 offset:60784
	ds_write_b32 v253, v120 offset:59264
	ds_write_b32 v253, v121 offset:59792
	ds_write_b32 v253, v122 offset:60320
	ds_write_b32 v253, v123 offset:60848
	ds_write_b32 v253, v124 offset:59328
	ds_write_b32 v253, v125 offset:59856
	ds_write_b32 v253, v126 offset:60384
	ds_write_b32 v253, v127 offset:60912
.LBB0_1187:
	s_or_b64 exec, exec, s[24:25]
	v_lshlrev_b32_e32 v133, 3, v130
	v_and_b32_e32 v193, 56, v133
	v_ashrrev_i32_e32 v206, 3, v130
	v_mul_lo_u32 v133, v206, s35
	v_lshlrev_b32_e32 v207, 2, v193
	v_add3_u32 v135, 0, v133, v207
	s_waitcnt lgkmcnt(0)
	s_barrier
	ds_read_b128 v[136:139], v135 offset:256
	ds_read_b128 v[194:197], v135
	ds_read_b128 v[198:201], v135 offset:16
	ds_read_b128 v[202:205], v135 offset:272
	v_add_u32_e32 v130, 0x100, v130
	v_ashrrev_i32_e32 v210, 3, v130
	s_lshl_b32 s4, s44, 1
	v_mul_lo_u32 v130, v210, s35
	s_add_u32 s4, s38, s4
	v_add3_u32 v133, 0, v130, v207
	s_waitcnt lgkmcnt(2)
	v_pk_mul_f32 v[136:137], v[194:195], v[136:137]
	v_pk_mul_f32 v[138:139], v[196:197], v[138:139]
	s_waitcnt lgkmcnt(0)
	v_pk_mul_f32 v[196:197], v[198:199], v[202:203]
	v_pk_mul_f32 v[198:199], v[200:201], v[204:205]
	v_ashrrev_i32_e32 v207, 31, v206
	s_addc_u32 s25, s39, 0
	s_lshl_b32 s24, s43, 7
	v_cvt_pk_bf16_f32 v194, v136, v137
	v_cvt_pk_bf16_f32 v196, v196, v197
	v_cvt_pk_bf16_f32 v197, v198, v199
	v_lshlrev_b64 v[136:137], 11, v[206:207]
	ds_read_b128 v[198:201], v133 offset:256
	ds_read_b128 v[202:205], v133
	ds_read_b128 v[206:209], v133 offset:16
	ds_read_b128 v[214:217], v133 offset:272
	s_add_u32 s24, s4, s24
	s_addc_u32 s25, s25, 0
	v_lshl_add_u64 v[136:137], s[24:25], 0, v[136:137]
	v_lshlrev_b32_e32 v130, 1, v193
	v_cvt_pk_bf16_f32 v195, v138, v139
	v_lshl_add_u64 v[136:137], v[136:137], 0, v[130:131]
	global_store_dwordx4 v[136:137], v[194:197], off
	s_waitcnt lgkmcnt(2)
	v_pk_mul_f32 v[138:139], v[202:203], v[198:199]
	s_waitcnt lgkmcnt(0)
	v_pk_mul_f32 v[198:199], v[206:207], v[214:215]
	v_pk_mul_f32 v[196:197], v[208:209], v[216:217]
	v_pk_mul_f32 v[194:195], v[204:205], v[200:201]
	v_cvt_pk_bf16_f32 v197, v196, v197
	v_cvt_pk_bf16_f32 v196, v198, v199
	ds_read_b128 v[198:201], v135 offset:34048
	ds_read_b128 v[202:205], v135 offset:33792
	ds_read_b128 v[206:209], v135 offset:33808
	ds_read_b128 v[214:217], v135 offset:34064
	v_ashrrev_i32_e32 v211, 31, v210
	v_cvt_pk_bf16_f32 v195, v194, v195
	v_cvt_pk_bf16_f32 v194, v138, v139
	v_lshlrev_b64 v[138:139], 11, v[210:211]
	v_lshl_add_u64 v[138:139], s[24:25], 0, v[138:139]
	v_lshl_add_u64 v[138:139], v[138:139], 0, v[130:131]
	global_store_dwordx4 v[138:139], v[194:197], off
	v_add_co_u32_e32 v210, vcc, s40, v136
	s_waitcnt lgkmcnt(2)
	v_pk_mul_f32 v[194:195], v[202:203], v[198:199]
	v_pk_mul_f32 v[196:197], v[204:205], v[200:201]
	s_waitcnt lgkmcnt(0)
	v_pk_mul_f32 v[198:199], v[206:207], v[214:215]
	v_pk_mul_f32 v[200:201], v[208:209], v[216:217]
	v_cvt_pk_bf16_f32 v194, v194, v195
	v_cvt_pk_bf16_f32 v195, v196, v197
	v_cvt_pk_bf16_f32 v196, v198, v199
	v_cvt_pk_bf16_f32 v197, v200, v201
	ds_read_b128 v[198:201], v133 offset:33792
	ds_read_b128 v[202:205], v133 offset:33808
	ds_read_b128 v[206:209], v133 offset:34048
	ds_read_b128 v[214:217], v133 offset:34064
	v_addc_co_u32_e32 v211, vcc, 0, v137, vcc
	global_store_dwordx4 v[210:211], v[194:197], off
	s_waitcnt lgkmcnt(1)
	v_pk_mul_f32 v[198:199], v[198:199], v[206:207]
	v_pk_mul_f32 v[194:195], v[200:201], v[208:209]
	s_waitcnt lgkmcnt(0)
	v_pk_mul_f32 v[200:201], v[202:203], v[214:215]
	v_pk_mul_f32 v[196:197], v[204:205], v[216:217]
	v_cvt_pk_bf16_f32 v195, v194, v195
	v_cvt_pk_bf16_f32 v194, v198, v199
	v_add_co_u32_e32 v198, vcc, 0x20000, v138
	v_cvt_pk_bf16_f32 v197, v196, v197
	v_cvt_pk_bf16_f32 v196, v200, v201
	v_addc_co_u32_e32 v199, vcc, 0, v139, vcc
	global_store_dwordx4 v[198:199], v[194:197], off
	s_barrier
	s_and_saveexec_b64 s[24:25], s[8:9]
	s_cbranch_execz .LBB0_1172
	v_and_b32_e32 v254, 63, v180
	v_lshrrev_b32_e32 v253, 4, v254
	v_mul_u32_u24_e32 v253, 0x840, v253
	v_and_b32_e32 v254, 15, v254
	v_lshl_add_u32 v253, v254, 2, v253
	v_and_b32_e32 v254, 64, v180
	v_lshl_add_u32 v253, v254, 2, v253
	ds_write_b32 v253, v0 offset:0
	ds_write_b32 v253, v1 offset:528
	ds_write_b32 v253, v2 offset:1056
	ds_write_b32 v253, v3 offset:1584
	ds_write_b32 v253, v4 offset:64
	ds_write_b32 v253, v5 offset:592
	ds_write_b32 v253, v6 offset:1120
	ds_write_b32 v253, v7 offset:1648
	ds_write_b32 v253, v8 offset:128
	ds_write_b32 v253, v9 offset:656
	ds_write_b32 v253, v10 offset:1184
	ds_write_b32 v253, v11 offset:1712
	ds_write_b32 v253, v12 offset:192
	ds_write_b32 v253, v13 offset:720
	ds_write_b32 v253, v14 offset:1248
	ds_write_b32 v253, v15 offset:1776
	ds_write_b32 v253, v16 offset:8448
	ds_write_b32 v253, v17 offset:8976
	ds_write_b32 v253, v18 offset:9504
	ds_write_b32 v253, v19 offset:10032
	ds_write_b32 v253, v20 offset:8512
	ds_write_b32 v253, v21 offset:9040
	ds_write_b32 v253, v22 offset:9568
	ds_write_b32 v253, v23 offset:10096
	ds_write_b32 v253, v24 offset:8576
	ds_write_b32 v253, v25 offset:9104
	ds_write_b32 v253, v26 offset:9632
	ds_write_b32 v253, v27 offset:10160
	ds_write_b32 v253, v28 offset:8640
	ds_write_b32 v253, v29 offset:9168
	ds_write_b32 v253, v30 offset:9696
	ds_write_b32 v253, v31 offset:10224
	ds_write_b32 v253, v32 offset:16896
	ds_write_b32 v253, v33 offset:17424
	ds_write_b32 v253, v34 offset:17952
	ds_write_b32 v253, v35 offset:18480
	ds_write_b32 v253, v36 offset:16960
	ds_write_b32 v253, v37 offset:17488
	ds_write_b32 v253, v38 offset:18016
	ds_write_b32 v253, v39 offset:18544
	ds_write_b32 v253, v40 offset:17024
	ds_write_b32 v253, v41 offset:17552
	ds_write_b32 v253, v42 offset:18080
	ds_write_b32 v253, v43 offset:18608
	ds_write_b32 v253, v44 offset:17088
	ds_write_b32 v253, v45 offset:17616
	ds_write_b32 v253, v46 offset:18144
	ds_write_b32 v253, v47 offset:18672
	ds_write_b32 v253, v48 offset:25344
	ds_write_b32 v253, v49 offset:25872
	ds_write_b32 v253, v50 offset:26400
	ds_write_b32 v253, v51 offset:26928
	ds_write_b32 v253, v52 offset:25408
	ds_write_b32 v253, v53 offset:25936
	ds_write_b32 v253, v54 offset:26464
	ds_write_b32 v253, v55 offset:26992
	ds_write_b32 v253, v56 offset:25472
	ds_write_b32 v253, v57 offset:26000
	ds_write_b32 v253, v58 offset:26528
	ds_write_b32 v253, v59 offset:27056
	ds_write_b32 v253, v60 offset:25536
	ds_write_b32 v253, v61 offset:26064
	ds_write_b32 v253, v62 offset:26592
	ds_write_b32 v253, v63 offset:27120
	ds_write_b32 v253, v64 offset:33792
	ds_write_b32 v253, v65 offset:34320
	ds_write_b32 v253, v66 offset:34848
	ds_write_b32 v253, v67 offset:35376
	ds_write_b32 v253, v68 offset:33856
	ds_write_b32 v253, v69 offset:34384
	ds_write_b32 v253, v70 offset:34912
	ds_write_b32 v253, v71 offset:35440
	ds_write_b32 v253, v72 offset:33920
	ds_write_b32 v253, v73 offset:34448
	ds_write_b32 v253, v74 offset:34976
	ds_write_b32 v253, v75 offset:35504
	ds_write_b32 v253, v76 offset:33984
	ds_write_b32 v253, v77 offset:34512
	ds_write_b32 v253, v78 offset:35040
	ds_write_b32 v253, v79 offset:35568
	ds_write_b32 v253, v80 offset:42240
	ds_write_b32 v253, v81 offset:42768
	ds_write_b32 v253, v82 offset:43296
	ds_write_b32 v253, v83 offset:43824
	ds_write_b32 v253, v84 offset:42304
	ds_write_b32 v253, v85 offset:42832
	ds_write_b32 v253, v86 offset:43360
	ds_write_b32 v253, v87 offset:43888
	ds_write_b32 v253, v88 offset:42368
	ds_write_b32 v253, v89 offset:42896
	ds_write_b32 v253, v90 offset:43424
	ds_write_b32 v253, v91 offset:43952
	ds_write_b32 v253, v92 offset:42432
	ds_write_b32 v253, v93 offset:42960
	ds_write_b32 v253, v94 offset:43488
	ds_write_b32 v253, v95 offset:44016
	ds_write_b32 v253, v96 offset:50688
	ds_write_b32 v253, v97 offset:51216
	ds_write_b32 v253, v98 offset:51744
	ds_write_b32 v253, v99 offset:52272
	ds_write_b32 v253, v100 offset:50752
	ds_write_b32 v253, v101 offset:51280
	ds_write_b32 v253, v102 offset:51808
	ds_write_b32 v253, v103 offset:52336
	ds_write_b32 v253, v104 offset:50816
	ds_write_b32 v253, v105 offset:51344
	ds_write_b32 v253, v106 offset:51872
	ds_write_b32 v253, v107 offset:52400
	ds_write_b32 v253, v108 offset:50880
	ds_write_b32 v253, v109 offset:51408
	ds_write_b32 v253, v110 offset:51936
	ds_write_b32 v253, v111 offset:52464
	ds_write_b32 v253, v112 offset:59136
	ds_write_b32 v253, v113 offset:59664
	ds_write_b32 v253, v114 offset:60192
	ds_write_b32 v253, v115 offset:60720
	ds_write_b32 v253, v116 offset:59200
	ds_write_b32 v253, v117 offset:59728
	ds_write_b32 v253, v118 offset:60256
	ds_write_b32 v253, v119 offset:60784
	ds_write_b32 v253, v120 offset:59264
	ds_write_b32 v253, v121 offset:59792
	ds_write_b32 v253, v122 offset:60320
	ds_write_b32 v253, v123 offset:60848
	ds_write_b32 v253, v124 offset:59328
	ds_write_b32 v253, v125 offset:59856
	ds_write_b32 v253, v126 offset:60384
	ds_write_b32 v253, v127 offset:60912
	s_branch .LBB0_1172

.LBB0_1315:
	s_lshr_b32 s4, s23, 3
	s_or_b32 s4, s4, s24
	s_lshl_b32 s30, s4, 18
	s_and_b32 s29, s23, 7
	v_or_b32_e32 v1, s30, v129
	s_lshl_b32 s4, s29, 18
	s_add_u32 s16, s18, s4
	v_or_b32_e32 v0, v1, v128
	v_readfirstlane_b32 s4, v148
	v_lshlrev_b32_e32 v130, 1, v0
	s_mov_b32 m0, s4
	v_readfirstlane_b32 s4, v157
	v_add_lshl_u32 v0, v1, v154, 1
	s_waitcnt vmcnt(0)
	s_barrier
	s_nop 0
	s_mov_b32 m0, s4
	v_readfirstlane_b32 s4, v158
	s_addc_u32 s17, s19, 0
	v_add_lshl_u32 v2, v1, v155, 1
	s_nop 0
	s_mov_b32 m0, s4
	v_readfirstlane_b32 s4, v159
	v_add_lshl_u32 v4, v1, v156, 1
	v_lshl_add_u64 v[6:7], s[16:17], 0, v[132:133]
	s_nop 0
	s_mov_b32 m0, s4
	v_readfirstlane_b32 s4, v160
	v_lshl_add_u64 v[136:137], v[6:7], 0, v[134:135]
	s_nop 0
	s_mov_b32 m0, s4
	v_readfirstlane_b32 s4, v161
	v_lshl_add_u64 v[138:139], s[2:3], 0, v[130:131]
	v_mov_b32_e32 v1, v131
	v_lshl_add_u64 v[146:147], v[136:137], 0, s[10:11]
	s_nop 0
	s_mov_b32 m0, s4
	v_readfirstlane_b32 s4, v162
	v_lshl_add_u64 v[140:141], s[2:3], 0, v[0:1]
	v_mov_b32_e32 v3, v131
	s_nop 0
	v_lshl_add_u64 v[0:1], v[138:139], 0, 64
	s_mov_b32 m0, s4
	v_readfirstlane_b32 s4, v163
	v_lshl_add_u64 v[142:143], s[2:3], 0, v[2:3]
	v_mov_b32_e32 v5, v131
	s_nop 0
	v_lshl_add_u64 v[0:1], v[140:141], 0, 64
	s_mov_b32 m0, s4
	v_readfirstlane_b32 s4, v164
	v_lshl_add_u64 v[144:145], s[2:3], 0, v[4:5]
	s_nop 0
	v_lshl_add_u64 v[0:1], v[142:143], 0, 64
	s_mov_b32 m0, s4
	v_readfirstlane_b32 s4, v165
	s_nop 0
	v_lshl_add_u64 v[0:1], v[144:145], 0, 64
	s_mov_b32 m0, s4
	v_readfirstlane_b32 s4, v166
	s_nop 0
	v_lshl_add_u64 v[0:1], v[136:137], 0, 64
	s_mov_b32 m0, s4
	v_readfirstlane_b32 s4, v167
	s_nop 0
	v_lshl_add_u64 v[0:1], v[136:137], 0, s[12:13]
	s_mov_b32 m0, s4
	s_mov_b32 s16, s5
	s_nop 0
	s_mov_b32 s17, 2
	s_mov_b32 s31, s5
	v_mov_b32_e32 v0, 0
	v_mov_b32_e32 v1, v131
	v_mov_b32_e32 v2, v131
	v_mov_b32_e32 v4, v131
	v_mov_b32_e32 v6, v131
	v_mov_b32_e32 v7, v131
	v_mov_b32_e32 v8, v131
	v_mov_b32_e32 v9, v131
	v_mov_b32_e32 v10, v131
	v_mov_b32_e32 v11, v131
	v_mov_b32_e32 v12, v131
	v_mov_b32_e32 v13, v131
	v_mov_b32_e32 v14, v131
	v_mov_b32_e32 v15, v131
	v_mov_b32_e32 v16, 0
	v_mov_b32_e32 v17, v131
	v_mov_b32_e32 v18, v131
	v_mov_b32_e32 v19, v131
	v_mov_b32_e32 v20, v131
	v_mov_b32_e32 v21, v131
	v_mov_b32_e32 v22, v131
	v_mov_b32_e32 v23, v131
	v_mov_b32_e32 v24, v131
	v_mov_b32_e32 v25, v131
	v_mov_b32_e32 v26, v131
	v_mov_b32_e32 v27, v131
	v_mov_b32_e32 v28, v131
	v_mov_b32_e32 v29, v131
	v_mov_b32_e32 v30, v131
	v_mov_b32_e32 v31, v131
	v_mov_b32_e32 v32, 0
	v_mov_b32_e32 v33, v131
	v_mov_b32_e32 v34, v131
	v_mov_b32_e32 v35, v131
	v_mov_b32_e32 v36, v131
	v_mov_b32_e32 v37, v131
	v_mov_b32_e32 v38, v131
	v_mov_b32_e32 v39, v131
	v_mov_b32_e32 v40, v131
	v_mov_b32_e32 v41, v131
	v_mov_b32_e32 v42, v131
	v_mov_b32_e32 v43, v131
	v_mov_b32_e32 v44, v131
	v_mov_b32_e32 v45, v131
	v_mov_b32_e32 v46, v131
	v_mov_b32_e32 v47, v131
	v_mov_b32_e32 v48, 0
	v_mov_b32_e32 v49, v131
	v_mov_b32_e32 v50, v131
	v_mov_b32_e32 v51, v131
	v_mov_b32_e32 v52, v131
	v_mov_b32_e32 v53, v131
	v_mov_b32_e32 v54, v131
	v_mov_b32_e32 v55, v131
	v_mov_b32_e32 v56, v131
	v_mov_b32_e32 v57, v131
	v_mov_b32_e32 v58, v131
	v_mov_b32_e32 v59, v131
	v_mov_b32_e32 v60, v131
	v_mov_b32_e32 v61, v131
	v_mov_b32_e32 v62, v131
	v_mov_b32_e32 v63, v131
	v_mov_b32_e32 v64, 0
	v_mov_b32_e32 v65, v131
	v_mov_b32_e32 v66, v131
	v_mov_b32_e32 v67, v131
	v_mov_b32_e32 v68, v131
	v_mov_b32_e32 v69, v131
	v_mov_b32_e32 v70, v131
	v_mov_b32_e32 v71, v131
	v_mov_b32_e32 v72, v131
	v_mov_b32_e32 v73, v131
	v_mov_b32_e32 v74, v131
	v_mov_b32_e32 v75, v131
	v_mov_b32_e32 v76, v131
	v_mov_b32_e32 v77, v131
	v_mov_b32_e32 v78, v131
	v_mov_b32_e32 v79, v131
	v_mov_b32_e32 v80, 0
	v_mov_b32_e32 v81, v131
	v_mov_b32_e32 v82, v131
	v_mov_b32_e32 v83, v131
	v_mov_b32_e32 v84, v131
	v_mov_b32_e32 v85, v131
	v_mov_b32_e32 v86, v131
	v_mov_b32_e32 v87, v131
	v_mov_b32_e32 v88, v131
	v_mov_b32_e32 v89, v131
	v_mov_b32_e32 v90, v131
	v_mov_b32_e32 v91, v131
	v_mov_b32_e32 v92, v131
	v_mov_b32_e32 v93, v131
	v_mov_b32_e32 v94, v131
	v_mov_b32_e32 v95, v131
	v_mov_b32_e32 v96, 0
	v_mov_b32_e32 v97, v131
	v_mov_b32_e32 v98, v131
	v_mov_b32_e32 v99, v131
	v_mov_b32_e32 v100, v131
	v_mov_b32_e32 v101, v131
	v_mov_b32_e32 v102, v131
	v_mov_b32_e32 v103, v131
	v_mov_b32_e32 v104, v131
	v_mov_b32_e32 v105, v131
	v_mov_b32_e32 v106, v131
	v_mov_b32_e32 v107, v131
	v_mov_b32_e32 v108, v131
	v_mov_b32_e32 v109, v131
	v_mov_b32_e32 v110, v131
	v_mov_b32_e32 v111, v131
	v_mov_b32_e32 v112, 0
	v_mov_b32_e32 v113, v131
	v_mov_b32_e32 v114, v131
	v_mov_b32_e32 v115, v131
	v_mov_b32_e32 v116, v131
	v_mov_b32_e32 v117, v131
	v_mov_b32_e32 v118, v131
	v_mov_b32_e32 v119, v131
	v_mov_b32_e32 v120, v131
	v_mov_b32_e32 v121, v131
	v_mov_b32_e32 v122, v131
	v_mov_b32_e32 v123, v131
	v_mov_b32_e32 v124, v131
	v_mov_b32_e32 v125, v131
	v_mov_b32_e32 v126, v131
	v_mov_b32_e32 v127, v131
	s_mov_b64 s[54:55], 0x80
	v_lshrrev_b32_e32 v174, 6, v180
	v_lshlrev_b32_e32 v184, 11, v174
	v_and_b32_e32 v170, 63, v180
	v_readfirstlane_b32 s53, v184
	v_lshrrev_b32_e32 v171, 4, v170
	v_bfe_u32 v172, v170, 1, 3
	v_xor_b32_e32 v172, v171, v172
	v_and_b32_e32 v173, 31, v170
	v_lshlrev_b32_e32 v173, 7, v173
	v_lshrrev_b32_e32 v173, 3, v170
	v_lshlrev_b32_e32 v184, 4, v173
	v_add_u32_e32 v185, 0x80, v184
	v_and_b32_e32 v173, 7, v170
	v_lshrrev_b32_e32 v171, 4, v170
	v_xor_b32_e32 v171, v173, v171
	v_lshrrev_b32_e32 v173, 5, v170
	v_sub_u32_e32 v190, v171, v173
	v_xor_b32_e32 v171, 4, v171
	v_add_u32_e32 v173, 2, v173
	v_sub_u32_e32 v192, v171, v173
	v_lshlrev_b32_e32 v190, 4, v190
	v_ashrrev_i32_e32 v191, 31, v190
	v_lshlrev_b32_e32 v192, 4, v192
	v_ashrrev_i32_e32 v193, 31, v192
	ds_bpermute_b32 v242, v184, v136
	ds_bpermute_b32 v243, v184, v137
	ds_bpermute_b32 v244, v185, v136
	ds_bpermute_b32 v245, v185, v137
	ds_bpermute_b32 v246, v184, v146
	ds_bpermute_b32 v247, v184, v147
	ds_bpermute_b32 v248, v185, v146
	ds_bpermute_b32 v249, v185, v147
	s_waitcnt lgkmcnt(0)
	ds_bpermute_b32 v178, v184, v138
	ds_bpermute_b32 v179, v184, v139
	ds_bpermute_b32 v186, v185, v138
	ds_bpermute_b32 v187, v185, v139
	ds_bpermute_b32 v234, v184, v140
	ds_bpermute_b32 v235, v184, v141
	ds_bpermute_b32 v236, v185, v140
	ds_bpermute_b32 v237, v185, v141
	ds_bpermute_b32 v238, v184, v142
	ds_bpermute_b32 v239, v184, v143
	ds_bpermute_b32 v240, v185, v142
	ds_bpermute_b32 v241, v185, v143
	ds_bpermute_b32 v136, v184, v144
	ds_bpermute_b32 v137, v184, v145
	ds_bpermute_b32 v146, v185, v144
	ds_bpermute_b32 v147, v185, v145
	s_waitcnt lgkmcnt(0)
	v_and_b32_e32 v173, 15, v170
	v_lshlrev_b32_e32 v173, 7, v173
	v_lshrrev_b32_e32 v171, 1, v174
	v_lshl_add_u32 v138, v171, 14, v173
	v_and_b32_e32 v171, 1, v174
	v_lshl_add_u32 v142, v171, 13, v173
	v_add_u32_e32 v142, 0x10000, v142
	v_xor_b32_e32 v173, 4, v172
	v_lshl_add_u32 v139, v173, 4, v138
	v_lshl_add_u32 v143, v173, 4, v142
	v_xor_b32_e32 v173, 0, v172
	v_lshl_add_u32 v138, v173, 4, v138
	v_lshl_add_u32 v142, v173, 4, v142
	v_lshl_add_u64 v[178:179], v[178:179], 0, v[190:191]
	v_lshl_add_u64 v[186:187], v[186:187], 0, v[192:193]
	v_lshl_add_u64 v[234:235], v[234:235], 0, v[190:191]
	v_lshl_add_u64 v[236:237], v[236:237], 0, v[192:193]
	v_lshl_add_u64 v[238:239], v[238:239], 0, v[190:191]
	v_lshl_add_u64 v[240:241], v[240:241], 0, v[192:193]
	v_lshl_add_u64 v[136:137], v[136:137], 0, v[190:191]
	v_lshl_add_u64 v[146:147], v[146:147], 0, v[192:193]
	v_lshl_add_u64 v[242:243], v[242:243], 0, v[190:191]
	v_lshl_add_u64 v[244:245], v[244:245], 0, v[192:193]
	v_lshl_add_u64 v[246:247], v[246:247], 0, v[190:191]
	v_lshl_add_u64 v[248:249], v[248:249], 0, v[192:193]
	s_mov_b32 s58, s53
	s_add_i32 m0, s58, 0x0
	s_nop 0
	global_load_lds_dwordx4 v[178:179], off
	s_add_i32 m0, s58, 0x400
	v_lshl_add_u64 v[178:179], v[178:179], 0, s[54:55]
	global_load_lds_dwordx4 v[186:187], off
	s_add_i32 m0, s58, 0x2000
	v_lshl_add_u64 v[186:187], v[186:187], 0, s[54:55]
	global_load_lds_dwordx4 v[234:235], off
	s_add_i32 m0, s58, 0x2400
	v_lshl_add_u64 v[234:235], v[234:235], 0, s[54:55]
	global_load_lds_dwordx4 v[236:237], off
	s_add_i32 m0, s58, 0x4000
	v_lshl_add_u64 v[236:237], v[236:237], 0, s[54:55]
	global_load_lds_dwordx4 v[238:239], off
	s_add_i32 m0, s58, 0x4400
	v_lshl_add_u64 v[238:239], v[238:239], 0, s[54:55]
	global_load_lds_dwordx4 v[240:241], off
	s_add_i32 m0, s58, 0x6000
	v_lshl_add_u64 v[240:241], v[240:241], 0, s[54:55]
	global_load_lds_dwordx4 v[136:137], off
	s_add_i32 m0, s58, 0x6400
	v_lshl_add_u64 v[136:137], v[136:137], 0, s[54:55]
	global_load_lds_dwordx4 v[146:147], off
	v_lshl_add_u64 v[146:147], v[146:147], 0, s[54:55]
	s_add_i32 s58, s53, 0x10000
	s_add_i32 m0, s58, 0x0
	s_nop 0
	global_load_lds_dwordx4 v[242:243], off
	s_add_i32 m0, s58, 0x400
	v_lshl_add_u64 v[242:243], v[242:243], 0, s[54:55]
	global_load_lds_dwordx4 v[244:245], off
	s_add_i32 m0, s58, 0x2000
	v_lshl_add_u64 v[244:245], v[244:245], 0, s[54:55]
	global_load_lds_dwordx4 v[246:247], off
	s_add_i32 m0, s58, 0x2400
	v_lshl_add_u64 v[246:247], v[246:247], 0, s[54:55]
	global_load_lds_dwordx4 v[248:249], off
	v_lshl_add_u64 v[248:249], v[248:249], 0, s[54:55]
	s_mov_b32 s16, 0
	s_mov_b32 s17, 0

.Lg_ph13_noA:
	ds_read_b128 v[194:197], v142
	ds_read_b128 v[198:201], v142 offset:2048
	ds_read_b128 v[202:205], v142 offset:4096
	ds_read_b128 v[206:209], v142 offset:6144
	ds_read_b128 v[214:217], v143
	ds_read_b128 v[222:225], v143 offset:2048
	ds_read_b128 v[226:229], v143 offset:4096
	ds_read_b128 v[230:233], v143 offset:6144
	ds_read_b128 v[170:173], v138
	ds_read_b128 v[174:177], v138 offset:2048
	ds_read_b128 v[182:185], v138 offset:4096
	ds_read_b128 v[190:193], v138 offset:6144
	s_waitcnt lgkmcnt(4)
	s_barrier
	s_cmp_eq_u32 s16, 15
	s_cbranch_scc1 .Lg_ph13_noB
	s_add_i32 s58, s53, 0x10000
	s_add_i32 m0, s58, 0x0
	s_nop 0
	global_load_lds_dwordx4 v[242:243], off
	s_add_i32 m0, s58, 0x400
	v_lshl_add_u64 v[242:243], v[242:243], 0, s[54:55]
	global_load_lds_dwordx4 v[244:245], off
	s_add_i32 m0, s58, 0x2000
	v_lshl_add_u64 v[244:245], v[244:245], 0, s[54:55]
	global_load_lds_dwordx4 v[246:247], off
	s_add_i32 m0, s58, 0x2400
	v_lshl_add_u64 v[246:247], v[246:247], 0, s[54:55]
	global_load_lds_dwordx4 v[248:249], off
	v_lshl_add_u64 v[248:249], v[248:249], 0, s[54:55]
.Lg_ph13_noB:
	s_waitcnt lgkmcnt(3)
	v_mfma_f32_16x16x32_bf16 v[0:3], v[170:173], v[194:197], v[0:3]
	v_mfma_f32_16x16x32_bf16 v[4:7], v[170:173], v[198:201], v[4:7]
	v_mfma_f32_16x16x32_bf16 v[8:11], v[170:173], v[202:205], v[8:11]
	v_mfma_f32_16x16x32_bf16 v[12:15], v[170:173], v[206:209], v[12:15]
	ds_read_b128 v[170:173], v138 offset:8192
	s_waitcnt lgkmcnt(3)
	v_mfma_f32_16x16x32_bf16 v[16:19], v[174:177], v[194:197], v[16:19]
	v_mfma_f32_16x16x32_bf16 v[20:23], v[174:177], v[198:201], v[20:23]
	v_mfma_f32_16x16x32_bf16 v[24:27], v[174:177], v[202:205], v[24:27]
	v_mfma_f32_16x16x32_bf16 v[28:31], v[174:177], v[206:209], v[28:31]
	ds_read_b128 v[174:177], v138 offset:10240
	s_waitcnt lgkmcnt(3)
	v_mfma_f32_16x16x32_bf16 v[32:35], v[182:185], v[194:197], v[32:35]
	v_mfma_f32_16x16x32_bf16 v[36:39], v[182:185], v[198:201], v[36:39]
	v_mfma_f32_16x16x32_bf16 v[40:43], v[182:185], v[202:205], v[40:43]
	v_mfma_f32_16x16x32_bf16 v[44:47], v[182:185], v[206:209], v[44:47]
	ds_read_b128 v[182:185], v138 offset:12288
	s_waitcnt lgkmcnt(3)
	v_mfma_f32_16x16x32_bf16 v[48:51], v[190:193], v[194:197], v[48:51]
	v_mfma_f32_16x16x32_bf16 v[52:55], v[190:193], v[198:201], v[52:55]
	v_mfma_f32_16x16x32_bf16 v[56:59], v[190:193], v[202:205], v[56:59]
	v_mfma_f32_16x16x32_bf16 v[60:63], v[190:193], v[206:209], v[60:63]
	ds_read_b128 v[190:193], v138 offset:14336
	s_waitcnt lgkmcnt(3)
	v_mfma_f32_16x16x32_bf16 v[64:67], v[170:173], v[194:197], v[64:67]
	v_mfma_f32_16x16x32_bf16 v[68:71], v[170:173], v[198:201], v[68:71]
	v_mfma_f32_16x16x32_bf16 v[72:75], v[170:173], v[202:205], v[72:75]
	v_mfma_f32_16x16x32_bf16 v[76:79], v[170:173], v[206:209], v[76:79]
	ds_read_b128 v[170:173], v139
	s_waitcnt lgkmcnt(3)
	v_mfma_f32_16x16x32_bf16 v[80:83], v[174:177], v[194:197], v[80:83]
	v_mfma_f32_16x16x32_bf16 v[84:87], v[174:177], v[198:201], v[84:87]
	v_mfma_f32_16x16x32_bf16 v[88:91], v[174:177], v[202:205], v[88:91]
	v_mfma_f32_16x16x32_bf16 v[92:95], v[174:177], v[206:209], v[92:95]
	ds_read_b128 v[174:177], v139 offset:2048
	s_waitcnt lgkmcnt(3)
	v_mfma_f32_16x16x32_bf16 v[96:99], v[182:185], v[194:197], v[96:99]
	v_mfma_f32_16x16x32_bf16 v[100:103], v[182:185], v[198:201], v[100:103]
	v_mfma_f32_16x16x32_bf16 v[104:107], v[182:185], v[202:205], v[104:107]
	v_mfma_f32_16x16x32_bf16 v[108:111], v[182:185], v[206:209], v[108:111]
	ds_read_b128 v[182:185], v139 offset:4096
	s_waitcnt lgkmcnt(3)
	v_mfma_f32_16x16x32_bf16 v[112:115], v[190:193], v[194:197], v[112:115]
	v_mfma_f32_16x16x32_bf16 v[116:119], v[190:193], v[198:201], v[116:119]
	v_mfma_f32_16x16x32_bf16 v[120:123], v[190:193], v[202:205], v[120:123]
	v_mfma_f32_16x16x32_bf16 v[124:127], v[190:193], v[206:209], v[124:127]
	ds_read_b128 v[190:193], v139 offset:6144
	s_waitcnt lgkmcnt(3)
	v_mfma_f32_16x16x32_bf16 v[0:3], v[170:173], v[214:217], v[0:3]
	v_mfma_f32_16x16x32_bf16 v[4:7], v[170:173], v[222:225], v[4:7]
	v_mfma_f32_16x16x32_bf16 v[8:11], v[170:173], v[226:229], v[8:11]
	v_mfma_f32_16x16x32_bf16 v[12:15], v[170:173], v[230:233], v[12:15]
	ds_read_b128 v[170:173], v139 offset:8192
	s_waitcnt lgkmcnt(3)
	v_mfma_f32_16x16x32_bf16 v[16:19], v[174:177], v[214:217], v[16:19]
	v_mfma_f32_16x16x32_bf16 v[20:23], v[174:177], v[222:225], v[20:23]
	v_mfma_f32_16x16x32_bf16 v[24:27], v[174:177], v[226:229], v[24:27]
	v_mfma_f32_16x16x32_bf16 v[28:31], v[174:177], v[230:233], v[28:31]
	ds_read_b128 v[174:177], v139 offset:10240
	s_waitcnt lgkmcnt(3)
	v_mfma_f32_16x16x32_bf16 v[32:35], v[182:185], v[214:217], v[32:35]
	v_mfma_f32_16x16x32_bf16 v[36:39], v[182:185], v[222:225], v[36:39]
	v_mfma_f32_16x16x32_bf16 v[40:43], v[182:185], v[226:229], v[40:43]
	v_mfma_f32_16x16x32_bf16 v[44:47], v[182:185], v[230:233], v[44:47]
	ds_read_b128 v[182:185], v139 offset:12288
	s_waitcnt lgkmcnt(3)
	v_mfma_f32_16x16x32_bf16 v[48:51], v[190:193], v[214:217], v[48:51]
	v_mfma_f32_16x16x32_bf16 v[52:55], v[190:193], v[222:225], v[52:55]
	v_mfma_f32_16x16x32_bf16 v[56:59], v[190:193], v[226:229], v[56:59]
	v_mfma_f32_16x16x32_bf16 v[60:63], v[190:193], v[230:233], v[60:63]
	ds_read_b128 v[190:193], v139 offset:14336
	s_waitcnt lgkmcnt(3)
	v_mfma_f32_16x16x32_bf16 v[64:67], v[170:173], v[214:217], v[64:67]
	v_mfma_f32_16x16x32_bf16 v[68:71], v[170:173], v[222:225], v[68:71]
	v_mfma_f32_16x16x32_bf16 v[72:75], v[170:173], v[226:229], v[72:75]
	v_mfma_f32_16x16x32_bf16 v[76:79], v[170:173], v[230:233], v[76:79]
	s_waitcnt lgkmcnt(2)
	v_mfma_f32_16x16x32_bf16 v[80:83], v[174:177], v[214:217], v[80:83]
	v_mfma_f32_16x16x32_bf16 v[84:87], v[174:177], v[222:225], v[84:87]
	v_mfma_f32_16x16x32_bf16 v[88:91], v[174:177], v[226:229], v[88:91]
	v_mfma_f32_16x16x32_bf16 v[92:95], v[174:177], v[230:233], v[92:95]
	s_waitcnt lgkmcnt(1)
	v_mfma_f32_16x16x32_bf16 v[96:99], v[182:185], v[214:217], v[96:99]
	v_mfma_f32_16x16x32_bf16 v[100:103], v[182:185], v[222:225], v[100:103]
	v_mfma_f32_16x16x32_bf16 v[104:107], v[182:185], v[226:229], v[104:107]
	v_mfma_f32_16x16x32_bf16 v[108:111], v[182:185], v[230:233], v[108:111]
	s_waitcnt lgkmcnt(0)
	v_mfma_f32_16x16x32_bf16 v[112:115], v[190:193], v[214:217], v[112:115]
	v_mfma_f32_16x16x32_bf16 v[116:119], v[190:193], v[222:225], v[116:119]
	v_mfma_f32_16x16x32_bf16 v[120:123], v[190:193], v[226:229], v[120:123]
	v_mfma_f32_16x16x32_bf16 v[124:127], v[190:193], v[230:233], v[124:127]
	v_xor_b32_e32 v138, 0x8000, v138
	v_xor_b32_e32 v139, 0x8000, v139
	s_xor_b32 s17, s17, 0x8000
	s_add_i32 s16, s16, 1
	s_cmp_eq_u32 s16, 16
	s_cbranch_scc0 .Lg_ph13_top
	s_waitcnt vmcnt(0)
	v_mov_b32_e32 v130, v180
	v_add_u32_e32 v202, 0x400, v153
	v_add_u32_e32 v201, 0x1000, v153
	v_add_u32_e32 v200, 0x1400, v153
	v_add_u32_e32 v199, 0x2000, v153
	v_add_u32_e32 v193, 0x2400, v153
	v_add_u32_e32 v194, 0x3000, v153
	v_add_u32_e32 v195, 0x3200, v153
	v_add_u32_e32 v196, 0x3400, v153
	v_add_u32_e32 v197, 0x3600, v153
	v_add_u32_e32 v198, 0x4000, v153
	v_add_u32_e32 v190, 0x4400, v153
	v_add_u32_e32 v191, 0x4800, v153
	v_add_u32_e32 v192, 0x5000, v153
	v_add_u32_e32 v186, 0x5400, v153
	v_add_u32_e32 v187, 0x5800, v153
	v_add_u32_e32 v189, 0x6000, v153
	v_add_u32_e32 v179, 0x6400, v153
	v_add_u32_e32 v181, 0x6800, v153
	v_add_u32_e32 v182, 0x7200, v153
	v_add_u32_e32 v183, 0x7400, v153
	v_add_u32_e32 v184, 0x7600, v153
	v_add_u32_e32 v185, 0x7800, v153
	v_add_u32_e32 v178, 0x8400, v153
	v_add_u32_e32 v177, 0x8800, v153
	v_add_u32_e32 v176, 0x9400, v153
	v_add_u32_e32 v175, 0x9800, v153
	v_add_u32_e32 v174, 0xa400, v153
	v_add_u32_e32 v147, 0xa800, v153
	v_add_u32_e32 v169, 0xb400, v153
	v_add_u32_e32 v170, 0xb600, v153
	v_add_u32_e32 v171, 0xb800, v153
	v_add_u32_e32 v172, 0xba00, v153
	s_waitcnt vmcnt(0)
	s_barrier
	s_and_saveexec_b64 s[16:17], s[6:7]
	s_cbranch_execz .LBB0_1319
	v_and_b32_e32 v254, 63, v180
	v_lshrrev_b32_e32 v253, 4, v254
	v_mul_u32_u24_e32 v253, 0x840, v253
	v_and_b32_e32 v254, 15, v254
	v_lshl_add_u32 v253, v254, 2, v253
	v_and_b32_e32 v254, 64, v180
	v_lshl_add_u32 v253, v254, 2, v253
	ds_write_b32 v253, v0 offset:0
	ds_write_b32 v253, v1 offset:528
	ds_write_b32 v253, v2 offset:1056
	ds_write_b32 v253, v3 offset:1584
	ds_write_b32 v253, v4 offset:64
	ds_write_b32 v253, v5 offset:592
	ds_write_b32 v253, v6 offset:1120
	ds_write_b32 v253, v7 offset:1648
	ds_write_b32 v253, v8 offset:128
	ds_write_b32 v253, v9 offset:656
	ds_write_b32 v253, v10 offset:1184
	ds_write_b32 v253, v11 offset:1712
	ds_write_b32 v253, v12 offset:192
	ds_write_b32 v253, v13 offset:720
	ds_write_b32 v253, v14 offset:1248
	ds_write_b32 v253, v15 offset:1776
	ds_write_b32 v253, v16 offset:8448
	ds_write_b32 v253, v17 offset:8976
	ds_write_b32 v253, v18 offset:9504
	ds_write_b32 v253, v19 offset:10032
	ds_write_b32 v253, v20 offset:8512
	ds_write_b32 v253, v21 offset:9040
	ds_write_b32 v253, v22 offset:9568
	ds_write_b32 v253, v23 offset:10096
	ds_write_b32 v253, v24 offset:8576
	ds_write_b32 v253, v25 offset:9104
	ds_write_b32 v253, v26 offset:9632
	ds_write_b32 v253, v27 offset:10160
	ds_write_b32 v253, v28 offset:8640
	ds_write_b32 v253, v29 offset:9168
	ds_write_b32 v253, v30 offset:9696
	ds_write_b32 v253, v31 offset:10224
	ds_write_b32 v253, v32 offset:16896
	ds_write_b32 v253, v33 offset:17424
	ds_write_b32 v253, v34 offset:17952
	ds_write_b32 v253, v35 offset:18480
	ds_write_b32 v253, v36 offset:16960
	ds_write_b32 v253, v37 offset:17488
	ds_write_b32 v253, v38 offset:18016
	ds_write_b32 v253, v39 offset:18544
	ds_write_b32 v253, v40 offset:17024
	ds_write_b32 v253, v41 offset:17552
	ds_write_b32 v253, v42 offset:18080
	ds_write_b32 v253, v43 offset:18608
	ds_write_b32 v253, v44 offset:17088
	ds_write_b32 v253, v45 offset:17616
	ds_write_b32 v253, v46 offset:18144
	ds_write_b32 v253, v47 offset:18672
	ds_write_b32 v253, v48 offset:25344
	ds_write_b32 v253, v49 offset:25872
	ds_write_b32 v253, v50 offset:26400
	ds_write_b32 v253, v51 offset:26928
	ds_write_b32 v253, v52 offset:25408
	ds_write_b32 v253, v53 offset:25936
	ds_write_b32 v253, v54 offset:26464
	ds_write_b32 v253, v55 offset:26992
	ds_write_b32 v253, v56 offset:25472
	ds_write_b32 v253, v57 offset:26000
	ds_write_b32 v253, v58 offset:26528
	ds_write_b32 v253, v59 offset:27056
	ds_write_b32 v253, v60 offset:25536
	ds_write_b32 v253, v61 offset:26064
	ds_write_b32 v253, v62 offset:26592
	ds_write_b32 v253, v63 offset:27120
	ds_write_b32 v253, v64 offset:33792
	ds_write_b32 v253, v65 offset:34320
	ds_write_b32 v253, v66 offset:34848
	ds_write_b32 v253, v67 offset:35376
	ds_write_b32 v253, v68 offset:33856
	ds_write_b32 v253, v69 offset:34384
	ds_write_b32 v253, v70 offset:34912
	ds_write_b32 v253, v71 offset:35440
	ds_write_b32 v253, v72 offset:33920
	ds_write_b32 v253, v73 offset:34448
	ds_write_b32 v253, v74 offset:34976
	ds_write_b32 v253, v75 offset:35504
	ds_write_b32 v253, v76 offset:33984
	ds_write_b32 v253, v77 offset:34512
	ds_write_b32 v253, v78 offset:35040
	ds_write_b32 v253, v79 offset:35568
	ds_write_b32 v253, v80 offset:42240
	ds_write_b32 v253, v81 offset:42768
	ds_write_b32 v253, v82 offset:43296
	ds_write_b32 v253, v83 offset:43824
	ds_write_b32 v253, v84 offset:42304
	ds_write_b32 v253, v85 offset:42832
	ds_write_b32 v253, v86 offset:43360
	ds_write_b32 v253, v87 offset:43888
	ds_write_b32 v253, v88 offset:42368
	ds_write_b32 v253, v89 offset:42896
	ds_write_b32 v253, v90 offset:43424
	ds_write_b32 v253, v91 offset:43952
	ds_write_b32 v253, v92 offset:42432
	ds_write_b32 v253, v93 offset:42960
	ds_write_b32 v253, v94 offset:43488
	ds_write_b32 v253, v95 offset:44016
	ds_write_b32 v253, v96 offset:50688
	ds_write_b32 v253, v97 offset:51216
	ds_write_b32 v253, v98 offset:51744
	ds_write_b32 v253, v99 offset:52272
	ds_write_b32 v253, v100 offset:50752
	ds_write_b32 v253, v101 offset:51280
	ds_write_b32 v253, v102 offset:51808
	ds_write_b32 v253, v103 offset:52336
	ds_write_b32 v253, v104 offset:50816
	ds_write_b32 v253, v105 offset:51344
	ds_write_b32 v253, v106 offset:51872
	ds_write_b32 v253, v107 offset:52400
	ds_write_b32 v253, v108 offset:50880
	ds_write_b32 v253, v109 offset:51408
	ds_write_b32 v253, v110 offset:51936
	ds_write_b32 v253, v111 offset:52464
	ds_write_b32 v253, v112 offset:59136
	ds_write_b32 v253, v113 offset:59664
	ds_write_b32 v253, v114 offset:60192
	ds_write_b32 v253, v115 offset:60720
	ds_write_b32 v253, v116 offset:59200
	ds_write_b32 v253, v117 offset:59728
	ds_write_b32 v253, v118 offset:60256
	ds_write_b32 v253, v119 offset:60784
	ds_write_b32 v253, v120 offset:59264
	ds_write_b32 v253, v121 offset:59792
	ds_write_b32 v253, v122 offset:60320
	ds_write_b32 v253, v123 offset:60848
	ds_write_b32 v253, v124 offset:59328
	ds_write_b32 v253, v125 offset:59856
	ds_write_b32 v253, v126 offset:60384
	ds_write_b32 v253, v127 offset:60912
.LBB0_1319:
	s_or_b64 exec, exec, s[16:17]
	v_lshlrev_b32_e32 v136, 3, v130
	v_and_b32_e32 v146, 0x78, v136
	v_ashrrev_i32_e32 v208, 4, v130
	v_add_u32_e32 v137, 0x100, v130
	v_lshl_add_u32 v173, v146, 2, 0
	v_mul_lo_u32 v136, v208, s25
	v_ashrrev_i32_e32 v214, 4, v137
	v_add_u32_e32 v137, 0x200, v130
	v_add_u32_e32 v144, v173, v136
	v_ashrrev_i32_e32 v218, 4, v137
	s_waitcnt lgkmcnt(0)
	s_barrier
	ds_read_b128 v[136:139], v144
	ds_read_b128 v[140:143], v144 offset:16
	s_lshl_b32 s4, s30, 1
	v_mul_lo_u32 v145, v214, s25
	s_add_u32 s4, s20, s4
	v_ashrrev_i32_e32 v209, 31, v208
	v_add_u32_e32 v145, v173, v145
	s_addc_u32 s17, s21, 0
	s_lshl_b32 s16, s29, 8
	s_waitcnt lgkmcnt(1)
	v_cvt_pk_bf16_f32 v204, v136, v137
	v_lshlrev_b64 v[136:137], 11, v[208:209]
	ds_read_b128 v[208:211], v145 offset:16
	s_add_u32 s16, s4, s16
	v_cvt_pk_bf16_f32 v205, v138, v139
	s_waitcnt lgkmcnt(1)
	v_cvt_pk_bf16_f32 v206, v140, v141
	ds_read_b128 v[138:141], v145
	s_addc_u32 s17, s17, 0
	v_add_u32_e32 v130, 0x300, v130
	v_mul_lo_u32 v203, v218, s25
	v_ashrrev_i32_e32 v220, 4, v130
	v_lshl_add_u64 v[136:137], s[16:17], 0, v[136:137]
	v_lshlrev_b32_e32 v130, 1, v146
	v_cvt_pk_bf16_f32 v207, v142, v143
	v_lshl_add_u64 v[136:137], v[136:137], 0, v[130:131]
	v_add_u32_e32 v146, v173, v203
	global_store_dwordx4 v[136:137], v[204:207], off
	v_ashrrev_i32_e32 v215, 31, v214
	v_mul_lo_u32 v213, v220, s25
	s_waitcnt lgkmcnt(1)
	v_cvt_pk_bf16_f32 v206, v208, v209
	v_cvt_pk_bf16_f32 v207, v210, v211
	ds_read_b128 v[208:211], v146 offset:16
	s_waitcnt lgkmcnt(1)
	v_cvt_pk_bf16_f32 v204, v138, v139
	v_lshlrev_b64 v[138:139], 11, v[214:215]
	v_cvt_pk_bf16_f32 v205, v140, v141
	ds_read_b128 v[140:143], v146
	v_lshl_add_u64 v[138:139], s[16:17], 0, v[138:139]
	v_lshl_add_u64 v[138:139], v[138:139], 0, v[130:131]
	global_store_dwordx4 v[138:139], v[204:207], off
	v_add_u32_e32 v173, v173, v213
	v_ashrrev_i32_e32 v219, 31, v218
	s_waitcnt lgkmcnt(1)
	v_cvt_pk_bf16_f32 v206, v208, v209
	v_cvt_pk_bf16_f32 v207, v210, v211
	ds_read_b128 v[208:211], v173
	ds_read_b128 v[214:217], v173 offset:16
	s_waitcnt lgkmcnt(2)
	v_cvt_pk_bf16_f32 v204, v140, v141
	v_lshlrev_b64 v[140:141], 11, v[218:219]
	v_lshl_add_u64 v[140:141], s[16:17], 0, v[140:141]
	v_cvt_pk_bf16_f32 v205, v142, v143
	v_lshl_add_u64 v[140:141], v[140:141], 0, v[130:131]
	global_store_dwordx4 v[140:141], v[204:207], off
	v_ashrrev_i32_e32 v221, 31, v220
	v_lshlrev_b64 v[142:143], 11, v[220:221]
	s_waitcnt lgkmcnt(0)
	v_cvt_pk_bf16_f32 v207, v216, v217
	v_cvt_pk_bf16_f32 v206, v214, v215
	v_cvt_pk_bf16_f32 v205, v210, v211
	v_cvt_pk_bf16_f32 v204, v208, v209
	ds_read_b128 v[208:211], v144 offset:33792
	ds_read_b128 v[214:217], v144 offset:33808
	v_lshl_add_u64 v[142:143], s[16:17], 0, v[142:143]
	v_lshl_add_u64 v[142:143], v[142:143], 0, v[130:131]
	global_store_dwordx4 v[142:143], v[204:207], off
	v_add_co_u32_e32 v218, vcc, s26, v136
	s_waitcnt lgkmcnt(1)
	v_cvt_pk_bf16_f32 v204, v208, v209
	v_cvt_pk_bf16_f32 v205, v210, v211
	s_waitcnt lgkmcnt(0)
	v_cvt_pk_bf16_f32 v206, v214, v215
	v_cvt_pk_bf16_f32 v207, v216, v217
	ds_read_b128 v[208:211], v145 offset:33792
	ds_read_b128 v[214:217], v145 offset:33808
	v_addc_co_u32_e32 v219, vcc, 0, v137, vcc
	global_store_dwordx4 v[218:219], v[204:207], off
	v_add_co_u32_e32 v218, vcc, s26, v138
	s_waitcnt lgkmcnt(1)
	v_cvt_pk_bf16_f32 v204, v208, v209
	v_cvt_pk_bf16_f32 v205, v210, v211
	s_waitcnt lgkmcnt(0)
	v_cvt_pk_bf16_f32 v206, v214, v215
	v_cvt_pk_bf16_f32 v207, v216, v217
	ds_read_b128 v[208:211], v146 offset:33792
	ds_read_b128 v[214:217], v146 offset:33808
	v_addc_co_u32_e32 v219, vcc, 0, v139, vcc
	global_store_dwordx4 v[218:219], v[204:207], off
	v_add_co_u32_e32 v218, vcc, s26, v140
	s_waitcnt lgkmcnt(1)
	v_cvt_pk_bf16_f32 v204, v208, v209
	v_cvt_pk_bf16_f32 v205, v210, v211
	s_waitcnt lgkmcnt(0)
	v_cvt_pk_bf16_f32 v206, v214, v215
	v_cvt_pk_bf16_f32 v207, v216, v217
	ds_read_b128 v[208:211], v173 offset:33792
	ds_read_b128 v[214:217], v173 offset:33808
	v_addc_co_u32_e32 v219, vcc, 0, v141, vcc
	global_store_dwordx4 v[218:219], v[204:207], off
	s_waitcnt lgkmcnt(1)
	s_nop 0
	v_cvt_pk_bf16_f32 v204, v208, v209
	v_add_co_u32_e32 v208, vcc, 0x20000, v142
	s_waitcnt lgkmcnt(0)
	v_cvt_pk_bf16_f32 v207, v216, v217
	v_cvt_pk_bf16_f32 v206, v214, v215
	v_cvt_pk_bf16_f32 v205, v210, v211
	v_addc_co_u32_e32 v209, vcc, 0, v143, vcc
	global_store_dwordx4 v[208:209], v[204:207], off
	s_barrier
	s_and_saveexec_b64 s[16:17], s[8:9]
	s_cbranch_execz .LBB0_1314
	v_and_b32_e32 v254, 63, v180
	v_lshrrev_b32_e32 v253, 4, v254
	v_mul_u32_u24_e32 v253, 0x840, v253
	v_and_b32_e32 v254, 15, v254
	v_lshl_add_u32 v253, v254, 2, v253
	v_and_b32_e32 v254, 64, v180
	v_lshl_add_u32 v253, v254, 2, v253
	ds_write_b32 v253, v0 offset:0
	ds_write_b32 v253, v1 offset:528
	ds_write_b32 v253, v2 offset:1056
	ds_write_b32 v253, v3 offset:1584
	ds_write_b32 v253, v4 offset:64
	ds_write_b32 v253, v5 offset:592
	ds_write_b32 v253, v6 offset:1120
	ds_write_b32 v253, v7 offset:1648
	ds_write_b32 v253, v8 offset:128
	ds_write_b32 v253, v9 offset:656
	ds_write_b32 v253, v10 offset:1184
	ds_write_b32 v253, v11 offset:1712
	ds_write_b32 v253, v12 offset:192
	ds_write_b32 v253, v13 offset:720
	ds_write_b32 v253, v14 offset:1248
	ds_write_b32 v253, v15 offset:1776
	ds_write_b32 v253, v16 offset:8448
	ds_write_b32 v253, v17 offset:8976
	ds_write_b32 v253, v18 offset:9504
	ds_write_b32 v253, v19 offset:10032
	ds_write_b32 v253, v20 offset:8512
	ds_write_b32 v253, v21 offset:9040
	ds_write_b32 v253, v22 offset:9568
	ds_write_b32 v253, v23 offset:10096
	ds_write_b32 v253, v24 offset:8576
	ds_write_b32 v253, v25 offset:9104
	ds_write_b32 v253, v26 offset:9632
	ds_write_b32 v253, v27 offset:10160
	ds_write_b32 v253, v28 offset:8640
	ds_write_b32 v253, v29 offset:9168
	ds_write_b32 v253, v30 offset:9696
	ds_write_b32 v253, v31 offset:10224
	ds_write_b32 v253, v32 offset:16896
	ds_write_b32 v253, v33 offset:17424
	ds_write_b32 v253, v34 offset:17952
	ds_write_b32 v253, v35 offset:18480
	ds_write_b32 v253, v36 offset:16960
	ds_write_b32 v253, v37 offset:17488
	ds_write_b32 v253, v38 offset:18016
	ds_write_b32 v253, v39 offset:18544
	ds_write_b32 v253, v40 offset:17024
	ds_write_b32 v253, v41 offset:17552
	ds_write_b32 v253, v42 offset:18080
	ds_write_b32 v253, v43 offset:18608
	ds_write_b32 v253, v44 offset:17088
	ds_write_b32 v253, v45 offset:17616
	ds_write_b32 v253, v46 offset:18144
	ds_write_b32 v253, v47 offset:18672
	ds_write_b32 v253, v48 offset:25344
	ds_write_b32 v253, v49 offset:25872
	ds_write_b32 v253, v50 offset:26400
	ds_write_b32 v253, v51 offset:26928
	ds_write_b32 v253, v52 offset:25408
	ds_write_b32 v253, v53 offset:25936
	ds_write_b32 v253, v54 offset:26464
	ds_write_b32 v253, v55 offset:26992
	ds_write_b32 v253, v56 offset:25472
	ds_write_b32 v253, v57 offset:26000
	ds_write_b32 v253, v58 offset:26528
	ds_write_b32 v253, v59 offset:27056
	ds_write_b32 v253, v60 offset:25536
	ds_write_b32 v253, v61 offset:26064
	ds_write_b32 v253, v62 offset:26592
	ds_write_b32 v253, v63 offset:27120
	ds_write_b32 v253, v64 offset:33792
	ds_write_b32 v253, v65 offset:34320
	ds_write_b32 v253, v66 offset:34848
	ds_write_b32 v253, v67 offset:35376
	ds_write_b32 v253, v68 offset:33856
	ds_write_b32 v253, v69 offset:34384
	ds_write_b32 v253, v70 offset:34912
	ds_write_b32 v253, v71 offset:35440
	ds_write_b32 v253, v72 offset:33920
	ds_write_b32 v253, v73 offset:34448
	ds_write_b32 v253, v74 offset:34976
	ds_write_b32 v253, v75 offset:35504
	ds_write_b32 v253, v76 offset:33984
	ds_write_b32 v253, v77 offset:34512
	ds_write_b32 v253, v78 offset:35040
	ds_write_b32 v253, v79 offset:35568
	ds_write_b32 v253, v80 offset:42240
	ds_write_b32 v253, v81 offset:42768
	ds_write_b32 v253, v82 offset:43296
	ds_write_b32 v253, v83 offset:43824
	ds_write_b32 v253, v84 offset:42304
	ds_write_b32 v253, v85 offset:42832
	ds_write_b32 v253, v86 offset:43360
	ds_write_b32 v253, v87 offset:43888
	ds_write_b32 v253, v88 offset:42368
	ds_write_b32 v253, v89 offset:42896
	ds_write_b32 v253, v90 offset:43424
	ds_write_b32 v253, v91 offset:43952
	ds_write_b32 v253, v92 offset:42432
	ds_write_b32 v253, v93 offset:42960
	ds_write_b32 v253, v94 offset:43488
	ds_write_b32 v253, v95 offset:44016
	ds_write_b32 v253, v96 offset:50688
	ds_write_b32 v253, v97 offset:51216
	ds_write_b32 v253, v98 offset:51744
	ds_write_b32 v253, v99 offset:52272
	ds_write_b32 v253, v100 offset:50752
	ds_write_b32 v253, v101 offset:51280
	ds_write_b32 v253, v102 offset:51808
	ds_write_b32 v253, v103 offset:52336
	ds_write_b32 v253, v104 offset:50816
	ds_write_b32 v253, v105 offset:51344
	ds_write_b32 v253, v106 offset:51872
	ds_write_b32 v253, v107 offset:52400
	ds_write_b32 v253, v108 offset:50880
	ds_write_b32 v253, v109 offset:51408
	ds_write_b32 v253, v110 offset:51936
	ds_write_b32 v253, v111 offset:52464
	ds_write_b32 v253, v112 offset:59136
	ds_write_b32 v253, v113 offset:59664
	ds_write_b32 v253, v114 offset:60192
	ds_write_b32 v253, v115 offset:60720
	ds_write_b32 v253, v116 offset:59200
	ds_write_b32 v253, v117 offset:59728
	ds_write_b32 v253, v118 offset:60256
	ds_write_b32 v253, v119 offset:60784
	ds_write_b32 v253, v120 offset:59264
	ds_write_b32 v253, v121 offset:59792
	ds_write_b32 v253, v122 offset:60320
	ds_write_b32 v253, v123 offset:60848
	ds_write_b32 v253, v124 offset:59328
	ds_write_b32 v253, v125 offset:59856
	ds_write_b32 v253, v126 offset:60384
	ds_write_b32 v253, v127 offset:60912
	s_branch .LBB0_1314

.LBB0_1670:
	s_lshr_b32 s10, s19, 4
	s_and_b32 s10, s10, 12
	s_bfe_u32 s15, s19, 0x20001
	s_or_b32 s10, s10, s20
	s_lshl_b32 s14, s15, 4
	s_and_b32 s26, s19, 1
	s_or_b32 s27, s14, s10
	s_lshl_b32 s14, s27, 9
	s_lshl_b32 s28, s26, 8
	s_or_b32 s14, s14, s28
	v_or_b32_e32 v0, s14, v146
	v_lshlrev_b32_e32 v0, 2, v0
	global_load_dword v2, v0, s[2:3]
	global_load_dword v4, v0, s[2:3] offset:256
	global_load_dword v10, v0, s[2:3] offset:512
	global_load_dword v11, v0, s[2:3] offset:768
	s_lshl_b32 s15, s15, 22
	s_bfe_u32 s28, s19, 0x30003
	v_readfirstlane_b32 s29, v148
	v_readfirstlane_b32 s30, v154
	s_or_b32 s28, s28, s21
	s_mov_b32 m0, s29
	v_readfirstlane_b32 s31, v155
	s_lshl_b32 s43, s28, 17
	s_lshl_b32 s10, s10, 21
	s_waitcnt vmcnt(0)
	s_barrier
	v_readfirstlane_b32 s34, v156
	s_or_b32 s10, s10, s43
	v_readfirstlane_b32 s35, v157
	s_bitset1_b32 s10, 25
	v_readfirstlane_b32 s36, v158
	v_lshl_add_u64 v[134:135], v[130:131], 0, s[10:11]
	v_mov_b32_e32 v1, v129
	v_readfirstlane_b32 s37, v159
	v_lshl_add_u64 v[136:137], v[132:133], 0, s[10:11]
	v_mov_b32_e32 v3, v129
	v_readfirstlane_b32 s38, v160
	v_mov_b32_e32 v5, v129
	v_readfirstlane_b32 s39, v161
	v_readfirstlane_b32 s40, v162
	v_readfirstlane_b32 s41, v163
	v_readfirstlane_b32 s42, v164
	v_lshl_add_u64 v[6:7], v[134:135], 0, 64
	v_lshl_add_u64 v[8:9], v[136:137], 0, 64
	s_mov_b32 s14, s11
	s_mov_b32 s29, s11
	v_mov_b32_e32 v16, 0
	v_mov_b32_e32 v17, v129
	v_mov_b32_e32 v18, v129
	v_mov_b32_e32 v19, v129
	v_mov_b32_e32 v20, v129
	v_mov_b32_e32 v21, v129
	v_mov_b32_e32 v22, v129
	v_mov_b32_e32 v23, v129
	v_mov_b32_e32 v24, v129
	v_mov_b32_e32 v25, v129
	v_mov_b32_e32 v26, v129
	v_mov_b32_e32 v27, v129
	v_mov_b32_e32 v28, v129
	v_mov_b32_e32 v29, v129
	v_mov_b32_e32 v30, v129
	v_mov_b32_e32 v31, v129
	v_mov_b32_e32 v32, 0
	v_mov_b32_e32 v33, v129
	v_mov_b32_e32 v34, v129
	v_mov_b32_e32 v35, v129
	v_mov_b32_e32 v36, v129
	v_mov_b32_e32 v37, v129
	v_mov_b32_e32 v38, v129
	v_mov_b32_e32 v39, v129
	v_mov_b32_e32 v40, v129
	v_mov_b32_e32 v41, v129
	v_mov_b32_e32 v42, v129
	v_mov_b32_e32 v43, v129
	v_mov_b32_e32 v44, v129
	v_mov_b32_e32 v45, v129
	v_mov_b32_e32 v46, v129
	v_mov_b32_e32 v47, v129
	v_mov_b32_e32 v48, 0
	v_mov_b32_e32 v49, v129
	v_mov_b32_e32 v50, v129
	v_mov_b32_e32 v51, v129
	v_mov_b32_e32 v52, v129
	v_mov_b32_e32 v53, v129
	v_mov_b32_e32 v54, v129
	v_mov_b32_e32 v55, v129
	v_mov_b32_e32 v56, v129
	v_mov_b32_e32 v57, v129
	v_mov_b32_e32 v58, v129
	s_waitcnt vmcnt(3)
	v_lshl_add_u32 v0, v2, 10, s15
	s_waitcnt vmcnt(2)
	v_lshl_add_u32 v2, v4, 10, s15
	v_or_b32_e32 v0, v0, v147
	s_waitcnt vmcnt(1)
	v_lshl_add_u32 v4, v10, 10, s15
	v_or_b32_e32 v2, v2, v147
	v_lshlrev_b32_e32 v128, 1, v0
	s_waitcnt vmcnt(0)
	v_lshl_add_u32 v10, v11, 10, s15
	v_or_b32_e32 v4, v4, v147
	v_lshlrev_b32_e32 v0, 1, v2
	s_nop 0
	s_mov_b32 m0, s30
	v_or_b32_e32 v10, v10, v147
	v_lshlrev_b32_e32 v2, 1, v4
	s_nop 0
	s_mov_b32 m0, s31
	v_lshlrev_b32_e32 v4, 1, v10
	s_nop 0
	s_mov_b32 m0, s34
	v_lshl_add_u64 v[138:139], s[4:5], 0, v[128:129]
	s_nop 0
	s_mov_b32 m0, s35
	v_lshl_add_u64 v[140:141], s[4:5], 0, v[0:1]
	s_nop 0
	s_mov_b32 m0, s36
	v_lshl_add_u64 v[0:1], v[138:139], 0, 64
	s_nop 0
	s_mov_b32 m0, s37
	v_lshl_add_u64 v[142:143], s[4:5], 0, v[2:3]
	v_lshl_add_u64 v[10:11], v[140:141], 0, 64
	s_nop 0
	s_mov_b32 m0, s38
	v_lshl_add_u64 v[144:145], s[4:5], 0, v[4:5]
	v_lshl_add_u64 v[12:13], v[142:143], 0, 64
	s_nop 0
	s_mov_b32 m0, s39
	v_lshl_add_u64 v[14:15], v[144:145], 0, 64
	s_nop 0
	s_mov_b32 m0, s40
	s_mov_b32 s15, 2
	s_nop 0
	s_mov_b32 m0, s41
	v_mov_b32_e32 v0, 0
	s_nop 0
	s_mov_b32 m0, s42
	v_mov_b32_e32 v1, v129
	s_nop 0
	v_mov_b32_e32 v2, v129
	v_mov_b32_e32 v4, v129
	v_mov_b32_e32 v6, v129
	v_mov_b32_e32 v7, v129
	v_mov_b32_e32 v8, v129
	v_mov_b32_e32 v9, v129
	v_mov_b32_e32 v10, v129
	v_mov_b32_e32 v11, v129
	v_mov_b32_e32 v12, v129
	v_mov_b32_e32 v13, v129
	v_mov_b32_e32 v14, v129
	v_mov_b32_e32 v15, v129
	v_mov_b32_e32 v59, v129
	v_mov_b32_e32 v60, v129
	v_mov_b32_e32 v61, v129
	v_mov_b32_e32 v62, v129
	v_mov_b32_e32 v63, v129
	v_mov_b32_e32 v64, 0
	v_mov_b32_e32 v65, v129
	v_mov_b32_e32 v66, v129
	v_mov_b32_e32 v67, v129
	v_mov_b32_e32 v68, v129
	v_mov_b32_e32 v69, v129
	v_mov_b32_e32 v70, v129
	v_mov_b32_e32 v71, v129
	v_mov_b32_e32 v72, v129
	v_mov_b32_e32 v73, v129
	v_mov_b32_e32 v74, v129
	v_mov_b32_e32 v75, v129
	v_mov_b32_e32 v76, v129
	v_mov_b32_e32 v77, v129
	v_mov_b32_e32 v78, v129
	v_mov_b32_e32 v79, v129
	v_mov_b32_e32 v80, 0
	v_mov_b32_e32 v81, v129
	v_mov_b32_e32 v82, v129
	v_mov_b32_e32 v83, v129
	v_mov_b32_e32 v84, v129
	v_mov_b32_e32 v85, v129
	v_mov_b32_e32 v86, v129
	v_mov_b32_e32 v87, v129
	v_mov_b32_e32 v88, v129
	v_mov_b32_e32 v89, v129
	v_mov_b32_e32 v90, v129
	v_mov_b32_e32 v91, v129
	v_mov_b32_e32 v92, v129
	v_mov_b32_e32 v93, v129
	v_mov_b32_e32 v94, v129
	v_mov_b32_e32 v95, v129
	v_mov_b32_e32 v96, 0
	v_mov_b32_e32 v97, v129
	v_mov_b32_e32 v98, v129
	v_mov_b32_e32 v99, v129
	v_mov_b32_e32 v100, v129
	v_mov_b32_e32 v101, v129
	v_mov_b32_e32 v102, v129
	v_mov_b32_e32 v103, v129
	v_mov_b32_e32 v104, v129
	v_mov_b32_e32 v105, v129
	v_mov_b32_e32 v106, v129
	v_mov_b32_e32 v107, v129
	v_mov_b32_e32 v108, v129
	v_mov_b32_e32 v109, v129
	v_mov_b32_e32 v110, v129
	v_mov_b32_e32 v111, v129
	v_mov_b32_e32 v112, 0
	v_mov_b32_e32 v113, v129
	v_mov_b32_e32 v114, v129
	v_mov_b32_e32 v115, v129
	v_mov_b32_e32 v116, v129
	v_mov_b32_e32 v117, v129
	v_mov_b32_e32 v118, v129
	v_mov_b32_e32 v119, v129
	v_mov_b32_e32 v120, v129
	v_mov_b32_e32 v121, v129
	v_mov_b32_e32 v122, v129
	v_mov_b32_e32 v123, v129
	v_mov_b32_e32 v124, v129
	v_mov_b32_e32 v125, v129
	v_mov_b32_e32 v126, v129
	v_mov_b32_e32 v127, v129
	s_mov_b64 s[54:55], 0x80
	v_lshrrev_b32_e32 v170, 6, v180
	v_lshlrev_b32_e32 v176, 11, v170
	v_and_b32_e32 v166, 63, v180
	v_readfirstlane_b32 s53, v176
	v_lshrrev_b32_e32 v167, 4, v166
	v_bfe_u32 v168, v166, 1, 3
	v_xor_b32_e32 v168, v167, v168
	v_and_b32_e32 v169, 31, v166
	v_lshlrev_b32_e32 v169, 7, v169
	v_lshrrev_b32_e32 v169, 3, v166
	v_lshlrev_b32_e32 v176, 4, v169
	v_add_u32_e32 v177, 0x80, v176
	v_and_b32_e32 v169, 7, v166
	v_lshrrev_b32_e32 v167, 4, v166
	v_xor_b32_e32 v167, v169, v167
	v_lshrrev_b32_e32 v169, 5, v166
	v_sub_u32_e32 v182, v167, v169
	v_xor_b32_e32 v167, 4, v167
	v_add_u32_e32 v169, 2, v169
	v_sub_u32_e32 v184, v167, v169
	v_lshlrev_b32_e32 v182, 4, v182
	v_ashrrev_i32_e32 v183, 31, v182
	v_lshlrev_b32_e32 v184, 4, v184
	v_ashrrev_i32_e32 v185, 31, v184
	ds_bpermute_b32 v240, v176, v134
	ds_bpermute_b32 v241, v176, v135
	ds_bpermute_b32 v242, v177, v134
	ds_bpermute_b32 v243, v177, v135
	ds_bpermute_b32 v244, v176, v136
	ds_bpermute_b32 v245, v176, v137
	ds_bpermute_b32 v246, v177, v136
	ds_bpermute_b32 v247, v177, v137
	s_waitcnt lgkmcnt(0)
	ds_bpermute_b32 v178, v176, v138
	ds_bpermute_b32 v179, v176, v139
	ds_bpermute_b32 v230, v177, v138
	ds_bpermute_b32 v231, v177, v139
	ds_bpermute_b32 v232, v176, v140
	ds_bpermute_b32 v233, v176, v141
	ds_bpermute_b32 v234, v177, v140
	ds_bpermute_b32 v235, v177, v141
	ds_bpermute_b32 v236, v176, v142
	ds_bpermute_b32 v237, v176, v143
	ds_bpermute_b32 v238, v177, v142
	ds_bpermute_b32 v239, v177, v143
	ds_bpermute_b32 v134, v176, v144
	ds_bpermute_b32 v135, v176, v145
	ds_bpermute_b32 v136, v177, v144
	ds_bpermute_b32 v137, v177, v145
	s_waitcnt lgkmcnt(0)
	v_and_b32_e32 v169, 15, v166
	v_lshlrev_b32_e32 v169, 7, v169
	v_lshrrev_b32_e32 v167, 1, v170
	v_lshl_add_u32 v138, v167, 14, v169
	v_and_b32_e32 v167, 1, v170
	v_lshl_add_u32 v142, v167, 13, v169
	v_add_u32_e32 v142, 0x10000, v142
	v_xor_b32_e32 v169, 4, v168
	v_lshl_add_u32 v139, v169, 4, v138
	v_lshl_add_u32 v143, v169, 4, v142
	v_xor_b32_e32 v169, 0, v168
	v_lshl_add_u32 v138, v169, 4, v138
	v_lshl_add_u32 v142, v169, 4, v142
	v_lshl_add_u64 v[178:179], v[178:179], 0, v[182:183]
	v_lshl_add_u64 v[230:231], v[230:231], 0, v[184:185]
	v_lshl_add_u64 v[232:233], v[232:233], 0, v[182:183]
	v_lshl_add_u64 v[234:235], v[234:235], 0, v[184:185]
	v_lshl_add_u64 v[236:237], v[236:237], 0, v[182:183]
	v_lshl_add_u64 v[238:239], v[238:239], 0, v[184:185]
	v_lshl_add_u64 v[134:135], v[134:135], 0, v[182:183]
	v_lshl_add_u64 v[136:137], v[136:137], 0, v[184:185]
	v_lshl_add_u64 v[240:241], v[240:241], 0, v[182:183]
	v_lshl_add_u64 v[242:243], v[242:243], 0, v[184:185]
	v_lshl_add_u64 v[244:245], v[244:245], 0, v[182:183]
	v_lshl_add_u64 v[246:247], v[246:247], 0, v[184:185]
	s_mov_b32 s58, s53
	s_add_i32 m0, s58, 0x0
	s_nop 0
	global_load_lds_dwordx4 v[178:179], off
	s_add_i32 m0, s58, 0x400
	v_lshl_add_u64 v[178:179], v[178:179], 0, s[54:55]
	global_load_lds_dwordx4 v[230:231], off
	s_add_i32 m0, s58, 0x2000
	v_lshl_add_u64 v[230:231], v[230:231], 0, s[54:55]
	global_load_lds_dwordx4 v[232:233], off
	s_add_i32 m0, s58, 0x2400
	v_lshl_add_u64 v[232:233], v[232:233], 0, s[54:55]
	global_load_lds_dwordx4 v[234:235], off
	s_add_i32 m0, s58, 0x4000
	v_lshl_add_u64 v[234:235], v[234:235], 0, s[54:55]
	global_load_lds_dwordx4 v[236:237], off
	s_add_i32 m0, s58, 0x4400
	v_lshl_add_u64 v[236:237], v[236:237], 0, s[54:55]
	global_load_lds_dwordx4 v[238:239], off
	s_add_i32 m0, s58, 0x6000
	v_lshl_add_u64 v[238:239], v[238:239], 0, s[54:55]
	global_load_lds_dwordx4 v[134:135], off
	s_add_i32 m0, s58, 0x6400
	v_lshl_add_u64 v[134:135], v[134:135], 0, s[54:55]
	global_load_lds_dwordx4 v[136:137], off
	v_lshl_add_u64 v[136:137], v[136:137], 0, s[54:55]
	s_add_i32 s58, s53, 0x10000
	s_add_i32 m0, s58, 0x0
	s_nop 0
	global_load_lds_dwordx4 v[240:241], off
	s_add_i32 m0, s58, 0x400
	v_lshl_add_u64 v[240:241], v[240:241], 0, s[54:55]
	global_load_lds_dwordx4 v[242:243], off
	s_add_i32 m0, s58, 0x2000
	v_lshl_add_u64 v[242:243], v[242:243], 0, s[54:55]
	global_load_lds_dwordx4 v[244:245], off
	s_add_i32 m0, s58, 0x2400
	v_lshl_add_u64 v[244:245], v[244:245], 0, s[54:55]
	global_load_lds_dwordx4 v[246:247], off
	v_lshl_add_u64 v[246:247], v[246:247], 0, s[54:55]
	s_mov_b32 s14, 0
	s_mov_b32 s15, 0

.Lg_ph16_noA:
	ds_read_b128 v[186:189], v142
	ds_read_b128 v[190:193], v142 offset:2048
	ds_read_b128 v[194:197], v142 offset:4096
	ds_read_b128 v[198:201], v142 offset:6144
	ds_read_b128 v[202:205], v143
	ds_read_b128 v[218:221], v143 offset:2048
	ds_read_b128 v[222:225], v143 offset:4096
	ds_read_b128 v[226:229], v143 offset:6144
	ds_read_b128 v[166:169], v138
	ds_read_b128 v[170:173], v138 offset:2048
	ds_read_b128 v[174:177], v138 offset:4096
	ds_read_b128 v[182:185], v138 offset:6144
	s_waitcnt lgkmcnt(4)
	s_barrier
	s_cmp_eq_u32 s14, 15
	s_cbranch_scc1 .Lg_ph16_noB
	s_add_i32 s58, s53, 0x10000
	s_add_i32 m0, s58, 0x0
	s_nop 0
	global_load_lds_dwordx4 v[240:241], off
	s_add_i32 m0, s58, 0x400
	v_lshl_add_u64 v[240:241], v[240:241], 0, s[54:55]
	global_load_lds_dwordx4 v[242:243], off
	s_add_i32 m0, s58, 0x2000
	v_lshl_add_u64 v[242:243], v[242:243], 0, s[54:55]
	global_load_lds_dwordx4 v[244:245], off
	s_add_i32 m0, s58, 0x2400
	v_lshl_add_u64 v[244:245], v[244:245], 0, s[54:55]
	global_load_lds_dwordx4 v[246:247], off
	v_lshl_add_u64 v[246:247], v[246:247], 0, s[54:55]
.Lg_ph16_noB:
	s_waitcnt lgkmcnt(3)
	v_mfma_f32_16x16x32_bf16 v[0:3], v[166:169], v[186:189], v[0:3]
	v_mfma_f32_16x16x32_bf16 v[4:7], v[166:169], v[190:193], v[4:7]
	v_mfma_f32_16x16x32_bf16 v[8:11], v[166:169], v[194:197], v[8:11]
	v_mfma_f32_16x16x32_bf16 v[12:15], v[166:169], v[198:201], v[12:15]
	ds_read_b128 v[166:169], v138 offset:8192
	s_waitcnt lgkmcnt(3)
	v_mfma_f32_16x16x32_bf16 v[16:19], v[170:173], v[186:189], v[16:19]
	v_mfma_f32_16x16x32_bf16 v[20:23], v[170:173], v[190:193], v[20:23]
	v_mfma_f32_16x16x32_bf16 v[24:27], v[170:173], v[194:197], v[24:27]
	v_mfma_f32_16x16x32_bf16 v[28:31], v[170:173], v[198:201], v[28:31]
	ds_read_b128 v[170:173], v138 offset:10240
	s_waitcnt lgkmcnt(3)
	v_mfma_f32_16x16x32_bf16 v[32:35], v[174:177], v[186:189], v[32:35]
	v_mfma_f32_16x16x32_bf16 v[36:39], v[174:177], v[190:193], v[36:39]
	v_mfma_f32_16x16x32_bf16 v[40:43], v[174:177], v[194:197], v[40:43]
	v_mfma_f32_16x16x32_bf16 v[44:47], v[174:177], v[198:201], v[44:47]
	ds_read_b128 v[174:177], v138 offset:12288
	s_waitcnt lgkmcnt(3)
	v_mfma_f32_16x16x32_bf16 v[48:51], v[182:185], v[186:189], v[48:51]
	v_mfma_f32_16x16x32_bf16 v[52:55], v[182:185], v[190:193], v[52:55]
	v_mfma_f32_16x16x32_bf16 v[56:59], v[182:185], v[194:197], v[56:59]
	v_mfma_f32_16x16x32_bf16 v[60:63], v[182:185], v[198:201], v[60:63]
	ds_read_b128 v[182:185], v138 offset:14336
	s_waitcnt lgkmcnt(3)
	v_mfma_f32_16x16x32_bf16 v[64:67], v[166:169], v[186:189], v[64:67]
	v_mfma_f32_16x16x32_bf16 v[68:71], v[166:169], v[190:193], v[68:71]
	v_mfma_f32_16x16x32_bf16 v[72:75], v[166:169], v[194:197], v[72:75]
	v_mfma_f32_16x16x32_bf16 v[76:79], v[166:169], v[198:201], v[76:79]
	ds_read_b128 v[166:169], v139
	s_waitcnt lgkmcnt(3)
	v_mfma_f32_16x16x32_bf16 v[80:83], v[170:173], v[186:189], v[80:83]
	v_mfma_f32_16x16x32_bf16 v[84:87], v[170:173], v[190:193], v[84:87]
	v_mfma_f32_16x16x32_bf16 v[88:91], v[170:173], v[194:197], v[88:91]
	v_mfma_f32_16x16x32_bf16 v[92:95], v[170:173], v[198:201], v[92:95]
	ds_read_b128 v[170:173], v139 offset:2048
	s_waitcnt lgkmcnt(3)
	v_mfma_f32_16x16x32_bf16 v[96:99], v[174:177], v[186:189], v[96:99]
	v_mfma_f32_16x16x32_bf16 v[100:103], v[174:177], v[190:193], v[100:103]
	v_mfma_f32_16x16x32_bf16 v[104:107], v[174:177], v[194:197], v[104:107]
	v_mfma_f32_16x16x32_bf16 v[108:111], v[174:177], v[198:201], v[108:111]
	ds_read_b128 v[174:177], v139 offset:4096
	s_waitcnt lgkmcnt(3)
	v_mfma_f32_16x16x32_bf16 v[112:115], v[182:185], v[186:189], v[112:115]
	v_mfma_f32_16x16x32_bf16 v[116:119], v[182:185], v[190:193], v[116:119]
	v_mfma_f32_16x16x32_bf16 v[120:123], v[182:185], v[194:197], v[120:123]
	v_mfma_f32_16x16x32_bf16 v[124:127], v[182:185], v[198:201], v[124:127]
	ds_read_b128 v[182:185], v139 offset:6144
	s_waitcnt lgkmcnt(3)
	v_mfma_f32_16x16x32_bf16 v[0:3], v[166:169], v[202:205], v[0:3]
	v_mfma_f32_16x16x32_bf16 v[4:7], v[166:169], v[218:221], v[4:7]
	v_mfma_f32_16x16x32_bf16 v[8:11], v[166:169], v[222:225], v[8:11]
	v_mfma_f32_16x16x32_bf16 v[12:15], v[166:169], v[226:229], v[12:15]
	ds_read_b128 v[166:169], v139 offset:8192
	s_waitcnt lgkmcnt(3)
	v_mfma_f32_16x16x32_bf16 v[16:19], v[170:173], v[202:205], v[16:19]
	v_mfma_f32_16x16x32_bf16 v[20:23], v[170:173], v[218:221], v[20:23]
	v_mfma_f32_16x16x32_bf16 v[24:27], v[170:173], v[222:225], v[24:27]
	v_mfma_f32_16x16x32_bf16 v[28:31], v[170:173], v[226:229], v[28:31]
	ds_read_b128 v[170:173], v139 offset:10240
	s_waitcnt lgkmcnt(3)
	v_mfma_f32_16x16x32_bf16 v[32:35], v[174:177], v[202:205], v[32:35]
	v_mfma_f32_16x16x32_bf16 v[36:39], v[174:177], v[218:221], v[36:39]
	v_mfma_f32_16x16x32_bf16 v[40:43], v[174:177], v[222:225], v[40:43]
	v_mfma_f32_16x16x32_bf16 v[44:47], v[174:177], v[226:229], v[44:47]
	ds_read_b128 v[174:177], v139 offset:12288
	s_waitcnt lgkmcnt(3)
	v_mfma_f32_16x16x32_bf16 v[48:51], v[182:185], v[202:205], v[48:51]
	v_mfma_f32_16x16x32_bf16 v[52:55], v[182:185], v[218:221], v[52:55]
	v_mfma_f32_16x16x32_bf16 v[56:59], v[182:185], v[222:225], v[56:59]
	v_mfma_f32_16x16x32_bf16 v[60:63], v[182:185], v[226:229], v[60:63]
	ds_read_b128 v[182:185], v139 offset:14336
	s_waitcnt lgkmcnt(3)
	v_mfma_f32_16x16x32_bf16 v[64:67], v[166:169], v[202:205], v[64:67]
	v_mfma_f32_16x16x32_bf16 v[68:71], v[166:169], v[218:221], v[68:71]
	v_mfma_f32_16x16x32_bf16 v[72:75], v[166:169], v[222:225], v[72:75]
	v_mfma_f32_16x16x32_bf16 v[76:79], v[166:169], v[226:229], v[76:79]
	s_waitcnt lgkmcnt(2)
	v_mfma_f32_16x16x32_bf16 v[80:83], v[170:173], v[202:205], v[80:83]
	v_mfma_f32_16x16x32_bf16 v[84:87], v[170:173], v[218:221], v[84:87]
	v_mfma_f32_16x16x32_bf16 v[88:91], v[170:173], v[222:225], v[88:91]
	v_mfma_f32_16x16x32_bf16 v[92:95], v[170:173], v[226:229], v[92:95]
	s_waitcnt lgkmcnt(1)
	v_mfma_f32_16x16x32_bf16 v[96:99], v[174:177], v[202:205], v[96:99]
	v_mfma_f32_16x16x32_bf16 v[100:103], v[174:177], v[218:221], v[100:103]
	v_mfma_f32_16x16x32_bf16 v[104:107], v[174:177], v[222:225], v[104:107]
	v_mfma_f32_16x16x32_bf16 v[108:111], v[174:177], v[226:229], v[108:111]
	s_waitcnt lgkmcnt(0)
	v_mfma_f32_16x16x32_bf16 v[112:115], v[182:185], v[202:205], v[112:115]
	v_mfma_f32_16x16x32_bf16 v[116:119], v[182:185], v[218:221], v[116:119]
	v_mfma_f32_16x16x32_bf16 v[120:123], v[182:185], v[222:225], v[120:123]
	v_mfma_f32_16x16x32_bf16 v[124:127], v[182:185], v[226:229], v[124:127]
	v_xor_b32_e32 v138, 0x8000, v138
	v_xor_b32_e32 v139, 0x8000, v139
	s_xor_b32 s15, s15, 0x8000
	s_add_i32 s14, s14, 1
	s_cmp_eq_u32 s14, 16
	s_cbranch_scc0 .Lg_ph16_top
	s_waitcnt vmcnt(0)
	v_mov_b32_e32 v128, v180
	v_add_u32_e32 v192, 0x400, v153
	v_add_u32_e32 v191, 0x1000, v153
	v_add_u32_e32 v190, 0x1400, v153
	v_add_u32_e32 v189, 0x2000, v153
	v_add_u32_e32 v183, 0x2400, v153
	v_add_u32_e32 v184, 0x3000, v153
	v_add_u32_e32 v185, 0x3200, v153
	v_add_u32_e32 v186, 0x3400, v153
	v_add_u32_e32 v187, 0x3600, v153
	v_add_u32_e32 v188, 0x4000, v153
	v_add_u32_e32 v179, 0x4400, v153
	v_add_u32_e32 v181, 0x4800, v153
	v_add_u32_e32 v182, 0x5000, v153
	v_add_u32_e32 v176, 0x5400, v153
	v_add_u32_e32 v177, 0x5800, v153
	v_add_u32_e32 v178, 0x6000, v153
	v_add_u32_e32 v170, 0x6400, v153
	v_add_u32_e32 v171, 0x6800, v153
	v_add_u32_e32 v172, 0x7200, v153
	v_add_u32_e32 v173, 0x7400, v153
	v_add_u32_e32 v174, 0x7600, v153
	v_add_u32_e32 v175, 0x7800, v153
	v_add_u32_e32 v169, 0x8400, v153
	v_add_u32_e32 v168, 0x8800, v153
	v_add_u32_e32 v167, 0x9400, v153
	v_add_u32_e32 v166, 0x9800, v153
	v_add_u32_e32 v145, 0xa400, v153
	v_add_u32_e32 v140, 0xa800, v153
	v_add_u32_e32 v141, 0xb400, v153
	v_add_u32_e32 v142, 0xb600, v153
	v_add_u32_e32 v143, 0xb800, v153
	v_add_u32_e32 v144, 0xba00, v153
	s_waitcnt vmcnt(0)
	s_barrier
	s_and_saveexec_b64 s[14:15], s[6:7]
	s_cbranch_execz .LBB0_1674
	v_and_b32_e32 v254, 63, v180
	v_lshrrev_b32_e32 v253, 4, v254
	v_mul_u32_u24_e32 v253, 0x840, v253
	v_and_b32_e32 v254, 15, v254
	v_lshl_add_u32 v253, v254, 2, v253
	v_and_b32_e32 v254, 64, v180
	v_lshl_add_u32 v253, v254, 2, v253
	ds_write_b32 v253, v0 offset:0
	ds_write_b32 v253, v1 offset:528
	ds_write_b32 v253, v2 offset:1056
	ds_write_b32 v253, v3 offset:1584
	ds_write_b32 v253, v4 offset:64
	ds_write_b32 v253, v5 offset:592
	ds_write_b32 v253, v6 offset:1120
	ds_write_b32 v253, v7 offset:1648
	ds_write_b32 v253, v8 offset:128
	ds_write_b32 v253, v9 offset:656
	ds_write_b32 v253, v10 offset:1184
	ds_write_b32 v253, v11 offset:1712
	ds_write_b32 v253, v12 offset:192
	ds_write_b32 v253, v13 offset:720
	ds_write_b32 v253, v14 offset:1248
	ds_write_b32 v253, v15 offset:1776
	ds_write_b32 v253, v16 offset:8448
	ds_write_b32 v253, v17 offset:8976
	ds_write_b32 v253, v18 offset:9504
	ds_write_b32 v253, v19 offset:10032
	ds_write_b32 v253, v20 offset:8512
	ds_write_b32 v253, v21 offset:9040
	ds_write_b32 v253, v22 offset:9568
	ds_write_b32 v253, v23 offset:10096
	ds_write_b32 v253, v24 offset:8576
	ds_write_b32 v253, v25 offset:9104
	ds_write_b32 v253, v26 offset:9632
	ds_write_b32 v253, v27 offset:10160
	ds_write_b32 v253, v28 offset:8640
	ds_write_b32 v253, v29 offset:9168
	ds_write_b32 v253, v30 offset:9696
	ds_write_b32 v253, v31 offset:10224
	ds_write_b32 v253, v32 offset:16896
	ds_write_b32 v253, v33 offset:17424
	ds_write_b32 v253, v34 offset:17952
	ds_write_b32 v253, v35 offset:18480
	ds_write_b32 v253, v36 offset:16960
	ds_write_b32 v253, v37 offset:17488
	ds_write_b32 v253, v38 offset:18016
	ds_write_b32 v253, v39 offset:18544
	ds_write_b32 v253, v40 offset:17024
	ds_write_b32 v253, v41 offset:17552
	ds_write_b32 v253, v42 offset:18080
	ds_write_b32 v253, v43 offset:18608
	ds_write_b32 v253, v44 offset:17088
	ds_write_b32 v253, v45 offset:17616
	ds_write_b32 v253, v46 offset:18144
	ds_write_b32 v253, v47 offset:18672
	ds_write_b32 v253, v48 offset:25344
	ds_write_b32 v253, v49 offset:25872
	ds_write_b32 v253, v50 offset:26400
	ds_write_b32 v253, v51 offset:26928
	ds_write_b32 v253, v52 offset:25408
	ds_write_b32 v253, v53 offset:25936
	ds_write_b32 v253, v54 offset:26464
	ds_write_b32 v253, v55 offset:26992
	ds_write_b32 v253, v56 offset:25472
	ds_write_b32 v253, v57 offset:26000
	ds_write_b32 v253, v58 offset:26528
	ds_write_b32 v253, v59 offset:27056
	ds_write_b32 v253, v60 offset:25536
	ds_write_b32 v253, v61 offset:26064
	ds_write_b32 v253, v62 offset:26592
	ds_write_b32 v253, v63 offset:27120
	ds_write_b32 v253, v64 offset:33792
	ds_write_b32 v253, v65 offset:34320
	ds_write_b32 v253, v66 offset:34848
	ds_write_b32 v253, v67 offset:35376
	ds_write_b32 v253, v68 offset:33856
	ds_write_b32 v253, v69 offset:34384
	ds_write_b32 v253, v70 offset:34912
	ds_write_b32 v253, v71 offset:35440
	ds_write_b32 v253, v72 offset:33920
	ds_write_b32 v253, v73 offset:34448
	ds_write_b32 v253, v74 offset:34976
	ds_write_b32 v253, v75 offset:35504
	ds_write_b32 v253, v76 offset:33984
	ds_write_b32 v253, v77 offset:34512
	ds_write_b32 v253, v78 offset:35040
	ds_write_b32 v253, v79 offset:35568
	ds_write_b32 v253, v80 offset:42240
	ds_write_b32 v253, v81 offset:42768
	ds_write_b32 v253, v82 offset:43296
	ds_write_b32 v253, v83 offset:43824
	ds_write_b32 v253, v84 offset:42304
	ds_write_b32 v253, v85 offset:42832
	ds_write_b32 v253, v86 offset:43360
	ds_write_b32 v253, v87 offset:43888
	ds_write_b32 v253, v88 offset:42368
	ds_write_b32 v253, v89 offset:42896
	ds_write_b32 v253, v90 offset:43424
	ds_write_b32 v253, v91 offset:43952
	ds_write_b32 v253, v92 offset:42432
	ds_write_b32 v253, v93 offset:42960
	ds_write_b32 v253, v94 offset:43488
	ds_write_b32 v253, v95 offset:44016
	ds_write_b32 v253, v96 offset:50688
	ds_write_b32 v253, v97 offset:51216
	ds_write_b32 v253, v98 offset:51744
	ds_write_b32 v253, v99 offset:52272
	ds_write_b32 v253, v100 offset:50752
	ds_write_b32 v253, v101 offset:51280
	ds_write_b32 v253, v102 offset:51808
	ds_write_b32 v253, v103 offset:52336
	ds_write_b32 v253, v104 offset:50816
	ds_write_b32 v253, v105 offset:51344
	ds_write_b32 v253, v106 offset:51872
	ds_write_b32 v253, v107 offset:52400
	ds_write_b32 v253, v108 offset:50880
	ds_write_b32 v253, v109 offset:51408
	ds_write_b32 v253, v110 offset:51936
	ds_write_b32 v253, v111 offset:52464
	ds_write_b32 v253, v112 offset:59136
	ds_write_b32 v253, v113 offset:59664
	ds_write_b32 v253, v114 offset:60192
	ds_write_b32 v253, v115 offset:60720
	ds_write_b32 v253, v116 offset:59200
	ds_write_b32 v253, v117 offset:59728
	ds_write_b32 v253, v118 offset:60256
	ds_write_b32 v253, v119 offset:60784
	ds_write_b32 v253, v120 offset:59264
	ds_write_b32 v253, v121 offset:59792
	ds_write_b32 v253, v122 offset:60320
	ds_write_b32 v253, v123 offset:60848
	ds_write_b32 v253, v124 offset:59328
	ds_write_b32 v253, v125 offset:59856
	ds_write_b32 v253, v126 offset:60384
	ds_write_b32 v253, v127 offset:60912
.LBB0_1674:
	s_or_b64 exec, exec, s[14:15]
	v_lshlrev_b32_e32 v134, 3, v128
	v_and_b32_e32 v137, 56, v134
	v_ashrrev_i32_e32 v134, 3, v128
	v_mul_lo_u32 v135, v134, s22
	v_lshlrev_b32_e32 v138, 2, v137
	v_add3_u32 v139, 0, v135, v138
	s_waitcnt lgkmcnt(0)
	s_barrier
	ds_read_b128 v[194:197], v139
	v_add_u32_e32 v128, 0x100, v128
	s_lshl_b32 s10, s26, 19
	s_lshl_b32 s14, s27, 20
	v_ashrrev_i32_e32 v136, 3, v128
	s_waitcnt lgkmcnt(0)
	v_mul_f32_e32 v135, 0xbfb8aa3b, v194
	v_exp_f32_e32 v202, v135
	v_mul_f32_e32 v135, 0xbfb8aa3b, v195
	v_exp_f32_e32 v203, v135
	v_mul_lo_u32 v193, v136, s22
	v_add3_u32 v138, 0, v193, v138
	ds_read_b128 v[198:201], v139 offset:16
	v_pk_add_f32 v[206:207], v[202:203], 1.0 op_sel_hi:[1,0]
	ds_read_b128 v[202:205], v139 offset:256
	v_div_scale_f32 v128, s[26:27], v207, v207, v195
	v_rcp_f32_e32 v135, v128
	s_or_b32 s10, s14, s10
	s_add_u32 s10, s16, s10
	s_addc_u32 s15, s17, 0
	v_fma_f32 v193, -v128, v135, 1.0
	v_fmac_f32_e32 v135, v193, v135
	v_div_scale_f32 v193, vcc, v195, v207, v195
	v_mul_f32_e32 v208, v193, v135
	v_fma_f32 v209, -v128, v208, v193
	v_fmac_f32_e32 v208, v209, v135
	v_fma_f32 v128, -v128, v208, v193
	v_div_scale_f32 v193, s[26:27], v206, v206, v194
	v_rcp_f32_e32 v210, v193
	v_div_fmas_f32 v128, v128, v135, v208
	v_div_fixup_f32 v195, v128, v207, v195
	s_lshl_b32 s14, s28, 7
	v_fma_f32 v128, -v193, v210, 1.0
	v_fmac_f32_e32 v210, v128, v210
	v_div_scale_f32 v128, vcc, v194, v206, v194
	v_mul_f32_e32 v135, v128, v210
	v_fma_f32 v207, -v193, v135, v128
	v_fmac_f32_e32 v135, v207, v210
	v_mul_f32_e32 v207, 0xbfb8aa3b, v196
	v_exp_f32_e32 v208, v207
	v_mul_f32_e32 v207, 0xbfb8aa3b, v197
	v_exp_f32_e32 v209, v207
	v_fma_f32 v128, -v193, v135, v128
	v_div_fmas_f32 v128, v128, v210, v135
	v_div_fixup_f32 v194, v128, v206, v194
	v_pk_add_f32 v[210:211], v[208:209], 1.0 op_sel_hi:[1,0]
	s_waitcnt lgkmcnt(0)
	v_pk_mul_f32 v[194:195], v[194:195], v[202:203]
	v_div_scale_f32 v135, s[26:27], v211, v211, v197
	v_rcp_f32_e32 v193, v135
	ds_read_b128 v[206:209], v139 offset:272
	s_add_u32 s14, s10, s14
	s_addc_u32 s15, s15, 0
	v_fma_f32 v128, -v135, v193, 1.0
	v_fmac_f32_e32 v193, v128, v193
	v_div_scale_f32 v128, vcc, v197, v211, v197
	v_mul_f32_e32 v202, v128, v193
	v_fma_f32 v203, -v135, v202, v128
	v_fmac_f32_e32 v202, v203, v193
	v_fma_f32 v128, -v135, v202, v128
	v_div_scale_f32 v135, s[26:27], v210, v210, v196
	v_rcp_f32_e32 v213, v135
	v_div_fmas_f32 v128, v128, v193, v202
	v_mul_f32_e32 v202, 0xbfb8aa3b, v198
	v_mul_f32_e32 v203, 0xbfb8aa3b, v199
	v_div_fixup_f32 v197, v128, v211, v197
	v_fma_f32 v128, -v135, v213, 1.0
	v_exp_f32_e32 v202, v202
	v_exp_f32_e32 v203, v203
	v_fmac_f32_e32 v213, v128, v213
	v_div_scale_f32 v128, vcc, v196, v210, v196
	v_mul_f32_e32 v193, v128, v213
	v_fma_f32 v211, -v135, v193, v128
	v_fmac_f32_e32 v193, v211, v213
	v_pk_add_f32 v[202:203], v[202:203], 1.0 op_sel_hi:[1,0]
	v_fma_f32 v128, -v135, v193, v128
	v_div_scale_f32 v135, s[26:27], v203, v203, v199
	v_rcp_f32_e32 v211, v135
	v_div_fmas_f32 v128, v128, v213, v193
	v_div_fixup_f32 v196, v128, v210, v196
	v_pk_mul_f32 v[196:197], v[196:197], v[204:205]
	v_fma_f32 v128, -v135, v211, 1.0
	v_fmac_f32_e32 v211, v128, v211
	v_div_scale_f32 v128, vcc, v199, v203, v199
	v_mul_f32_e32 v193, v128, v211
	v_fma_f32 v204, -v135, v193, v128
	v_fmac_f32_e32 v193, v204, v211
	v_fma_f32 v128, -v135, v193, v128
	v_div_scale_f32 v135, s[26:27], v202, v202, v198
	v_rcp_f32_e32 v210, v135
	v_div_fmas_f32 v128, v128, v211, v193
	v_div_fixup_f32 v199, v128, v203, v199
	v_mul_f32_e32 v203, 0xbfb8aa3b, v200
	v_exp_f32_e32 v204, v203
	v_mul_f32_e32 v203, 0xbfb8aa3b, v201
	v_fma_f32 v128, -v135, v210, 1.0
	v_exp_f32_e32 v205, v203
	v_fmac_f32_e32 v210, v128, v210
	v_div_scale_f32 v128, vcc, v198, v202, v198
	v_mul_f32_e32 v193, v128, v210
	v_fma_f32 v203, -v135, v193, v128
	v_fmac_f32_e32 v193, v203, v210
	v_pk_add_f32 v[204:205], v[204:205], 1.0 op_sel_hi:[1,0]
	v_fma_f32 v128, -v135, v193, v128
	v_div_scale_f32 v135, s[26:27], v205, v205, v201
	v_rcp_f32_e32 v211, v135
	v_div_fmas_f32 v128, v128, v210, v193
	v_div_fixup_f32 v198, v128, v202, v198
	s_waitcnt lgkmcnt(0)
	v_pk_mul_f32 v[202:203], v[198:199], v[206:207]
	v_fma_f32 v128, -v135, v211, 1.0
	v_fmac_f32_e32 v211, v128, v211
	v_div_scale_f32 v128, vcc, v201, v205, v201
	v_mul_f32_e32 v193, v128, v211
	v_fma_f32 v198, -v135, v193, v128
	v_fmac_f32_e32 v193, v198, v211
	v_fma_f32 v128, -v135, v193, v128
	v_div_scale_f32 v135, s[26:27], v204, v204, v200
	v_rcp_f32_e32 v198, v135
	v_div_fmas_f32 v128, v128, v211, v193
	v_div_fixup_f32 v199, v128, v205, v201
	v_cvt_pk_bf16_f32 v194, v194, v195
	v_fma_f32 v128, -v135, v198, 1.0
	v_fmac_f32_e32 v198, v128, v198
	v_div_scale_f32 v128, vcc, v200, v204, v200
	v_mul_f32_e32 v193, v128, v198
	v_fma_f32 v201, -v135, v193, v128
	v_fmac_f32_e32 v193, v201, v198
	v_fma_f32 v128, -v135, v193, v128
	v_div_fmas_f32 v128, v128, v198, v193
	v_div_fixup_f32 v198, v128, v204, v200
	v_pk_mul_f32 v[204:205], v[198:199], v[208:209]
	ds_read_b128 v[198:201], v138
	v_ashrrev_i32_e32 v135, 31, v134
	v_lshlrev_b64 v[134:135], 11, v[134:135]
	v_lshl_add_u64 v[134:135], s[14:15], 0, v[134:135]
	v_cvt_pk_bf16_f32 v195, v196, v197
	s_waitcnt lgkmcnt(0)
	v_mul_f32_e32 v128, 0xbfb8aa3b, v198
	v_exp_f32_e32 v206, v128
	v_mul_f32_e32 v128, 0xbfb8aa3b, v199
	v_exp_f32_e32 v207, v128
	v_lshlrev_b32_e32 v128, 1, v137
	v_cvt_pk_bf16_f32 v196, v202, v203
	v_cvt_pk_bf16_f32 v197, v204, v205
	v_pk_add_f32 v[206:207], v[206:207], 1.0 op_sel_hi:[1,0]
	v_lshl_add_u64 v[134:135], v[134:135], 0, v[128:129]
	v_div_scale_f32 v137, s[26:27], v207, v207, v199
	v_rcp_f32_e32 v193, v137
	global_store_dwordx4 v[134:135], v[194:197], off
	ds_read_b128 v[194:197], v138 offset:256
	ds_read_b128 v[202:205], v138 offset:16
	v_fma_f32 v208, -v137, v193, 1.0
	v_fmac_f32_e32 v193, v208, v193
	v_div_scale_f32 v208, vcc, v199, v207, v199
	v_mul_f32_e32 v209, v208, v193
	v_fma_f32 v210, -v137, v209, v208
	v_fmac_f32_e32 v209, v210, v193
	v_div_scale_f32 v210, s[26:27], v206, v206, v198
	v_rcp_f32_e32 v211, v210
	v_fma_f32 v137, -v137, v209, v208
	v_div_fmas_f32 v137, v137, v193, v209
	v_div_fixup_f32 v199, v137, v207, v199
	v_fma_f32 v137, -v210, v211, 1.0
	v_fmac_f32_e32 v211, v137, v211
	v_div_scale_f32 v137, vcc, v198, v206, v198
	v_mul_f32_e32 v193, v137, v211
	v_fma_f32 v207, -v210, v193, v137
	v_fmac_f32_e32 v193, v207, v211
	v_mul_f32_e32 v207, 0xbfb8aa3b, v200
	v_exp_f32_e32 v208, v207
	v_mul_f32_e32 v207, 0xbfb8aa3b, v201
	v_exp_f32_e32 v209, v207
	v_fma_f32 v137, -v210, v193, v137
	v_div_fmas_f32 v137, v137, v211, v193
	v_div_fixup_f32 v198, v137, v206, v198
	v_pk_add_f32 v[210:211], v[208:209], 1.0 op_sel_hi:[1,0]
	s_waitcnt lgkmcnt(1)
	v_pk_mul_f32 v[214:215], v[198:199], v[194:195]
	v_div_scale_f32 v193, s[26:27], v211, v211, v201
	v_rcp_f32_e32 v213, v193
	s_waitcnt lgkmcnt(0)
	v_mul_f32_e32 v198, 0xbfb8aa3b, v202
	v_mul_f32_e32 v199, 0xbfb8aa3b, v203
	v_exp_f32_e32 v198, v198
	v_fma_f32 v137, -v193, v213, 1.0
	v_fmac_f32_e32 v213, v137, v213
	v_div_scale_f32 v137, vcc, v201, v211, v201
	v_mul_f32_e32 v194, v137, v213
	v_fma_f32 v195, -v193, v194, v137
	v_fmac_f32_e32 v194, v195, v213
	v_fma_f32 v137, -v193, v194, v137
	v_div_scale_f32 v193, s[26:27], v210, v210, v200
	v_rcp_f32_e32 v216, v193
	v_div_fmas_f32 v137, v137, v213, v194
	v_div_fixup_f32 v195, v137, v211, v201
	v_exp_f32_e32 v199, v199
	v_fma_f32 v137, -v193, v216, 1.0
	v_fmac_f32_e32 v216, v137, v216
	v_div_scale_f32 v137, vcc, v200, v210, v200
	v_mul_f32_e32 v194, v137, v216
	v_fma_f32 v201, -v193, v194, v137
	v_fmac_f32_e32 v194, v201, v216
	v_pk_add_f32 v[198:199], v[198:199], 1.0 op_sel_hi:[1,0]
	v_fma_f32 v137, -v193, v194, v137
	v_div_scale_f32 v193, s[26:27], v199, v199, v203
	v_rcp_f32_e32 v201, v193
	v_div_fmas_f32 v137, v137, v216, v194
	v_div_fixup_f32 v194, v137, v210, v200
	v_pk_mul_f32 v[194:195], v[194:195], v[196:197]
	v_fma_f32 v137, -v193, v201, 1.0
	v_fmac_f32_e32 v201, v137, v201
	v_div_scale_f32 v137, vcc, v203, v199, v203
	v_mul_f32_e32 v196, v137, v201
	v_fma_f32 v197, -v193, v196, v137
	v_fmac_f32_e32 v196, v197, v201
	v_fma_f32 v137, -v193, v196, v137
	v_div_scale_f32 v193, s[26:27], v198, v198, v202
	v_rcp_f32_e32 v210, v193
	v_div_fmas_f32 v137, v137, v201, v196
	v_div_fixup_f32 v197, v137, v199, v203
	v_mul_f32_e32 v199, 0xbfb8aa3b, v204
	v_exp_f32_e32 v200, v199
	v_mul_f32_e32 v199, 0xbfb8aa3b, v205
	v_fma_f32 v137, -v193, v210, 1.0
	v_exp_f32_e32 v201, v199
	v_fmac_f32_e32 v210, v137, v210
	v_div_scale_f32 v137, vcc, v202, v198, v202
	v_mul_f32_e32 v196, v137, v210
	v_fma_f32 v199, -v193, v196, v137
	v_fmac_f32_e32 v196, v199, v210
	v_pk_add_f32 v[200:201], v[200:201], 1.0 op_sel_hi:[1,0]
	v_fma_f32 v137, -v193, v196, v137
	v_div_scale_f32 v193, s[26:27], v201, v201, v205
	v_rcp_f32_e32 v199, v193
	ds_read_b128 v[206:209], v138 offset:272
	v_div_fmas_f32 v137, v137, v210, v196
	v_div_fixup_f32 v196, v137, v198, v202
	v_fma_f32 v137, -v193, v199, 1.0
	v_fmac_f32_e32 v199, v137, v199
	v_div_scale_f32 v137, vcc, v205, v201, v205
	s_waitcnt lgkmcnt(0)
	v_pk_mul_f32 v[202:203], v[196:197], v[206:207]
	v_mul_f32_e32 v196, v137, v199
	v_fma_f32 v197, -v193, v196, v137
	v_fmac_f32_e32 v196, v197, v199
	v_fma_f32 v137, -v193, v196, v137
	v_div_scale_f32 v193, s[26:27], v200, v200, v204
	v_rcp_f32_e32 v198, v193
	v_div_fmas_f32 v137, v137, v199, v196
	v_div_fixup_f32 v197, v137, v201, v205
	v_cvt_pk_bf16_f32 v195, v194, v195
	v_fma_f32 v137, -v193, v198, 1.0
	v_fmac_f32_e32 v198, v137, v198
	v_div_scale_f32 v137, vcc, v204, v200, v204
	v_mul_f32_e32 v196, v137, v198
	v_fma_f32 v199, -v193, v196, v137
	v_fmac_f32_e32 v196, v199, v198
	v_fma_f32 v137, -v193, v196, v137
	v_div_fmas_f32 v137, v137, v198, v196
	v_div_fixup_f32 v196, v137, v200, v204
	ds_read_b128 v[198:201], v139 offset:33792
	v_pk_mul_f32 v[196:197], v[196:197], v[208:209]
	v_cvt_pk_bf16_f32 v194, v214, v215
	v_cvt_pk_bf16_f32 v197, v196, v197
	v_cvt_pk_bf16_f32 v196, v202, v203
	s_waitcnt lgkmcnt(0)
	v_mul_f32_e32 v137, 0xbfb8aa3b, v198
	v_exp_f32_e32 v206, v137
	v_mul_f32_e32 v137, 0xbfb8aa3b, v199
	v_exp_f32_e32 v207, v137
	v_ashrrev_i32_e32 v137, 31, v136
	v_lshlrev_b64 v[136:137], 11, v[136:137]
	v_lshl_add_u64 v[136:137], s[14:15], 0, v[136:137]
	v_pk_add_f32 v[206:207], v[206:207], 1.0 op_sel_hi:[1,0]
	v_lshl_add_u64 v[136:137], v[136:137], 0, v[128:129]
	v_div_scale_f32 v193, s[14:15], v207, v207, v199
	v_rcp_f32_e32 v208, v193
	global_store_dwordx4 v[136:137], v[194:197], off
	ds_read_b128 v[194:197], v139 offset:34048
	ds_read_b128 v[202:205], v139 offset:33808
	v_fma_f32 v128, -v193, v208, 1.0
	v_fmac_f32_e32 v208, v128, v208
	v_div_scale_f32 v128, vcc, v199, v207, v199
	v_mul_f32_e32 v209, v128, v208
	v_fma_f32 v210, -v193, v209, v128
	v_fmac_f32_e32 v209, v210, v208
	v_fma_f32 v128, -v193, v209, v128
	v_div_scale_f32 v193, s[14:15], v206, v206, v198
	v_rcp_f32_e32 v210, v193
	v_div_fmas_f32 v128, v128, v208, v209
	v_div_fixup_f32 v199, v128, v207, v199
	v_mul_f32_e32 v209, 0xbfb8aa3b, v201
	v_fma_f32 v128, -v193, v210, 1.0
	v_fmac_f32_e32 v210, v128, v210
	v_div_scale_f32 v128, vcc, v198, v206, v198
	v_mul_f32_e32 v207, v128, v210
	v_fma_f32 v208, -v193, v207, v128
	v_fmac_f32_e32 v207, v208, v210
	v_mul_f32_e32 v208, 0xbfb8aa3b, v200
	v_exp_f32_e32 v208, v208
	v_exp_f32_e32 v209, v209
	v_fma_f32 v128, -v193, v207, v128
	v_div_fmas_f32 v128, v128, v210, v207
	v_div_fixup_f32 v198, v128, v206, v198
	v_pk_add_f32 v[210:211], v[208:209], 1.0 op_sel_hi:[1,0]
	s_waitcnt lgkmcnt(1)
	v_pk_mul_f32 v[198:199], v[198:199], v[194:195]
	v_div_scale_f32 v193, s[14:15], v211, v211, v201
	v_rcp_f32_e32 v213, v193
	ds_read_b128 v[206:209], v139 offset:34064
	v_cvt_pk_bf16_f32 v198, v198, v199
	v_fma_f32 v128, -v193, v213, 1.0
	v_fmac_f32_e32 v213, v128, v213
	v_div_scale_f32 v128, vcc, v201, v211, v201
	v_mul_f32_e32 v194, v128, v213
	v_fma_f32 v195, -v193, v194, v128
	v_fmac_f32_e32 v194, v195, v213
	v_fma_f32 v128, -v193, v194, v128
	v_div_scale_f32 v193, s[14:15], v210, v210, v200
	v_rcp_f32_e32 v216, v193
	v_div_fmas_f32 v128, v128, v213, v194
	v_div_fixup_f32 v195, v128, v211, v201
	s_waitcnt lgkmcnt(1)
	v_mul_f32_e32 v201, 0xbfb8aa3b, v202
	v_exp_f32_e32 v214, v201
	v_mul_f32_e32 v201, 0xbfb8aa3b, v203
	v_fma_f32 v128, -v193, v216, 1.0
	v_exp_f32_e32 v215, v201
	v_fmac_f32_e32 v216, v128, v216
	v_div_scale_f32 v128, vcc, v200, v210, v200
	v_mul_f32_e32 v194, v128, v216
	v_fma_f32 v201, -v193, v194, v128
	v_fmac_f32_e32 v194, v201, v216
	v_pk_add_f32 v[214:215], v[214:215], 1.0 op_sel_hi:[1,0]
	v_fma_f32 v128, -v193, v194, v128
	v_div_scale_f32 v193, s[14:15], v215, v215, v203
	v_rcp_f32_e32 v211, v193
	v_div_fmas_f32 v128, v128, v216, v194
	v_div_fixup_f32 v194, v128, v210, v200
	v_pk_mul_f32 v[200:201], v[194:195], v[196:197]
	v_fma_f32 v128, -v193, v211, 1.0
	v_fmac_f32_e32 v211, v128, v211
	v_div_scale_f32 v128, vcc, v203, v215, v203
	v_mul_f32_e32 v194, v128, v211
	v_fma_f32 v195, -v193, v194, v128
	v_fmac_f32_e32 v194, v195, v211
	v_fma_f32 v128, -v193, v194, v128
	v_div_scale_f32 v193, s[14:15], v214, v214, v202
	v_rcp_f32_e32 v213, v193
	v_div_fmas_f32 v128, v128, v211, v194
	v_mul_f32_e32 v196, 0xbfb8aa3b, v204
	v_mul_f32_e32 v197, 0xbfb8aa3b, v205
	v_div_fixup_f32 v195, v128, v215, v203
	v_fma_f32 v128, -v193, v213, 1.0
	v_exp_f32_e32 v196, v196
	v_exp_f32_e32 v197, v197
	v_fmac_f32_e32 v213, v128, v213
	v_div_scale_f32 v128, vcc, v202, v214, v202
	v_mul_f32_e32 v194, v128, v213
	v_fma_f32 v203, -v193, v194, v128
	v_fmac_f32_e32 v194, v203, v213
	v_pk_add_f32 v[210:211], v[196:197], 1.0 op_sel_hi:[1,0]
	v_fma_f32 v128, -v193, v194, v128
	v_div_scale_f32 v193, s[14:15], v211, v211, v205
	v_rcp_f32_e32 v196, v193
	v_div_fmas_f32 v128, v128, v213, v194
	v_div_fixup_f32 v194, v128, v214, v202
	s_waitcnt lgkmcnt(0)
	v_pk_mul_f32 v[206:207], v[194:195], v[206:207]
	v_fma_f32 v128, -v193, v196, 1.0
	v_fmac_f32_e32 v196, v128, v196
	v_div_scale_f32 v128, vcc, v205, v211, v205
	v_mul_f32_e32 v194, v128, v196
	v_fma_f32 v195, -v193, v194, v128
	v_fmac_f32_e32 v194, v195, v196
	v_fma_f32 v128, -v193, v194, v128
	v_div_scale_f32 v193, s[14:15], v210, v210, v204
	v_rcp_f32_e32 v195, v193
	v_div_fmas_f32 v128, v128, v196, v194
	v_div_fixup_f32 v203, v128, v211, v205
	v_cvt_pk_bf16_f32 v199, v200, v201
	v_fma_f32 v128, -v193, v195, 1.0
	v_fmac_f32_e32 v195, v128, v195
	v_div_scale_f32 v128, vcc, v204, v210, v204
	v_mul_f32_e32 v194, v128, v195
	v_fma_f32 v196, -v193, v194, v128
	v_fmac_f32_e32 v194, v196, v195
	v_fma_f32 v128, -v193, v194, v128
	v_div_fmas_f32 v128, v128, v195, v194
	ds_read_b128 v[194:197], v138 offset:33792
	v_div_fixup_f32 v202, v128, v210, v204
	v_cvt_pk_bf16_f32 v200, v206, v207
	v_pk_mul_f32 v[208:209], v[202:203], v[208:209]
	ds_read_b128 v[202:205], v138 offset:33808
	s_waitcnt lgkmcnt(1)
	v_mul_f32_e32 v128, 0xbfb8aa3b, v194
	v_exp_f32_e32 v210, v128
	v_mul_f32_e32 v128, 0xbfb8aa3b, v195
	v_exp_f32_e32 v211, v128
	v_cvt_pk_bf16_f32 v201, v208, v209
	v_add_co_u32_e32 v208, vcc, s23, v134
	v_pk_add_f32 v[206:207], v[210:211], 1.0 op_sel_hi:[1,0]
	s_nop 0
	v_addc_co_u32_e32 v209, vcc, 0, v135, vcc
	v_div_scale_f32 v128, s[14:15], v207, v207, v195
	v_rcp_f32_e32 v193, v128
	global_store_dwordx4 v[208:209], v[198:201], off
	ds_read_b128 v[198:201], v138 offset:34048
	v_fma_f32 v208, -v128, v193, 1.0
	v_fmac_f32_e32 v193, v208, v193
	v_div_scale_f32 v208, vcc, v195, v207, v195
	v_mul_f32_e32 v209, v208, v193
	v_fma_f32 v210, -v128, v209, v208
	v_fmac_f32_e32 v209, v210, v193
	v_div_scale_f32 v210, s[14:15], v206, v206, v194
	v_rcp_f32_e32 v211, v210
	v_fma_f32 v128, -v128, v209, v208
	v_div_fmas_f32 v128, v128, v193, v209
	v_div_fixup_f32 v195, v128, v207, v195
	v_fma_f32 v128, -v210, v211, 1.0
	v_fmac_f32_e32 v211, v128, v211
	v_div_scale_f32 v128, vcc, v194, v206, v194
	v_mul_f32_e32 v193, v128, v211
	v_fma_f32 v207, -v210, v193, v128
	v_fmac_f32_e32 v193, v207, v211
	v_mul_f32_e32 v207, 0xbfb8aa3b, v196
	v_exp_f32_e32 v208, v207
	v_mul_f32_e32 v207, 0xbfb8aa3b, v197
	v_exp_f32_e32 v209, v207
	v_fma_f32 v128, -v210, v193, v128
	v_div_fmas_f32 v128, v128, v211, v193
	v_div_fixup_f32 v194, v128, v206, v194
	v_pk_add_f32 v[210:211], v[208:209], 1.0 op_sel_hi:[1,0]
	s_waitcnt lgkmcnt(0)
	v_pk_mul_f32 v[198:199], v[194:195], v[198:199]
	v_div_scale_f32 v193, s[14:15], v211, v211, v197
	v_rcp_f32_e32 v213, v193
	ds_read_b128 v[206:209], v138 offset:34064
	v_fma_f32 v128, -v193, v213, 1.0
	v_fmac_f32_e32 v213, v128, v213
	v_div_scale_f32 v128, vcc, v197, v211, v197
	v_mul_f32_e32 v194, v128, v213
	v_fma_f32 v195, -v193, v194, v128
	v_fmac_f32_e32 v194, v195, v213
	v_fma_f32 v128, -v193, v194, v128
	v_div_scale_f32 v193, s[14:15], v210, v210, v196
	v_rcp_f32_e32 v216, v193
	v_div_fmas_f32 v128, v128, v213, v194
	v_div_fixup_f32 v195, v128, v211, v197
	v_mul_f32_e32 v197, 0xbfb8aa3b, v202
	v_exp_f32_e32 v214, v197
	v_mul_f32_e32 v197, 0xbfb8aa3b, v203
	v_fma_f32 v128, -v193, v216, 1.0
	v_exp_f32_e32 v215, v197
	v_fmac_f32_e32 v216, v128, v216
	v_div_scale_f32 v128, vcc, v196, v210, v196
	v_mul_f32_e32 v194, v128, v216
	v_fma_f32 v197, -v193, v194, v128
	v_fmac_f32_e32 v194, v197, v216
	v_pk_add_f32 v[214:215], v[214:215], 1.0 op_sel_hi:[1,0]
	v_fma_f32 v128, -v193, v194, v128
	v_div_scale_f32 v193, s[14:15], v215, v215, v203
	v_rcp_f32_e32 v197, v193
	v_div_fmas_f32 v128, v128, v216, v194
	v_div_fixup_f32 v194, v128, v210, v196
	v_pk_mul_f32 v[194:195], v[194:195], v[200:201]
	v_fma_f32 v128, -v193, v197, 1.0
	v_fmac_f32_e32 v197, v128, v197
	v_div_scale_f32 v128, vcc, v203, v215, v203
	v_mul_f32_e32 v196, v128, v197
	v_fma_f32 v200, -v193, v196, v128
	v_fmac_f32_e32 v196, v200, v197
	v_fma_f32 v128, -v193, v196, v128
	v_div_scale_f32 v193, s[14:15], v214, v214, v202
	v_rcp_f32_e32 v210, v193
	v_div_fmas_f32 v128, v128, v197, v196
	v_mul_f32_e32 v200, 0xbfb8aa3b, v204
	v_mul_f32_e32 v201, 0xbfb8aa3b, v205
	v_div_fixup_f32 v197, v128, v215, v203
	v_fma_f32 v128, -v193, v210, 1.0
	v_exp_f32_e32 v200, v200
	v_exp_f32_e32 v201, v201
	v_fmac_f32_e32 v210, v128, v210
	v_div_scale_f32 v128, vcc, v202, v214, v202
	v_mul_f32_e32 v196, v128, v210
	v_fma_f32 v203, -v193, v196, v128
	v_fmac_f32_e32 v196, v203, v210
	v_pk_add_f32 v[200:201], v[200:201], 1.0 op_sel_hi:[1,0]
	v_fma_f32 v128, -v193, v196, v128
	v_div_scale_f32 v193, s[14:15], v201, v201, v205
	v_rcp_f32_e32 v211, v193
	v_div_fmas_f32 v128, v128, v210, v196
	v_div_fixup_f32 v196, v128, v214, v202
	s_waitcnt lgkmcnt(0)
	v_pk_mul_f32 v[202:203], v[196:197], v[206:207]
	v_fma_f32 v128, -v193, v211, 1.0
	v_fmac_f32_e32 v211, v128, v211
	v_div_scale_f32 v128, vcc, v205, v201, v205
	v_mul_f32_e32 v196, v128, v211
	v_fma_f32 v197, -v193, v196, v128
	v_fmac_f32_e32 v196, v197, v211
	v_fma_f32 v128, -v193, v196, v128
	v_div_scale_f32 v193, s[14:15], v200, v200, v204
	v_rcp_f32_e32 v206, v193
	v_div_fmas_f32 v128, v128, v211, v196
	v_div_fixup_f32 v197, v128, v201, v205
	v_cvt_pk_bf16_f32 v195, v194, v195
	v_fma_f32 v128, -v193, v206, 1.0
	v_fmac_f32_e32 v206, v128, v206
	v_div_scale_f32 v128, vcc, v204, v200, v204
	v_mul_f32_e32 v196, v128, v206
	v_fma_f32 v201, -v193, v196, v128
	v_fmac_f32_e32 v196, v201, v206
	v_fma_f32 v128, -v193, v196, v128
	v_div_fmas_f32 v128, v128, v206, v196
	v_div_fixup_f32 v196, v128, v200, v204
	v_pk_mul_f32 v[196:197], v[196:197], v[208:209]
	v_cvt_pk_bf16_f32 v194, v198, v199
	v_add_co_u32_e32 v198, vcc, 0x20000, v136
	v_cvt_pk_bf16_f32 v197, v196, v197
	v_cvt_pk_bf16_f32 v196, v202, v203
	v_addc_co_u32_e32 v199, vcc, 0, v137, vcc
	global_store_dwordx4 v[198:199], v[194:197], off
	s_barrier
	s_and_saveexec_b64 s[14:15], s[8:9]
	s_cbranch_execz .LBB0_1669
	v_and_b32_e32 v254, 63, v180
	v_lshrrev_b32_e32 v253, 4, v254
	v_mul_u32_u24_e32 v253, 0x840, v253
	v_and_b32_e32 v254, 15, v254
	v_lshl_add_u32 v253, v254, 2, v253
	v_and_b32_e32 v254, 64, v180
	v_lshl_add_u32 v253, v254, 2, v253
	ds_write_b32 v253, v0 offset:0
	ds_write_b32 v253, v1 offset:528
	ds_write_b32 v253, v2 offset:1056
	ds_write_b32 v253, v3 offset:1584
	ds_write_b32 v253, v4 offset:64
	ds_write_b32 v253, v5 offset:592
	ds_write_b32 v253, v6 offset:1120
	ds_write_b32 v253, v7 offset:1648
	ds_write_b32 v253, v8 offset:128
	ds_write_b32 v253, v9 offset:656
	ds_write_b32 v253, v10 offset:1184
	ds_write_b32 v253, v11 offset:1712
	ds_write_b32 v253, v12 offset:192
	ds_write_b32 v253, v13 offset:720
	ds_write_b32 v253, v14 offset:1248
	ds_write_b32 v253, v15 offset:1776
	ds_write_b32 v253, v16 offset:8448
	ds_write_b32 v253, v17 offset:8976
	ds_write_b32 v253, v18 offset:9504
	ds_write_b32 v253, v19 offset:10032
	ds_write_b32 v253, v20 offset:8512
	ds_write_b32 v253, v21 offset:9040
	ds_write_b32 v253, v22 offset:9568
	ds_write_b32 v253, v23 offset:10096
	ds_write_b32 v253, v24 offset:8576
	ds_write_b32 v253, v25 offset:9104
	ds_write_b32 v253, v26 offset:9632
	ds_write_b32 v253, v27 offset:10160
	ds_write_b32 v253, v28 offset:8640
	ds_write_b32 v253, v29 offset:9168
	ds_write_b32 v253, v30 offset:9696
	ds_write_b32 v253, v31 offset:10224
	ds_write_b32 v253, v32 offset:16896
	ds_write_b32 v253, v33 offset:17424
	ds_write_b32 v253, v34 offset:17952
	ds_write_b32 v253, v35 offset:18480
	ds_write_b32 v253, v36 offset:16960
	ds_write_b32 v253, v37 offset:17488
	ds_write_b32 v253, v38 offset:18016
	ds_write_b32 v253, v39 offset:18544
	ds_write_b32 v253, v40 offset:17024
	ds_write_b32 v253, v41 offset:17552
	ds_write_b32 v253, v42 offset:18080
	ds_write_b32 v253, v43 offset:18608
	ds_write_b32 v253, v44 offset:17088
	ds_write_b32 v253, v45 offset:17616
	ds_write_b32 v253, v46 offset:18144
	ds_write_b32 v253, v47 offset:18672
	ds_write_b32 v253, v48 offset:25344
	ds_write_b32 v253, v49 offset:25872
	ds_write_b32 v253, v50 offset:26400
	ds_write_b32 v253, v51 offset:26928
	ds_write_b32 v253, v52 offset:25408
	ds_write_b32 v253, v53 offset:25936
	ds_write_b32 v253, v54 offset:26464
	ds_write_b32 v253, v55 offset:26992
	ds_write_b32 v253, v56 offset:25472
	ds_write_b32 v253, v57 offset:26000
	ds_write_b32 v253, v58 offset:26528
	ds_write_b32 v253, v59 offset:27056
	ds_write_b32 v253, v60 offset:25536
	ds_write_b32 v253, v61 offset:26064
	ds_write_b32 v253, v62 offset:26592
	ds_write_b32 v253, v63 offset:27120
	ds_write_b32 v253, v64 offset:33792
	ds_write_b32 v253, v65 offset:34320
	ds_write_b32 v253, v66 offset:34848
	ds_write_b32 v253, v67 offset:35376
	ds_write_b32 v253, v68 offset:33856
	ds_write_b32 v253, v69 offset:34384
	ds_write_b32 v253, v70 offset:34912
	ds_write_b32 v253, v71 offset:35440
	ds_write_b32 v253, v72 offset:33920
	ds_write_b32 v253, v73 offset:34448
	ds_write_b32 v253, v74 offset:34976
	ds_write_b32 v253, v75 offset:35504
	ds_write_b32 v253, v76 offset:33984
	ds_write_b32 v253, v77 offset:34512
	ds_write_b32 v253, v78 offset:35040
	ds_write_b32 v253, v79 offset:35568
	ds_write_b32 v253, v80 offset:42240
	ds_write_b32 v253, v81 offset:42768
	ds_write_b32 v253, v82 offset:43296
	ds_write_b32 v253, v83 offset:43824
	ds_write_b32 v253, v84 offset:42304
	ds_write_b32 v253, v85 offset:42832
	ds_write_b32 v253, v86 offset:43360
	ds_write_b32 v253, v87 offset:43888
	ds_write_b32 v253, v88 offset:42368
	ds_write_b32 v253, v89 offset:42896
	ds_write_b32 v253, v90 offset:43424
	ds_write_b32 v253, v91 offset:43952
	ds_write_b32 v253, v92 offset:42432
	ds_write_b32 v253, v93 offset:42960
	ds_write_b32 v253, v94 offset:43488
	ds_write_b32 v253, v95 offset:44016
	ds_write_b32 v253, v96 offset:50688
	ds_write_b32 v253, v97 offset:51216
	ds_write_b32 v253, v98 offset:51744
	ds_write_b32 v253, v99 offset:52272
	ds_write_b32 v253, v100 offset:50752
	ds_write_b32 v253, v101 offset:51280
	ds_write_b32 v253, v102 offset:51808
	ds_write_b32 v253, v103 offset:52336
	ds_write_b32 v253, v104 offset:50816
	ds_write_b32 v253, v105 offset:51344
	ds_write_b32 v253, v106 offset:51872
	ds_write_b32 v253, v107 offset:52400
	ds_write_b32 v253, v108 offset:50880
	ds_write_b32 v253, v109 offset:51408
	ds_write_b32 v253, v110 offset:51936
	ds_write_b32 v253, v111 offset:52464
	ds_write_b32 v253, v112 offset:59136
	ds_write_b32 v253, v113 offset:59664
	ds_write_b32 v253, v114 offset:60192
	ds_write_b32 v253, v115 offset:60720
	ds_write_b32 v253, v116 offset:59200
	ds_write_b32 v253, v117 offset:59728
	ds_write_b32 v253, v118 offset:60256
	ds_write_b32 v253, v119 offset:60784
	ds_write_b32 v253, v120 offset:59264
	ds_write_b32 v253, v121 offset:59792
	ds_write_b32 v253, v122 offset:60320
	ds_write_b32 v253, v123 offset:60848
	ds_write_b32 v253, v124 offset:59328
	ds_write_b32 v253, v125 offset:59856
	ds_write_b32 v253, v126 offset:60384
	ds_write_b32 v253, v127 offset:60912
	s_branch .LBB0_1669

.LBB0_1736:
	s_lshr_b32 s4, s30, 3
	s_and_b32 s4, s4, 8
	s_lshl_b32 s20, s30, 3
	s_or_b32 s4, s4, s28
	s_and_b32 s37, s30, 1
	s_and_b32 s20, s20, 48
	s_or_b32 s38, s4, s20
	s_lshl_b32 s22, s37, 8
	s_lshl_b32 s20, s30, 4
	s_lshl_b32 s23, s38, 9
	v_or_b32_e32 v0, s22, v129
	s_and_b32 s39, s20, 0x380
	v_or_b32_e32 v0, s23, v0
	s_lshl_b32 s20, s39, 11
	s_lshl_b32 s4, s4, 21
	v_lshlrev_b32_e32 v1, 10, v0
	s_or_b32 s4, s4, s20
	s_add_u32 s20, s94, s4
	v_or_b32_e32 v0, v1, v128
	v_readfirstlane_b32 s4, v152
	v_lshlrev_b32_e32 v130, 1, v0
	s_mov_b32 m0, s4
	v_readfirstlane_b32 s4, v161
	s_addc_u32 s21, s95, 0
	v_add_lshl_u32 v0, v1, v158, 1
	s_waitcnt vmcnt(0)
	s_barrier
	s_nop 0
	s_mov_b32 m0, s4
	v_readfirstlane_b32 s4, v162
	v_add_lshl_u32 v2, v1, v159, 1
	v_lshl_add_u64 v[6:7], s[20:21], 0, v[132:133]
	s_nop 0
	s_mov_b32 m0, s4
	v_readfirstlane_b32 s4, v163
	v_add_lshl_u32 v4, v1, v160, 1
	v_lshl_add_u64 v[6:7], v[6:7], 0, v[134:135]
	s_nop 0
	s_mov_b32 m0, s4
	v_readfirstlane_b32 s4, v164
	v_lshl_add_u64 v[136:137], v[6:7], 0, s[10:11]
	s_nop 0
	s_mov_b32 m0, s4
	v_readfirstlane_b32 s4, v165
	v_lshl_add_u64 v[138:139], s[2:3], 0, v[130:131]
	v_mov_b32_e32 v1, v131
	v_lshl_add_u64 v[146:147], v[6:7], 0, s[12:13]
	s_nop 0
	s_mov_b32 m0, s4
	v_readfirstlane_b32 s4, v166
	v_lshl_add_u64 v[140:141], s[2:3], 0, v[0:1]
	v_mov_b32_e32 v3, v131
	s_nop 0
	v_lshl_add_u64 v[0:1], v[138:139], 0, 64
	s_mov_b32 m0, s4
	v_readfirstlane_b32 s4, v167
	v_lshl_add_u64 v[142:143], s[2:3], 0, v[2:3]
	v_mov_b32_e32 v5, v131
	s_nop 0
	v_lshl_add_u64 v[0:1], v[140:141], 0, 64
	s_mov_b32 m0, s4
	v_readfirstlane_b32 s4, v168
	v_lshl_add_u64 v[144:145], s[2:3], 0, v[4:5]
	s_nop 0
	v_lshl_add_u64 v[0:1], v[142:143], 0, 64
	s_mov_b32 m0, s4
	v_readfirstlane_b32 s4, v169
	s_nop 0
	v_lshl_add_u64 v[0:1], v[144:145], 0, 64
	s_mov_b32 m0, s4
	v_readfirstlane_b32 s4, v170
	s_nop 0
	v_lshl_add_u64 v[0:1], v[6:7], 0, s[14:15]
	s_mov_b32 m0, s4
	v_readfirstlane_b32 s4, v171
	s_nop 0
	v_lshl_add_u64 v[0:1], v[6:7], 0, s[16:17]
	s_mov_b32 m0, s4
	s_mov_b32 s20, s5
	s_nop 0
	s_mov_b32 s21, 2
	s_mov_b32 s40, s5
	v_mov_b32_e32 v0, 0
	v_mov_b32_e32 v1, v131
	v_mov_b32_e32 v2, v131
	v_mov_b32_e32 v4, v131
	v_mov_b32_e32 v6, v131
	v_mov_b32_e32 v7, v131
	v_mov_b32_e32 v8, v131
	v_mov_b32_e32 v9, v131
	v_mov_b32_e32 v10, v131
	v_mov_b32_e32 v11, v131
	v_mov_b32_e32 v12, v131
	v_mov_b32_e32 v13, v131
	v_mov_b32_e32 v14, v131
	v_mov_b32_e32 v15, v131
	v_mov_b32_e32 v16, 0
	v_mov_b32_e32 v17, v131
	v_mov_b32_e32 v18, v131
	v_mov_b32_e32 v19, v131
	v_mov_b32_e32 v20, v131
	v_mov_b32_e32 v21, v131
	v_mov_b32_e32 v22, v131
	v_mov_b32_e32 v23, v131
	v_mov_b32_e32 v24, v131
	v_mov_b32_e32 v25, v131
	v_mov_b32_e32 v26, v131
	v_mov_b32_e32 v27, v131
	v_mov_b32_e32 v28, v131
	v_mov_b32_e32 v29, v131
	v_mov_b32_e32 v30, v131
	v_mov_b32_e32 v31, v131
	v_mov_b32_e32 v32, 0
	v_mov_b32_e32 v33, v131
	v_mov_b32_e32 v34, v131
	v_mov_b32_e32 v35, v131
	v_mov_b32_e32 v36, v131
	v_mov_b32_e32 v37, v131
	v_mov_b32_e32 v38, v131
	v_mov_b32_e32 v39, v131
	v_mov_b32_e32 v40, v131
	v_mov_b32_e32 v41, v131
	v_mov_b32_e32 v42, v131
	v_mov_b32_e32 v43, v131
	v_mov_b32_e32 v44, v131
	v_mov_b32_e32 v45, v131
	v_mov_b32_e32 v46, v131
	v_mov_b32_e32 v47, v131
	v_mov_b32_e32 v48, 0
	v_mov_b32_e32 v49, v131
	v_mov_b32_e32 v50, v131
	v_mov_b32_e32 v51, v131
	v_mov_b32_e32 v52, v131
	v_mov_b32_e32 v53, v131
	v_mov_b32_e32 v54, v131
	v_mov_b32_e32 v55, v131
	v_mov_b32_e32 v56, v131
	v_mov_b32_e32 v57, v131
	v_mov_b32_e32 v58, v131
	v_mov_b32_e32 v59, v131
	v_mov_b32_e32 v60, v131
	v_mov_b32_e32 v61, v131
	v_mov_b32_e32 v62, v131
	v_mov_b32_e32 v63, v131
	v_mov_b32_e32 v64, 0
	v_mov_b32_e32 v65, v131
	v_mov_b32_e32 v66, v131
	v_mov_b32_e32 v67, v131
	v_mov_b32_e32 v68, v131
	v_mov_b32_e32 v69, v131
	v_mov_b32_e32 v70, v131
	v_mov_b32_e32 v71, v131
	v_mov_b32_e32 v72, v131
	v_mov_b32_e32 v73, v131
	v_mov_b32_e32 v74, v131
	v_mov_b32_e32 v75, v131
	v_mov_b32_e32 v76, v131
	v_mov_b32_e32 v77, v131
	v_mov_b32_e32 v78, v131
	v_mov_b32_e32 v79, v131
	v_mov_b32_e32 v80, 0
	v_mov_b32_e32 v81, v131
	v_mov_b32_e32 v82, v131
	v_mov_b32_e32 v83, v131
	v_mov_b32_e32 v84, v131
	v_mov_b32_e32 v85, v131
	v_mov_b32_e32 v86, v131
	v_mov_b32_e32 v87, v131
	v_mov_b32_e32 v88, v131
	v_mov_b32_e32 v89, v131
	v_mov_b32_e32 v90, v131
	v_mov_b32_e32 v91, v131
	v_mov_b32_e32 v92, v131
	v_mov_b32_e32 v93, v131
	v_mov_b32_e32 v94, v131
	v_mov_b32_e32 v95, v131
	v_mov_b32_e32 v96, 0
	v_mov_b32_e32 v97, v131
	v_mov_b32_e32 v98, v131
	v_mov_b32_e32 v99, v131
	v_mov_b32_e32 v100, v131
	v_mov_b32_e32 v101, v131
	v_mov_b32_e32 v102, v131
	v_mov_b32_e32 v103, v131
	v_mov_b32_e32 v104, v131
	v_mov_b32_e32 v105, v131
	v_mov_b32_e32 v106, v131
	v_mov_b32_e32 v107, v131
	v_mov_b32_e32 v108, v131
	v_mov_b32_e32 v109, v131
	v_mov_b32_e32 v110, v131
	v_mov_b32_e32 v111, v131
	v_mov_b32_e32 v112, 0
	v_mov_b32_e32 v113, v131
	v_mov_b32_e32 v114, v131
	v_mov_b32_e32 v115, v131
	v_mov_b32_e32 v116, v131
	v_mov_b32_e32 v117, v131
	v_mov_b32_e32 v118, v131
	v_mov_b32_e32 v119, v131
	v_mov_b32_e32 v120, v131
	v_mov_b32_e32 v121, v131
	v_mov_b32_e32 v122, v131
	v_mov_b32_e32 v123, v131
	v_mov_b32_e32 v124, v131
	v_mov_b32_e32 v125, v131
	v_mov_b32_e32 v126, v131
	v_mov_b32_e32 v127, v131
	s_mov_b64 s[54:55], 0x80
	v_lshrrev_b32_e32 v174, 6, v180
	v_lshlrev_b32_e32 v184, 11, v174
	v_and_b32_e32 v148, 63, v180
	v_readfirstlane_b32 s53, v184
	v_lshrrev_b32_e32 v149, 4, v148
	v_bfe_u32 v150, v148, 1, 3
	v_xor_b32_e32 v150, v149, v150
	v_and_b32_e32 v151, 31, v148
	v_lshlrev_b32_e32 v151, 7, v151
	v_lshrrev_b32_e32 v151, 3, v148
	v_lshlrev_b32_e32 v184, 4, v151
	v_add_u32_e32 v185, 0x80, v184
	v_and_b32_e32 v151, 7, v148
	v_lshrrev_b32_e32 v149, 4, v148
	v_xor_b32_e32 v149, v151, v149
	v_lshrrev_b32_e32 v151, 5, v148
	v_sub_u32_e32 v186, v149, v151
	v_xor_b32_e32 v149, 4, v149
	v_add_u32_e32 v151, 2, v151
	v_sub_u32_e32 v188, v149, v151
	v_lshlrev_b32_e32 v186, 4, v186
	v_ashrrev_i32_e32 v187, 31, v186
	v_lshlrev_b32_e32 v188, 4, v188
	v_ashrrev_i32_e32 v189, 31, v188
	ds_bpermute_b32 v246, v184, v136
	ds_bpermute_b32 v247, v184, v137
	ds_bpermute_b32 v248, v185, v136
	ds_bpermute_b32 v249, v185, v137
	ds_bpermute_b32 v250, v184, v146
	ds_bpermute_b32 v251, v184, v147
	ds_bpermute_b32 v252, v185, v146
	ds_bpermute_b32 v253, v185, v147
	s_waitcnt lgkmcnt(0)
	ds_bpermute_b32 v178, v184, v138
	ds_bpermute_b32 v179, v184, v139
	ds_bpermute_b32 v236, v185, v138
	ds_bpermute_b32 v237, v185, v139
	ds_bpermute_b32 v238, v184, v140
	ds_bpermute_b32 v239, v184, v141
	ds_bpermute_b32 v240, v185, v140
	ds_bpermute_b32 v241, v185, v141
	ds_bpermute_b32 v242, v184, v142
	ds_bpermute_b32 v243, v184, v143
	ds_bpermute_b32 v244, v185, v142
	ds_bpermute_b32 v245, v185, v143
	ds_bpermute_b32 v136, v184, v144
	ds_bpermute_b32 v137, v184, v145
	ds_bpermute_b32 v146, v185, v144
	ds_bpermute_b32 v147, v185, v145
	s_waitcnt lgkmcnt(0)
	v_and_b32_e32 v151, 15, v148
	v_lshlrev_b32_e32 v151, 7, v151
	v_lshrrev_b32_e32 v149, 1, v174
	v_lshl_add_u32 v138, v149, 14, v151
	v_and_b32_e32 v149, 1, v174
	v_lshl_add_u32 v142, v149, 13, v151
	v_add_u32_e32 v142, 0x10000, v142
	v_xor_b32_e32 v151, 4, v150
	v_lshl_add_u32 v139, v151, 4, v138
	v_lshl_add_u32 v143, v151, 4, v142
	v_xor_b32_e32 v151, 0, v150
	v_lshl_add_u32 v138, v151, 4, v138
	v_lshl_add_u32 v142, v151, 4, v142
	v_lshl_add_u64 v[178:179], v[178:179], 0, v[186:187]
	v_lshl_add_u64 v[236:237], v[236:237], 0, v[188:189]
	v_lshl_add_u64 v[238:239], v[238:239], 0, v[186:187]
	v_lshl_add_u64 v[240:241], v[240:241], 0, v[188:189]
	v_lshl_add_u64 v[242:243], v[242:243], 0, v[186:187]
	v_lshl_add_u64 v[244:245], v[244:245], 0, v[188:189]
	v_lshl_add_u64 v[136:137], v[136:137], 0, v[186:187]
	v_lshl_add_u64 v[146:147], v[146:147], 0, v[188:189]
	v_lshl_add_u64 v[246:247], v[246:247], 0, v[186:187]
	v_lshl_add_u64 v[248:249], v[248:249], 0, v[188:189]
	v_lshl_add_u64 v[250:251], v[250:251], 0, v[186:187]
	v_lshl_add_u64 v[252:253], v[252:253], 0, v[188:189]
	s_mov_b32 s58, s53
	s_add_i32 m0, s58, 0x0
	s_nop 0
	global_load_lds_dwordx4 v[178:179], off
	s_add_i32 m0, s58, 0x400
	v_lshl_add_u64 v[178:179], v[178:179], 0, s[54:55]
	global_load_lds_dwordx4 v[236:237], off
	s_add_i32 m0, s58, 0x2000
	v_lshl_add_u64 v[236:237], v[236:237], 0, s[54:55]
	global_load_lds_dwordx4 v[238:239], off
	s_add_i32 m0, s58, 0x2400
	v_lshl_add_u64 v[238:239], v[238:239], 0, s[54:55]
	global_load_lds_dwordx4 v[240:241], off
	s_add_i32 m0, s58, 0x4000
	v_lshl_add_u64 v[240:241], v[240:241], 0, s[54:55]
	global_load_lds_dwordx4 v[242:243], off
	s_add_i32 m0, s58, 0x4400
	v_lshl_add_u64 v[242:243], v[242:243], 0, s[54:55]
	global_load_lds_dwordx4 v[244:245], off
	s_add_i32 m0, s58, 0x6000
	v_lshl_add_u64 v[244:245], v[244:245], 0, s[54:55]
	global_load_lds_dwordx4 v[136:137], off
	s_add_i32 m0, s58, 0x6400
	v_lshl_add_u64 v[136:137], v[136:137], 0, s[54:55]
	global_load_lds_dwordx4 v[146:147], off
	v_lshl_add_u64 v[146:147], v[146:147], 0, s[54:55]
	s_add_i32 s58, s53, 0x10000
	s_add_i32 m0, s58, 0x0
	s_nop 0
	global_load_lds_dwordx4 v[246:247], off
	s_add_i32 m0, s58, 0x400
	v_lshl_add_u64 v[246:247], v[246:247], 0, s[54:55]
	global_load_lds_dwordx4 v[248:249], off
	s_add_i32 m0, s58, 0x2000
	v_lshl_add_u64 v[248:249], v[248:249], 0, s[54:55]
	global_load_lds_dwordx4 v[250:251], off
	s_add_i32 m0, s58, 0x2400
	v_lshl_add_u64 v[250:251], v[250:251], 0, s[54:55]
	global_load_lds_dwordx4 v[252:253], off
	v_lshl_add_u64 v[252:253], v[252:253], 0, s[54:55]
	s_mov_b32 s20, 0
	s_mov_b32 s21, 0

.Lg_ph17_noA:
	ds_read_b128 v[190:193], v142
	ds_read_b128 v[194:197], v142 offset:2048
	ds_read_b128 v[198:201], v142 offset:4096
	ds_read_b128 v[202:205], v142 offset:6144
	ds_read_b128 v[206:209], v143
	ds_read_b128 v[224:227], v143 offset:2048
	ds_read_b128 v[228:231], v143 offset:4096
	ds_read_b128 v[232:235], v143 offset:6144
	ds_read_b128 v[148:151], v138
	ds_read_b128 v[174:177], v138 offset:2048
	ds_read_b128 v[182:185], v138 offset:4096
	ds_read_b128 v[186:189], v138 offset:6144
	s_waitcnt lgkmcnt(4)
	s_barrier
	s_cmp_eq_u32 s20, 15
	s_cbranch_scc1 .Lg_ph17_noB
	s_add_i32 s58, s53, 0x10000
	s_add_i32 m0, s58, 0x0
	s_nop 0
	global_load_lds_dwordx4 v[246:247], off
	s_add_i32 m0, s58, 0x400
	v_lshl_add_u64 v[246:247], v[246:247], 0, s[54:55]
	global_load_lds_dwordx4 v[248:249], off
	s_add_i32 m0, s58, 0x2000
	v_lshl_add_u64 v[248:249], v[248:249], 0, s[54:55]
	global_load_lds_dwordx4 v[250:251], off
	s_add_i32 m0, s58, 0x2400
	v_lshl_add_u64 v[250:251], v[250:251], 0, s[54:55]
	global_load_lds_dwordx4 v[252:253], off
	v_lshl_add_u64 v[252:253], v[252:253], 0, s[54:55]
.Lg_ph17_noB:
	s_waitcnt lgkmcnt(3)
	v_mfma_f32_16x16x32_bf16 v[0:3], v[148:151], v[190:193], v[0:3]
	v_mfma_f32_16x16x32_bf16 v[4:7], v[148:151], v[194:197], v[4:7]
	v_mfma_f32_16x16x32_bf16 v[8:11], v[148:151], v[198:201], v[8:11]
	v_mfma_f32_16x16x32_bf16 v[12:15], v[148:151], v[202:205], v[12:15]
	ds_read_b128 v[148:151], v138 offset:8192
	s_waitcnt lgkmcnt(3)
	v_mfma_f32_16x16x32_bf16 v[16:19], v[174:177], v[190:193], v[16:19]
	v_mfma_f32_16x16x32_bf16 v[20:23], v[174:177], v[194:197], v[20:23]
	v_mfma_f32_16x16x32_bf16 v[24:27], v[174:177], v[198:201], v[24:27]
	v_mfma_f32_16x16x32_bf16 v[28:31], v[174:177], v[202:205], v[28:31]
	ds_read_b128 v[174:177], v138 offset:10240
	s_waitcnt lgkmcnt(3)
	v_mfma_f32_16x16x32_bf16 v[32:35], v[182:185], v[190:193], v[32:35]
	v_mfma_f32_16x16x32_bf16 v[36:39], v[182:185], v[194:197], v[36:39]
	v_mfma_f32_16x16x32_bf16 v[40:43], v[182:185], v[198:201], v[40:43]
	v_mfma_f32_16x16x32_bf16 v[44:47], v[182:185], v[202:205], v[44:47]
	ds_read_b128 v[182:185], v138 offset:12288
	s_waitcnt lgkmcnt(3)
	v_mfma_f32_16x16x32_bf16 v[48:51], v[186:189], v[190:193], v[48:51]
	v_mfma_f32_16x16x32_bf16 v[52:55], v[186:189], v[194:197], v[52:55]
	v_mfma_f32_16x16x32_bf16 v[56:59], v[186:189], v[198:201], v[56:59]
	v_mfma_f32_16x16x32_bf16 v[60:63], v[186:189], v[202:205], v[60:63]
	ds_read_b128 v[186:189], v138 offset:14336
	s_waitcnt lgkmcnt(3)
	v_mfma_f32_16x16x32_bf16 v[64:67], v[148:151], v[190:193], v[64:67]
	v_mfma_f32_16x16x32_bf16 v[68:71], v[148:151], v[194:197], v[68:71]
	v_mfma_f32_16x16x32_bf16 v[72:75], v[148:151], v[198:201], v[72:75]
	v_mfma_f32_16x16x32_bf16 v[76:79], v[148:151], v[202:205], v[76:79]
	ds_read_b128 v[148:151], v139
	s_waitcnt lgkmcnt(3)
	v_mfma_f32_16x16x32_bf16 v[80:83], v[174:177], v[190:193], v[80:83]
	v_mfma_f32_16x16x32_bf16 v[84:87], v[174:177], v[194:197], v[84:87]
	v_mfma_f32_16x16x32_bf16 v[88:91], v[174:177], v[198:201], v[88:91]
	v_mfma_f32_16x16x32_bf16 v[92:95], v[174:177], v[202:205], v[92:95]
	ds_read_b128 v[174:177], v139 offset:2048
	s_waitcnt lgkmcnt(3)
	v_mfma_f32_16x16x32_bf16 v[96:99], v[182:185], v[190:193], v[96:99]
	v_mfma_f32_16x16x32_bf16 v[100:103], v[182:185], v[194:197], v[100:103]
	v_mfma_f32_16x16x32_bf16 v[104:107], v[182:185], v[198:201], v[104:107]
	v_mfma_f32_16x16x32_bf16 v[108:111], v[182:185], v[202:205], v[108:111]
	ds_read_b128 v[182:185], v139 offset:4096
	s_waitcnt lgkmcnt(3)
	v_mfma_f32_16x16x32_bf16 v[112:115], v[186:189], v[190:193], v[112:115]
	v_mfma_f32_16x16x32_bf16 v[116:119], v[186:189], v[194:197], v[116:119]
	v_mfma_f32_16x16x32_bf16 v[120:123], v[186:189], v[198:201], v[120:123]
	v_mfma_f32_16x16x32_bf16 v[124:127], v[186:189], v[202:205], v[124:127]
	ds_read_b128 v[186:189], v139 offset:6144
	s_waitcnt lgkmcnt(3)
	v_mfma_f32_16x16x32_bf16 v[0:3], v[148:151], v[206:209], v[0:3]
	v_mfma_f32_16x16x32_bf16 v[4:7], v[148:151], v[224:227], v[4:7]
	v_mfma_f32_16x16x32_bf16 v[8:11], v[148:151], v[228:231], v[8:11]
	v_mfma_f32_16x16x32_bf16 v[12:15], v[148:151], v[232:235], v[12:15]
	ds_read_b128 v[148:151], v139 offset:8192
	s_waitcnt lgkmcnt(3)
	v_mfma_f32_16x16x32_bf16 v[16:19], v[174:177], v[206:209], v[16:19]
	v_mfma_f32_16x16x32_bf16 v[20:23], v[174:177], v[224:227], v[20:23]
	v_mfma_f32_16x16x32_bf16 v[24:27], v[174:177], v[228:231], v[24:27]
	v_mfma_f32_16x16x32_bf16 v[28:31], v[174:177], v[232:235], v[28:31]
	ds_read_b128 v[174:177], v139 offset:10240
	s_waitcnt lgkmcnt(3)
	v_mfma_f32_16x16x32_bf16 v[32:35], v[182:185], v[206:209], v[32:35]
	v_mfma_f32_16x16x32_bf16 v[36:39], v[182:185], v[224:227], v[36:39]
	v_mfma_f32_16x16x32_bf16 v[40:43], v[182:185], v[228:231], v[40:43]
	v_mfma_f32_16x16x32_bf16 v[44:47], v[182:185], v[232:235], v[44:47]
	ds_read_b128 v[182:185], v139 offset:12288
	s_waitcnt lgkmcnt(3)
	v_mfma_f32_16x16x32_bf16 v[48:51], v[186:189], v[206:209], v[48:51]
	v_mfma_f32_16x16x32_bf16 v[52:55], v[186:189], v[224:227], v[52:55]
	v_mfma_f32_16x16x32_bf16 v[56:59], v[186:189], v[228:231], v[56:59]
	v_mfma_f32_16x16x32_bf16 v[60:63], v[186:189], v[232:235], v[60:63]
	ds_read_b128 v[186:189], v139 offset:14336
	s_waitcnt lgkmcnt(3)
	v_mfma_f32_16x16x32_bf16 v[64:67], v[148:151], v[206:209], v[64:67]
	v_mfma_f32_16x16x32_bf16 v[68:71], v[148:151], v[224:227], v[68:71]
	v_mfma_f32_16x16x32_bf16 v[72:75], v[148:151], v[228:231], v[72:75]
	v_mfma_f32_16x16x32_bf16 v[76:79], v[148:151], v[232:235], v[76:79]
	s_waitcnt lgkmcnt(2)
	v_mfma_f32_16x16x32_bf16 v[80:83], v[174:177], v[206:209], v[80:83]
	v_mfma_f32_16x16x32_bf16 v[84:87], v[174:177], v[224:227], v[84:87]
	v_mfma_f32_16x16x32_bf16 v[88:91], v[174:177], v[228:231], v[88:91]
	v_mfma_f32_16x16x32_bf16 v[92:95], v[174:177], v[232:235], v[92:95]
	s_waitcnt lgkmcnt(1)
	v_mfma_f32_16x16x32_bf16 v[96:99], v[182:185], v[206:209], v[96:99]
	v_mfma_f32_16x16x32_bf16 v[100:103], v[182:185], v[224:227], v[100:103]
	v_mfma_f32_16x16x32_bf16 v[104:107], v[182:185], v[228:231], v[104:107]
	v_mfma_f32_16x16x32_bf16 v[108:111], v[182:185], v[232:235], v[108:111]
	s_waitcnt lgkmcnt(0)
	v_mfma_f32_16x16x32_bf16 v[112:115], v[186:189], v[206:209], v[112:115]
	v_mfma_f32_16x16x32_bf16 v[116:119], v[186:189], v[224:227], v[116:119]
	v_mfma_f32_16x16x32_bf16 v[120:123], v[186:189], v[228:231], v[120:123]
	v_mfma_f32_16x16x32_bf16 v[124:127], v[186:189], v[232:235], v[124:127]
	v_xor_b32_e32 v138, 0x8000, v138
	v_xor_b32_e32 v139, 0x8000, v139
	s_xor_b32 s21, s21, 0x8000
	s_add_i32 s20, s20, 1
	s_cmp_eq_u32 s20, 16
	s_cbranch_scc0 .Lg_ph17_top
	s_waitcnt vmcnt(0)
	v_mov_b32_e32 v146, v180
	v_add_u32_e32 v208, 0x400, v157
	v_add_u32_e32 v207, 0x1000, v157
	v_add_u32_e32 v206, 0x1400, v157
	v_add_u32_e32 v205, 0x2000, v157
	v_add_u32_e32 v199, 0x2400, v157
	v_add_u32_e32 v200, 0x3000, v157
	v_add_u32_e32 v201, 0x3200, v157
	v_add_u32_e32 v202, 0x3400, v157
	v_add_u32_e32 v203, 0x3600, v157
	v_add_u32_e32 v204, 0x4000, v157
	v_add_u32_e32 v196, 0x4400, v157
	v_add_u32_e32 v197, 0x4800, v157
	v_add_u32_e32 v198, 0x5000, v157
	v_add_u32_e32 v193, 0x5400, v157
	v_add_u32_e32 v194, 0x5800, v157
	v_add_u32_e32 v195, 0x6000, v157
	v_add_u32_e32 v187, 0x6400, v157
	v_add_u32_e32 v188, 0x6800, v157
	v_add_u32_e32 v189, 0x7200, v157
	v_add_u32_e32 v190, 0x7400, v157
	v_add_u32_e32 v191, 0x7600, v157
	v_add_u32_e32 v192, 0x7800, v157
	v_add_u32_e32 v186, 0x8400, v157
	v_add_u32_e32 v185, 0x8800, v157
	v_add_u32_e32 v184, 0x9400, v157
	v_add_u32_e32 v183, 0x9800, v157
	v_add_u32_e32 v181, 0xa400, v157
	v_add_u32_e32 v174, 0xa800, v157
	v_add_u32_e32 v175, 0xb400, v157
	v_add_u32_e32 v176, 0xb600, v157
	v_add_u32_e32 v177, 0xb800, v157
	v_add_u32_e32 v178, 0xba00, v157
	s_waitcnt vmcnt(0)
	s_barrier
	s_and_saveexec_b64 s[20:21], s[6:7]
	s_cbranch_execz .LBB0_1740
	v_and_b32_e32 v254, 63, v180
	v_lshrrev_b32_e32 v253, 4, v254
	v_mul_u32_u24_e32 v253, 0x840, v253
	v_and_b32_e32 v254, 15, v254
	v_lshl_add_u32 v253, v254, 2, v253
	v_and_b32_e32 v254, 64, v180
	v_lshl_add_u32 v253, v254, 2, v253
	ds_write_b32 v253, v0 offset:0
	ds_write_b32 v253, v1 offset:528
	ds_write_b32 v253, v2 offset:1056
	ds_write_b32 v253, v3 offset:1584
	ds_write_b32 v253, v4 offset:64
	ds_write_b32 v253, v5 offset:592
	ds_write_b32 v253, v6 offset:1120
	ds_write_b32 v253, v7 offset:1648
	ds_write_b32 v253, v8 offset:128
	ds_write_b32 v253, v9 offset:656
	ds_write_b32 v253, v10 offset:1184
	ds_write_b32 v253, v11 offset:1712
	ds_write_b32 v253, v12 offset:192
	ds_write_b32 v253, v13 offset:720
	ds_write_b32 v253, v14 offset:1248
	ds_write_b32 v253, v15 offset:1776
	ds_write_b32 v253, v16 offset:8448
	ds_write_b32 v253, v17 offset:8976
	ds_write_b32 v253, v18 offset:9504
	ds_write_b32 v253, v19 offset:10032
	ds_write_b32 v253, v20 offset:8512
	ds_write_b32 v253, v21 offset:9040
	ds_write_b32 v253, v22 offset:9568
	ds_write_b32 v253, v23 offset:10096
	ds_write_b32 v253, v24 offset:8576
	ds_write_b32 v253, v25 offset:9104
	ds_write_b32 v253, v26 offset:9632
	ds_write_b32 v253, v27 offset:10160
	ds_write_b32 v253, v28 offset:8640
	ds_write_b32 v253, v29 offset:9168
	ds_write_b32 v253, v30 offset:9696
	ds_write_b32 v253, v31 offset:10224
	ds_write_b32 v253, v32 offset:16896
	ds_write_b32 v253, v33 offset:17424
	ds_write_b32 v253, v34 offset:17952
	ds_write_b32 v253, v35 offset:18480
	ds_write_b32 v253, v36 offset:16960
	ds_write_b32 v253, v37 offset:17488
	ds_write_b32 v253, v38 offset:18016
	ds_write_b32 v253, v39 offset:18544
	ds_write_b32 v253, v40 offset:17024
	ds_write_b32 v253, v41 offset:17552
	ds_write_b32 v253, v42 offset:18080
	ds_write_b32 v253, v43 offset:18608
	ds_write_b32 v253, v44 offset:17088
	ds_write_b32 v253, v45 offset:17616
	ds_write_b32 v253, v46 offset:18144
	ds_write_b32 v253, v47 offset:18672
	ds_write_b32 v253, v48 offset:25344
	ds_write_b32 v253, v49 offset:25872
	ds_write_b32 v253, v50 offset:26400
	ds_write_b32 v253, v51 offset:26928
	ds_write_b32 v253, v52 offset:25408
	ds_write_b32 v253, v53 offset:25936
	ds_write_b32 v253, v54 offset:26464
	ds_write_b32 v253, v55 offset:26992
	ds_write_b32 v253, v56 offset:25472
	ds_write_b32 v253, v57 offset:26000
	ds_write_b32 v253, v58 offset:26528
	ds_write_b32 v253, v59 offset:27056
	ds_write_b32 v253, v60 offset:25536
	ds_write_b32 v253, v61 offset:26064
	ds_write_b32 v253, v62 offset:26592
	ds_write_b32 v253, v63 offset:27120
	ds_write_b32 v253, v64 offset:33792
	ds_write_b32 v253, v65 offset:34320
	ds_write_b32 v253, v66 offset:34848
	ds_write_b32 v253, v67 offset:35376
	ds_write_b32 v253, v68 offset:33856
	ds_write_b32 v253, v69 offset:34384
	ds_write_b32 v253, v70 offset:34912
	ds_write_b32 v253, v71 offset:35440
	ds_write_b32 v253, v72 offset:33920
	ds_write_b32 v253, v73 offset:34448
	ds_write_b32 v253, v74 offset:34976
	ds_write_b32 v253, v75 offset:35504
	ds_write_b32 v253, v76 offset:33984
	ds_write_b32 v253, v77 offset:34512
	ds_write_b32 v253, v78 offset:35040
	ds_write_b32 v253, v79 offset:35568
	ds_write_b32 v253, v80 offset:42240
	ds_write_b32 v253, v81 offset:42768
	ds_write_b32 v253, v82 offset:43296
	ds_write_b32 v253, v83 offset:43824
	ds_write_b32 v253, v84 offset:42304
	ds_write_b32 v253, v85 offset:42832
	ds_write_b32 v253, v86 offset:43360
	ds_write_b32 v253, v87 offset:43888
	ds_write_b32 v253, v88 offset:42368
	ds_write_b32 v253, v89 offset:42896
	ds_write_b32 v253, v90 offset:43424
	ds_write_b32 v253, v91 offset:43952
	ds_write_b32 v253, v92 offset:42432
	ds_write_b32 v253, v93 offset:42960
	ds_write_b32 v253, v94 offset:43488
	ds_write_b32 v253, v95 offset:44016
	ds_write_b32 v253, v96 offset:50688
	ds_write_b32 v253, v97 offset:51216
	ds_write_b32 v253, v98 offset:51744
	ds_write_b32 v253, v99 offset:52272
	ds_write_b32 v253, v100 offset:50752
	ds_write_b32 v253, v101 offset:51280
	ds_write_b32 v253, v102 offset:51808
	ds_write_b32 v253, v103 offset:52336
	ds_write_b32 v253, v104 offset:50816
	ds_write_b32 v253, v105 offset:51344
	ds_write_b32 v253, v106 offset:51872
	ds_write_b32 v253, v107 offset:52400
	ds_write_b32 v253, v108 offset:50880
	ds_write_b32 v253, v109 offset:51408
	ds_write_b32 v253, v110 offset:51936
	ds_write_b32 v253, v111 offset:52464
	ds_write_b32 v253, v112 offset:59136
	ds_write_b32 v253, v113 offset:59664
	ds_write_b32 v253, v114 offset:60192
	ds_write_b32 v253, v115 offset:60720
	ds_write_b32 v253, v116 offset:59200
	ds_write_b32 v253, v117 offset:59728
	ds_write_b32 v253, v118 offset:60256
	ds_write_b32 v253, v119 offset:60784
	ds_write_b32 v253, v120 offset:59264
	ds_write_b32 v253, v121 offset:59792
	ds_write_b32 v253, v122 offset:60320
	ds_write_b32 v253, v123 offset:60848
	ds_write_b32 v253, v124 offset:59328
	ds_write_b32 v253, v125 offset:59856
	ds_write_b32 v253, v126 offset:60384
	ds_write_b32 v253, v127 offset:60912
.LBB0_1740:
	s_or_b64 exec, exec, s[20:21]
	s_lshl_b32 s4, s37, 19
	s_lshl_b32 s20, s38, 20
	s_or_b32 s4, s20, s4
	s_add_u32 s4, s24, s4
	s_addc_u32 s21, s25, 0
	s_lshl_b32 s20, s23, 2
	s_add_u32 s23, s26, s20
	s_addc_u32 s37, s27, 0
	s_lshl_b32 s20, s39, 1
	s_add_u32 s20, s4, s20
	s_addc_u32 s21, s21, 0
	s_lshl_b32 s4, s22, 2
	s_add_u32 s22, s23, s4
	v_ashrrev_i32_e32 v138, 4, v146
	s_addc_u32 s23, s37, 0
	v_ashrrev_i32_e32 v139, 31, v138
	v_lshl_add_u64 v[136:137], v[138:139], 2, s[22:23]
	s_waitcnt lgkmcnt(0)
	s_barrier
	global_load_dword v182, v[136:137], off
	v_lshlrev_b32_e32 v130, 3, v146
	v_and_b32_e32 v130, 0x78, v130
	v_mul_lo_u32 v141, v138, s31
	v_lshl_add_u32 v213, v130, 2, 0
	v_add_u32_e32 v173, v213, v141
	ds_read_b128 v[142:145], v173
	ds_read_b128 v[148:151], v173 offset:16
	v_add_u32_e32 v140, 0x100, v146
	v_lshlrev_b64 v[138:139], 11, v[138:139]
	v_ashrrev_i32_e32 v210, 4, v140
	v_lshlrev_b32_e32 v130, 1, v130
	v_lshl_add_u64 v[138:139], s[20:21], 0, v[138:139]
	v_ashrrev_i32_e32 v211, 31, v210
	v_lshl_add_u64 v[140:141], v[138:139], 0, v[130:131]
	v_lshl_add_u64 v[138:139], v[210:211], 2, s[22:23]
	s_waitcnt vmcnt(0) lgkmcnt(1)
	v_pk_mul_f32 v[142:143], v[142:143], v[182:183] op_sel_hi:[1,0]
	v_pk_mul_f32 v[144:145], v[144:145], v[182:183] op_sel_hi:[1,0]
	s_waitcnt lgkmcnt(0)
	v_pk_mul_f32 v[148:149], v[148:149], v[182:183] op_sel_hi:[1,0]
	v_pk_mul_f32 v[150:151], v[150:151], v[182:183] op_sel_hi:[1,0]
	v_cvt_pk_bf16_f32 v142, v142, v143
	v_cvt_pk_bf16_f32 v143, v144, v145
	v_cvt_pk_bf16_f32 v144, v148, v149
	v_cvt_pk_bf16_f32 v145, v150, v151
	global_store_dwordx4 v[140:141], v[142:145], off
	global_load_dword v182, v[138:139], off
	s_nop 0
	v_add_u32_e32 v142, 0x200, v146
	v_ashrrev_i32_e32 v218, 4, v142
	v_mul_lo_u32 v142, v210, s31
	v_add_u32_e32 v179, v213, v142
	ds_read_b128 v[148:151], v179
	ds_read_b128 v[214:217], v179 offset:16
	v_lshlrev_b64 v[142:143], 11, v[210:211]
	v_lshl_add_u64 v[142:143], s[20:21], 0, v[142:143]
	v_ashrrev_i32_e32 v219, 31, v218
	v_lshl_add_u64 v[144:145], v[142:143], 0, v[130:131]
	v_lshl_add_u64 v[142:143], v[218:219], 2, s[22:23]
	v_add_u32_e32 v146, 0x300, v146
	v_ashrrev_i32_e32 v146, 4, v146
	v_ashrrev_i32_e32 v147, 31, v146
	s_waitcnt vmcnt(0) lgkmcnt(1)
	v_pk_mul_f32 v[148:149], v[148:149], v[182:183] op_sel_hi:[1,0]
	v_pk_mul_f32 v[150:151], v[150:151], v[182:183] op_sel_hi:[1,0]
	s_waitcnt lgkmcnt(0)
	v_pk_mul_f32 v[210:211], v[214:215], v[182:183] op_sel_hi:[1,0]
	v_pk_mul_f32 v[214:215], v[216:217], v[182:183] op_sel_hi:[1,0]
	v_cvt_pk_bf16_f32 v148, v148, v149
	v_cvt_pk_bf16_f32 v149, v150, v151
	v_cvt_pk_bf16_f32 v150, v210, v211
	v_cvt_pk_bf16_f32 v151, v214, v215
	global_store_dwordx4 v[144:145], v[148:151], off
	global_load_dword v182, v[142:143], off
	s_nop 0
	v_mul_lo_u32 v148, v218, s31
	v_add_u32_e32 v209, v213, v148
	v_lshlrev_b64 v[148:149], 11, v[218:219]
	ds_read_b128 v[214:217], v209
	ds_read_b128 v[218:221], v209 offset:16
	v_lshl_add_u64 v[148:149], s[20:21], 0, v[148:149]
	v_lshl_add_u64 v[150:151], v[148:149], 0, v[130:131]
	v_lshl_add_u64 v[148:149], v[146:147], 2, s[22:23]
	s_waitcnt vmcnt(0) lgkmcnt(1)
	v_pk_mul_f32 v[210:211], v[214:215], v[182:183] op_sel_hi:[1,0]
	v_pk_mul_f32 v[216:217], v[216:217], v[182:183] op_sel_hi:[1,0]
	s_waitcnt lgkmcnt(0)
	v_pk_mul_f32 v[218:219], v[218:219], v[182:183] op_sel_hi:[1,0]
	v_pk_mul_f32 v[220:221], v[220:221], v[182:183] op_sel_hi:[1,0]
	v_cvt_pk_bf16_f32 v214, v210, v211
	v_cvt_pk_bf16_f32 v215, v216, v217
	v_cvt_pk_bf16_f32 v216, v218, v219
	v_cvt_pk_bf16_f32 v217, v220, v221
	global_store_dwordx4 v[150:151], v[214:217], off
	global_load_dword v210, v[148:149], off
	v_mul_lo_u32 v182, v146, s31
	v_add_u32_e32 v182, v213, v182
	ds_read_b128 v[214:217], v182
	ds_read_b128 v[218:221], v182 offset:16
	v_lshlrev_b64 v[146:147], 11, v[146:147]
	v_lshl_add_u64 v[146:147], s[20:21], 0, v[146:147]
	v_lshl_add_u64 v[146:147], v[146:147], 0, v[130:131]
	s_waitcnt vmcnt(0) lgkmcnt(1)
	v_pk_mul_f32 v[222:223], v[214:215], v[210:211] op_sel_hi:[1,0]
	v_pk_mul_f32 v[214:215], v[216:217], v[210:211] op_sel_hi:[1,0]
	s_waitcnt lgkmcnt(0)
	v_pk_mul_f32 v[218:219], v[218:219], v[210:211] op_sel_hi:[1,0]
	v_pk_mul_f32 v[210:211], v[220:221], v[210:211] op_sel_hi:[1,0]
	v_cvt_pk_bf16_f32 v216, v218, v219
	v_cvt_pk_bf16_f32 v217, v210, v211
	v_cvt_pk_bf16_f32 v215, v214, v215
	v_cvt_pk_bf16_f32 v214, v222, v223
	global_store_dwordx4 v[146:147], v[214:217], off
	global_load_dword v130, v[136:137], off offset:256
	ds_read_b128 v[214:217], v173 offset:33792
	ds_read_b128 v[218:221], v173 offset:33808
	v_add_co_u32_e32 v210, vcc, s34, v140
	s_waitcnt vmcnt(0) lgkmcnt(1)
	v_pk_mul_f32 v[214:215], v[214:215], v[130:131] op_sel_hi:[1,0]
	v_pk_mul_f32 v[216:217], v[216:217], v[130:131] op_sel_hi:[1,0]
	s_waitcnt lgkmcnt(0)
	v_pk_mul_f32 v[218:219], v[218:219], v[130:131] op_sel_hi:[1,0]
	v_pk_mul_f32 v[220:221], v[220:221], v[130:131] op_sel_hi:[1,0]
	v_addc_co_u32_e32 v211, vcc, 0, v141, vcc
	v_cvt_pk_bf16_f32 v214, v214, v215
	v_cvt_pk_bf16_f32 v215, v216, v217
	v_cvt_pk_bf16_f32 v216, v218, v219
	v_cvt_pk_bf16_f32 v217, v220, v221
	global_store_dwordx4 v[210:211], v[214:217], off
	global_load_dword v130, v[138:139], off offset:256
	ds_read_b128 v[214:217], v179 offset:33792
	ds_read_b128 v[218:221], v179 offset:33808
	v_add_co_u32_e32 v210, vcc, s34, v144
	s_waitcnt vmcnt(0) lgkmcnt(1)
	v_pk_mul_f32 v[214:215], v[214:215], v[130:131] op_sel_hi:[1,0]
	v_pk_mul_f32 v[216:217], v[216:217], v[130:131] op_sel_hi:[1,0]
	s_waitcnt lgkmcnt(0)
	v_pk_mul_f32 v[218:219], v[218:219], v[130:131] op_sel_hi:[1,0]
	v_pk_mul_f32 v[220:221], v[220:221], v[130:131] op_sel_hi:[1,0]
	v_addc_co_u32_e32 v211, vcc, 0, v145, vcc
	v_cvt_pk_bf16_f32 v214, v214, v215
	v_cvt_pk_bf16_f32 v215, v216, v217
	v_cvt_pk_bf16_f32 v216, v218, v219
	v_cvt_pk_bf16_f32 v217, v220, v221
	global_store_dwordx4 v[210:211], v[214:217], off
	global_load_dword v130, v[142:143], off offset:256
	ds_read_b128 v[214:217], v209 offset:33792
	ds_read_b128 v[218:221], v209 offset:33808
	v_add_co_u32_e32 v210, vcc, s34, v150
	s_waitcnt vmcnt(0) lgkmcnt(1)
	v_pk_mul_f32 v[214:215], v[214:215], v[130:131] op_sel_hi:[1,0]
	v_pk_mul_f32 v[216:217], v[216:217], v[130:131] op_sel_hi:[1,0]
	s_waitcnt lgkmcnt(0)
	v_pk_mul_f32 v[218:219], v[218:219], v[130:131] op_sel_hi:[1,0]
	v_pk_mul_f32 v[220:221], v[220:221], v[130:131] op_sel_hi:[1,0]
	v_addc_co_u32_e32 v211, vcc, 0, v151, vcc
	v_cvt_pk_bf16_f32 v214, v214, v215
	v_cvt_pk_bf16_f32 v215, v216, v217
	v_cvt_pk_bf16_f32 v216, v218, v219
	v_cvt_pk_bf16_f32 v217, v220, v221
	global_store_dwordx4 v[210:211], v[214:217], off
	global_load_dword v130, v[148:149], off offset:256
	ds_read_b128 v[214:217], v182 offset:33792
	ds_read_b128 v[218:221], v182 offset:33808
	v_add_co_u32_e32 v210, vcc, 0x20000, v146
	s_waitcnt vmcnt(0) lgkmcnt(1)
	v_pk_mul_f32 v[222:223], v[214:215], v[130:131] op_sel_hi:[1,0]
	v_pk_mul_f32 v[214:215], v[216:217], v[130:131] op_sel_hi:[1,0]
	s_waitcnt lgkmcnt(0)
	v_pk_mul_f32 v[218:219], v[218:219], v[130:131] op_sel_hi:[1,0]
	v_pk_mul_f32 v[216:217], v[220:221], v[130:131] op_sel_hi:[1,0]
	v_addc_co_u32_e32 v211, vcc, 0, v147, vcc
	v_cvt_pk_bf16_f32 v217, v216, v217
	v_cvt_pk_bf16_f32 v216, v218, v219
	v_cvt_pk_bf16_f32 v215, v214, v215
	v_cvt_pk_bf16_f32 v214, v222, v223
	global_store_dwordx4 v[210:211], v[214:217], off
	s_barrier
	s_and_saveexec_b64 s[20:21], s[8:9]
	s_cbranch_execz .LBB0_1735
	v_and_b32_e32 v254, 63, v180
	v_lshrrev_b32_e32 v253, 4, v254
	v_mul_u32_u24_e32 v253, 0x840, v253
	v_and_b32_e32 v254, 15, v254
	v_lshl_add_u32 v253, v254, 2, v253
	v_and_b32_e32 v254, 64, v180
	v_lshl_add_u32 v253, v254, 2, v253
	ds_write_b32 v253, v0 offset:0
	ds_write_b32 v253, v1 offset:528
	ds_write_b32 v253, v2 offset:1056
	ds_write_b32 v253, v3 offset:1584
	ds_write_b32 v253, v4 offset:64
	ds_write_b32 v253, v5 offset:592
	ds_write_b32 v253, v6 offset:1120
	ds_write_b32 v253, v7 offset:1648
	ds_write_b32 v253, v8 offset:128
	ds_write_b32 v253, v9 offset:656
	ds_write_b32 v253, v10 offset:1184
	ds_write_b32 v253, v11 offset:1712
	ds_write_b32 v253, v12 offset:192
	ds_write_b32 v253, v13 offset:720
	ds_write_b32 v253, v14 offset:1248
	ds_write_b32 v253, v15 offset:1776
	ds_write_b32 v253, v16 offset:8448
	ds_write_b32 v253, v17 offset:8976
	ds_write_b32 v253, v18 offset:9504
	ds_write_b32 v253, v19 offset:10032
	ds_write_b32 v253, v20 offset:8512
	ds_write_b32 v253, v21 offset:9040
	ds_write_b32 v253, v22 offset:9568
	ds_write_b32 v253, v23 offset:10096
	ds_write_b32 v253, v24 offset:8576
	ds_write_b32 v253, v25 offset:9104
	ds_write_b32 v253, v26 offset:9632
	ds_write_b32 v253, v27 offset:10160
	ds_write_b32 v253, v28 offset:8640
	ds_write_b32 v253, v29 offset:9168
	ds_write_b32 v253, v30 offset:9696
	ds_write_b32 v253, v31 offset:10224
	ds_write_b32 v253, v32 offset:16896
	ds_write_b32 v253, v33 offset:17424
	ds_write_b32 v253, v34 offset:17952
	ds_write_b32 v253, v35 offset:18480
	ds_write_b32 v253, v36 offset:16960
	ds_write_b32 v253, v37 offset:17488
	ds_write_b32 v253, v38 offset:18016
	ds_write_b32 v253, v39 offset:18544
	ds_write_b32 v253, v40 offset:17024
	ds_write_b32 v253, v41 offset:17552
	ds_write_b32 v253, v42 offset:18080
	ds_write_b32 v253, v43 offset:18608
	ds_write_b32 v253, v44 offset:17088
	ds_write_b32 v253, v45 offset:17616
	ds_write_b32 v253, v46 offset:18144
	ds_write_b32 v253, v47 offset:18672
	ds_write_b32 v253, v48 offset:25344
	ds_write_b32 v253, v49 offset:25872
	ds_write_b32 v253, v50 offset:26400
	ds_write_b32 v253, v51 offset:26928
	ds_write_b32 v253, v52 offset:25408
	ds_write_b32 v253, v53 offset:25936
	ds_write_b32 v253, v54 offset:26464
	ds_write_b32 v253, v55 offset:26992
	ds_write_b32 v253, v56 offset:25472
	ds_write_b32 v253, v57 offset:26000
	ds_write_b32 v253, v58 offset:26528
	ds_write_b32 v253, v59 offset:27056
	ds_write_b32 v253, v60 offset:25536
	ds_write_b32 v253, v61 offset:26064
	ds_write_b32 v253, v62 offset:26592
	ds_write_b32 v253, v63 offset:27120
	ds_write_b32 v253, v64 offset:33792
	ds_write_b32 v253, v65 offset:34320
	ds_write_b32 v253, v66 offset:34848
	ds_write_b32 v253, v67 offset:35376
	ds_write_b32 v253, v68 offset:33856
	ds_write_b32 v253, v69 offset:34384
	ds_write_b32 v253, v70 offset:34912
	ds_write_b32 v253, v71 offset:35440
	ds_write_b32 v253, v72 offset:33920
	ds_write_b32 v253, v73 offset:34448
	ds_write_b32 v253, v74 offset:34976
	ds_write_b32 v253, v75 offset:35504
	ds_write_b32 v253, v76 offset:33984
	ds_write_b32 v253, v77 offset:34512
	ds_write_b32 v253, v78 offset:35040
	ds_write_b32 v253, v79 offset:35568
	ds_write_b32 v253, v80 offset:42240
	ds_write_b32 v253, v81 offset:42768
	ds_write_b32 v253, v82 offset:43296
	ds_write_b32 v253, v83 offset:43824
	ds_write_b32 v253, v84 offset:42304
	ds_write_b32 v253, v85 offset:42832
	ds_write_b32 v253, v86 offset:43360
	ds_write_b32 v253, v87 offset:43888
	ds_write_b32 v253, v88 offset:42368
	ds_write_b32 v253, v89 offset:42896
	ds_write_b32 v253, v90 offset:43424
	ds_write_b32 v253, v91 offset:43952
	ds_write_b32 v253, v92 offset:42432
	ds_write_b32 v253, v93 offset:42960
	ds_write_b32 v253, v94 offset:43488
	ds_write_b32 v253, v95 offset:44016
	ds_write_b32 v253, v96 offset:50688
	ds_write_b32 v253, v97 offset:51216
	ds_write_b32 v253, v98 offset:51744
	ds_write_b32 v253, v99 offset:52272
	ds_write_b32 v253, v100 offset:50752
	ds_write_b32 v253, v101 offset:51280
	ds_write_b32 v253, v102 offset:51808
	ds_write_b32 v253, v103 offset:52336
	ds_write_b32 v253, v104 offset:50816
	ds_write_b32 v253, v105 offset:51344
	ds_write_b32 v253, v106 offset:51872
	ds_write_b32 v253, v107 offset:52400
	ds_write_b32 v253, v108 offset:50880
	ds_write_b32 v253, v109 offset:51408
	ds_write_b32 v253, v110 offset:51936
	ds_write_b32 v253, v111 offset:52464
	ds_write_b32 v253, v112 offset:59136
	ds_write_b32 v253, v113 offset:59664
	ds_write_b32 v253, v114 offset:60192
	ds_write_b32 v253, v115 offset:60720
	ds_write_b32 v253, v116 offset:59200
	ds_write_b32 v253, v117 offset:59728
	ds_write_b32 v253, v118 offset:60256
	ds_write_b32 v253, v119 offset:60784
	ds_write_b32 v253, v120 offset:59264
	ds_write_b32 v253, v121 offset:59792
	ds_write_b32 v253, v122 offset:60320
	ds_write_b32 v253, v123 offset:60848
	ds_write_b32 v253, v124 offset:59328
	ds_write_b32 v253, v125 offset:59856
	ds_write_b32 v253, v126 offset:60384
	ds_write_b32 v253, v127 offset:60912
	s_branch .LBB0_1735
